# baseline (speedup 1.0000x reference)
; #define STAGE(P, RS, SOFF, OFF, kt) do { const int _so = (SOFF) + (kt) * (BK * 2); \
;     _Pragma("unroll") for (int _i = 0; _i < 2; ++_i) { \
;       __builtin_amdgcn_raw_ptr_buffer_load_lds(RS, (__attribute__((address_space(3))) void*)((P) + wave * 1024 + _i * 8192), 16, OFF[_i], _so, 0, 0); } } while (0)
; #define LDA(dst, b, h) _Pragma("unroll") for (int m = 0; m < 4; ++m) _Pragma("unroll") for (int k = 0; k < 2; ++k) \
;     dst[m][k] = *reinterpret_cast<const bf16x8*>(SA(b, h) + lds_byte(wr * 64 + m * 16 + fr, k * 32 + fq * 8))
; #define LDB(dst, b, h) _Pragma("unroll") for (int n = 0; n < 2; ++n) _Pragma("unroll") for (int k = 0; k < 2; ++k) \
;     dst[n][k] = *reinterpret_cast<const bf16x8*>(SB(b, h) + lds_byte(wc * 32 + n * 16 + fr, k * 32 + fq * 8))
; #define WAIT_V(n) asm volatile("s_waitcnt vmcnt(" #n ")" ::: "memory")
; #define WAIT_L(n) asm volatile("s_waitcnt lgkmcnt(" #n ")" ::: "memory")
; #define BAR __builtin_amdgcn_s_barrier()
; #define SCHED __builtin_amdgcn_sched_barrier(0)
;     ...
;       LDB(B0, 0, 0); SCHED; LDA(At, 0, 0); STAGE(SA(1, 1), rsA, sA1, offA, t + 1);
;       WAIT_L(8); BAR; WAIT_L(0); MMA(0, 0, At, B0); BAR; SCHED;
;       LDB(B1, 0, 1); STAGE(SB(0, 0), rsB, sB0, offB, t + 2);
;       BAR; WAIT_L(0); MMA(0, 1, At, B1); BAR;
;       LDA(At, 0, 1); STAGE(SA(0, 0), rsA, sA0, offA, t + 2);
;       BAR; WAIT_L(0); MMA(1, 0, At, B0); BAR; SCHED;
;       STAGE(SB(0, 1), rsB, sB1, offB, t + 2);
;       WAIT_V(6); BAR; MMA(1, 1, At, B1); BAR;
.LBB0_95:
	ds_read_b128 v[154:157], v149
	ds_read_b128 v[158:161], v150
	ds_read_b128 v[162:165], v151
	ds_read_b128 v[166:169], v152
	s_add_i32 s43, s37, s15
	s_add_i32 s10, s43, 0x80
	s_mov_b32 m0, s30
	ds_read_b128 v[170:173], v131
	ds_read_b128 v[174:177], v131 offset:1024
	ds_read_b128 v[178:181], v134
	ds_read_b128 v[182:185], v134 offset:1024
	ds_read_b128 v[186:189], v133
	ds_read_b128 v[190:193], v133 offset:1024
	ds_read_b128 v[194:197], v132
	ds_read_b128 v[198:201], v132 offset:1024
	buffer_load_dwordx4 v143, s[4:7], s10 offen lds
	s_mov_b32 m0, s31
	s_nop 0
	buffer_load_dwordx4 v144, s[4:7], s10 offen lds
	s_waitcnt lgkmcnt(8)
	s_barrier
	s_waitcnt lgkmcnt(0)
	v_mfma_f32_16x16x32_bf16 v[124:127], v[154:157], v[170:173], v[124:127]
	v_mfma_f32_16x16x32_bf16 v[120:123], v[162:165], v[170:173], v[120:123]
	v_mfma_f32_16x16x32_bf16 v[116:119], v[154:157], v[178:181], v[116:119]
	v_mfma_f32_16x16x32_bf16 v[112:115], v[162:165], v[178:181], v[112:115]
	v_mfma_f32_16x16x32_bf16 v[108:111], v[154:157], v[186:189], v[108:111]
	v_mfma_f32_16x16x32_bf16 v[104:107], v[162:165], v[186:189], v[104:107]
	v_mfma_f32_16x16x32_bf16 v[100:103], v[154:157], v[194:197], v[100:103]
	v_mfma_f32_16x16x32_bf16 v[96:99], v[162:165], v[194:197], v[96:99]
	v_mfma_f32_16x16x32_bf16 v[124:127], v[158:161], v[174:177], v[124:127]
	v_mfma_f32_16x16x32_bf16 v[120:123], v[166:169], v[174:177], v[120:123]
	v_mfma_f32_16x16x32_bf16 v[116:119], v[158:161], v[182:185], v[116:119]
	v_mfma_f32_16x16x32_bf16 v[112:115], v[166:169], v[182:185], v[112:115]
	v_mfma_f32_16x16x32_bf16 v[108:111], v[158:161], v[190:193], v[108:111]
	v_mfma_f32_16x16x32_bf16 v[104:107], v[166:169], v[190:193], v[104:107]
	v_mfma_f32_16x16x32_bf16 v[100:103], v[158:161], v[198:201], v[100:103]
	v_mfma_f32_16x16x32_bf16 v[96:99], v[166:169], v[198:201], v[96:99]
	s_barrier
	s_add_i32 s44, s39, s15
	s_add_i32 s45, s44, 0x100
	s_mov_b32 s10, s6
	s_mov_b32 s11, s7
	s_mov_b32 m0, s1
	ds_read_b128 v[202:205], v145
	ds_read_b128 v[206:209], v146
	ds_read_b128 v[210:213], v147
	ds_read_b128 v[214:217], v148
	buffer_load_dwordx4 v143, s[8:11], s45 offen lds
	s_mov_b32 m0, s3
	s_nop 0
	buffer_load_dwordx4 v144, s[8:11], s45 offen lds
	s_barrier
	s_waitcnt lgkmcnt(0)
	v_mfma_f32_16x16x32_bf16 v[92:95], v[202:205], v[170:173], v[92:95]
	v_mfma_f32_16x16x32_bf16 v[88:91], v[210:213], v[170:173], v[88:91]
	v_mfma_f32_16x16x32_bf16 v[84:87], v[202:205], v[178:181], v[84:87]
	v_mfma_f32_16x16x32_bf16 v[80:83], v[210:213], v[178:181], v[80:83]
	v_mfma_f32_16x16x32_bf16 v[76:79], v[202:205], v[186:189], v[76:79]
	v_mfma_f32_16x16x32_bf16 v[72:75], v[210:213], v[186:189], v[72:75]
	v_mfma_f32_16x16x32_bf16 v[68:71], v[202:205], v[194:197], v[68:71]
	v_mfma_f32_16x16x32_bf16 v[64:67], v[210:213], v[194:197], v[64:67]
	v_mfma_f32_16x16x32_bf16 v[92:95], v[206:209], v[174:177], v[92:95]
	v_mfma_f32_16x16x32_bf16 v[88:91], v[214:217], v[174:177], v[88:91]
	v_mfma_f32_16x16x32_bf16 v[84:87], v[206:209], v[182:185], v[84:87]
	v_mfma_f32_16x16x32_bf16 v[80:83], v[214:217], v[182:185], v[80:83]
	v_mfma_f32_16x16x32_bf16 v[76:79], v[206:209], v[190:193], v[76:79]
	v_mfma_f32_16x16x32_bf16 v[72:75], v[214:217], v[190:193], v[72:75]
	v_mfma_f32_16x16x32_bf16 v[68:71], v[206:209], v[198:201], v[68:71]
	v_mfma_f32_16x16x32_bf16 v[64:67], v[214:217], v[198:201], v[64:67]
	s_barrier
	s_add_i32 s45, s38, s15
	s_add_i32 s46, s45, 0x100
	s_mov_b32 m0, s0
	ds_read_b128 v[170:173], v131 offset:16384
	ds_read_b128 v[174:177], v131 offset:17408
	ds_read_b128 v[178:181], v134 offset:16384
	ds_read_b128 v[182:185], v134 offset:17408
	ds_read_b128 v[186:189], v133 offset:16384
	ds_read_b128 v[190:193], v133 offset:17408
	ds_read_b128 v[194:197], v132 offset:16384
	ds_read_b128 v[198:201], v132 offset:17408
	buffer_load_dwordx4 v143, s[4:7], s46 offen lds
	s_mov_b32 m0, s18
	s_nop 0
	buffer_load_dwordx4 v144, s[4:7], s46 offen lds
	s_barrier
	s_waitcnt lgkmcnt(0)
	v_mfma_f32_16x16x32_bf16 v[60:63], v[154:157], v[170:173], v[60:63]
	v_mfma_f32_16x16x32_bf16 v[56:59], v[162:165], v[170:173], v[56:59]
	v_mfma_f32_16x16x32_bf16 v[52:55], v[154:157], v[178:181], v[52:55]
	v_mfma_f32_16x16x32_bf16 v[48:51], v[162:165], v[178:181], v[48:51]
	v_mfma_f32_16x16x32_bf16 v[44:47], v[154:157], v[186:189], v[44:47]
	v_mfma_f32_16x16x32_bf16 v[40:43], v[162:165], v[186:189], v[40:43]
	v_mfma_f32_16x16x32_bf16 v[36:39], v[154:157], v[194:197], v[36:39]
	v_mfma_f32_16x16x32_bf16 v[32:35], v[162:165], v[194:197], v[32:35]
	v_mfma_f32_16x16x32_bf16 v[60:63], v[158:161], v[174:177], v[60:63]
	v_mfma_f32_16x16x32_bf16 v[56:59], v[166:169], v[174:177], v[56:59]
	v_mfma_f32_16x16x32_bf16 v[52:55], v[158:161], v[182:185], v[52:55]
	v_mfma_f32_16x16x32_bf16 v[48:51], v[166:169], v[182:185], v[48:51]
	v_mfma_f32_16x16x32_bf16 v[44:47], v[158:161], v[190:193], v[44:47]
	v_mfma_f32_16x16x32_bf16 v[40:43], v[166:169], v[190:193], v[40:43]
	v_mfma_f32_16x16x32_bf16 v[36:39], v[158:161], v[198:201], v[36:39]
	v_mfma_f32_16x16x32_bf16 v[32:35], v[166:169], v[198:201], v[32:35]
	s_barrier
	s_add_i32 s46, s40, s15
	s_add_i32 s47, s46, 0x100
	s_mov_b32 m0, s19
	s_nop 0
	buffer_load_dwordx4 v143, s[8:11], s47 offen lds
	s_mov_b32 m0, s20
	s_nop 0
	buffer_load_dwordx4 v144, s[8:11], s47 offen lds
	s_waitcnt vmcnt(6)
	s_barrier
; #define STAGE(P, RS, SOFF, OFF, kt) do { const int _so = (SOFF) + (kt) * (BK * 2); \
;     _Pragma("unroll") for (int _i = 0; _i < 2; ++_i) { \
;       __builtin_amdgcn_raw_ptr_buffer_load_lds(RS, (__attribute__((address_space(3))) void*)((P) + wave * 1024 + _i * 8192), 16, OFF[_i], _so, 0, 0); } } while (0)
; #define LDA(dst, b, h) _Pragma("unroll") for (int m = 0; m < 4; ++m) _Pragma("unroll") for (int k = 0; k < 2; ++k) \
;     dst[m][k] = *reinterpret_cast<const bf16x8*>(SA(b, h) + lds_byte(wr * 64 + m * 16 + fr, k * 32 + fq * 8))
; #define LDB(dst, b, h) _Pragma("unroll") for (int n = 0; n < 2; ++n) _Pragma("unroll") for (int k = 0; k < 2; ++k) \
;     dst[n][k] = *reinterpret_cast<const bf16x8*>(SB(b, h) + lds_byte(wc * 32 + n * 16 + fr, k * 32 + fq * 8))
; #define WAIT_V(n) asm volatile("s_waitcnt vmcnt(" #n ")" ::: "memory")
; #define WAIT_L(n) asm volatile("s_waitcnt lgkmcnt(" #n ")" ::: "memory")
; #define BAR __builtin_amdgcn_s_barrier()
; #define SCHED __builtin_amdgcn_sched_barrier(0)
;     ...
;       WAIT_V(6); BAR; MMA(1, 1, At, B1); BAR;
;       LDB(B0, 1, 0); SCHED; LDA(At, 1, 0); STAGE(SA(0, 1), rsA, sA1, offA, t + 2);
;       WAIT_L(8); BAR; WAIT_L(0); MMA(0, 0, At, B0); BAR; SCHED;
;       LDB(B1, 1, 1); STAGE(SB(1, 0), rsB, sB0, offB, t + 3);
;       BAR; WAIT_L(0); MMA(0, 1, At, B1); BAR;
;       LDA(At, 1, 1); STAGE(SA(1, 0), rsA, sA0, offA, t + 3);
;       BAR; WAIT_L(0); MMA(1, 0, At, B0); BAR; SCHED;
	v_mfma_f32_16x16x32_bf16 v[28:31], v[202:205], v[170:173], v[28:31]
	v_mfma_f32_16x16x32_bf16 v[24:27], v[210:213], v[170:173], v[24:27]
	v_mfma_f32_16x16x32_bf16 v[20:23], v[202:205], v[178:181], v[20:23]
	v_mfma_f32_16x16x32_bf16 v[16:19], v[210:213], v[178:181], v[16:19]
	v_mfma_f32_16x16x32_bf16 v[12:15], v[202:205], v[186:189], v[12:15]
	v_mfma_f32_16x16x32_bf16 v[8:11], v[210:213], v[186:189], v[8:11]
	v_mfma_f32_16x16x32_bf16 v[4:7], v[202:205], v[194:197], v[4:7]
	v_mfma_f32_16x16x32_bf16 v[0:3], v[210:213], v[194:197], v[0:3]
	v_mfma_f32_16x16x32_bf16 v[28:31], v[206:209], v[174:177], v[28:31]
	v_mfma_f32_16x16x32_bf16 v[24:27], v[214:217], v[174:177], v[24:27]
	v_mfma_f32_16x16x32_bf16 v[20:23], v[206:209], v[182:185], v[20:23]
	v_mfma_f32_16x16x32_bf16 v[16:19], v[214:217], v[182:185], v[16:19]
	v_mfma_f32_16x16x32_bf16 v[12:15], v[206:209], v[190:193], v[12:15]
	v_mfma_f32_16x16x32_bf16 v[8:11], v[214:217], v[190:193], v[8:11]
	v_mfma_f32_16x16x32_bf16 v[4:7], v[206:209], v[198:201], v[4:7]
	v_mfma_f32_16x16x32_bf16 v[0:3], v[214:217], v[198:201], v[0:3]
	s_barrier
	ds_read_b128 v[154:157], v139
	ds_read_b128 v[158:161], v140
	ds_read_b128 v[162:165], v141
	ds_read_b128 v[166:169], v142
	s_addk_i32 s43, 0x100
	s_mov_b32 m0, s21
	ds_read_b128 v[170:173], v131 offset:32768
	ds_read_b128 v[174:177], v131 offset:33792
	ds_read_b128 v[178:181], v134 offset:32768
	ds_read_b128 v[182:185], v134 offset:33792
	ds_read_b128 v[186:189], v133 offset:32768
	ds_read_b128 v[190:193], v133 offset:33792
	ds_read_b128 v[194:197], v132 offset:32768
	ds_read_b128 v[198:201], v132 offset:33792
	buffer_load_dwordx4 v143, s[4:7], s43 offen lds
	s_mov_b32 m0, s22
	s_nop 0
	buffer_load_dwordx4 v144, s[4:7], s43 offen lds
	s_waitcnt lgkmcnt(8)
	s_barrier
	s_waitcnt lgkmcnt(0)
	v_mfma_f32_16x16x32_bf16 v[124:127], v[154:157], v[170:173], v[124:127]
	v_mfma_f32_16x16x32_bf16 v[120:123], v[162:165], v[170:173], v[120:123]
	v_mfma_f32_16x16x32_bf16 v[116:119], v[154:157], v[178:181], v[116:119]
	v_mfma_f32_16x16x32_bf16 v[112:115], v[162:165], v[178:181], v[112:115]
	v_mfma_f32_16x16x32_bf16 v[108:111], v[154:157], v[186:189], v[108:111]
	v_mfma_f32_16x16x32_bf16 v[104:107], v[162:165], v[186:189], v[104:107]
	v_mfma_f32_16x16x32_bf16 v[100:103], v[154:157], v[194:197], v[100:103]
	v_mfma_f32_16x16x32_bf16 v[96:99], v[162:165], v[194:197], v[96:99]
	v_mfma_f32_16x16x32_bf16 v[124:127], v[158:161], v[174:177], v[124:127]
	v_mfma_f32_16x16x32_bf16 v[120:123], v[166:169], v[174:177], v[120:123]
	v_mfma_f32_16x16x32_bf16 v[116:119], v[158:161], v[182:185], v[116:119]
	v_mfma_f32_16x16x32_bf16 v[112:115], v[166:169], v[182:185], v[112:115]
	v_mfma_f32_16x16x32_bf16 v[108:111], v[158:161], v[190:193], v[108:111]
	v_mfma_f32_16x16x32_bf16 v[104:107], v[166:169], v[190:193], v[104:107]
	v_mfma_f32_16x16x32_bf16 v[100:103], v[158:161], v[198:201], v[100:103]
	v_mfma_f32_16x16x32_bf16 v[96:99], v[166:169], v[198:201], v[96:99]
	s_barrier
	s_addk_i32 s44, 0x180
	s_mov_b32 m0, s23
	ds_read_b128 v[202:205], v135
	ds_read_b128 v[206:209], v136
	ds_read_b128 v[210:213], v137
	ds_read_b128 v[214:217], v138
	buffer_load_dwordx4 v143, s[8:11], s44 offen lds
	s_mov_b32 m0, s24
	s_nop 0
	buffer_load_dwordx4 v144, s[8:11], s44 offen lds
	s_barrier
	s_waitcnt lgkmcnt(0)
	v_mfma_f32_16x16x32_bf16 v[92:95], v[202:205], v[170:173], v[92:95]
	v_mfma_f32_16x16x32_bf16 v[88:91], v[210:213], v[170:173], v[88:91]
	v_mfma_f32_16x16x32_bf16 v[84:87], v[202:205], v[178:181], v[84:87]
	v_mfma_f32_16x16x32_bf16 v[80:83], v[210:213], v[178:181], v[80:83]
	v_mfma_f32_16x16x32_bf16 v[76:79], v[202:205], v[186:189], v[76:79]
	v_mfma_f32_16x16x32_bf16 v[72:75], v[210:213], v[186:189], v[72:75]
	v_mfma_f32_16x16x32_bf16 v[68:71], v[202:205], v[194:197], v[68:71]
	v_mfma_f32_16x16x32_bf16 v[64:67], v[210:213], v[194:197], v[64:67]
	v_mfma_f32_16x16x32_bf16 v[92:95], v[206:209], v[174:177], v[92:95]
	v_mfma_f32_16x16x32_bf16 v[88:91], v[214:217], v[174:177], v[88:91]
	v_mfma_f32_16x16x32_bf16 v[84:87], v[206:209], v[182:185], v[84:87]
	v_mfma_f32_16x16x32_bf16 v[80:83], v[214:217], v[182:185], v[80:83]
	v_mfma_f32_16x16x32_bf16 v[76:79], v[206:209], v[190:193], v[76:79]
	v_mfma_f32_16x16x32_bf16 v[72:75], v[214:217], v[190:193], v[72:75]
	v_mfma_f32_16x16x32_bf16 v[68:71], v[206:209], v[198:201], v[68:71]
	v_mfma_f32_16x16x32_bf16 v[64:67], v[214:217], v[198:201], v[64:67]
	s_barrier
	s_addk_i32 s45, 0x180
	s_mov_b32 m0, s25
	ds_read_b128 v[170:173], v131 offset:49152
	ds_read_b128 v[174:177], v131 offset:50176
	ds_read_b128 v[178:181], v134 offset:49152
	ds_read_b128 v[182:185], v134 offset:50176
	ds_read_b128 v[186:189], v133 offset:49152
	ds_read_b128 v[190:193], v133 offset:50176
	ds_read_b128 v[194:197], v132 offset:49152
	ds_read_b128 v[198:201], v132 offset:50176
	buffer_load_dwordx4 v143, s[4:7], s45 offen lds
	s_mov_b32 m0, s26
	s_nop 0
	buffer_load_dwordx4 v144, s[4:7], s45 offen lds
	s_barrier
	s_waitcnt lgkmcnt(0)
	v_mfma_f32_16x16x32_bf16 v[60:63], v[154:157], v[170:173], v[60:63]
	v_mfma_f32_16x16x32_bf16 v[56:59], v[162:165], v[170:173], v[56:59]
	v_mfma_f32_16x16x32_bf16 v[52:55], v[154:157], v[178:181], v[52:55]
	v_mfma_f32_16x16x32_bf16 v[48:51], v[162:165], v[178:181], v[48:51]
	v_mfma_f32_16x16x32_bf16 v[44:47], v[154:157], v[186:189], v[44:47]
	v_mfma_f32_16x16x32_bf16 v[40:43], v[162:165], v[186:189], v[40:43]
	v_mfma_f32_16x16x32_bf16 v[36:39], v[154:157], v[194:197], v[36:39]
	v_mfma_f32_16x16x32_bf16 v[32:35], v[162:165], v[194:197], v[32:35]
	v_mfma_f32_16x16x32_bf16 v[60:63], v[158:161], v[174:177], v[60:63]
	v_mfma_f32_16x16x32_bf16 v[56:59], v[166:169], v[174:177], v[56:59]
	v_mfma_f32_16x16x32_bf16 v[52:55], v[158:161], v[182:185], v[52:55]
	v_mfma_f32_16x16x32_bf16 v[48:51], v[166:169], v[182:185], v[48:51]
	v_mfma_f32_16x16x32_bf16 v[44:47], v[158:161], v[190:193], v[44:47]
	v_mfma_f32_16x16x32_bf16 v[40:43], v[166:169], v[190:193], v[40:43]
	v_mfma_f32_16x16x32_bf16 v[36:39], v[158:161], v[198:201], v[36:39]
	v_mfma_f32_16x16x32_bf16 v[32:35], v[166:169], v[198:201], v[32:35]
	s_barrier
; #define STAGE(P, RS, SOFF, OFF, kt) do { const int _so = (SOFF) + (kt) * (BK * 2); \
;     _Pragma("unroll") for (int _i = 0; _i < 2; ++_i) { \
;       __builtin_amdgcn_raw_ptr_buffer_load_lds(RS, (__attribute__((address_space(3))) void*)((P) + wave * 1024 + _i * 8192), 16, OFF[_i], _so, 0, 0); } } while (0)
; #define LDA(dst, b, h) _Pragma("unroll") for (int m = 0; m < 4; ++m) _Pragma("unroll") for (int k = 0; k < 2; ++k) \
;     dst[m][k] = *reinterpret_cast<const bf16x8*>(SA(b, h) + lds_byte(wr * 64 + m * 16 + fr, k * 32 + fq * 8))
; #define LDB(dst, b, h) _Pragma("unroll") for (int n = 0; n < 2; ++n) _Pragma("unroll") for (int k = 0; k < 2; ++k) \
;     dst[n][k] = *reinterpret_cast<const bf16x8*>(SB(b, h) + lds_byte(wc * 32 + n * 16 + fr, k * 32 + fq * 8))
; #define WAIT_V(n) asm volatile("s_waitcnt vmcnt(" #n ")" ::: "memory")
; #define WAIT_L(n) asm volatile("s_waitcnt lgkmcnt(" #n ")" ::: "memory")
; #define BAR __builtin_amdgcn_s_barrier()
;     ...
;       STAGE(SB(1, 1), rsB, sB1, offB, t + 3);
;       WAIT_V(6); BAR; MMA(1, 1, At, B1); BAR;
;     }
;     { LDB(B0, 0, 0); LDA(At, 0, 0); STAGE(SA(1, 1), rsA, sA1, offA, nt - 1);
;       BAR; WAIT_L(0); MMA(0, 0, At, B0); BAR;
;       LDB(B1, 0, 1); BAR; WAIT_L(0); MMA(0, 1, At, B1); BAR;
;       LDA(At, 0, 1); WAIT_V(4); BAR; WAIT_L(0); MMA(1, 0, At, B0); MMA(1, 1, At, B1); BAR; }
	s_addk_i32 s46, 0x180
	s_mov_b32 m0, s27
	s_nop 0
	buffer_load_dwordx4 v143, s[8:11], s46 offen lds
	s_mov_b32 m0, s28
	s_nop 0
	buffer_load_dwordx4 v144, s[8:11], s46 offen lds
	s_waitcnt vmcnt(6)
	s_barrier
	v_mfma_f32_16x16x32_bf16 v[28:31], v[202:205], v[170:173], v[28:31]
	v_mfma_f32_16x16x32_bf16 v[24:27], v[210:213], v[170:173], v[24:27]
	v_mfma_f32_16x16x32_bf16 v[20:23], v[202:205], v[178:181], v[20:23]
	v_mfma_f32_16x16x32_bf16 v[16:19], v[210:213], v[178:181], v[16:19]
	v_mfma_f32_16x16x32_bf16 v[12:15], v[202:205], v[186:189], v[12:15]
	v_mfma_f32_16x16x32_bf16 v[8:11], v[210:213], v[186:189], v[8:11]
	v_mfma_f32_16x16x32_bf16 v[4:7], v[202:205], v[194:197], v[4:7]
	v_mfma_f32_16x16x32_bf16 v[0:3], v[210:213], v[194:197], v[0:3]
	v_mfma_f32_16x16x32_bf16 v[28:31], v[206:209], v[174:177], v[28:31]
	v_mfma_f32_16x16x32_bf16 v[24:27], v[214:217], v[174:177], v[24:27]
	v_mfma_f32_16x16x32_bf16 v[20:23], v[206:209], v[182:185], v[20:23]
	v_mfma_f32_16x16x32_bf16 v[16:19], v[214:217], v[182:185], v[16:19]
	v_mfma_f32_16x16x32_bf16 v[12:15], v[206:209], v[190:193], v[12:15]
	v_mfma_f32_16x16x32_bf16 v[8:11], v[214:217], v[190:193], v[8:11]
	v_mfma_f32_16x16x32_bf16 v[4:7], v[206:209], v[198:201], v[4:7]
	v_mfma_f32_16x16x32_bf16 v[0:3], v[214:217], v[198:201], v[0:3]
	s_barrier
	s_add_i32 s14, s14, 2
	s_addk_i32 s15, 0x100
	s_cmp_gt_u32 s14, 27
	s_cbranch_scc0 .LBB0_95
	s_add_i32 s10, s37, 0xf80
	s_mov_b32 m0, s30
	ds_read_b128 v[154:157], v149
	ds_read_b128 v[158:161], v150
	ds_read_b128 v[162:165], v151
	ds_read_b128 v[150:153], v152
	ds_read_b128 v[166:169], v131
	ds_read_b128 v[170:173], v131 offset:1024
	ds_read_b128 v[174:177], v134
	ds_read_b128 v[178:181], v134 offset:1024
	ds_read_b128 v[182:185], v133
	ds_read_b128 v[186:189], v133 offset:1024
	ds_read_b128 v[190:193], v132
	ds_read_b128 v[194:197], v132 offset:1024
	buffer_load_dwordx4 v143, s[4:7], s10 offen lds
	s_mov_b32 m0, s31
	s_nop 0
	buffer_load_dwordx4 v144, s[4:7], s10 offen lds
	s_barrier
	s_waitcnt lgkmcnt(0)
	v_mfma_f32_16x16x32_bf16 v[124:127], v[154:157], v[166:169], v[124:127]
	v_mfma_f32_16x16x32_bf16 v[120:123], v[162:165], v[166:169], v[120:123]
	v_mfma_f32_16x16x32_bf16 v[116:119], v[154:157], v[174:177], v[116:119]
	v_mfma_f32_16x16x32_bf16 v[112:115], v[162:165], v[174:177], v[112:115]
	v_mfma_f32_16x16x32_bf16 v[108:111], v[154:157], v[182:185], v[108:111]
	v_mfma_f32_16x16x32_bf16 v[104:107], v[162:165], v[182:185], v[104:107]
	v_mfma_f32_16x16x32_bf16 v[100:103], v[154:157], v[190:193], v[100:103]
	v_mfma_f32_16x16x32_bf16 v[96:99], v[162:165], v[190:193], v[96:99]
	v_mfma_f32_16x16x32_bf16 v[124:127], v[158:161], v[170:173], v[124:127]
	v_mfma_f32_16x16x32_bf16 v[120:123], v[150:153], v[170:173], v[120:123]
	v_mfma_f32_16x16x32_bf16 v[116:119], v[158:161], v[178:181], v[116:119]
	v_mfma_f32_16x16x32_bf16 v[112:115], v[150:153], v[178:181], v[112:115]
	v_mfma_f32_16x16x32_bf16 v[108:111], v[158:161], v[186:189], v[108:111]
	v_mfma_f32_16x16x32_bf16 v[104:107], v[150:153], v[186:189], v[104:107]
	v_mfma_f32_16x16x32_bf16 v[100:103], v[158:161], v[194:197], v[100:103]
	v_mfma_f32_16x16x32_bf16 v[96:99], v[150:153], v[194:197], v[96:99]
	s_barrier
	ds_read_b128 v[198:201], v145
	ds_read_b128 v[202:205], v146
	ds_read_b128 v[144:147], v147
	ds_read_b128 v[206:209], v148
	s_barrier
	s_waitcnt lgkmcnt(0)
	v_mfma_f32_16x16x32_bf16 v[92:95], v[198:201], v[166:169], v[92:95]
	v_mfma_f32_16x16x32_bf16 v[84:87], v[198:201], v[174:177], v[84:87]
	v_mfma_f32_16x16x32_bf16 v[76:79], v[198:201], v[182:185], v[76:79]
	v_mfma_f32_16x16x32_bf16 v[68:71], v[198:201], v[190:193], v[68:71]
	v_mfma_f32_16x16x32_bf16 v[88:91], v[144:147], v[166:169], v[88:91]
	v_mfma_f32_16x16x32_bf16 v[80:83], v[144:147], v[174:177], v[80:83]
	v_mfma_f32_16x16x32_bf16 v[72:75], v[144:147], v[182:185], v[72:75]
	v_mfma_f32_16x16x32_bf16 v[64:67], v[144:147], v[190:193], v[64:67]
	v_mfma_f32_16x16x32_bf16 v[92:95], v[202:205], v[170:173], v[92:95]
	v_mfma_f32_16x16x32_bf16 v[84:87], v[202:205], v[178:181], v[84:87]
	v_mfma_f32_16x16x32_bf16 v[76:79], v[202:205], v[186:189], v[76:79]
	v_mfma_f32_16x16x32_bf16 v[68:71], v[202:205], v[194:197], v[68:71]
	v_mfma_f32_16x16x32_bf16 v[166:169], v[206:209], v[170:173], v[88:91]
	v_mfma_f32_16x16x32_bf16 v[170:173], v[206:209], v[178:181], v[80:83]
	v_mfma_f32_16x16x32_bf16 v[174:177], v[206:209], v[186:189], v[72:75]
	v_mfma_f32_16x16x32_bf16 v[178:181], v[206:209], v[194:197], v[64:67]
	s_barrier
	s_nop 0
	ds_read_b128 v[64:67], v131 offset:16384
	ds_read_b128 v[72:75], v131 offset:17408
	ds_read_b128 v[80:83], v134 offset:16384
	ds_read_b128 v[88:91], v134 offset:17408
	ds_read_b128 v[182:185], v133 offset:16384
	ds_read_b128 v[186:189], v133 offset:17408
	ds_read_b128 v[190:193], v132 offset:16384
	ds_read_b128 v[194:197], v132 offset:17408
	s_waitcnt vmcnt(4)
	s_barrier
; #define LDA(dst, b, h) _Pragma("unroll") for (int m = 0; m < 4; ++m) _Pragma("unroll") for (int k = 0; k < 2; ++k) \
;     dst[m][k] = *reinterpret_cast<const bf16x8*>(SA(b, h) + lds_byte(wr * 64 + m * 16 + fr, k * 32 + fq * 8))
; #define LDB(dst, b, h) _Pragma("unroll") for (int n = 0; n < 2; ++n) _Pragma("unroll") for (int k = 0; k < 2; ++k) \
;     dst[n][k] = *reinterpret_cast<const bf16x8*>(SB(b, h) + lds_byte(wc * 32 + n * 16 + fr, k * 32 + fq * 8))
; #define WAIT_V(n) asm volatile("s_waitcnt vmcnt(" #n ")" ::: "memory")
; #define WAIT_L(n) asm volatile("s_waitcnt lgkmcnt(" #n ")" ::: "memory")
; #define BAR __builtin_amdgcn_s_barrier()
;     ...
;       LDA(At, 0, 1); WAIT_V(4); BAR; WAIT_L(0); MMA(1, 0, At, B0); MMA(1, 1, At, B1); BAR; }
;     { LDB(B0, 1, 0); LDA(At, 1, 0); WAIT_V(2); BAR; WAIT_L(0); MMA(0, 0, At, B0); BAR;
;       LDB(B1, 1, 1); WAIT_V(0); BAR; WAIT_L(0); MMA(0, 1, At, B1); BAR;
	s_waitcnt lgkmcnt(0)
	v_mfma_f32_16x16x32_bf16 v[60:63], v[154:157], v[64:67], v[60:63]
	v_mfma_f32_16x16x32_bf16 v[56:59], v[162:165], v[64:67], v[56:59]
	v_mfma_f32_16x16x32_bf16 v[52:55], v[154:157], v[80:83], v[52:55]
	v_mfma_f32_16x16x32_bf16 v[48:51], v[162:165], v[80:83], v[48:51]
	v_mfma_f32_16x16x32_bf16 v[44:47], v[154:157], v[182:185], v[44:47]
	v_mfma_f32_16x16x32_bf16 v[40:43], v[162:165], v[182:185], v[40:43]
	v_mfma_f32_16x16x32_bf16 v[36:39], v[154:157], v[190:193], v[36:39]
	v_mfma_f32_16x16x32_bf16 v[32:35], v[162:165], v[190:193], v[32:35]
	v_mfma_f32_16x16x32_bf16 v[60:63], v[158:161], v[72:75], v[60:63]
	v_mfma_f32_16x16x32_bf16 v[56:59], v[150:153], v[72:75], v[56:59]
	v_mfma_f32_16x16x32_bf16 v[52:55], v[158:161], v[88:91], v[52:55]
	v_mfma_f32_16x16x32_bf16 v[48:51], v[150:153], v[88:91], v[48:51]
	v_mfma_f32_16x16x32_bf16 v[44:47], v[158:161], v[186:189], v[44:47]
	v_mfma_f32_16x16x32_bf16 v[40:43], v[150:153], v[186:189], v[40:43]
	v_mfma_f32_16x16x32_bf16 v[36:39], v[158:161], v[194:197], v[36:39]
	v_mfma_f32_16x16x32_bf16 v[32:35], v[150:153], v[194:197], v[32:35]
	v_mfma_f32_16x16x32_bf16 v[28:31], v[198:201], v[64:67], v[28:31]
	v_mfma_f32_16x16x32_bf16 v[20:23], v[198:201], v[80:83], v[20:23]
	v_mfma_f32_16x16x32_bf16 v[12:15], v[198:201], v[182:185], v[12:15]
	v_mfma_f32_16x16x32_bf16 v[4:7], v[198:201], v[190:193], v[4:7]
	v_mfma_f32_16x16x32_bf16 v[24:27], v[144:147], v[64:67], v[24:27]
	v_mfma_f32_16x16x32_bf16 v[16:19], v[144:147], v[80:83], v[16:19]
	v_mfma_f32_16x16x32_bf16 v[8:11], v[144:147], v[182:185], v[8:11]
	v_mfma_f32_16x16x32_bf16 v[0:3], v[144:147], v[190:193], v[0:3]
	v_mfma_f32_16x16x32_bf16 v[28:31], v[202:205], v[72:75], v[28:31]
	v_mfma_f32_16x16x32_bf16 v[20:23], v[202:205], v[88:91], v[20:23]
	v_mfma_f32_16x16x32_bf16 v[12:15], v[202:205], v[186:189], v[12:15]
	v_mfma_f32_16x16x32_bf16 v[4:7], v[202:205], v[194:197], v[4:7]
	v_mfma_f32_16x16x32_bf16 v[144:147], v[206:209], v[72:75], v[24:27]
	v_mfma_f32_16x16x32_bf16 v[148:151], v[206:209], v[88:91], v[16:19]
	v_mfma_f32_16x16x32_bf16 v[152:155], v[206:209], v[186:189], v[8:11]
	v_mfma_f32_16x16x32_bf16 v[156:159], v[206:209], v[194:197], v[0:3]
	s_barrier
	s_nop 0
	ds_read_b128 v[0:3], v139
	ds_read_b128 v[8:11], v140
	ds_read_b128 v[16:19], v141
	ds_read_b128 v[140:143], v142
	ds_read_b128 v[24:27], v131 offset:32768
	ds_read_b128 v[160:163], v131 offset:33792
	ds_read_b128 v[182:185], v134 offset:32768
	ds_read_b128 v[186:189], v134 offset:33792
	ds_read_b128 v[190:193], v133 offset:32768
	ds_read_b128 v[194:197], v133 offset:33792
	ds_read_b128 v[198:201], v132 offset:32768
	ds_read_b128 v[202:205], v132 offset:33792
	s_waitcnt vmcnt(2)
	s_barrier
	s_waitcnt lgkmcnt(0)
	v_mfma_f32_16x16x32_bf16 v[64:67], v[0:3], v[24:27], v[124:127]
	v_mfma_f32_16x16x32_bf16 v[72:75], v[16:19], v[24:27], v[120:123]
	v_mfma_f32_16x16x32_bf16 v[80:83], v[0:3], v[182:185], v[116:119]
	v_mfma_f32_16x16x32_bf16 v[88:91], v[16:19], v[182:185], v[112:115]
	v_mfma_f32_16x16x32_bf16 v[108:111], v[0:3], v[190:193], v[108:111]
	v_mfma_f32_16x16x32_bf16 v[116:119], v[16:19], v[190:193], v[104:107]
	v_mfma_f32_16x16x32_bf16 v[100:103], v[0:3], v[198:201], v[100:103]
	v_mfma_f32_16x16x32_bf16 v[124:127], v[16:19], v[198:201], v[96:99]
	v_mfma_f32_16x16x32_bf16 v[120:123], v[8:11], v[160:163], v[64:67]
	v_mfma_f32_16x16x32_bf16 v[112:115], v[140:143], v[160:163], v[72:75]
	v_mfma_f32_16x16x32_bf16 v[104:107], v[8:11], v[186:189], v[80:83]
	v_mfma_f32_16x16x32_bf16 v[96:99], v[140:143], v[186:189], v[88:91]
	v_mfma_f32_16x16x32_bf16 v[88:91], v[8:11], v[194:197], v[108:111]
	v_mfma_f32_16x16x32_bf16 v[80:83], v[140:143], v[194:197], v[116:119]
	v_mfma_f32_16x16x32_bf16 v[72:75], v[8:11], v[202:205], v[100:103]
	v_mfma_f32_16x16x32_bf16 v[64:67], v[140:143], v[202:205], v[124:127]
	s_barrier
	ds_read_b128 v[206:209], v135
	ds_read_b128 v[210:213], v136
	ds_read_b128 v[214:217], v137
	ds_read_b128 v[136:139], v138
	s_waitcnt vmcnt(0)
	s_barrier
; #define LDA(dst, b, h) _Pragma("unroll") for (int m = 0; m < 4; ++m) _Pragma("unroll") for (int k = 0; k < 2; ++k) \
;     dst[m][k] = *reinterpret_cast<const bf16x8*>(SA(b, h) + lds_byte(wr * 64 + m * 16 + fr, k * 32 + fq * 8))
; #define LDB(dst, b, h) _Pragma("unroll") for (int n = 0; n < 2; ++n) _Pragma("unroll") for (int k = 0; k < 2; ++k) \
;     dst[n][k] = *reinterpret_cast<const bf16x8*>(SB(b, h) + lds_byte(wc * 32 + n * 16 + fr, k * 32 + fq * 8))
; #define WAIT_V(n) asm volatile("s_waitcnt vmcnt(" #n ")" ::: "memory")
; #define WAIT_L(n) asm volatile("s_waitcnt lgkmcnt(" #n ")" ::: "memory")
; #define BAR __builtin_amdgcn_s_barrier()
;     ...
;       LDB(B1, 1, 1); WAIT_V(0); BAR; WAIT_L(0); MMA(0, 1, At, B1); BAR;
;       LDA(At, 1, 1); BAR; WAIT_L(0); MMA(1, 0, At, B0); MMA(1, 1, At, B1); BAR; }
;     if (wr == 0) BAR;
	s_waitcnt lgkmcnt(0)
	v_mfma_f32_16x16x32_bf16 v[92:95], v[206:209], v[24:27], v[92:95]
	v_mfma_f32_16x16x32_bf16 v[24:27], v[214:217], v[24:27], v[166:169]
	v_mfma_f32_16x16x32_bf16 v[84:87], v[206:209], v[182:185], v[84:87]
	v_mfma_f32_16x16x32_bf16 v[100:103], v[214:217], v[182:185], v[170:173]
	v_mfma_f32_16x16x32_bf16 v[76:79], v[206:209], v[190:193], v[76:79]
	v_mfma_f32_16x16x32_bf16 v[164:167], v[214:217], v[190:193], v[174:177]
	v_mfma_f32_16x16x32_bf16 v[68:71], v[206:209], v[198:201], v[68:71]
	v_mfma_f32_16x16x32_bf16 v[168:171], v[214:217], v[198:201], v[178:181]
	v_mfma_f32_16x16x32_bf16 v[124:127], v[210:213], v[160:163], v[92:95]
	v_mfma_f32_16x16x32_bf16 v[116:119], v[136:139], v[160:163], v[24:27]
	v_mfma_f32_16x16x32_bf16 v[108:111], v[210:213], v[186:189], v[84:87]
	v_mfma_f32_16x16x32_bf16 v[100:103], v[136:139], v[186:189], v[100:103]
	v_mfma_f32_16x16x32_bf16 v[92:95], v[210:213], v[194:197], v[76:79]
	v_mfma_f32_16x16x32_bf16 v[84:87], v[136:139], v[194:197], v[164:167]
	v_mfma_f32_16x16x32_bf16 v[76:79], v[210:213], v[202:205], v[68:71]
	v_mfma_f32_16x16x32_bf16 v[68:71], v[136:139], v[202:205], v[168:171]
	s_barrier
	ds_read_b128 v[160:163], v131 offset:49152
	ds_read_b128 v[164:167], v131 offset:50176
	ds_read_b128 v[168:171], v134 offset:49152
	ds_read_b128 v[172:175], v134 offset:50176
	ds_read_b128 v[176:179], v133 offset:49152
	ds_read_b128 v[180:183], v133 offset:50176
	ds_read_b128 v[184:187], v132 offset:49152
	ds_read_b128 v[132:135], v132 offset:50176
	s_barrier
	s_waitcnt lgkmcnt(0)
	v_mfma_f32_16x16x32_bf16 v[24:27], v[0:3], v[160:163], v[60:63]
	v_mfma_f32_16x16x32_bf16 v[60:63], v[16:19], v[160:163], v[56:59]
	v_mfma_f32_16x16x32_bf16 v[52:55], v[0:3], v[168:171], v[52:55]
	v_mfma_f32_16x16x32_bf16 v[188:191], v[16:19], v[168:171], v[48:51]
	v_mfma_f32_16x16x32_bf16 v[44:47], v[0:3], v[176:179], v[44:47]
	v_mfma_f32_16x16x32_bf16 v[192:195], v[16:19], v[176:179], v[40:43]
	v_mfma_f32_16x16x32_bf16 v[0:3], v[0:3], v[184:187], v[36:39]
	v_mfma_f32_16x16x32_bf16 v[36:39], v[16:19], v[184:187], v[32:35]
	v_mfma_f32_16x16x32_bf16 v[56:59], v[8:11], v[164:167], v[24:27]
	v_mfma_f32_16x16x32_bf16 v[48:51], v[140:143], v[164:167], v[60:63]
	v_mfma_f32_16x16x32_bf16 v[40:43], v[8:11], v[172:175], v[52:55]
	v_mfma_f32_16x16x32_bf16 v[32:35], v[140:143], v[172:175], v[188:191]
	v_mfma_f32_16x16x32_bf16 v[24:27], v[8:11], v[180:183], v[44:47]
	v_mfma_f32_16x16x32_bf16 v[16:19], v[140:143], v[180:183], v[192:195]
	v_mfma_f32_16x16x32_bf16 v[8:11], v[8:11], v[132:135], v[0:3]
	v_mfma_f32_16x16x32_bf16 v[0:3], v[140:143], v[132:135], v[36:39]
	v_mfma_f32_16x16x32_bf16 v[28:31], v[206:209], v[160:163], v[28:31]
	v_mfma_f32_16x16x32_bf16 v[36:39], v[214:217], v[160:163], v[144:147]
	v_mfma_f32_16x16x32_bf16 v[20:23], v[206:209], v[168:171], v[20:23]
	v_mfma_f32_16x16x32_bf16 v[140:143], v[214:217], v[168:171], v[148:151]
	v_mfma_f32_16x16x32_bf16 v[12:15], v[206:209], v[176:179], v[12:15]
	v_mfma_f32_16x16x32_bf16 v[144:147], v[214:217], v[176:179], v[152:155]
	v_mfma_f32_16x16x32_bf16 v[4:7], v[206:209], v[184:187], v[4:7]
	v_mfma_f32_16x16x32_bf16 v[148:151], v[214:217], v[184:187], v[156:159]
	v_mfma_f32_16x16x32_bf16 v[60:63], v[210:213], v[164:167], v[28:31]
	v_mfma_f32_16x16x32_bf16 v[52:55], v[136:139], v[164:167], v[36:39]
	v_mfma_f32_16x16x32_bf16 v[44:47], v[210:213], v[172:175], v[20:23]
	v_mfma_f32_16x16x32_bf16 v[36:39], v[136:139], v[172:175], v[140:143]
	v_mfma_f32_16x16x32_bf16 v[28:31], v[210:213], v[180:183], v[12:15]
	v_mfma_f32_16x16x32_bf16 v[20:23], v[136:139], v[180:183], v[144:147]
	v_mfma_f32_16x16x32_bf16 v[12:15], v[210:213], v[132:135], v[4:7]
	v_mfma_f32_16x16x32_bf16 v[4:7], v[136:139], v[132:135], v[148:151]
	v_cmp_gt_u32_e32 vcc, s35, v130
	s_barrier
	s_and_saveexec_b64 s[10:11], vcc
	s_cbranch_execz .LBB0_98
	s_barrier

; #define STAGE(P, RS, SOFF, OFF, kt) do { const int _so = (SOFF) + (kt) * (BK * 2); \
;     _Pragma("unroll") for (int _i = 0; _i < 2; ++_i) { \
;       __builtin_amdgcn_raw_ptr_buffer_load_lds(RS, (__attribute__((address_space(3))) void*)((P) + wave * 1024 + _i * 8192), 16, OFF[_i], _so, 0, 0); } } while (0)
; #define LDA(dst, b, h) _Pragma("unroll") for (int m = 0; m < 4; ++m) _Pragma("unroll") for (int k = 0; k < 2; ++k) \
;     dst[m][k] = *reinterpret_cast<const bf16x8*>(SA(b, h) + lds_byte(wr * 64 + m * 16 + fr, k * 32 + fq * 8))
; #define LDB(dst, b, h) _Pragma("unroll") for (int n = 0; n < 2; ++n) _Pragma("unroll") for (int k = 0; k < 2; ++k) \
;     dst[n][k] = *reinterpret_cast<const bf16x8*>(SB(b, h) + lds_byte(wc * 32 + n * 16 + fr, k * 32 + fq * 8))
; #define WAIT_V(n) asm volatile("s_waitcnt vmcnt(" #n ")" ::: "memory")
; #define WAIT_L(n) asm volatile("s_waitcnt lgkmcnt(" #n ")" ::: "memory")
; #define BAR __builtin_amdgcn_s_barrier()
; #define SCHED __builtin_amdgcn_sched_barrier(0)
;     ...
;       LDB(B0, 0, 0); SCHED; LDA(At, 0, 0); STAGE(SA(1, 1), rsA, sA1, offA, t + 1);
;       WAIT_L(8); BAR; WAIT_L(0); MMA(0, 0, At, B0); BAR; SCHED;
;       LDB(B1, 0, 1); STAGE(SB(0, 0), rsB, sB0, offB, t + 2);
;       BAR; WAIT_L(0); MMA(0, 1, At, B1); BAR;
;       LDA(At, 0, 1); STAGE(SA(0, 0), rsA, sA0, offA, t + 2);
;       BAR; WAIT_L(0); MMA(1, 0, At, B0); BAR; SCHED;
;       STAGE(SB(0, 1), rsB, sB1, offB, t + 2);
;       WAIT_V(6); BAR; MMA(1, 1, At, B1); BAR;
.LBB0_110:
	ds_read_b128 v[156:159], v151
	ds_read_b128 v[160:163], v152
	ds_read_b128 v[164:167], v153
	ds_read_b128 v[168:171], v154
	s_add_i32 s44, s38, s17
	s_add_i32 s10, s44, 0x80
	s_mov_b32 m0, s31
	ds_read_b128 v[172:175], v131
	ds_read_b128 v[176:179], v131 offset:1024
	ds_read_b128 v[180:183], v138
	ds_read_b128 v[184:187], v138 offset:1024
	ds_read_b128 v[188:191], v137
	ds_read_b128 v[192:195], v137 offset:1024
	ds_read_b128 v[196:199], v135
	ds_read_b128 v[200:203], v135 offset:1024
	buffer_load_dwordx4 v128, s[4:7], s10 offen lds
	s_mov_b32 m0, s33
	s_nop 0
	buffer_load_dwordx4 v132, s[4:7], s10 offen lds
	s_waitcnt lgkmcnt(8)
	s_barrier
	s_waitcnt lgkmcnt(0)
	v_mfma_f32_16x16x32_bf16 v[124:127], v[156:159], v[172:175], v[124:127]
	v_mfma_f32_16x16x32_bf16 v[120:123], v[164:167], v[172:175], v[120:123]
	v_mfma_f32_16x16x32_bf16 v[116:119], v[156:159], v[180:183], v[116:119]
	v_mfma_f32_16x16x32_bf16 v[112:115], v[164:167], v[180:183], v[112:115]
	v_mfma_f32_16x16x32_bf16 v[108:111], v[156:159], v[188:191], v[108:111]
	v_mfma_f32_16x16x32_bf16 v[104:107], v[164:167], v[188:191], v[104:107]
	v_mfma_f32_16x16x32_bf16 v[100:103], v[156:159], v[196:199], v[100:103]
	v_mfma_f32_16x16x32_bf16 v[96:99], v[164:167], v[196:199], v[96:99]
	v_mfma_f32_16x16x32_bf16 v[124:127], v[160:163], v[176:179], v[124:127]
	v_mfma_f32_16x16x32_bf16 v[120:123], v[168:171], v[176:179], v[120:123]
	v_mfma_f32_16x16x32_bf16 v[116:119], v[160:163], v[184:187], v[116:119]
	v_mfma_f32_16x16x32_bf16 v[112:115], v[168:171], v[184:187], v[112:115]
	v_mfma_f32_16x16x32_bf16 v[108:111], v[160:163], v[192:195], v[108:111]
	v_mfma_f32_16x16x32_bf16 v[104:107], v[168:171], v[192:195], v[104:107]
	v_mfma_f32_16x16x32_bf16 v[100:103], v[160:163], v[200:203], v[100:103]
	v_mfma_f32_16x16x32_bf16 v[96:99], v[168:171], v[200:203], v[96:99]
	s_barrier
	s_add_i32 s45, s40, s17
	s_add_i32 s46, s45, 0x100
	s_mov_b32 s10, s6
	s_mov_b32 s11, s7
	s_mov_b32 m0, s3
	ds_read_b128 v[204:207], v147
	ds_read_b128 v[208:211], v148
	ds_read_b128 v[212:215], v149
	ds_read_b128 v[216:219], v150
	buffer_load_dwordx4 v130, s[8:11], s46 offen lds
	s_mov_b32 m0, s18
	s_nop 0
	buffer_load_dwordx4 v134, s[8:11], s46 offen lds
	s_barrier
	s_waitcnt lgkmcnt(0)
	v_mfma_f32_16x16x32_bf16 v[92:95], v[204:207], v[172:175], v[92:95]
	v_mfma_f32_16x16x32_bf16 v[88:91], v[212:215], v[172:175], v[88:91]
	v_mfma_f32_16x16x32_bf16 v[84:87], v[204:207], v[180:183], v[84:87]
	v_mfma_f32_16x16x32_bf16 v[80:83], v[212:215], v[180:183], v[80:83]
	v_mfma_f32_16x16x32_bf16 v[76:79], v[204:207], v[188:191], v[76:79]
	v_mfma_f32_16x16x32_bf16 v[72:75], v[212:215], v[188:191], v[72:75]
	v_mfma_f32_16x16x32_bf16 v[68:71], v[204:207], v[196:199], v[68:71]
	v_mfma_f32_16x16x32_bf16 v[64:67], v[212:215], v[196:199], v[64:67]
	v_mfma_f32_16x16x32_bf16 v[92:95], v[208:211], v[176:179], v[92:95]
	v_mfma_f32_16x16x32_bf16 v[88:91], v[216:219], v[176:179], v[88:91]
	v_mfma_f32_16x16x32_bf16 v[84:87], v[208:211], v[184:187], v[84:87]
	v_mfma_f32_16x16x32_bf16 v[80:83], v[216:219], v[184:187], v[80:83]
	v_mfma_f32_16x16x32_bf16 v[76:79], v[208:211], v[192:195], v[76:79]
	v_mfma_f32_16x16x32_bf16 v[72:75], v[216:219], v[192:195], v[72:75]
	v_mfma_f32_16x16x32_bf16 v[68:71], v[208:211], v[200:203], v[68:71]
	v_mfma_f32_16x16x32_bf16 v[64:67], v[216:219], v[200:203], v[64:67]
	s_barrier
	s_add_i32 s46, s39, s17
	s_add_i32 s47, s46, 0x100
	s_mov_b32 m0, s0
	ds_read_b128 v[172:175], v131 offset:16384
	ds_read_b128 v[176:179], v131 offset:17408
	ds_read_b128 v[180:183], v138 offset:16384
	ds_read_b128 v[184:187], v138 offset:17408
	ds_read_b128 v[188:191], v137 offset:16384
	ds_read_b128 v[192:195], v137 offset:17408
	ds_read_b128 v[196:199], v135 offset:16384
	ds_read_b128 v[200:203], v135 offset:17408
	buffer_load_dwordx4 v128, s[4:7], s47 offen lds
	s_mov_b32 m0, s19
	s_nop 0
	buffer_load_dwordx4 v132, s[4:7], s47 offen lds
	s_barrier
	s_waitcnt lgkmcnt(0)
	v_mfma_f32_16x16x32_bf16 v[60:63], v[156:159], v[172:175], v[60:63]
	v_mfma_f32_16x16x32_bf16 v[56:59], v[164:167], v[172:175], v[56:59]
	v_mfma_f32_16x16x32_bf16 v[52:55], v[156:159], v[180:183], v[52:55]
	v_mfma_f32_16x16x32_bf16 v[48:51], v[164:167], v[180:183], v[48:51]
	v_mfma_f32_16x16x32_bf16 v[44:47], v[156:159], v[188:191], v[44:47]
	v_mfma_f32_16x16x32_bf16 v[40:43], v[164:167], v[188:191], v[40:43]
	v_mfma_f32_16x16x32_bf16 v[36:39], v[156:159], v[196:199], v[36:39]
	v_mfma_f32_16x16x32_bf16 v[32:35], v[164:167], v[196:199], v[32:35]
	v_mfma_f32_16x16x32_bf16 v[60:63], v[160:163], v[176:179], v[60:63]
	v_mfma_f32_16x16x32_bf16 v[56:59], v[168:171], v[176:179], v[56:59]
	v_mfma_f32_16x16x32_bf16 v[52:55], v[160:163], v[184:187], v[52:55]
	v_mfma_f32_16x16x32_bf16 v[48:51], v[168:171], v[184:187], v[48:51]
	v_mfma_f32_16x16x32_bf16 v[44:47], v[160:163], v[192:195], v[44:47]
	v_mfma_f32_16x16x32_bf16 v[40:43], v[168:171], v[192:195], v[40:43]
	v_mfma_f32_16x16x32_bf16 v[36:39], v[160:163], v[200:203], v[36:39]
	v_mfma_f32_16x16x32_bf16 v[32:35], v[168:171], v[200:203], v[32:35]
	s_barrier
	s_add_i32 s47, s41, s17
	s_add_i32 s48, s47, 0x100
	s_mov_b32 m0, s20
	s_nop 0
	buffer_load_dwordx4 v130, s[8:11], s48 offen lds
	s_mov_b32 m0, s21
	s_nop 0
	buffer_load_dwordx4 v134, s[8:11], s48 offen lds
	s_waitcnt vmcnt(6)
	s_barrier
; #define STAGE(P, RS, SOFF, OFF, kt) do { const int _so = (SOFF) + (kt) * (BK * 2); \
;     _Pragma("unroll") for (int _i = 0; _i < 2; ++_i) { \
;       __builtin_amdgcn_raw_ptr_buffer_load_lds(RS, (__attribute__((address_space(3))) void*)((P) + wave * 1024 + _i * 8192), 16, OFF[_i], _so, 0, 0); } } while (0)
; #define LDA(dst, b, h) _Pragma("unroll") for (int m = 0; m < 4; ++m) _Pragma("unroll") for (int k = 0; k < 2; ++k) \
;     dst[m][k] = *reinterpret_cast<const bf16x8*>(SA(b, h) + lds_byte(wr * 64 + m * 16 + fr, k * 32 + fq * 8))
; #define LDB(dst, b, h) _Pragma("unroll") for (int n = 0; n < 2; ++n) _Pragma("unroll") for (int k = 0; k < 2; ++k) \
;     dst[n][k] = *reinterpret_cast<const bf16x8*>(SB(b, h) + lds_byte(wc * 32 + n * 16 + fr, k * 32 + fq * 8))
; #define WAIT_V(n) asm volatile("s_waitcnt vmcnt(" #n ")" ::: "memory")
; #define WAIT_L(n) asm volatile("s_waitcnt lgkmcnt(" #n ")" ::: "memory")
; #define BAR __builtin_amdgcn_s_barrier()
; #define SCHED __builtin_amdgcn_sched_barrier(0)
;     ...
;       WAIT_V(6); BAR; MMA(1, 1, At, B1); BAR;
;       LDB(B0, 1, 0); SCHED; LDA(At, 1, 0); STAGE(SA(0, 1), rsA, sA1, offA, t + 2);
;       WAIT_L(8); BAR; WAIT_L(0); MMA(0, 0, At, B0); BAR; SCHED;
;       LDB(B1, 1, 1); STAGE(SB(1, 0), rsB, sB0, offB, t + 3);
;       BAR; WAIT_L(0); MMA(0, 1, At, B1); BAR;
;       LDA(At, 1, 1); STAGE(SA(1, 0), rsA, sA0, offA, t + 3);
;       BAR; WAIT_L(0); MMA(1, 0, At, B0); BAR; SCHED;
	v_mfma_f32_16x16x32_bf16 v[28:31], v[204:207], v[172:175], v[28:31]
	v_mfma_f32_16x16x32_bf16 v[24:27], v[212:215], v[172:175], v[24:27]
	v_mfma_f32_16x16x32_bf16 v[20:23], v[204:207], v[180:183], v[20:23]
	v_mfma_f32_16x16x32_bf16 v[16:19], v[212:215], v[180:183], v[16:19]
	v_mfma_f32_16x16x32_bf16 v[12:15], v[204:207], v[188:191], v[12:15]
	v_mfma_f32_16x16x32_bf16 v[8:11], v[212:215], v[188:191], v[8:11]
	v_mfma_f32_16x16x32_bf16 v[4:7], v[204:207], v[196:199], v[4:7]
	v_mfma_f32_16x16x32_bf16 v[0:3], v[212:215], v[196:199], v[0:3]
	v_mfma_f32_16x16x32_bf16 v[28:31], v[208:211], v[176:179], v[28:31]
	v_mfma_f32_16x16x32_bf16 v[24:27], v[216:219], v[176:179], v[24:27]
	v_mfma_f32_16x16x32_bf16 v[20:23], v[208:211], v[184:187], v[20:23]
	v_mfma_f32_16x16x32_bf16 v[16:19], v[216:219], v[184:187], v[16:19]
	v_mfma_f32_16x16x32_bf16 v[12:15], v[208:211], v[192:195], v[12:15]
	v_mfma_f32_16x16x32_bf16 v[8:11], v[216:219], v[192:195], v[8:11]
	v_mfma_f32_16x16x32_bf16 v[4:7], v[208:211], v[200:203], v[4:7]
	v_mfma_f32_16x16x32_bf16 v[0:3], v[216:219], v[200:203], v[0:3]
	s_barrier
	ds_read_b128 v[156:159], v143
	ds_read_b128 v[160:163], v144
	ds_read_b128 v[164:167], v145
	ds_read_b128 v[168:171], v146
	s_addk_i32 s44, 0x100
	s_mov_b32 m0, s22
	ds_read_b128 v[172:175], v131 offset:32768
	ds_read_b128 v[176:179], v131 offset:33792
	ds_read_b128 v[180:183], v138 offset:32768
	ds_read_b128 v[184:187], v138 offset:33792
	ds_read_b128 v[188:191], v137 offset:32768
	ds_read_b128 v[192:195], v137 offset:33792
	ds_read_b128 v[196:199], v135 offset:32768
	ds_read_b128 v[200:203], v135 offset:33792
	buffer_load_dwordx4 v128, s[4:7], s44 offen lds
	s_mov_b32 m0, s23
	s_nop 0
	buffer_load_dwordx4 v132, s[4:7], s44 offen lds
	s_waitcnt lgkmcnt(8)
	s_barrier
	s_waitcnt lgkmcnt(0)
	v_mfma_f32_16x16x32_bf16 v[124:127], v[156:159], v[172:175], v[124:127]
	v_mfma_f32_16x16x32_bf16 v[120:123], v[164:167], v[172:175], v[120:123]
	v_mfma_f32_16x16x32_bf16 v[116:119], v[156:159], v[180:183], v[116:119]
	v_mfma_f32_16x16x32_bf16 v[112:115], v[164:167], v[180:183], v[112:115]
	v_mfma_f32_16x16x32_bf16 v[108:111], v[156:159], v[188:191], v[108:111]
	v_mfma_f32_16x16x32_bf16 v[104:107], v[164:167], v[188:191], v[104:107]
	v_mfma_f32_16x16x32_bf16 v[100:103], v[156:159], v[196:199], v[100:103]
	v_mfma_f32_16x16x32_bf16 v[96:99], v[164:167], v[196:199], v[96:99]
	v_mfma_f32_16x16x32_bf16 v[124:127], v[160:163], v[176:179], v[124:127]
	v_mfma_f32_16x16x32_bf16 v[120:123], v[168:171], v[176:179], v[120:123]
	v_mfma_f32_16x16x32_bf16 v[116:119], v[160:163], v[184:187], v[116:119]
	v_mfma_f32_16x16x32_bf16 v[112:115], v[168:171], v[184:187], v[112:115]
	v_mfma_f32_16x16x32_bf16 v[108:111], v[160:163], v[192:195], v[108:111]
	v_mfma_f32_16x16x32_bf16 v[104:107], v[168:171], v[192:195], v[104:107]
	v_mfma_f32_16x16x32_bf16 v[100:103], v[160:163], v[200:203], v[100:103]
	v_mfma_f32_16x16x32_bf16 v[96:99], v[168:171], v[200:203], v[96:99]
	s_barrier
	s_addk_i32 s45, 0x180
	s_mov_b32 m0, s24
	ds_read_b128 v[204:207], v139
	ds_read_b128 v[208:211], v140
	ds_read_b128 v[212:215], v141
	ds_read_b128 v[216:219], v142
	buffer_load_dwordx4 v130, s[8:11], s45 offen lds
	s_mov_b32 m0, s25
	s_nop 0
	buffer_load_dwordx4 v134, s[8:11], s45 offen lds
	s_barrier
	s_waitcnt lgkmcnt(0)
	v_mfma_f32_16x16x32_bf16 v[92:95], v[204:207], v[172:175], v[92:95]
	v_mfma_f32_16x16x32_bf16 v[88:91], v[212:215], v[172:175], v[88:91]
	v_mfma_f32_16x16x32_bf16 v[84:87], v[204:207], v[180:183], v[84:87]
	v_mfma_f32_16x16x32_bf16 v[80:83], v[212:215], v[180:183], v[80:83]
	v_mfma_f32_16x16x32_bf16 v[76:79], v[204:207], v[188:191], v[76:79]
	v_mfma_f32_16x16x32_bf16 v[72:75], v[212:215], v[188:191], v[72:75]
	v_mfma_f32_16x16x32_bf16 v[68:71], v[204:207], v[196:199], v[68:71]
	v_mfma_f32_16x16x32_bf16 v[64:67], v[212:215], v[196:199], v[64:67]
	v_mfma_f32_16x16x32_bf16 v[92:95], v[208:211], v[176:179], v[92:95]
	v_mfma_f32_16x16x32_bf16 v[88:91], v[216:219], v[176:179], v[88:91]
	v_mfma_f32_16x16x32_bf16 v[84:87], v[208:211], v[184:187], v[84:87]
	v_mfma_f32_16x16x32_bf16 v[80:83], v[216:219], v[184:187], v[80:83]
	v_mfma_f32_16x16x32_bf16 v[76:79], v[208:211], v[192:195], v[76:79]
	v_mfma_f32_16x16x32_bf16 v[72:75], v[216:219], v[192:195], v[72:75]
	v_mfma_f32_16x16x32_bf16 v[68:71], v[208:211], v[200:203], v[68:71]
	v_mfma_f32_16x16x32_bf16 v[64:67], v[216:219], v[200:203], v[64:67]
	s_barrier
	s_addk_i32 s46, 0x180
	s_mov_b32 m0, s26
	ds_read_b128 v[172:175], v131 offset:49152
	ds_read_b128 v[176:179], v131 offset:50176
	ds_read_b128 v[180:183], v138 offset:49152
	ds_read_b128 v[184:187], v138 offset:50176
	ds_read_b128 v[188:191], v137 offset:49152
	ds_read_b128 v[192:195], v137 offset:50176
	ds_read_b128 v[196:199], v135 offset:49152
	ds_read_b128 v[200:203], v135 offset:50176
	buffer_load_dwordx4 v128, s[4:7], s46 offen lds
	s_mov_b32 m0, s27
	s_nop 0
	buffer_load_dwordx4 v132, s[4:7], s46 offen lds
	s_barrier
	s_waitcnt lgkmcnt(0)
	v_mfma_f32_16x16x32_bf16 v[60:63], v[156:159], v[172:175], v[60:63]
	v_mfma_f32_16x16x32_bf16 v[56:59], v[164:167], v[172:175], v[56:59]
	v_mfma_f32_16x16x32_bf16 v[52:55], v[156:159], v[180:183], v[52:55]
	v_mfma_f32_16x16x32_bf16 v[48:51], v[164:167], v[180:183], v[48:51]
	v_mfma_f32_16x16x32_bf16 v[44:47], v[156:159], v[188:191], v[44:47]
	v_mfma_f32_16x16x32_bf16 v[40:43], v[164:167], v[188:191], v[40:43]
	v_mfma_f32_16x16x32_bf16 v[36:39], v[156:159], v[196:199], v[36:39]
	v_mfma_f32_16x16x32_bf16 v[32:35], v[164:167], v[196:199], v[32:35]
	v_mfma_f32_16x16x32_bf16 v[60:63], v[160:163], v[176:179], v[60:63]
	v_mfma_f32_16x16x32_bf16 v[56:59], v[168:171], v[176:179], v[56:59]
	v_mfma_f32_16x16x32_bf16 v[52:55], v[160:163], v[184:187], v[52:55]
	v_mfma_f32_16x16x32_bf16 v[48:51], v[168:171], v[184:187], v[48:51]
	v_mfma_f32_16x16x32_bf16 v[44:47], v[160:163], v[192:195], v[44:47]
	v_mfma_f32_16x16x32_bf16 v[40:43], v[168:171], v[192:195], v[40:43]
	v_mfma_f32_16x16x32_bf16 v[36:39], v[160:163], v[200:203], v[36:39]
	v_mfma_f32_16x16x32_bf16 v[32:35], v[168:171], v[200:203], v[32:35]
	s_barrier
; #define STAGE(P, RS, SOFF, OFF, kt) do { const int _so = (SOFF) + (kt) * (BK * 2); \
;     _Pragma("unroll") for (int _i = 0; _i < 2; ++_i) { \
;       __builtin_amdgcn_raw_ptr_buffer_load_lds(RS, (__attribute__((address_space(3))) void*)((P) + wave * 1024 + _i * 8192), 16, OFF[_i], _so, 0, 0); } } while (0)
; #define LDA(dst, b, h) _Pragma("unroll") for (int m = 0; m < 4; ++m) _Pragma("unroll") for (int k = 0; k < 2; ++k) \
;     dst[m][k] = *reinterpret_cast<const bf16x8*>(SA(b, h) + lds_byte(wr * 64 + m * 16 + fr, k * 32 + fq * 8))
; #define LDB(dst, b, h) _Pragma("unroll") for (int n = 0; n < 2; ++n) _Pragma("unroll") for (int k = 0; k < 2; ++k) \
;     dst[n][k] = *reinterpret_cast<const bf16x8*>(SB(b, h) + lds_byte(wc * 32 + n * 16 + fr, k * 32 + fq * 8))
; #define WAIT_V(n) asm volatile("s_waitcnt vmcnt(" #n ")" ::: "memory")
; #define WAIT_L(n) asm volatile("s_waitcnt lgkmcnt(" #n ")" ::: "memory")
; #define BAR __builtin_amdgcn_s_barrier()
;     ...
;       STAGE(SB(1, 1), rsB, sB1, offB, t + 3);
;       WAIT_V(6); BAR; MMA(1, 1, At, B1); BAR;
;     }
;     { LDB(B0, 0, 0); LDA(At, 0, 0); STAGE(SA(1, 1), rsA, sA1, offA, nt - 1);
;       BAR; WAIT_L(0); MMA(0, 0, At, B0); BAR;
;       LDB(B1, 0, 1); BAR; WAIT_L(0); MMA(0, 1, At, B1); BAR;
;       LDA(At, 0, 1); WAIT_V(4); BAR; WAIT_L(0); MMA(1, 0, At, B0); MMA(1, 1, At, B1); BAR; }
	s_addk_i32 s47, 0x180
	s_mov_b32 m0, s28
	s_nop 0
	buffer_load_dwordx4 v130, s[8:11], s47 offen lds
	s_mov_b32 m0, s29
	s_nop 0
	buffer_load_dwordx4 v134, s[8:11], s47 offen lds
	s_waitcnt vmcnt(6)
	s_barrier
	v_mfma_f32_16x16x32_bf16 v[28:31], v[204:207], v[172:175], v[28:31]
	v_mfma_f32_16x16x32_bf16 v[24:27], v[212:215], v[172:175], v[24:27]
	v_mfma_f32_16x16x32_bf16 v[20:23], v[204:207], v[180:183], v[20:23]
	v_mfma_f32_16x16x32_bf16 v[16:19], v[212:215], v[180:183], v[16:19]
	v_mfma_f32_16x16x32_bf16 v[12:15], v[204:207], v[188:191], v[12:15]
	v_mfma_f32_16x16x32_bf16 v[8:11], v[212:215], v[188:191], v[8:11]
	v_mfma_f32_16x16x32_bf16 v[4:7], v[204:207], v[196:199], v[4:7]
	v_mfma_f32_16x16x32_bf16 v[0:3], v[212:215], v[196:199], v[0:3]
	v_mfma_f32_16x16x32_bf16 v[28:31], v[208:211], v[176:179], v[28:31]
	v_mfma_f32_16x16x32_bf16 v[24:27], v[216:219], v[176:179], v[24:27]
	v_mfma_f32_16x16x32_bf16 v[20:23], v[208:211], v[184:187], v[20:23]
	v_mfma_f32_16x16x32_bf16 v[16:19], v[216:219], v[184:187], v[16:19]
	v_mfma_f32_16x16x32_bf16 v[12:15], v[208:211], v[192:195], v[12:15]
	v_mfma_f32_16x16x32_bf16 v[8:11], v[216:219], v[192:195], v[8:11]
	v_mfma_f32_16x16x32_bf16 v[4:7], v[208:211], v[200:203], v[4:7]
	v_mfma_f32_16x16x32_bf16 v[0:3], v[216:219], v[200:203], v[0:3]
	s_barrier
	s_add_i32 s16, s16, 2
	s_addk_i32 s17, 0x100
	s_cmp_gt_u32 s16, 3
	s_cbranch_scc0 .LBB0_110
	s_add_i32 s10, s38, 0x380
	s_mov_b32 m0, s31
	ds_read_b128 v[156:159], v151
	ds_read_b128 v[160:163], v152
	ds_read_b128 v[164:167], v153
	ds_read_b128 v[152:155], v154
	ds_read_b128 v[168:171], v131
	ds_read_b128 v[172:175], v131 offset:1024
	ds_read_b128 v[176:179], v138
	ds_read_b128 v[180:183], v138 offset:1024
	ds_read_b128 v[184:187], v137
	ds_read_b128 v[188:191], v137 offset:1024
	ds_read_b128 v[192:195], v135
	ds_read_b128 v[196:199], v135 offset:1024
	buffer_load_dwordx4 v128, s[4:7], s10 offen lds
	s_mov_b32 m0, s33
	s_nop 0
	buffer_load_dwordx4 v132, s[4:7], s10 offen lds
	s_barrier
	s_waitcnt lgkmcnt(0)
	v_mfma_f32_16x16x32_bf16 v[124:127], v[156:159], v[168:171], v[124:127]
	v_mfma_f32_16x16x32_bf16 v[120:123], v[164:167], v[168:171], v[120:123]
	v_mfma_f32_16x16x32_bf16 v[116:119], v[156:159], v[176:179], v[116:119]
	v_mfma_f32_16x16x32_bf16 v[112:115], v[164:167], v[176:179], v[112:115]
	v_mfma_f32_16x16x32_bf16 v[108:111], v[156:159], v[184:187], v[108:111]
	v_mfma_f32_16x16x32_bf16 v[104:107], v[164:167], v[184:187], v[104:107]
	v_mfma_f32_16x16x32_bf16 v[100:103], v[156:159], v[192:195], v[100:103]
	v_mfma_f32_16x16x32_bf16 v[96:99], v[164:167], v[192:195], v[96:99]
	v_mfma_f32_16x16x32_bf16 v[124:127], v[160:163], v[172:175], v[124:127]
	v_mfma_f32_16x16x32_bf16 v[120:123], v[152:155], v[172:175], v[120:123]
	v_mfma_f32_16x16x32_bf16 v[116:119], v[160:163], v[180:183], v[116:119]
	v_mfma_f32_16x16x32_bf16 v[112:115], v[152:155], v[180:183], v[112:115]
	v_mfma_f32_16x16x32_bf16 v[108:111], v[160:163], v[188:191], v[108:111]
	v_mfma_f32_16x16x32_bf16 v[104:107], v[152:155], v[188:191], v[104:107]
	v_mfma_f32_16x16x32_bf16 v[100:103], v[160:163], v[196:199], v[100:103]
	v_mfma_f32_16x16x32_bf16 v[96:99], v[152:155], v[196:199], v[96:99]
	s_barrier
	ds_read_b128 v[200:203], v147
	ds_read_b128 v[204:207], v148
	ds_read_b128 v[208:211], v149
	ds_read_b128 v[148:151], v150
	s_barrier
	s_waitcnt lgkmcnt(0)
	v_mfma_f32_16x16x32_bf16 v[92:95], v[200:203], v[168:171], v[92:95]
	v_mfma_f32_16x16x32_bf16 v[88:91], v[208:211], v[168:171], v[88:91]
	v_mfma_f32_16x16x32_bf16 v[84:87], v[200:203], v[176:179], v[84:87]
	v_mfma_f32_16x16x32_bf16 v[80:83], v[208:211], v[176:179], v[80:83]
	v_mfma_f32_16x16x32_bf16 v[76:79], v[200:203], v[184:187], v[76:79]
	v_mfma_f32_16x16x32_bf16 v[72:75], v[208:211], v[184:187], v[72:75]
	v_mfma_f32_16x16x32_bf16 v[68:71], v[200:203], v[192:195], v[68:71]
	v_mfma_f32_16x16x32_bf16 v[64:67], v[208:211], v[192:195], v[64:67]
	v_mfma_f32_16x16x32_bf16 v[92:95], v[204:207], v[172:175], v[92:95]
	v_mfma_f32_16x16x32_bf16 v[88:91], v[148:151], v[172:175], v[88:91]
	v_mfma_f32_16x16x32_bf16 v[84:87], v[204:207], v[180:183], v[84:87]
	v_mfma_f32_16x16x32_bf16 v[80:83], v[148:151], v[180:183], v[80:83]
	v_mfma_f32_16x16x32_bf16 v[76:79], v[204:207], v[188:191], v[76:79]
	v_mfma_f32_16x16x32_bf16 v[72:75], v[148:151], v[188:191], v[72:75]
	v_mfma_f32_16x16x32_bf16 v[68:71], v[204:207], v[196:199], v[68:71]
	v_mfma_f32_16x16x32_bf16 v[64:67], v[148:151], v[196:199], v[64:67]
	s_barrier
	ds_read_b128 v[168:171], v131 offset:16384
	ds_read_b128 v[172:175], v131 offset:17408
	ds_read_b128 v[176:179], v138 offset:16384
	ds_read_b128 v[180:183], v138 offset:17408
	ds_read_b128 v[184:187], v137 offset:16384
	ds_read_b128 v[188:191], v137 offset:17408
	ds_read_b128 v[192:195], v135 offset:16384
	ds_read_b128 v[196:199], v135 offset:17408
	s_waitcnt vmcnt(4)
	s_barrier
; #define LDA(dst, b, h) _Pragma("unroll") for (int m = 0; m < 4; ++m) _Pragma("unroll") for (int k = 0; k < 2; ++k) \
;     dst[m][k] = *reinterpret_cast<const bf16x8*>(SA(b, h) + lds_byte(wr * 64 + m * 16 + fr, k * 32 + fq * 8))
; #define LDB(dst, b, h) _Pragma("unroll") for (int n = 0; n < 2; ++n) _Pragma("unroll") for (int k = 0; k < 2; ++k) \
;     dst[n][k] = *reinterpret_cast<const bf16x8*>(SB(b, h) + lds_byte(wc * 32 + n * 16 + fr, k * 32 + fq * 8))
; #define WAIT_V(n) asm volatile("s_waitcnt vmcnt(" #n ")" ::: "memory")
; #define WAIT_L(n) asm volatile("s_waitcnt lgkmcnt(" #n ")" ::: "memory")
; #define BAR __builtin_amdgcn_s_barrier()
;     ...
;       LDA(At, 0, 1); WAIT_V(4); BAR; WAIT_L(0); MMA(1, 0, At, B0); MMA(1, 1, At, B1); BAR; }
;     { LDB(B0, 1, 0); LDA(At, 1, 0); WAIT_V(2); BAR; WAIT_L(0); MMA(0, 0, At, B0); BAR;
	s_waitcnt lgkmcnt(0)
	v_mfma_f32_16x16x32_bf16 v[60:63], v[156:159], v[168:171], v[60:63]
	v_mfma_f32_16x16x32_bf16 v[56:59], v[164:167], v[168:171], v[56:59]
	v_mfma_f32_16x16x32_bf16 v[52:55], v[156:159], v[176:179], v[52:55]
	v_mfma_f32_16x16x32_bf16 v[48:51], v[164:167], v[176:179], v[48:51]
	v_mfma_f32_16x16x32_bf16 v[44:47], v[156:159], v[184:187], v[44:47]
	v_mfma_f32_16x16x32_bf16 v[40:43], v[164:167], v[184:187], v[40:43]
	v_mfma_f32_16x16x32_bf16 v[36:39], v[156:159], v[192:195], v[36:39]
	v_mfma_f32_16x16x32_bf16 v[32:35], v[164:167], v[192:195], v[32:35]
	v_mfma_f32_16x16x32_bf16 v[60:63], v[160:163], v[172:175], v[60:63]
	v_mfma_f32_16x16x32_bf16 v[56:59], v[152:155], v[172:175], v[56:59]
	v_mfma_f32_16x16x32_bf16 v[52:55], v[160:163], v[180:183], v[52:55]
	v_mfma_f32_16x16x32_bf16 v[48:51], v[152:155], v[180:183], v[48:51]
	v_mfma_f32_16x16x32_bf16 v[44:47], v[160:163], v[188:191], v[44:47]
	v_mfma_f32_16x16x32_bf16 v[40:43], v[152:155], v[188:191], v[40:43]
	v_mfma_f32_16x16x32_bf16 v[36:39], v[160:163], v[196:199], v[36:39]
	v_mfma_f32_16x16x32_bf16 v[32:35], v[152:155], v[196:199], v[32:35]
	v_mfma_f32_16x16x32_bf16 v[28:31], v[200:203], v[168:171], v[28:31]
	v_mfma_f32_16x16x32_bf16 v[24:27], v[208:211], v[168:171], v[24:27]
	v_mfma_f32_16x16x32_bf16 v[20:23], v[200:203], v[176:179], v[20:23]
	v_mfma_f32_16x16x32_bf16 v[16:19], v[208:211], v[176:179], v[16:19]
	v_mfma_f32_16x16x32_bf16 v[12:15], v[200:203], v[184:187], v[12:15]
	v_mfma_f32_16x16x32_bf16 v[8:11], v[208:211], v[184:187], v[8:11]
	v_mfma_f32_16x16x32_bf16 v[4:7], v[200:203], v[192:195], v[4:7]
	v_mfma_f32_16x16x32_bf16 v[0:3], v[208:211], v[192:195], v[0:3]
	v_mfma_f32_16x16x32_bf16 v[28:31], v[204:207], v[172:175], v[28:31]
	v_mfma_f32_16x16x32_bf16 v[24:27], v[148:151], v[172:175], v[24:27]
	v_mfma_f32_16x16x32_bf16 v[20:23], v[204:207], v[180:183], v[20:23]
	v_mfma_f32_16x16x32_bf16 v[16:19], v[148:151], v[180:183], v[16:19]
	v_mfma_f32_16x16x32_bf16 v[12:15], v[204:207], v[188:191], v[12:15]
	v_mfma_f32_16x16x32_bf16 v[8:11], v[148:151], v[188:191], v[8:11]
	v_mfma_f32_16x16x32_bf16 v[4:7], v[204:207], v[196:199], v[4:7]
	v_mfma_f32_16x16x32_bf16 v[0:3], v[148:151], v[196:199], v[0:3]
	s_barrier
	ds_read_b128 v[148:151], v143
	ds_read_b128 v[152:155], v144
	ds_read_b128 v[156:159], v145
	ds_read_b128 v[144:147], v146
	ds_read_b128 v[160:163], v131 offset:32768
	ds_read_b128 v[164:167], v131 offset:33792
	ds_read_b128 v[168:171], v138 offset:32768
	ds_read_b128 v[172:175], v138 offset:33792
	ds_read_b128 v[176:179], v137 offset:32768
	ds_read_b128 v[180:183], v137 offset:33792
	ds_read_b128 v[184:187], v135 offset:32768
	ds_read_b128 v[188:191], v135 offset:33792
	s_waitcnt vmcnt(2)
	s_barrier
	s_waitcnt lgkmcnt(0)
	v_mfma_f32_16x16x32_bf16 v[124:127], v[148:151], v[160:163], v[124:127]
	v_mfma_f32_16x16x32_bf16 v[120:123], v[156:159], v[160:163], v[120:123]
	v_mfma_f32_16x16x32_bf16 v[116:119], v[148:151], v[168:171], v[116:119]
	v_mfma_f32_16x16x32_bf16 v[112:115], v[156:159], v[168:171], v[112:115]
	v_mfma_f32_16x16x32_bf16 v[108:111], v[148:151], v[176:179], v[108:111]
	v_mfma_f32_16x16x32_bf16 v[104:107], v[156:159], v[176:179], v[104:107]
	v_mfma_f32_16x16x32_bf16 v[100:103], v[148:151], v[184:187], v[100:103]
	v_mfma_f32_16x16x32_bf16 v[96:99], v[156:159], v[184:187], v[96:99]
	v_mfma_f32_16x16x32_bf16 v[124:127], v[152:155], v[164:167], v[124:127]
	v_mfma_f32_16x16x32_bf16 v[120:123], v[144:147], v[164:167], v[120:123]
	v_mfma_f32_16x16x32_bf16 v[116:119], v[152:155], v[172:175], v[116:119]
	v_mfma_f32_16x16x32_bf16 v[112:115], v[144:147], v[172:175], v[112:115]
	v_mfma_f32_16x16x32_bf16 v[108:111], v[152:155], v[180:183], v[108:111]
	v_mfma_f32_16x16x32_bf16 v[104:107], v[144:147], v[180:183], v[104:107]
	v_mfma_f32_16x16x32_bf16 v[100:103], v[152:155], v[188:191], v[100:103]
	v_mfma_f32_16x16x32_bf16 v[96:99], v[144:147], v[188:191], v[96:99]
	s_barrier
; #define LDA(dst, b, h) _Pragma("unroll") for (int m = 0; m < 4; ++m) _Pragma("unroll") for (int k = 0; k < 2; ++k) \
;     dst[m][k] = *reinterpret_cast<const bf16x8*>(SA(b, h) + lds_byte(wr * 64 + m * 16 + fr, k * 32 + fq * 8))
; #define LDB(dst, b, h) _Pragma("unroll") for (int n = 0; n < 2; ++n) _Pragma("unroll") for (int k = 0; k < 2; ++k) \
;     dst[n][k] = *reinterpret_cast<const bf16x8*>(SB(b, h) + lds_byte(wc * 32 + n * 16 + fr, k * 32 + fq * 8))
; #define WAIT_V(n) asm volatile("s_waitcnt vmcnt(" #n ")" ::: "memory")
; #define WAIT_L(n) asm volatile("s_waitcnt lgkmcnt(" #n ")" ::: "memory")
; #define BAR __builtin_amdgcn_s_barrier()
;     ...
;       LDB(B1, 1, 1); WAIT_V(0); BAR; WAIT_L(0); MMA(0, 1, At, B1); BAR;
;       LDA(At, 1, 1); BAR; WAIT_L(0); MMA(1, 0, At, B0); MMA(1, 1, At, B1); BAR; }
;     if (wr == 0) BAR;
	ds_read_b128 v[192:195], v139
	ds_read_b128 v[196:199], v140
	ds_read_b128 v[200:203], v141
	ds_read_b128 v[140:143], v142
	s_waitcnt vmcnt(0)
	s_barrier
	s_waitcnt lgkmcnt(0)
	v_mfma_f32_16x16x32_bf16 v[92:95], v[192:195], v[160:163], v[92:95]
	v_mfma_f32_16x16x32_bf16 v[88:91], v[200:203], v[160:163], v[88:91]
	v_mfma_f32_16x16x32_bf16 v[84:87], v[192:195], v[168:171], v[84:87]
	v_mfma_f32_16x16x32_bf16 v[80:83], v[200:203], v[168:171], v[80:83]
	v_mfma_f32_16x16x32_bf16 v[76:79], v[192:195], v[176:179], v[76:79]
	v_mfma_f32_16x16x32_bf16 v[72:75], v[200:203], v[176:179], v[72:75]
	v_mfma_f32_16x16x32_bf16 v[68:71], v[192:195], v[184:187], v[68:71]
	v_mfma_f32_16x16x32_bf16 v[64:67], v[200:203], v[184:187], v[64:67]
	v_mfma_f32_16x16x32_bf16 v[92:95], v[196:199], v[164:167], v[92:95]
	v_mfma_f32_16x16x32_bf16 v[88:91], v[140:143], v[164:167], v[88:91]
	v_mfma_f32_16x16x32_bf16 v[84:87], v[196:199], v[172:175], v[84:87]
	v_mfma_f32_16x16x32_bf16 v[80:83], v[140:143], v[172:175], v[80:83]
	v_mfma_f32_16x16x32_bf16 v[76:79], v[196:199], v[180:183], v[76:79]
	v_mfma_f32_16x16x32_bf16 v[72:75], v[140:143], v[180:183], v[72:75]
	v_mfma_f32_16x16x32_bf16 v[68:71], v[196:199], v[188:191], v[68:71]
	v_mfma_f32_16x16x32_bf16 v[64:67], v[140:143], v[188:191], v[64:67]
	s_barrier
	ds_read_b128 v[160:163], v131 offset:49152
	ds_read_b128 v[164:167], v131 offset:50176
	ds_read_b128 v[168:171], v138 offset:49152
	ds_read_b128 v[172:175], v138 offset:50176
	ds_read_b128 v[176:179], v137 offset:49152
	ds_read_b128 v[180:183], v137 offset:50176
	ds_read_b128 v[184:187], v135 offset:49152
	ds_read_b128 v[188:191], v135 offset:50176
	s_barrier
	s_waitcnt lgkmcnt(0)
	v_mfma_f32_16x16x32_bf16 v[60:63], v[148:151], v[160:163], v[60:63]
	v_mfma_f32_16x16x32_bf16 v[56:59], v[156:159], v[160:163], v[56:59]
	v_mfma_f32_16x16x32_bf16 v[52:55], v[148:151], v[168:171], v[52:55]
	v_mfma_f32_16x16x32_bf16 v[48:51], v[156:159], v[168:171], v[48:51]
	v_mfma_f32_16x16x32_bf16 v[44:47], v[148:151], v[176:179], v[44:47]
	v_mfma_f32_16x16x32_bf16 v[40:43], v[156:159], v[176:179], v[40:43]
	v_mfma_f32_16x16x32_bf16 v[36:39], v[148:151], v[184:187], v[36:39]
	v_mfma_f32_16x16x32_bf16 v[32:35], v[156:159], v[184:187], v[32:35]
	v_mfma_f32_16x16x32_bf16 v[60:63], v[152:155], v[164:167], v[60:63]
	v_mfma_f32_16x16x32_bf16 v[56:59], v[144:147], v[164:167], v[56:59]
	v_mfma_f32_16x16x32_bf16 v[52:55], v[152:155], v[172:175], v[52:55]
	v_mfma_f32_16x16x32_bf16 v[48:51], v[144:147], v[172:175], v[48:51]
	v_mfma_f32_16x16x32_bf16 v[44:47], v[152:155], v[180:183], v[44:47]
	v_mfma_f32_16x16x32_bf16 v[40:43], v[144:147], v[180:183], v[40:43]
	v_mfma_f32_16x16x32_bf16 v[36:39], v[152:155], v[188:191], v[36:39]
	v_mfma_f32_16x16x32_bf16 v[32:35], v[144:147], v[188:191], v[32:35]
	v_mfma_f32_16x16x32_bf16 v[28:31], v[192:195], v[160:163], v[28:31]
	v_mfma_f32_16x16x32_bf16 v[24:27], v[200:203], v[160:163], v[24:27]
	v_mfma_f32_16x16x32_bf16 v[20:23], v[192:195], v[168:171], v[20:23]
	v_mfma_f32_16x16x32_bf16 v[16:19], v[200:203], v[168:171], v[16:19]
	v_mfma_f32_16x16x32_bf16 v[12:15], v[192:195], v[176:179], v[12:15]
	v_mfma_f32_16x16x32_bf16 v[8:11], v[200:203], v[176:179], v[8:11]
	v_mfma_f32_16x16x32_bf16 v[4:7], v[192:195], v[184:187], v[4:7]
	v_mfma_f32_16x16x32_bf16 v[0:3], v[200:203], v[184:187], v[0:3]
	v_mfma_f32_16x16x32_bf16 v[28:31], v[196:199], v[164:167], v[28:31]
	v_mfma_f32_16x16x32_bf16 v[24:27], v[140:143], v[164:167], v[24:27]
	v_mfma_f32_16x16x32_bf16 v[20:23], v[196:199], v[172:175], v[20:23]
	v_mfma_f32_16x16x32_bf16 v[16:19], v[140:143], v[172:175], v[16:19]
	v_mfma_f32_16x16x32_bf16 v[12:15], v[196:199], v[180:183], v[12:15]
	v_mfma_f32_16x16x32_bf16 v[8:11], v[140:143], v[180:183], v[8:11]
	v_mfma_f32_16x16x32_bf16 v[4:7], v[196:199], v[188:191], v[4:7]
	v_mfma_f32_16x16x32_bf16 v[0:3], v[140:143], v[188:191], v[0:3]
	v_cmp_gt_u32_e32 vcc, s36, v136
	s_barrier
	s_and_saveexec_b64 s[10:11], vcc
	s_cbranch_execz .LBB0_113
	s_barrier

; #define STAGE(P, RS, SOFF, OFF, kt) do { const int _so = (SOFF) + (kt) * (BK * 2); \
;     _Pragma("unroll") for (int _i = 0; _i < 2; ++_i) { \
;       __builtin_amdgcn_raw_ptr_buffer_load_lds(RS, (__attribute__((address_space(3))) void*)((P) + wave * 1024 + _i * 8192), 16, OFF[_i], _so, 0, 0); } } while (0)
; #define LDA(dst, b, h) _Pragma("unroll") for (int m = 0; m < 4; ++m) _Pragma("unroll") for (int k = 0; k < 2; ++k) \
;     dst[m][k] = *reinterpret_cast<const bf16x8*>(SA(b, h) + lds_byte(wr * 64 + m * 16 + fr, k * 32 + fq * 8))
; #define LDB(dst, b, h) _Pragma("unroll") for (int n = 0; n < 2; ++n) _Pragma("unroll") for (int k = 0; k < 2; ++k) \
;     dst[n][k] = *reinterpret_cast<const bf16x8*>(SB(b, h) + lds_byte(wc * 32 + n * 16 + fr, k * 32 + fq * 8))
; #define WAIT_V(n) asm volatile("s_waitcnt vmcnt(" #n ")" ::: "memory")
; #define WAIT_L(n) asm volatile("s_waitcnt lgkmcnt(" #n ")" ::: "memory")
; #define BAR __builtin_amdgcn_s_barrier()
; #define SCHED __builtin_amdgcn_sched_barrier(0)
;     ...
;       LDB(B0, 0, 0); SCHED; LDA(At, 0, 0); STAGE(SA(1, 1), rsA, sA1, offA, t + 1);
;       WAIT_L(8); BAR; WAIT_L(0); MMA(0, 0, At, B0); BAR; SCHED;
;       LDB(B1, 0, 1); STAGE(SB(0, 0), rsB, sB0, offB, t + 2);
;       BAR; WAIT_L(0); MMA(0, 1, At, B1); BAR;
;       LDA(At, 0, 1); STAGE(SA(0, 0), rsA, sA0, offA, t + 2);
;       BAR; WAIT_L(0); MMA(1, 0, At, B0); BAR; SCHED;
;       STAGE(SB(0, 1), rsB, sB1, offB, t + 2);
;       WAIT_V(6); BAR; MMA(1, 1, At, B1); BAR;
.LBB0_148:
	ds_read_b128 v[152:155], v147
	ds_read_b128 v[156:159], v148
	ds_read_b128 v[160:163], v149
	ds_read_b128 v[164:167], v150
	s_add_i32 s4, s82, s3
	s_add_i32 s5, s4, 0x80
	s_mov_b32 m0, s31
	ds_read_b128 v[168:171], v129
	ds_read_b128 v[172:175], v129 offset:1024
	ds_read_b128 v[176:179], v132
	ds_read_b128 v[180:183], v132 offset:1024
	ds_read_b128 v[184:187], v131
	ds_read_b128 v[188:191], v131 offset:1024
	ds_read_b128 v[192:195], v130
	ds_read_b128 v[196:199], v130 offset:1024
	buffer_load_dwordx4 v141, s[8:11], s5 offen lds
	s_mov_b32 m0, s58
	s_nop 0
	buffer_load_dwordx4 v142, s[8:11], s5 offen lds
	s_waitcnt lgkmcnt(8)
	s_barrier
	s_waitcnt lgkmcnt(0)
	v_mfma_f32_16x16x32_bf16 v[124:127], v[152:155], v[168:171], v[124:127]
	v_mfma_f32_16x16x32_bf16 v[120:123], v[160:163], v[168:171], v[120:123]
	v_mfma_f32_16x16x32_bf16 v[116:119], v[152:155], v[176:179], v[116:119]
	v_mfma_f32_16x16x32_bf16 v[112:115], v[160:163], v[176:179], v[112:115]
	v_mfma_f32_16x16x32_bf16 v[108:111], v[152:155], v[184:187], v[108:111]
	v_mfma_f32_16x16x32_bf16 v[104:107], v[160:163], v[184:187], v[104:107]
	v_mfma_f32_16x16x32_bf16 v[100:103], v[152:155], v[192:195], v[100:103]
	v_mfma_f32_16x16x32_bf16 v[96:99], v[160:163], v[192:195], v[96:99]
	v_mfma_f32_16x16x32_bf16 v[124:127], v[156:159], v[172:175], v[124:127]
	v_mfma_f32_16x16x32_bf16 v[120:123], v[164:167], v[172:175], v[120:123]
	v_mfma_f32_16x16x32_bf16 v[116:119], v[156:159], v[180:183], v[116:119]
	v_mfma_f32_16x16x32_bf16 v[112:115], v[164:167], v[180:183], v[112:115]
	v_mfma_f32_16x16x32_bf16 v[108:111], v[156:159], v[188:191], v[108:111]
	v_mfma_f32_16x16x32_bf16 v[104:107], v[164:167], v[188:191], v[104:107]
	v_mfma_f32_16x16x32_bf16 v[100:103], v[156:159], v[196:199], v[100:103]
	v_mfma_f32_16x16x32_bf16 v[96:99], v[164:167], v[196:199], v[96:99]
	s_barrier
	s_add_i32 s5, s84, s3
	s_add_i32 s6, s5, 0x100
	s_mov_b32 s14, s10
	s_mov_b32 s15, s11
	s_mov_b32 m0, s34
	ds_read_b128 v[200:203], v143
	ds_read_b128 v[204:207], v144
	ds_read_b128 v[208:211], v145
	ds_read_b128 v[212:215], v146
	buffer_load_dwordx4 v141, s[12:15], s6 offen lds
	s_mov_b32 m0, s43
	s_nop 0
	buffer_load_dwordx4 v142, s[12:15], s6 offen lds
	s_barrier
	s_waitcnt lgkmcnt(0)
	v_mfma_f32_16x16x32_bf16 v[92:95], v[200:203], v[168:171], v[92:95]
	v_mfma_f32_16x16x32_bf16 v[88:91], v[208:211], v[168:171], v[88:91]
	v_mfma_f32_16x16x32_bf16 v[80:83], v[200:203], v[176:179], v[80:83]
	v_mfma_f32_16x16x32_bf16 v[68:71], v[208:211], v[176:179], v[68:71]
	v_mfma_f32_16x16x32_bf16 v[60:63], v[200:203], v[184:187], v[60:63]
	v_mfma_f32_16x16x32_bf16 v[56:59], v[208:211], v[184:187], v[56:59]
	v_mfma_f32_16x16x32_bf16 v[52:55], v[200:203], v[192:195], v[52:55]
	v_mfma_f32_16x16x32_bf16 v[48:51], v[208:211], v[192:195], v[48:51]
	v_mfma_f32_16x16x32_bf16 v[92:95], v[204:207], v[172:175], v[92:95]
	v_mfma_f32_16x16x32_bf16 v[88:91], v[212:215], v[172:175], v[88:91]
	v_mfma_f32_16x16x32_bf16 v[80:83], v[204:207], v[180:183], v[80:83]
	v_mfma_f32_16x16x32_bf16 v[68:71], v[212:215], v[180:183], v[68:71]
	v_mfma_f32_16x16x32_bf16 v[60:63], v[204:207], v[188:191], v[60:63]
	v_mfma_f32_16x16x32_bf16 v[56:59], v[212:215], v[188:191], v[56:59]
	v_mfma_f32_16x16x32_bf16 v[52:55], v[204:207], v[196:199], v[52:55]
	v_mfma_f32_16x16x32_bf16 v[48:51], v[212:215], v[196:199], v[48:51]
	s_barrier
	s_add_i32 s6, s83, s3
	s_add_i32 s7, s6, 0x100
	s_mov_b32 m0, s30
	ds_read_b128 v[168:171], v129 offset:16384
	ds_read_b128 v[172:175], v129 offset:17408
	ds_read_b128 v[176:179], v132 offset:16384
	ds_read_b128 v[180:183], v132 offset:17408
	ds_read_b128 v[184:187], v131 offset:16384
	ds_read_b128 v[188:191], v131 offset:17408
	ds_read_b128 v[192:195], v130 offset:16384
	ds_read_b128 v[196:199], v130 offset:17408
	buffer_load_dwordx4 v141, s[8:11], s7 offen lds
	s_mov_b32 m0, s44
	s_nop 0
	buffer_load_dwordx4 v142, s[8:11], s7 offen lds
	s_barrier
	s_waitcnt lgkmcnt(0)
	v_mfma_f32_16x16x32_bf16 v[44:47], v[152:155], v[168:171], v[44:47]
	v_mfma_f32_16x16x32_bf16 v[40:43], v[160:163], v[168:171], v[40:43]
	v_mfma_f32_16x16x32_bf16 v[36:39], v[152:155], v[176:179], v[36:39]
	v_mfma_f32_16x16x32_bf16 v[32:35], v[160:163], v[176:179], v[32:35]
	v_mfma_f32_16x16x32_bf16 v[28:31], v[152:155], v[184:187], v[28:31]
	v_mfma_f32_16x16x32_bf16 v[24:27], v[160:163], v[184:187], v[24:27]
	v_mfma_f32_16x16x32_bf16 v[20:23], v[152:155], v[192:195], v[20:23]
	v_mfma_f32_16x16x32_bf16 v[16:19], v[160:163], v[192:195], v[16:19]
	v_mfma_f32_16x16x32_bf16 v[44:47], v[156:159], v[172:175], v[44:47]
	v_mfma_f32_16x16x32_bf16 v[40:43], v[164:167], v[172:175], v[40:43]
	v_mfma_f32_16x16x32_bf16 v[36:39], v[156:159], v[180:183], v[36:39]
	v_mfma_f32_16x16x32_bf16 v[32:35], v[164:167], v[180:183], v[32:35]
	v_mfma_f32_16x16x32_bf16 v[28:31], v[156:159], v[188:191], v[28:31]
	v_mfma_f32_16x16x32_bf16 v[24:27], v[164:167], v[188:191], v[24:27]
	v_mfma_f32_16x16x32_bf16 v[20:23], v[156:159], v[196:199], v[20:23]
	v_mfma_f32_16x16x32_bf16 v[16:19], v[164:167], v[196:199], v[16:19]
	s_barrier
	s_add_i32 s7, s85, s3
	s_add_i32 s19, s7, 0x100
	s_mov_b32 m0, s35
	s_nop 0
	buffer_load_dwordx4 v141, s[12:15], s19 offen lds
	s_mov_b32 m0, s45
	s_nop 0
	buffer_load_dwordx4 v142, s[12:15], s19 offen lds
	s_waitcnt vmcnt(6)
	s_barrier
; #define STAGE(P, RS, SOFF, OFF, kt) do { const int _so = (SOFF) + (kt) * (BK * 2); \
;     _Pragma("unroll") for (int _i = 0; _i < 2; ++_i) { \
;       __builtin_amdgcn_raw_ptr_buffer_load_lds(RS, (__attribute__((address_space(3))) void*)((P) + wave * 1024 + _i * 8192), 16, OFF[_i], _so, 0, 0); } } while (0)
; #define LDA(dst, b, h) _Pragma("unroll") for (int m = 0; m < 4; ++m) _Pragma("unroll") for (int k = 0; k < 2; ++k) \
;     dst[m][k] = *reinterpret_cast<const bf16x8*>(SA(b, h) + lds_byte(wr * 64 + m * 16 + fr, k * 32 + fq * 8))
; #define LDB(dst, b, h) _Pragma("unroll") for (int n = 0; n < 2; ++n) _Pragma("unroll") for (int k = 0; k < 2; ++k) \
;     dst[n][k] = *reinterpret_cast<const bf16x8*>(SB(b, h) + lds_byte(wc * 32 + n * 16 + fr, k * 32 + fq * 8))
; #define WAIT_V(n) asm volatile("s_waitcnt vmcnt(" #n ")" ::: "memory")
; #define WAIT_L(n) asm volatile("s_waitcnt lgkmcnt(" #n ")" ::: "memory")
; #define BAR __builtin_amdgcn_s_barrier()
; #define SCHED __builtin_amdgcn_sched_barrier(0)
;     ...
;       WAIT_V(6); BAR; MMA(1, 1, At, B1); BAR;
;       LDB(B0, 1, 0); SCHED; LDA(At, 1, 0); STAGE(SA(0, 1), rsA, sA1, offA, t + 2);
;       WAIT_L(8); BAR; WAIT_L(0); MMA(0, 0, At, B0); BAR; SCHED;
;       LDB(B1, 1, 1); STAGE(SB(1, 0), rsB, sB0, offB, t + 3);
;       BAR; WAIT_L(0); MMA(0, 1, At, B1); BAR;
;       LDA(At, 1, 1); STAGE(SA(1, 0), rsA, sA0, offA, t + 3);
;       BAR; WAIT_L(0); MMA(1, 0, At, B0); BAR; SCHED;
	v_mfma_f32_16x16x32_bf16 v[12:15], v[200:203], v[168:171], v[12:15]
	v_mfma_f32_16x16x32_bf16 v[8:11], v[208:211], v[168:171], v[8:11]
	v_mfma_f32_16x16x32_bf16 v[4:7], v[200:203], v[176:179], v[4:7]
	v_mfma_f32_16x16x32_bf16 v[0:3], v[208:211], v[176:179], v[0:3]
	v_mfma_f32_16x16x32_bf16 v[64:67], v[200:203], v[184:187], v[64:67]
	v_mfma_f32_16x16x32_bf16 v[72:75], v[208:211], v[184:187], v[72:75]
	v_mfma_f32_16x16x32_bf16 v[76:79], v[200:203], v[192:195], v[76:79]
	v_mfma_f32_16x16x32_bf16 v[84:87], v[208:211], v[192:195], v[84:87]
	v_mfma_f32_16x16x32_bf16 v[12:15], v[204:207], v[172:175], v[12:15]
	v_mfma_f32_16x16x32_bf16 v[8:11], v[212:215], v[172:175], v[8:11]
	v_mfma_f32_16x16x32_bf16 v[4:7], v[204:207], v[180:183], v[4:7]
	v_mfma_f32_16x16x32_bf16 v[0:3], v[212:215], v[180:183], v[0:3]
	v_mfma_f32_16x16x32_bf16 v[64:67], v[204:207], v[188:191], v[64:67]
	v_mfma_f32_16x16x32_bf16 v[72:75], v[212:215], v[188:191], v[72:75]
	v_mfma_f32_16x16x32_bf16 v[76:79], v[204:207], v[196:199], v[76:79]
	v_mfma_f32_16x16x32_bf16 v[84:87], v[212:215], v[196:199], v[84:87]
	s_barrier
	ds_read_b128 v[152:155], v137
	ds_read_b128 v[156:159], v138
	ds_read_b128 v[160:163], v139
	ds_read_b128 v[164:167], v140
	s_addk_i32 s4, 0x100
	s_mov_b32 m0, s36
	ds_read_b128 v[168:171], v129 offset:32768
	ds_read_b128 v[172:175], v129 offset:33792
	ds_read_b128 v[176:179], v132 offset:32768
	ds_read_b128 v[180:183], v132 offset:33792
	ds_read_b128 v[184:187], v131 offset:32768
	ds_read_b128 v[188:191], v131 offset:33792
	ds_read_b128 v[192:195], v130 offset:32768
	ds_read_b128 v[196:199], v130 offset:33792
	buffer_load_dwordx4 v141, s[8:11], s4 offen lds
	s_mov_b32 m0, s48
	s_nop 0
	buffer_load_dwordx4 v142, s[8:11], s4 offen lds
	s_waitcnt lgkmcnt(8)
	s_barrier
	s_waitcnt lgkmcnt(0)
	v_mfma_f32_16x16x32_bf16 v[124:127], v[152:155], v[168:171], v[124:127]
	v_mfma_f32_16x16x32_bf16 v[120:123], v[160:163], v[168:171], v[120:123]
	v_mfma_f32_16x16x32_bf16 v[116:119], v[152:155], v[176:179], v[116:119]
	v_mfma_f32_16x16x32_bf16 v[112:115], v[160:163], v[176:179], v[112:115]
	v_mfma_f32_16x16x32_bf16 v[108:111], v[152:155], v[184:187], v[108:111]
	v_mfma_f32_16x16x32_bf16 v[104:107], v[160:163], v[184:187], v[104:107]
	v_mfma_f32_16x16x32_bf16 v[100:103], v[152:155], v[192:195], v[100:103]
	v_mfma_f32_16x16x32_bf16 v[96:99], v[160:163], v[192:195], v[96:99]
	v_mfma_f32_16x16x32_bf16 v[124:127], v[156:159], v[172:175], v[124:127]
	v_mfma_f32_16x16x32_bf16 v[120:123], v[164:167], v[172:175], v[120:123]
	v_mfma_f32_16x16x32_bf16 v[116:119], v[156:159], v[180:183], v[116:119]
	v_mfma_f32_16x16x32_bf16 v[112:115], v[164:167], v[180:183], v[112:115]
	v_mfma_f32_16x16x32_bf16 v[108:111], v[156:159], v[188:191], v[108:111]
	v_mfma_f32_16x16x32_bf16 v[104:107], v[164:167], v[188:191], v[104:107]
	v_mfma_f32_16x16x32_bf16 v[100:103], v[156:159], v[196:199], v[100:103]
	v_mfma_f32_16x16x32_bf16 v[96:99], v[164:167], v[196:199], v[96:99]
	s_barrier
	s_addk_i32 s5, 0x180
	s_mov_b32 m0, s37
	ds_read_b128 v[200:203], v133
	ds_read_b128 v[204:207], v134
	ds_read_b128 v[208:211], v135
	ds_read_b128 v[212:215], v136
	buffer_load_dwordx4 v141, s[12:15], s5 offen lds
	s_mov_b32 m0, s49
	s_nop 0
	buffer_load_dwordx4 v142, s[12:15], s5 offen lds
	s_barrier
	s_waitcnt lgkmcnt(0)
	v_mfma_f32_16x16x32_bf16 v[92:95], v[200:203], v[168:171], v[92:95]
	v_mfma_f32_16x16x32_bf16 v[88:91], v[208:211], v[168:171], v[88:91]
	v_mfma_f32_16x16x32_bf16 v[80:83], v[200:203], v[176:179], v[80:83]
	v_mfma_f32_16x16x32_bf16 v[68:71], v[208:211], v[176:179], v[68:71]
	v_mfma_f32_16x16x32_bf16 v[60:63], v[200:203], v[184:187], v[60:63]
	v_mfma_f32_16x16x32_bf16 v[56:59], v[208:211], v[184:187], v[56:59]
	v_mfma_f32_16x16x32_bf16 v[52:55], v[200:203], v[192:195], v[52:55]
	v_mfma_f32_16x16x32_bf16 v[48:51], v[208:211], v[192:195], v[48:51]
	v_mfma_f32_16x16x32_bf16 v[92:95], v[204:207], v[172:175], v[92:95]
	v_mfma_f32_16x16x32_bf16 v[88:91], v[212:215], v[172:175], v[88:91]
	v_mfma_f32_16x16x32_bf16 v[80:83], v[204:207], v[180:183], v[80:83]
	v_mfma_f32_16x16x32_bf16 v[68:71], v[212:215], v[180:183], v[68:71]
	v_mfma_f32_16x16x32_bf16 v[60:63], v[204:207], v[188:191], v[60:63]
	v_mfma_f32_16x16x32_bf16 v[56:59], v[212:215], v[188:191], v[56:59]
	v_mfma_f32_16x16x32_bf16 v[52:55], v[204:207], v[196:199], v[52:55]
	v_mfma_f32_16x16x32_bf16 v[48:51], v[212:215], v[196:199], v[48:51]
	s_barrier
	s_addk_i32 s6, 0x180
	s_mov_b32 m0, s38
	ds_read_b128 v[168:171], v129 offset:49152
	ds_read_b128 v[172:175], v129 offset:50176
	ds_read_b128 v[176:179], v132 offset:49152
	ds_read_b128 v[180:183], v132 offset:50176
	ds_read_b128 v[184:187], v131 offset:49152
	ds_read_b128 v[188:191], v131 offset:50176
	ds_read_b128 v[192:195], v130 offset:49152
	ds_read_b128 v[196:199], v130 offset:50176
	buffer_load_dwordx4 v141, s[8:11], s6 offen lds
	s_mov_b32 m0, s54
	s_nop 0
	buffer_load_dwordx4 v142, s[8:11], s6 offen lds
	s_barrier
	s_waitcnt lgkmcnt(0)
	v_mfma_f32_16x16x32_bf16 v[44:47], v[152:155], v[168:171], v[44:47]
	v_mfma_f32_16x16x32_bf16 v[40:43], v[160:163], v[168:171], v[40:43]
	v_mfma_f32_16x16x32_bf16 v[36:39], v[152:155], v[176:179], v[36:39]
	v_mfma_f32_16x16x32_bf16 v[32:35], v[160:163], v[176:179], v[32:35]
	v_mfma_f32_16x16x32_bf16 v[28:31], v[152:155], v[184:187], v[28:31]
	v_mfma_f32_16x16x32_bf16 v[24:27], v[160:163], v[184:187], v[24:27]
	v_mfma_f32_16x16x32_bf16 v[20:23], v[152:155], v[192:195], v[20:23]
	v_mfma_f32_16x16x32_bf16 v[16:19], v[160:163], v[192:195], v[16:19]
	v_mfma_f32_16x16x32_bf16 v[44:47], v[156:159], v[172:175], v[44:47]
	v_mfma_f32_16x16x32_bf16 v[40:43], v[164:167], v[172:175], v[40:43]
	v_mfma_f32_16x16x32_bf16 v[36:39], v[156:159], v[180:183], v[36:39]
	v_mfma_f32_16x16x32_bf16 v[32:35], v[164:167], v[180:183], v[32:35]
	v_mfma_f32_16x16x32_bf16 v[28:31], v[156:159], v[188:191], v[28:31]
	v_mfma_f32_16x16x32_bf16 v[24:27], v[164:167], v[188:191], v[24:27]
	v_mfma_f32_16x16x32_bf16 v[20:23], v[156:159], v[196:199], v[20:23]
	v_mfma_f32_16x16x32_bf16 v[16:19], v[164:167], v[196:199], v[16:19]
	s_barrier
; #define STAGE(P, RS, SOFF, OFF, kt) do { const int _so = (SOFF) + (kt) * (BK * 2); \
;     _Pragma("unroll") for (int _i = 0; _i < 2; ++_i) { \
;       __builtin_amdgcn_raw_ptr_buffer_load_lds(RS, (__attribute__((address_space(3))) void*)((P) + wave * 1024 + _i * 8192), 16, OFF[_i], _so, 0, 0); } } while (0)
; #define LDA(dst, b, h) _Pragma("unroll") for (int m = 0; m < 4; ++m) _Pragma("unroll") for (int k = 0; k < 2; ++k) \
;     dst[m][k] = *reinterpret_cast<const bf16x8*>(SA(b, h) + lds_byte(wr * 64 + m * 16 + fr, k * 32 + fq * 8))
; #define LDB(dst, b, h) _Pragma("unroll") for (int n = 0; n < 2; ++n) _Pragma("unroll") for (int k = 0; k < 2; ++k) \
;     dst[n][k] = *reinterpret_cast<const bf16x8*>(SB(b, h) + lds_byte(wc * 32 + n * 16 + fr, k * 32 + fq * 8))
; #define WAIT_V(n) asm volatile("s_waitcnt vmcnt(" #n ")" ::: "memory")
; #define WAIT_L(n) asm volatile("s_waitcnt lgkmcnt(" #n ")" ::: "memory")
; #define BAR __builtin_amdgcn_s_barrier()
;     ...
;       STAGE(SB(1, 1), rsB, sB1, offB, t + 3);
;       WAIT_V(6); BAR; MMA(1, 1, At, B1); BAR;
;     }
;     { LDB(B0, 0, 0); LDA(At, 0, 0); STAGE(SA(1, 1), rsA, sA1, offA, nt - 1);
;       BAR; WAIT_L(0); MMA(0, 0, At, B0); BAR;
;       LDB(B1, 0, 1); BAR; WAIT_L(0); MMA(0, 1, At, B1); BAR;
;       LDA(At, 0, 1); WAIT_V(4); BAR; WAIT_L(0); MMA(1, 0, At, B0); MMA(1, 1, At, B1); BAR; }
	s_addk_i32 s7, 0x180
	s_mov_b32 m0, s39
	s_nop 0
	buffer_load_dwordx4 v141, s[12:15], s7 offen lds
	s_mov_b32 m0, s55
	s_nop 0
	buffer_load_dwordx4 v142, s[12:15], s7 offen lds
	s_waitcnt vmcnt(6)
	s_barrier
	v_mfma_f32_16x16x32_bf16 v[12:15], v[200:203], v[168:171], v[12:15]
	v_mfma_f32_16x16x32_bf16 v[8:11], v[208:211], v[168:171], v[8:11]
	v_mfma_f32_16x16x32_bf16 v[4:7], v[200:203], v[176:179], v[4:7]
	v_mfma_f32_16x16x32_bf16 v[0:3], v[208:211], v[176:179], v[0:3]
	v_mfma_f32_16x16x32_bf16 v[64:67], v[200:203], v[184:187], v[64:67]
	v_mfma_f32_16x16x32_bf16 v[72:75], v[208:211], v[184:187], v[72:75]
	v_mfma_f32_16x16x32_bf16 v[76:79], v[200:203], v[192:195], v[76:79]
	v_mfma_f32_16x16x32_bf16 v[84:87], v[208:211], v[192:195], v[84:87]
	v_mfma_f32_16x16x32_bf16 v[12:15], v[204:207], v[172:175], v[12:15]
	v_mfma_f32_16x16x32_bf16 v[8:11], v[212:215], v[172:175], v[8:11]
	v_mfma_f32_16x16x32_bf16 v[4:7], v[204:207], v[180:183], v[4:7]
	v_mfma_f32_16x16x32_bf16 v[0:3], v[212:215], v[180:183], v[0:3]
	v_mfma_f32_16x16x32_bf16 v[64:67], v[204:207], v[188:191], v[64:67]
	v_mfma_f32_16x16x32_bf16 v[72:75], v[212:215], v[188:191], v[72:75]
	v_mfma_f32_16x16x32_bf16 v[76:79], v[204:207], v[196:199], v[76:79]
	v_mfma_f32_16x16x32_bf16 v[84:87], v[212:215], v[196:199], v[84:87]
	s_barrier
	s_add_i32 s1, s1, 2
	s_addk_i32 s3, 0x100
	s_cmp_gt_u32 s1, 59
	s_cbranch_scc0 .LBB0_148
	s_add_i32 s1, s82, 0x1f80
	s_mov_b32 m0, s31
	ds_read_b128 v[152:155], v147
	ds_read_b128 v[156:159], v148
	ds_read_b128 v[160:163], v149
	ds_read_b128 v[148:151], v150
	ds_read_b128 v[164:167], v129
	ds_read_b128 v[168:171], v129 offset:1024
	ds_read_b128 v[172:175], v132
	ds_read_b128 v[176:179], v132 offset:1024
	ds_read_b128 v[180:183], v131
	ds_read_b128 v[184:187], v131 offset:1024
	ds_read_b128 v[188:191], v130
	ds_read_b128 v[192:195], v130 offset:1024
	buffer_load_dwordx4 v141, s[8:11], s1 offen lds
	s_mov_b32 m0, s58
	s_nop 0
	buffer_load_dwordx4 v142, s[8:11], s1 offen lds
	s_barrier
	s_waitcnt lgkmcnt(0)
	v_mfma_f32_16x16x32_bf16 v[124:127], v[152:155], v[164:167], v[124:127]
	v_mfma_f32_16x16x32_bf16 v[120:123], v[160:163], v[164:167], v[120:123]
	v_mfma_f32_16x16x32_bf16 v[116:119], v[152:155], v[172:175], v[116:119]
	v_mfma_f32_16x16x32_bf16 v[112:115], v[160:163], v[172:175], v[112:115]
	v_mfma_f32_16x16x32_bf16 v[108:111], v[152:155], v[180:183], v[108:111]
	v_mfma_f32_16x16x32_bf16 v[104:107], v[160:163], v[180:183], v[104:107]
	v_mfma_f32_16x16x32_bf16 v[100:103], v[152:155], v[188:191], v[100:103]
	v_mfma_f32_16x16x32_bf16 v[96:99], v[160:163], v[188:191], v[96:99]
	v_mfma_f32_16x16x32_bf16 v[124:127], v[156:159], v[168:171], v[124:127]
	v_mfma_f32_16x16x32_bf16 v[120:123], v[148:151], v[168:171], v[120:123]
	v_mfma_f32_16x16x32_bf16 v[116:119], v[156:159], v[176:179], v[116:119]
	v_mfma_f32_16x16x32_bf16 v[112:115], v[148:151], v[176:179], v[112:115]
	v_mfma_f32_16x16x32_bf16 v[108:111], v[156:159], v[184:187], v[108:111]
	v_mfma_f32_16x16x32_bf16 v[104:107], v[148:151], v[184:187], v[104:107]
	v_mfma_f32_16x16x32_bf16 v[100:103], v[156:159], v[192:195], v[100:103]
	v_mfma_f32_16x16x32_bf16 v[96:99], v[148:151], v[192:195], v[96:99]
	s_barrier
	ds_read_b128 v[196:199], v143
	ds_read_b128 v[200:203], v144
	ds_read_b128 v[142:145], v145
	ds_read_b128 v[204:207], v146
	s_barrier
	s_waitcnt lgkmcnt(0)
	v_mfma_f32_16x16x32_bf16 v[88:91], v[142:145], v[164:167], v[88:91]
	v_mfma_f32_16x16x32_bf16 v[80:83], v[196:199], v[172:175], v[80:83]
	v_mfma_f32_16x16x32_bf16 v[60:63], v[196:199], v[180:183], v[60:63]
	v_mfma_f32_16x16x32_bf16 v[56:59], v[142:145], v[180:183], v[56:59]
	v_mfma_f32_16x16x32_bf16 v[52:55], v[196:199], v[188:191], v[52:55]
	v_mfma_f32_16x16x32_bf16 v[48:51], v[142:145], v[188:191], v[48:51]
	v_mfma_f32_16x16x32_bf16 v[92:95], v[196:199], v[164:167], v[92:95]
	v_mfma_f32_16x16x32_bf16 v[68:71], v[142:145], v[172:175], v[68:71]
	v_mfma_f32_16x16x32_bf16 v[88:91], v[204:207], v[168:171], v[88:91]
	v_mfma_f32_16x16x32_bf16 v[80:83], v[200:203], v[176:179], v[80:83]
	v_mfma_f32_16x16x32_bf16 v[60:63], v[200:203], v[184:187], v[60:63]
	v_mfma_f32_16x16x32_bf16 v[56:59], v[204:207], v[184:187], v[56:59]
	v_mfma_f32_16x16x32_bf16 v[52:55], v[200:203], v[192:195], v[52:55]
	v_mfma_f32_16x16x32_bf16 v[48:51], v[204:207], v[192:195], v[48:51]
	v_mfma_f32_16x16x32_bf16 v[164:167], v[200:203], v[168:171], v[92:95]
	v_mfma_f32_16x16x32_bf16 v[168:171], v[204:207], v[176:179], v[68:71]
	s_barrier
	s_nop 0
	ds_read_b128 v[68:71], v129 offset:16384
	ds_read_b128 v[92:95], v129 offset:17408
	ds_read_b128 v[172:175], v132 offset:16384
	ds_read_b128 v[176:179], v132 offset:17408
	ds_read_b128 v[180:183], v131 offset:16384
	ds_read_b128 v[184:187], v131 offset:17408
	ds_read_b128 v[188:191], v130 offset:16384
	ds_read_b128 v[192:195], v130 offset:17408
	s_waitcnt vmcnt(4)
	s_barrier
; #define LDA(dst, b, h) _Pragma("unroll") for (int m = 0; m < 4; ++m) _Pragma("unroll") for (int k = 0; k < 2; ++k) \
;     dst[m][k] = *reinterpret_cast<const bf16x8*>(SA(b, h) + lds_byte(wr * 64 + m * 16 + fr, k * 32 + fq * 8))
; #define LDB(dst, b, h) _Pragma("unroll") for (int n = 0; n < 2; ++n) _Pragma("unroll") for (int k = 0; k < 2; ++k) \
;     dst[n][k] = *reinterpret_cast<const bf16x8*>(SB(b, h) + lds_byte(wc * 32 + n * 16 + fr, k * 32 + fq * 8))
; #define WAIT_V(n) asm volatile("s_waitcnt vmcnt(" #n ")" ::: "memory")
; #define WAIT_L(n) asm volatile("s_waitcnt lgkmcnt(" #n ")" ::: "memory")
; #define BAR __builtin_amdgcn_s_barrier()
;     ...
;       LDA(At, 0, 1); WAIT_V(4); BAR; WAIT_L(0); MMA(1, 0, At, B0); MMA(1, 1, At, B1); BAR; }
;     { LDB(B0, 1, 0); LDA(At, 1, 0); WAIT_V(2); BAR; WAIT_L(0); MMA(0, 0, At, B0); BAR;
	s_waitcnt lgkmcnt(0)
	v_mfma_f32_16x16x32_bf16 v[44:47], v[152:155], v[68:71], v[44:47]
	v_mfma_f32_16x16x32_bf16 v[40:43], v[160:163], v[68:71], v[40:43]
	v_mfma_f32_16x16x32_bf16 v[36:39], v[152:155], v[172:175], v[36:39]
	v_mfma_f32_16x16x32_bf16 v[32:35], v[160:163], v[172:175], v[32:35]
	v_mfma_f32_16x16x32_bf16 v[28:31], v[152:155], v[180:183], v[28:31]
	v_mfma_f32_16x16x32_bf16 v[24:27], v[160:163], v[180:183], v[24:27]
	v_mfma_f32_16x16x32_bf16 v[20:23], v[152:155], v[188:191], v[20:23]
	v_mfma_f32_16x16x32_bf16 v[16:19], v[160:163], v[188:191], v[16:19]
	v_mfma_f32_16x16x32_bf16 v[44:47], v[156:159], v[92:95], v[44:47]
	v_mfma_f32_16x16x32_bf16 v[40:43], v[148:151], v[92:95], v[40:43]
	v_mfma_f32_16x16x32_bf16 v[36:39], v[156:159], v[176:179], v[36:39]
	v_mfma_f32_16x16x32_bf16 v[32:35], v[148:151], v[176:179], v[32:35]
	v_mfma_f32_16x16x32_bf16 v[28:31], v[156:159], v[184:187], v[28:31]
	v_mfma_f32_16x16x32_bf16 v[24:27], v[148:151], v[184:187], v[24:27]
	v_mfma_f32_16x16x32_bf16 v[20:23], v[156:159], v[192:195], v[20:23]
	v_mfma_f32_16x16x32_bf16 v[16:19], v[148:151], v[192:195], v[16:19]
	v_mfma_f32_16x16x32_bf16 v[8:11], v[142:145], v[68:71], v[8:11]
	v_mfma_f32_16x16x32_bf16 v[0:3], v[142:145], v[172:175], v[0:3]
	v_mfma_f32_16x16x32_bf16 v[12:15], v[196:199], v[68:71], v[12:15]
	v_mfma_f32_16x16x32_bf16 v[4:7], v[196:199], v[172:175], v[4:7]
	v_mfma_f32_16x16x32_bf16 v[64:67], v[196:199], v[180:183], v[64:67]
	v_mfma_f32_16x16x32_bf16 v[68:71], v[142:145], v[180:183], v[72:75]
	v_mfma_f32_16x16x32_bf16 v[72:75], v[196:199], v[188:191], v[76:79]
	v_mfma_f32_16x16x32_bf16 v[76:79], v[142:145], v[188:191], v[84:87]
	v_mfma_f32_16x16x32_bf16 v[8:11], v[204:207], v[92:95], v[8:11]
	v_mfma_f32_16x16x32_bf16 v[0:3], v[204:207], v[176:179], v[0:3]
	v_mfma_f32_16x16x32_bf16 v[160:163], v[200:203], v[92:95], v[12:15]
	v_mfma_f32_16x16x32_bf16 v[172:175], v[200:203], v[176:179], v[4:7]
	v_mfma_f32_16x16x32_bf16 v[176:179], v[200:203], v[184:187], v[64:67]
	v_mfma_f32_16x16x32_bf16 v[180:183], v[204:207], v[184:187], v[68:71]
	v_mfma_f32_16x16x32_bf16 v[184:187], v[200:203], v[192:195], v[72:75]
	v_mfma_f32_16x16x32_bf16 v[188:191], v[204:207], v[192:195], v[76:79]
	s_barrier
	ds_read_b128 v[4:7], v137
	ds_read_b128 v[12:15], v138
	ds_read_b128 v[192:195], v139
	ds_read_b128 v[138:141], v140
	ds_read_b128 v[72:75], v129 offset:32768
	ds_read_b128 v[142:145], v129 offset:33792
	ds_read_b128 v[76:79], v132 offset:32768
	ds_read_b128 v[196:199], v132 offset:33792
	ds_read_b128 v[152:155], v131 offset:32768
	ds_read_b128 v[200:203], v131 offset:33792
	ds_read_b128 v[204:207], v130 offset:32768
	ds_read_b128 v[208:211], v130 offset:33792
	s_waitcnt vmcnt(2)
	s_barrier
	s_waitcnt lgkmcnt(0)
	v_mfma_f32_16x16x32_bf16 v[64:67], v[4:7], v[72:75], v[124:127]
	v_mfma_f32_16x16x32_bf16 v[84:87], v[192:195], v[72:75], v[120:123]
	v_mfma_f32_16x16x32_bf16 v[92:95], v[4:7], v[76:79], v[116:119]
	v_mfma_f32_16x16x32_bf16 v[112:115], v[192:195], v[76:79], v[112:115]
	v_mfma_f32_16x16x32_bf16 v[108:111], v[4:7], v[152:155], v[108:111]
	v_mfma_f32_16x16x32_bf16 v[104:107], v[192:195], v[152:155], v[104:107]
	v_mfma_f32_16x16x32_bf16 v[100:103], v[4:7], v[204:207], v[100:103]
	v_mfma_f32_16x16x32_bf16 v[96:99], v[192:195], v[204:207], v[96:99]
	v_mfma_f32_16x16x32_bf16 v[68:71], v[12:15], v[142:145], v[64:67]
	v_mfma_f32_16x16x32_bf16 v[64:67], v[138:141], v[142:145], v[84:87]
	v_mfma_f32_16x16x32_bf16 v[156:159], v[12:15], v[196:199], v[92:95]
	v_mfma_f32_16x16x32_bf16 v[148:151], v[138:141], v[196:199], v[112:115]
	v_mfma_f32_16x16x32_bf16 v[124:127], v[12:15], v[200:203], v[108:111]
	v_mfma_f32_16x16x32_bf16 v[116:119], v[138:141], v[200:203], v[104:107]
	v_mfma_f32_16x16x32_bf16 v[92:95], v[12:15], v[208:211], v[100:103]
	v_mfma_f32_16x16x32_bf16 v[84:87], v[138:141], v[208:211], v[96:99]
	s_barrier
; #define LDA(dst, b, h) _Pragma("unroll") for (int m = 0; m < 4; ++m) _Pragma("unroll") for (int k = 0; k < 2; ++k) \
;     dst[m][k] = *reinterpret_cast<const bf16x8*>(SA(b, h) + lds_byte(wr * 64 + m * 16 + fr, k * 32 + fq * 8))
; #define LDB(dst, b, h) _Pragma("unroll") for (int n = 0; n < 2; ++n) _Pragma("unroll") for (int k = 0; k < 2; ++k) \
;     dst[n][k] = *reinterpret_cast<const bf16x8*>(SB(b, h) + lds_byte(wc * 32 + n * 16 + fr, k * 32 + fq * 8))
; #define WAIT_V(n) asm volatile("s_waitcnt vmcnt(" #n ")" ::: "memory")
; #define WAIT_L(n) asm volatile("s_waitcnt lgkmcnt(" #n ")" ::: "memory")
; #define BAR __builtin_amdgcn_s_barrier()
;     ...
;       LDB(B1, 1, 1); WAIT_V(0); BAR; WAIT_L(0); MMA(0, 1, At, B1); BAR;
;       LDA(At, 1, 1); BAR; WAIT_L(0); MMA(1, 0, At, B0); MMA(1, 1, At, B1); BAR; }
;     if (wr == 0) BAR;
	s_nop 0
	ds_read_b128 v[96:99], v133
	ds_read_b128 v[100:103], v134
	ds_read_b128 v[104:107], v135
	ds_read_b128 v[108:111], v136
	s_waitcnt vmcnt(0)
	s_barrier
	s_waitcnt lgkmcnt(0)
	v_mfma_f32_16x16x32_bf16 v[112:115], v[96:99], v[72:75], v[164:167]
	v_mfma_f32_16x16x32_bf16 v[72:75], v[104:107], v[72:75], v[88:91]
	v_mfma_f32_16x16x32_bf16 v[80:83], v[96:99], v[76:79], v[80:83]
	v_mfma_f32_16x16x32_bf16 v[88:91], v[104:107], v[76:79], v[168:171]
	v_mfma_f32_16x16x32_bf16 v[60:63], v[96:99], v[152:155], v[60:63]
	v_mfma_f32_16x16x32_bf16 v[56:59], v[104:107], v[152:155], v[56:59]
	v_mfma_f32_16x16x32_bf16 v[52:55], v[96:99], v[204:207], v[52:55]
	v_mfma_f32_16x16x32_bf16 v[48:51], v[104:107], v[204:207], v[48:51]
	v_mfma_f32_16x16x32_bf16 v[76:79], v[100:103], v[142:145], v[112:115]
	v_mfma_f32_16x16x32_bf16 v[72:75], v[108:111], v[142:145], v[72:75]
	v_mfma_f32_16x16x32_bf16 v[152:155], v[100:103], v[196:199], v[80:83]
	v_mfma_f32_16x16x32_bf16 v[144:147], v[108:111], v[196:199], v[88:91]
	v_mfma_f32_16x16x32_bf16 v[120:123], v[100:103], v[200:203], v[60:63]
	v_mfma_f32_16x16x32_bf16 v[112:115], v[108:111], v[200:203], v[56:59]
	v_mfma_f32_16x16x32_bf16 v[88:91], v[100:103], v[208:211], v[52:55]
	v_mfma_f32_16x16x32_bf16 v[80:83], v[108:111], v[208:211], v[48:51]
	s_barrier
	s_nop 0
	ds_read_b128 v[48:51], v129 offset:49152
	ds_read_b128 v[134:137], v129 offset:50176
	ds_read_b128 v[56:59], v132 offset:49152
	ds_read_b128 v[164:167], v132 offset:50176
	ds_read_b128 v[168:171], v131 offset:49152
	ds_read_b128 v[196:199], v131 offset:50176
	ds_read_b128 v[200:203], v130 offset:49152
	ds_read_b128 v[130:133], v130 offset:50176
	s_barrier
	s_waitcnt lgkmcnt(0)
	v_mfma_f32_16x16x32_bf16 v[44:47], v[4:7], v[48:51], v[44:47]
	v_mfma_f32_16x16x32_bf16 v[40:43], v[192:195], v[48:51], v[40:43]
	v_mfma_f32_16x16x32_bf16 v[36:39], v[4:7], v[56:59], v[36:39]
	v_mfma_f32_16x16x32_bf16 v[32:35], v[192:195], v[56:59], v[32:35]
	v_mfma_f32_16x16x32_bf16 v[28:31], v[4:7], v[168:171], v[28:31]
	v_mfma_f32_16x16x32_bf16 v[24:27], v[192:195], v[168:171], v[24:27]
	v_mfma_f32_16x16x32_bf16 v[4:7], v[4:7], v[200:203], v[20:23]
	v_mfma_f32_16x16x32_bf16 v[16:19], v[192:195], v[200:203], v[16:19]
	v_mfma_f32_16x16x32_bf16 v[60:63], v[12:15], v[134:137], v[44:47]
	v_mfma_f32_16x16x32_bf16 v[52:55], v[138:141], v[134:137], v[40:43]
	v_mfma_f32_16x16x32_bf16 v[44:47], v[12:15], v[164:167], v[36:39]
	v_mfma_f32_16x16x32_bf16 v[36:39], v[138:141], v[164:167], v[32:35]
	v_mfma_f32_16x16x32_bf16 v[28:31], v[12:15], v[196:199], v[28:31]
	v_mfma_f32_16x16x32_bf16 v[20:23], v[138:141], v[196:199], v[24:27]
	v_mfma_f32_16x16x32_bf16 v[12:15], v[12:15], v[130:133], v[4:7]
	v_mfma_f32_16x16x32_bf16 v[4:7], v[138:141], v[130:133], v[16:19]
	v_mfma_f32_16x16x32_bf16 v[16:19], v[96:99], v[48:51], v[160:163]
	v_mfma_f32_16x16x32_bf16 v[8:11], v[104:107], v[48:51], v[8:11]
	v_mfma_f32_16x16x32_bf16 v[24:27], v[96:99], v[56:59], v[172:175]
	v_mfma_f32_16x16x32_bf16 v[0:3], v[104:107], v[56:59], v[0:3]
	v_mfma_f32_16x16x32_bf16 v[138:141], v[96:99], v[168:171], v[176:179]
	v_mfma_f32_16x16x32_bf16 v[160:163], v[104:107], v[168:171], v[180:183]
	v_mfma_f32_16x16x32_bf16 v[96:99], v[96:99], v[200:203], v[184:187]
	v_mfma_f32_16x16x32_bf16 v[104:107], v[104:107], v[200:203], v[188:191]
	v_mfma_f32_16x16x32_bf16 v[56:59], v[100:103], v[134:137], v[16:19]
	v_mfma_f32_16x16x32_bf16 v[48:51], v[108:111], v[134:137], v[8:11]
	v_mfma_f32_16x16x32_bf16 v[40:43], v[100:103], v[164:167], v[24:27]
	v_mfma_f32_16x16x32_bf16 v[32:35], v[108:111], v[164:167], v[0:3]
	v_mfma_f32_16x16x32_bf16 v[24:27], v[100:103], v[196:199], v[138:141]
	v_mfma_f32_16x16x32_bf16 v[16:19], v[108:111], v[196:199], v[160:163]
	v_mfma_f32_16x16x32_bf16 v[8:11], v[100:103], v[130:133], v[96:99]
	v_mfma_f32_16x16x32_bf16 v[0:3], v[108:111], v[130:133], v[104:107]
	v_cmp_gt_u32_e32 vcc, s60, v128
	s_barrier
	s_and_saveexec_b64 s[4:5], vcc
	s_cbranch_execz .LBB0_151
	s_barrier

; #define STAGE(P, RS, SOFF, OFF, kt) do { const int _so = (SOFF) + (kt) * (BK * 2); \
;     _Pragma("unroll") for (int _i = 0; _i < 2; ++_i) { \
;       __builtin_amdgcn_raw_ptr_buffer_load_lds(RS, (__attribute__((address_space(3))) void*)((P) + wave * 1024 + _i * 8192), 16, OFF[_i], _so, 0, 0); } } while (0)
; #define LDA(dst, b, h) _Pragma("unroll") for (int m = 0; m < 4; ++m) _Pragma("unroll") for (int k = 0; k < 2; ++k) \
;     dst[m][k] = *reinterpret_cast<const bf16x8*>(SA(b, h) + lds_byte(wr * 64 + m * 16 + fr, k * 32 + fq * 8))
; #define LDB(dst, b, h) _Pragma("unroll") for (int n = 0; n < 2; ++n) _Pragma("unroll") for (int k = 0; k < 2; ++k) \
;     dst[n][k] = *reinterpret_cast<const bf16x8*>(SB(b, h) + lds_byte(wc * 32 + n * 16 + fr, k * 32 + fq * 8))
; #define WAIT_V(n) asm volatile("s_waitcnt vmcnt(" #n ")" ::: "memory")
; #define WAIT_L(n) asm volatile("s_waitcnt lgkmcnt(" #n ")" ::: "memory")
; #define BAR __builtin_amdgcn_s_barrier()
; #define SCHED __builtin_amdgcn_sched_barrier(0)
;     ...
;       LDB(B0, 0, 0); SCHED; LDA(At, 0, 0); STAGE(SA(1, 1), rsA, sA1, offA, t + 1);
;       WAIT_L(8); BAR; WAIT_L(0); MMA(0, 0, At, B0); BAR; SCHED;
;       LDB(B1, 0, 1); STAGE(SB(0, 0), rsB, sB0, offB, t + 2);
;       BAR; WAIT_L(0); MMA(0, 1, At, B1); BAR;
;       LDA(At, 0, 1); STAGE(SA(0, 0), rsA, sA0, offA, t + 2);
;       BAR; WAIT_L(0); MMA(1, 0, At, B0); BAR; SCHED;
;       STAGE(SB(0, 1), rsB, sB1, offB, t + 2);
;       WAIT_V(6); BAR; MMA(1, 1, At, B1); BAR;
.LBB0_210:
	ds_read_b128 v[154:157], v149
	ds_read_b128 v[158:161], v150
	ds_read_b128 v[162:165], v151
	ds_read_b128 v[166:169], v152
	s_add_i32 s44, s38, s17
	s_add_i32 s10, s44, 0x80
	s_mov_b32 m0, s30
	ds_read_b128 v[170:173], v131
	ds_read_b128 v[174:177], v131 offset:1024
	ds_read_b128 v[178:181], v134
	ds_read_b128 v[182:185], v134 offset:1024
	ds_read_b128 v[186:189], v133
	ds_read_b128 v[190:193], v133 offset:1024
	ds_read_b128 v[194:197], v132
	ds_read_b128 v[198:201], v132 offset:1024
	buffer_load_dwordx4 v143, s[4:7], s10 offen lds
	s_mov_b32 m0, s31
	s_nop 0
	buffer_load_dwordx4 v144, s[4:7], s10 offen lds
	s_waitcnt lgkmcnt(8)
	s_barrier
	s_waitcnt lgkmcnt(0)
	v_mfma_f32_16x16x32_bf16 v[124:127], v[154:157], v[170:173], v[124:127]
	v_mfma_f32_16x16x32_bf16 v[120:123], v[162:165], v[170:173], v[120:123]
	v_mfma_f32_16x16x32_bf16 v[116:119], v[154:157], v[178:181], v[116:119]
	v_mfma_f32_16x16x32_bf16 v[112:115], v[162:165], v[178:181], v[112:115]
	v_mfma_f32_16x16x32_bf16 v[108:111], v[154:157], v[186:189], v[108:111]
	v_mfma_f32_16x16x32_bf16 v[104:107], v[162:165], v[186:189], v[104:107]
	v_mfma_f32_16x16x32_bf16 v[100:103], v[154:157], v[194:197], v[100:103]
	v_mfma_f32_16x16x32_bf16 v[96:99], v[162:165], v[194:197], v[96:99]
	v_mfma_f32_16x16x32_bf16 v[124:127], v[158:161], v[174:177], v[124:127]
	v_mfma_f32_16x16x32_bf16 v[120:123], v[166:169], v[174:177], v[120:123]
	v_mfma_f32_16x16x32_bf16 v[116:119], v[158:161], v[182:185], v[116:119]
	v_mfma_f32_16x16x32_bf16 v[112:115], v[166:169], v[182:185], v[112:115]
	v_mfma_f32_16x16x32_bf16 v[108:111], v[158:161], v[190:193], v[108:111]
	v_mfma_f32_16x16x32_bf16 v[104:107], v[166:169], v[190:193], v[104:107]
	v_mfma_f32_16x16x32_bf16 v[100:103], v[158:161], v[198:201], v[100:103]
	v_mfma_f32_16x16x32_bf16 v[96:99], v[166:169], v[198:201], v[96:99]
	s_barrier
	s_add_i32 s45, s40, s17
	s_add_i32 s46, s45, 0x100
	s_mov_b32 s10, s6
	s_mov_b32 s11, s7
	s_mov_b32 m0, s1
	ds_read_b128 v[202:205], v145
	ds_read_b128 v[206:209], v146
	ds_read_b128 v[210:213], v147
	ds_read_b128 v[214:217], v148
	buffer_load_dwordx4 v143, s[8:11], s46 offen lds
	s_mov_b32 m0, s3
	s_nop 0
	buffer_load_dwordx4 v144, s[8:11], s46 offen lds
	s_barrier
	s_waitcnt lgkmcnt(0)
	v_mfma_f32_16x16x32_bf16 v[92:95], v[202:205], v[170:173], v[92:95]
	v_mfma_f32_16x16x32_bf16 v[88:91], v[210:213], v[170:173], v[88:91]
	v_mfma_f32_16x16x32_bf16 v[84:87], v[202:205], v[178:181], v[84:87]
	v_mfma_f32_16x16x32_bf16 v[80:83], v[210:213], v[178:181], v[80:83]
	v_mfma_f32_16x16x32_bf16 v[76:79], v[202:205], v[186:189], v[76:79]
	v_mfma_f32_16x16x32_bf16 v[72:75], v[210:213], v[186:189], v[72:75]
	v_mfma_f32_16x16x32_bf16 v[68:71], v[202:205], v[194:197], v[68:71]
	v_mfma_f32_16x16x32_bf16 v[64:67], v[210:213], v[194:197], v[64:67]
	v_mfma_f32_16x16x32_bf16 v[92:95], v[206:209], v[174:177], v[92:95]
	v_mfma_f32_16x16x32_bf16 v[88:91], v[214:217], v[174:177], v[88:91]
	v_mfma_f32_16x16x32_bf16 v[84:87], v[206:209], v[182:185], v[84:87]
	v_mfma_f32_16x16x32_bf16 v[80:83], v[214:217], v[182:185], v[80:83]
	v_mfma_f32_16x16x32_bf16 v[76:79], v[206:209], v[190:193], v[76:79]
	v_mfma_f32_16x16x32_bf16 v[72:75], v[214:217], v[190:193], v[72:75]
	v_mfma_f32_16x16x32_bf16 v[68:71], v[206:209], v[198:201], v[68:71]
	v_mfma_f32_16x16x32_bf16 v[64:67], v[214:217], v[198:201], v[64:67]
	s_barrier
	s_add_i32 s46, s39, s17
	s_add_i32 s47, s46, 0x100
	s_mov_b32 m0, s0
	ds_read_b128 v[170:173], v131 offset:16384
	ds_read_b128 v[174:177], v131 offset:17408
	ds_read_b128 v[178:181], v134 offset:16384
	ds_read_b128 v[182:185], v134 offset:17408
	ds_read_b128 v[186:189], v133 offset:16384
	ds_read_b128 v[190:193], v133 offset:17408
	ds_read_b128 v[194:197], v132 offset:16384
	ds_read_b128 v[198:201], v132 offset:17408
	buffer_load_dwordx4 v143, s[4:7], s47 offen lds
	s_mov_b32 m0, s18
	s_nop 0
	buffer_load_dwordx4 v144, s[4:7], s47 offen lds
	s_barrier
	s_waitcnt lgkmcnt(0)
	v_mfma_f32_16x16x32_bf16 v[60:63], v[154:157], v[170:173], v[60:63]
	v_mfma_f32_16x16x32_bf16 v[56:59], v[162:165], v[170:173], v[56:59]
	v_mfma_f32_16x16x32_bf16 v[52:55], v[154:157], v[178:181], v[52:55]
	v_mfma_f32_16x16x32_bf16 v[48:51], v[162:165], v[178:181], v[48:51]
	v_mfma_f32_16x16x32_bf16 v[44:47], v[154:157], v[186:189], v[44:47]
	v_mfma_f32_16x16x32_bf16 v[40:43], v[162:165], v[186:189], v[40:43]
	v_mfma_f32_16x16x32_bf16 v[36:39], v[154:157], v[194:197], v[36:39]
	v_mfma_f32_16x16x32_bf16 v[32:35], v[162:165], v[194:197], v[32:35]
	v_mfma_f32_16x16x32_bf16 v[60:63], v[158:161], v[174:177], v[60:63]
	v_mfma_f32_16x16x32_bf16 v[56:59], v[166:169], v[174:177], v[56:59]
	v_mfma_f32_16x16x32_bf16 v[52:55], v[158:161], v[182:185], v[52:55]
	v_mfma_f32_16x16x32_bf16 v[48:51], v[166:169], v[182:185], v[48:51]
	v_mfma_f32_16x16x32_bf16 v[44:47], v[158:161], v[190:193], v[44:47]
	v_mfma_f32_16x16x32_bf16 v[40:43], v[166:169], v[190:193], v[40:43]
	v_mfma_f32_16x16x32_bf16 v[36:39], v[158:161], v[198:201], v[36:39]
	v_mfma_f32_16x16x32_bf16 v[32:35], v[166:169], v[198:201], v[32:35]
	s_barrier
	s_add_i32 s47, s41, s17
	s_add_i32 s48, s47, 0x100
	s_mov_b32 m0, s19
	s_nop 0
	buffer_load_dwordx4 v143, s[8:11], s48 offen lds
	s_mov_b32 m0, s20
	s_nop 0
	buffer_load_dwordx4 v144, s[8:11], s48 offen lds
	s_waitcnt vmcnt(6)
	s_barrier
; #define STAGE(P, RS, SOFF, OFF, kt) do { const int _so = (SOFF) + (kt) * (BK * 2); \
;     _Pragma("unroll") for (int _i = 0; _i < 2; ++_i) { \
;       __builtin_amdgcn_raw_ptr_buffer_load_lds(RS, (__attribute__((address_space(3))) void*)((P) + wave * 1024 + _i * 8192), 16, OFF[_i], _so, 0, 0); } } while (0)
; #define LDA(dst, b, h) _Pragma("unroll") for (int m = 0; m < 4; ++m) _Pragma("unroll") for (int k = 0; k < 2; ++k) \
;     dst[m][k] = *reinterpret_cast<const bf16x8*>(SA(b, h) + lds_byte(wr * 64 + m * 16 + fr, k * 32 + fq * 8))
; #define LDB(dst, b, h) _Pragma("unroll") for (int n = 0; n < 2; ++n) _Pragma("unroll") for (int k = 0; k < 2; ++k) \
;     dst[n][k] = *reinterpret_cast<const bf16x8*>(SB(b, h) + lds_byte(wc * 32 + n * 16 + fr, k * 32 + fq * 8))
; #define WAIT_V(n) asm volatile("s_waitcnt vmcnt(" #n ")" ::: "memory")
; #define WAIT_L(n) asm volatile("s_waitcnt lgkmcnt(" #n ")" ::: "memory")
; #define BAR __builtin_amdgcn_s_barrier()
; #define SCHED __builtin_amdgcn_sched_barrier(0)
;     ...
;       WAIT_V(6); BAR; MMA(1, 1, At, B1); BAR;
;       LDB(B0, 1, 0); SCHED; LDA(At, 1, 0); STAGE(SA(0, 1), rsA, sA1, offA, t + 2);
;       WAIT_L(8); BAR; WAIT_L(0); MMA(0, 0, At, B0); BAR; SCHED;
;       LDB(B1, 1, 1); STAGE(SB(1, 0), rsB, sB0, offB, t + 3);
;       BAR; WAIT_L(0); MMA(0, 1, At, B1); BAR;
;       LDA(At, 1, 1); STAGE(SA(1, 0), rsA, sA0, offA, t + 3);
;       BAR; WAIT_L(0); MMA(1, 0, At, B0); BAR; SCHED;
	v_mfma_f32_16x16x32_bf16 v[28:31], v[202:205], v[170:173], v[28:31]
	v_mfma_f32_16x16x32_bf16 v[24:27], v[210:213], v[170:173], v[24:27]
	v_mfma_f32_16x16x32_bf16 v[20:23], v[202:205], v[178:181], v[20:23]
	v_mfma_f32_16x16x32_bf16 v[16:19], v[210:213], v[178:181], v[16:19]
	v_mfma_f32_16x16x32_bf16 v[12:15], v[202:205], v[186:189], v[12:15]
	v_mfma_f32_16x16x32_bf16 v[8:11], v[210:213], v[186:189], v[8:11]
	v_mfma_f32_16x16x32_bf16 v[4:7], v[202:205], v[194:197], v[4:7]
	v_mfma_f32_16x16x32_bf16 v[0:3], v[210:213], v[194:197], v[0:3]
	v_mfma_f32_16x16x32_bf16 v[28:31], v[206:209], v[174:177], v[28:31]
	v_mfma_f32_16x16x32_bf16 v[24:27], v[214:217], v[174:177], v[24:27]
	v_mfma_f32_16x16x32_bf16 v[20:23], v[206:209], v[182:185], v[20:23]
	v_mfma_f32_16x16x32_bf16 v[16:19], v[214:217], v[182:185], v[16:19]
	v_mfma_f32_16x16x32_bf16 v[12:15], v[206:209], v[190:193], v[12:15]
	v_mfma_f32_16x16x32_bf16 v[8:11], v[214:217], v[190:193], v[8:11]
	v_mfma_f32_16x16x32_bf16 v[4:7], v[206:209], v[198:201], v[4:7]
	v_mfma_f32_16x16x32_bf16 v[0:3], v[214:217], v[198:201], v[0:3]
	s_barrier
	ds_read_b128 v[154:157], v139
	ds_read_b128 v[158:161], v140
	ds_read_b128 v[162:165], v141
	ds_read_b128 v[166:169], v142
	s_addk_i32 s44, 0x100
	s_mov_b32 m0, s21
	ds_read_b128 v[170:173], v131 offset:32768
	ds_read_b128 v[174:177], v131 offset:33792
	ds_read_b128 v[178:181], v134 offset:32768
	ds_read_b128 v[182:185], v134 offset:33792
	ds_read_b128 v[186:189], v133 offset:32768
	ds_read_b128 v[190:193], v133 offset:33792
	ds_read_b128 v[194:197], v132 offset:32768
	ds_read_b128 v[198:201], v132 offset:33792
	buffer_load_dwordx4 v143, s[4:7], s44 offen lds
	s_mov_b32 m0, s22
	s_nop 0
	buffer_load_dwordx4 v144, s[4:7], s44 offen lds
	s_waitcnt lgkmcnt(8)
	s_barrier
	s_waitcnt lgkmcnt(0)
	v_mfma_f32_16x16x32_bf16 v[124:127], v[154:157], v[170:173], v[124:127]
	v_mfma_f32_16x16x32_bf16 v[120:123], v[162:165], v[170:173], v[120:123]
	v_mfma_f32_16x16x32_bf16 v[116:119], v[154:157], v[178:181], v[116:119]
	v_mfma_f32_16x16x32_bf16 v[112:115], v[162:165], v[178:181], v[112:115]
	v_mfma_f32_16x16x32_bf16 v[108:111], v[154:157], v[186:189], v[108:111]
	v_mfma_f32_16x16x32_bf16 v[104:107], v[162:165], v[186:189], v[104:107]
	v_mfma_f32_16x16x32_bf16 v[100:103], v[154:157], v[194:197], v[100:103]
	v_mfma_f32_16x16x32_bf16 v[96:99], v[162:165], v[194:197], v[96:99]
	v_mfma_f32_16x16x32_bf16 v[124:127], v[158:161], v[174:177], v[124:127]
	v_mfma_f32_16x16x32_bf16 v[120:123], v[166:169], v[174:177], v[120:123]
	v_mfma_f32_16x16x32_bf16 v[116:119], v[158:161], v[182:185], v[116:119]
	v_mfma_f32_16x16x32_bf16 v[112:115], v[166:169], v[182:185], v[112:115]
	v_mfma_f32_16x16x32_bf16 v[108:111], v[158:161], v[190:193], v[108:111]
	v_mfma_f32_16x16x32_bf16 v[104:107], v[166:169], v[190:193], v[104:107]
	v_mfma_f32_16x16x32_bf16 v[100:103], v[158:161], v[198:201], v[100:103]
	v_mfma_f32_16x16x32_bf16 v[96:99], v[166:169], v[198:201], v[96:99]
	s_barrier
	s_addk_i32 s45, 0x180
	s_mov_b32 m0, s23
	ds_read_b128 v[202:205], v135
	ds_read_b128 v[206:209], v136
	ds_read_b128 v[210:213], v137
	ds_read_b128 v[214:217], v138
	buffer_load_dwordx4 v143, s[8:11], s45 offen lds
	s_mov_b32 m0, s24
	s_nop 0
	buffer_load_dwordx4 v144, s[8:11], s45 offen lds
	s_barrier
	s_waitcnt lgkmcnt(0)
	v_mfma_f32_16x16x32_bf16 v[92:95], v[202:205], v[170:173], v[92:95]
	v_mfma_f32_16x16x32_bf16 v[88:91], v[210:213], v[170:173], v[88:91]
	v_mfma_f32_16x16x32_bf16 v[84:87], v[202:205], v[178:181], v[84:87]
	v_mfma_f32_16x16x32_bf16 v[80:83], v[210:213], v[178:181], v[80:83]
	v_mfma_f32_16x16x32_bf16 v[76:79], v[202:205], v[186:189], v[76:79]
	v_mfma_f32_16x16x32_bf16 v[72:75], v[210:213], v[186:189], v[72:75]
	v_mfma_f32_16x16x32_bf16 v[68:71], v[202:205], v[194:197], v[68:71]
	v_mfma_f32_16x16x32_bf16 v[64:67], v[210:213], v[194:197], v[64:67]
	v_mfma_f32_16x16x32_bf16 v[92:95], v[206:209], v[174:177], v[92:95]
	v_mfma_f32_16x16x32_bf16 v[88:91], v[214:217], v[174:177], v[88:91]
	v_mfma_f32_16x16x32_bf16 v[84:87], v[206:209], v[182:185], v[84:87]
	v_mfma_f32_16x16x32_bf16 v[80:83], v[214:217], v[182:185], v[80:83]
	v_mfma_f32_16x16x32_bf16 v[76:79], v[206:209], v[190:193], v[76:79]
	v_mfma_f32_16x16x32_bf16 v[72:75], v[214:217], v[190:193], v[72:75]
	v_mfma_f32_16x16x32_bf16 v[68:71], v[206:209], v[198:201], v[68:71]
	v_mfma_f32_16x16x32_bf16 v[64:67], v[214:217], v[198:201], v[64:67]
	s_barrier
	s_addk_i32 s46, 0x180
	s_mov_b32 m0, s25
	ds_read_b128 v[170:173], v131 offset:49152
	ds_read_b128 v[174:177], v131 offset:50176
	ds_read_b128 v[178:181], v134 offset:49152
	ds_read_b128 v[182:185], v134 offset:50176
	ds_read_b128 v[186:189], v133 offset:49152
	ds_read_b128 v[190:193], v133 offset:50176
	ds_read_b128 v[194:197], v132 offset:49152
	ds_read_b128 v[198:201], v132 offset:50176
	buffer_load_dwordx4 v143, s[4:7], s46 offen lds
	s_mov_b32 m0, s26
	s_nop 0
	buffer_load_dwordx4 v144, s[4:7], s46 offen lds
	s_barrier
	s_waitcnt lgkmcnt(0)
	v_mfma_f32_16x16x32_bf16 v[60:63], v[154:157], v[170:173], v[60:63]
	v_mfma_f32_16x16x32_bf16 v[56:59], v[162:165], v[170:173], v[56:59]
	v_mfma_f32_16x16x32_bf16 v[52:55], v[154:157], v[178:181], v[52:55]
	v_mfma_f32_16x16x32_bf16 v[48:51], v[162:165], v[178:181], v[48:51]
	v_mfma_f32_16x16x32_bf16 v[44:47], v[154:157], v[186:189], v[44:47]
	v_mfma_f32_16x16x32_bf16 v[40:43], v[162:165], v[186:189], v[40:43]
	v_mfma_f32_16x16x32_bf16 v[36:39], v[154:157], v[194:197], v[36:39]
	v_mfma_f32_16x16x32_bf16 v[32:35], v[162:165], v[194:197], v[32:35]
	v_mfma_f32_16x16x32_bf16 v[60:63], v[158:161], v[174:177], v[60:63]
	v_mfma_f32_16x16x32_bf16 v[56:59], v[166:169], v[174:177], v[56:59]
	v_mfma_f32_16x16x32_bf16 v[52:55], v[158:161], v[182:185], v[52:55]
	v_mfma_f32_16x16x32_bf16 v[48:51], v[166:169], v[182:185], v[48:51]
	v_mfma_f32_16x16x32_bf16 v[44:47], v[158:161], v[190:193], v[44:47]
	v_mfma_f32_16x16x32_bf16 v[40:43], v[166:169], v[190:193], v[40:43]
	v_mfma_f32_16x16x32_bf16 v[36:39], v[158:161], v[198:201], v[36:39]
	v_mfma_f32_16x16x32_bf16 v[32:35], v[166:169], v[198:201], v[32:35]
	s_barrier
; #define STAGE(P, RS, SOFF, OFF, kt) do { const int _so = (SOFF) + (kt) * (BK * 2); \
;     _Pragma("unroll") for (int _i = 0; _i < 2; ++_i) { \
;       __builtin_amdgcn_raw_ptr_buffer_load_lds(RS, (__attribute__((address_space(3))) void*)((P) + wave * 1024 + _i * 8192), 16, OFF[_i], _so, 0, 0); } } while (0)
; #define LDA(dst, b, h) _Pragma("unroll") for (int m = 0; m < 4; ++m) _Pragma("unroll") for (int k = 0; k < 2; ++k) \
;     dst[m][k] = *reinterpret_cast<const bf16x8*>(SA(b, h) + lds_byte(wr * 64 + m * 16 + fr, k * 32 + fq * 8))
; #define LDB(dst, b, h) _Pragma("unroll") for (int n = 0; n < 2; ++n) _Pragma("unroll") for (int k = 0; k < 2; ++k) \
;     dst[n][k] = *reinterpret_cast<const bf16x8*>(SB(b, h) + lds_byte(wc * 32 + n * 16 + fr, k * 32 + fq * 8))
; #define WAIT_V(n) asm volatile("s_waitcnt vmcnt(" #n ")" ::: "memory")
; #define WAIT_L(n) asm volatile("s_waitcnt lgkmcnt(" #n ")" ::: "memory")
; #define BAR __builtin_amdgcn_s_barrier()
;     ...
;       STAGE(SB(1, 1), rsB, sB1, offB, t + 3);
;       WAIT_V(6); BAR; MMA(1, 1, At, B1); BAR;
;     }
;     { LDB(B0, 0, 0); LDA(At, 0, 0); STAGE(SA(1, 1), rsA, sA1, offA, nt - 1);
;       BAR; WAIT_L(0); MMA(0, 0, At, B0); BAR;
;       LDB(B1, 0, 1); BAR; WAIT_L(0); MMA(0, 1, At, B1); BAR;
;       LDA(At, 0, 1); WAIT_V(4); BAR; WAIT_L(0); MMA(1, 0, At, B0); MMA(1, 1, At, B1); BAR; }
	s_addk_i32 s47, 0x180
	s_mov_b32 m0, s27
	s_nop 0
	buffer_load_dwordx4 v143, s[8:11], s47 offen lds
	s_mov_b32 m0, s28
	s_nop 0
	buffer_load_dwordx4 v144, s[8:11], s47 offen lds
	s_waitcnt vmcnt(6)
	s_barrier
	v_mfma_f32_16x16x32_bf16 v[28:31], v[202:205], v[170:173], v[28:31]
	v_mfma_f32_16x16x32_bf16 v[24:27], v[210:213], v[170:173], v[24:27]
	v_mfma_f32_16x16x32_bf16 v[20:23], v[202:205], v[178:181], v[20:23]
	v_mfma_f32_16x16x32_bf16 v[16:19], v[210:213], v[178:181], v[16:19]
	v_mfma_f32_16x16x32_bf16 v[12:15], v[202:205], v[186:189], v[12:15]
	v_mfma_f32_16x16x32_bf16 v[8:11], v[210:213], v[186:189], v[8:11]
	v_mfma_f32_16x16x32_bf16 v[4:7], v[202:205], v[194:197], v[4:7]
	v_mfma_f32_16x16x32_bf16 v[0:3], v[210:213], v[194:197], v[0:3]
	v_mfma_f32_16x16x32_bf16 v[28:31], v[206:209], v[174:177], v[28:31]
	v_mfma_f32_16x16x32_bf16 v[24:27], v[214:217], v[174:177], v[24:27]
	v_mfma_f32_16x16x32_bf16 v[20:23], v[206:209], v[182:185], v[20:23]
	v_mfma_f32_16x16x32_bf16 v[16:19], v[214:217], v[182:185], v[16:19]
	v_mfma_f32_16x16x32_bf16 v[12:15], v[206:209], v[190:193], v[12:15]
	v_mfma_f32_16x16x32_bf16 v[8:11], v[214:217], v[190:193], v[8:11]
	v_mfma_f32_16x16x32_bf16 v[4:7], v[206:209], v[198:201], v[4:7]
	v_mfma_f32_16x16x32_bf16 v[0:3], v[214:217], v[198:201], v[0:3]
	s_barrier
	s_add_i32 s16, s16, 2
	s_addk_i32 s17, 0x100
	s_cmp_gt_u32 s16, 27
	s_cbranch_scc0 .LBB0_210
	s_add_i32 s10, s38, 0xf80
	s_mov_b32 m0, s30
	ds_read_b128 v[154:157], v149
	ds_read_b128 v[158:161], v150
	ds_read_b128 v[162:165], v151
	ds_read_b128 v[150:153], v152
	ds_read_b128 v[166:169], v131
	ds_read_b128 v[170:173], v131 offset:1024
	ds_read_b128 v[174:177], v134
	ds_read_b128 v[178:181], v134 offset:1024
	ds_read_b128 v[182:185], v133
	ds_read_b128 v[186:189], v133 offset:1024
	ds_read_b128 v[190:193], v132
	ds_read_b128 v[194:197], v132 offset:1024
	buffer_load_dwordx4 v143, s[4:7], s10 offen lds
	s_mov_b32 m0, s31
	s_nop 0
	buffer_load_dwordx4 v144, s[4:7], s10 offen lds
	s_barrier
	s_waitcnt lgkmcnt(0)
	v_mfma_f32_16x16x32_bf16 v[124:127], v[154:157], v[166:169], v[124:127]
	v_mfma_f32_16x16x32_bf16 v[120:123], v[162:165], v[166:169], v[120:123]
	v_mfma_f32_16x16x32_bf16 v[116:119], v[154:157], v[174:177], v[116:119]
	v_mfma_f32_16x16x32_bf16 v[112:115], v[162:165], v[174:177], v[112:115]
	v_mfma_f32_16x16x32_bf16 v[108:111], v[154:157], v[182:185], v[108:111]
	v_mfma_f32_16x16x32_bf16 v[104:107], v[162:165], v[182:185], v[104:107]
	v_mfma_f32_16x16x32_bf16 v[100:103], v[154:157], v[190:193], v[100:103]
	v_mfma_f32_16x16x32_bf16 v[96:99], v[162:165], v[190:193], v[96:99]
	v_mfma_f32_16x16x32_bf16 v[124:127], v[158:161], v[170:173], v[124:127]
	v_mfma_f32_16x16x32_bf16 v[120:123], v[150:153], v[170:173], v[120:123]
	v_mfma_f32_16x16x32_bf16 v[116:119], v[158:161], v[178:181], v[116:119]
	v_mfma_f32_16x16x32_bf16 v[112:115], v[150:153], v[178:181], v[112:115]
	v_mfma_f32_16x16x32_bf16 v[108:111], v[158:161], v[186:189], v[108:111]
	v_mfma_f32_16x16x32_bf16 v[104:107], v[150:153], v[186:189], v[104:107]
	v_mfma_f32_16x16x32_bf16 v[100:103], v[158:161], v[194:197], v[100:103]
	v_mfma_f32_16x16x32_bf16 v[96:99], v[150:153], v[194:197], v[96:99]
	s_barrier
	ds_read_b128 v[198:201], v145
	ds_read_b128 v[202:205], v146
	ds_read_b128 v[144:147], v147
	ds_read_b128 v[206:209], v148
	s_barrier
	s_waitcnt lgkmcnt(0)
	v_mfma_f32_16x16x32_bf16 v[92:95], v[198:201], v[166:169], v[92:95]
	v_mfma_f32_16x16x32_bf16 v[88:91], v[144:147], v[166:169], v[88:91]
	v_mfma_f32_16x16x32_bf16 v[84:87], v[198:201], v[174:177], v[84:87]
	v_mfma_f32_16x16x32_bf16 v[80:83], v[144:147], v[174:177], v[80:83]
	v_mfma_f32_16x16x32_bf16 v[76:79], v[198:201], v[182:185], v[76:79]
	v_mfma_f32_16x16x32_bf16 v[72:75], v[144:147], v[182:185], v[72:75]
	v_mfma_f32_16x16x32_bf16 v[68:71], v[198:201], v[190:193], v[68:71]
	v_mfma_f32_16x16x32_bf16 v[64:67], v[144:147], v[190:193], v[64:67]
	v_mfma_f32_16x16x32_bf16 v[92:95], v[202:205], v[170:173], v[92:95]
	v_mfma_f32_16x16x32_bf16 v[88:91], v[206:209], v[170:173], v[88:91]
	v_mfma_f32_16x16x32_bf16 v[84:87], v[202:205], v[178:181], v[84:87]
	v_mfma_f32_16x16x32_bf16 v[80:83], v[206:209], v[178:181], v[80:83]
	v_mfma_f32_16x16x32_bf16 v[76:79], v[202:205], v[186:189], v[76:79]
	v_mfma_f32_16x16x32_bf16 v[72:75], v[206:209], v[186:189], v[72:75]
	v_mfma_f32_16x16x32_bf16 v[68:71], v[202:205], v[194:197], v[68:71]
	v_mfma_f32_16x16x32_bf16 v[64:67], v[206:209], v[194:197], v[64:67]
	s_barrier
	ds_read_b128 v[166:169], v131 offset:16384
	ds_read_b128 v[170:173], v131 offset:17408
	ds_read_b128 v[174:177], v134 offset:16384
	ds_read_b128 v[178:181], v134 offset:17408
	ds_read_b128 v[182:185], v133 offset:16384
	ds_read_b128 v[186:189], v133 offset:17408
	ds_read_b128 v[190:193], v132 offset:16384
	ds_read_b128 v[194:197], v132 offset:17408
	s_waitcnt vmcnt(4)
	s_barrier
; #define LDA(dst, b, h) _Pragma("unroll") for (int m = 0; m < 4; ++m) _Pragma("unroll") for (int k = 0; k < 2; ++k) \
;     dst[m][k] = *reinterpret_cast<const bf16x8*>(SA(b, h) + lds_byte(wr * 64 + m * 16 + fr, k * 32 + fq * 8))
; #define LDB(dst, b, h) _Pragma("unroll") for (int n = 0; n < 2; ++n) _Pragma("unroll") for (int k = 0; k < 2; ++k) \
;     dst[n][k] = *reinterpret_cast<const bf16x8*>(SB(b, h) + lds_byte(wc * 32 + n * 16 + fr, k * 32 + fq * 8))
; #define WAIT_V(n) asm volatile("s_waitcnt vmcnt(" #n ")" ::: "memory")
; #define WAIT_L(n) asm volatile("s_waitcnt lgkmcnt(" #n ")" ::: "memory")
; #define BAR __builtin_amdgcn_s_barrier()
;     ...
;       LDA(At, 0, 1); WAIT_V(4); BAR; WAIT_L(0); MMA(1, 0, At, B0); MMA(1, 1, At, B1); BAR; }
;     { LDB(B0, 1, 0); LDA(At, 1, 0); WAIT_V(2); BAR; WAIT_L(0); MMA(0, 0, At, B0); BAR;
	s_waitcnt lgkmcnt(0)
	v_mfma_f32_16x16x32_bf16 v[60:63], v[154:157], v[166:169], v[60:63]
	v_mfma_f32_16x16x32_bf16 v[56:59], v[162:165], v[166:169], v[56:59]
	v_mfma_f32_16x16x32_bf16 v[52:55], v[154:157], v[174:177], v[52:55]
	v_mfma_f32_16x16x32_bf16 v[48:51], v[162:165], v[174:177], v[48:51]
	v_mfma_f32_16x16x32_bf16 v[44:47], v[154:157], v[182:185], v[44:47]
	v_mfma_f32_16x16x32_bf16 v[40:43], v[162:165], v[182:185], v[40:43]
	v_mfma_f32_16x16x32_bf16 v[36:39], v[154:157], v[190:193], v[36:39]
	v_mfma_f32_16x16x32_bf16 v[32:35], v[162:165], v[190:193], v[32:35]
	v_mfma_f32_16x16x32_bf16 v[60:63], v[158:161], v[170:173], v[60:63]
	v_mfma_f32_16x16x32_bf16 v[56:59], v[150:153], v[170:173], v[56:59]
	v_mfma_f32_16x16x32_bf16 v[52:55], v[158:161], v[178:181], v[52:55]
	v_mfma_f32_16x16x32_bf16 v[48:51], v[150:153], v[178:181], v[48:51]
	v_mfma_f32_16x16x32_bf16 v[44:47], v[158:161], v[186:189], v[44:47]
	v_mfma_f32_16x16x32_bf16 v[40:43], v[150:153], v[186:189], v[40:43]
	v_mfma_f32_16x16x32_bf16 v[36:39], v[158:161], v[194:197], v[36:39]
	v_mfma_f32_16x16x32_bf16 v[32:35], v[150:153], v[194:197], v[32:35]
	v_mfma_f32_16x16x32_bf16 v[28:31], v[198:201], v[166:169], v[28:31]
	v_mfma_f32_16x16x32_bf16 v[24:27], v[144:147], v[166:169], v[24:27]
	v_mfma_f32_16x16x32_bf16 v[20:23], v[198:201], v[174:177], v[20:23]
	v_mfma_f32_16x16x32_bf16 v[16:19], v[144:147], v[174:177], v[16:19]
	v_mfma_f32_16x16x32_bf16 v[12:15], v[198:201], v[182:185], v[12:15]
	v_mfma_f32_16x16x32_bf16 v[8:11], v[144:147], v[182:185], v[8:11]
	v_mfma_f32_16x16x32_bf16 v[4:7], v[198:201], v[190:193], v[4:7]
	v_mfma_f32_16x16x32_bf16 v[0:3], v[144:147], v[190:193], v[0:3]
	v_mfma_f32_16x16x32_bf16 v[28:31], v[202:205], v[170:173], v[28:31]
	v_mfma_f32_16x16x32_bf16 v[24:27], v[206:209], v[170:173], v[24:27]
	v_mfma_f32_16x16x32_bf16 v[20:23], v[202:205], v[178:181], v[20:23]
	v_mfma_f32_16x16x32_bf16 v[16:19], v[206:209], v[178:181], v[16:19]
	v_mfma_f32_16x16x32_bf16 v[12:15], v[202:205], v[186:189], v[12:15]
	v_mfma_f32_16x16x32_bf16 v[8:11], v[206:209], v[186:189], v[8:11]
	v_mfma_f32_16x16x32_bf16 v[4:7], v[202:205], v[194:197], v[4:7]
	v_mfma_f32_16x16x32_bf16 v[0:3], v[206:209], v[194:197], v[0:3]
	s_barrier
	ds_read_b128 v[144:147], v139
	ds_read_b128 v[148:151], v140
	ds_read_b128 v[152:155], v141
	ds_read_b128 v[140:143], v142
	ds_read_b128 v[156:159], v131 offset:32768
	ds_read_b128 v[160:163], v131 offset:33792
	ds_read_b128 v[164:167], v134 offset:32768
	ds_read_b128 v[168:171], v134 offset:33792
	ds_read_b128 v[172:175], v133 offset:32768
	ds_read_b128 v[176:179], v133 offset:33792
	ds_read_b128 v[180:183], v132 offset:32768
	ds_read_b128 v[184:187], v132 offset:33792
	s_waitcnt vmcnt(2)
	s_barrier
	s_waitcnt lgkmcnt(0)
	v_mfma_f32_16x16x32_bf16 v[124:127], v[144:147], v[156:159], v[124:127]
	v_mfma_f32_16x16x32_bf16 v[120:123], v[152:155], v[156:159], v[120:123]
	v_mfma_f32_16x16x32_bf16 v[116:119], v[144:147], v[164:167], v[116:119]
	v_mfma_f32_16x16x32_bf16 v[112:115], v[152:155], v[164:167], v[112:115]
	v_mfma_f32_16x16x32_bf16 v[108:111], v[144:147], v[172:175], v[108:111]
	v_mfma_f32_16x16x32_bf16 v[104:107], v[152:155], v[172:175], v[104:107]
	v_mfma_f32_16x16x32_bf16 v[100:103], v[144:147], v[180:183], v[100:103]
	v_mfma_f32_16x16x32_bf16 v[96:99], v[152:155], v[180:183], v[96:99]
	v_mfma_f32_16x16x32_bf16 v[124:127], v[148:151], v[160:163], v[124:127]
	v_mfma_f32_16x16x32_bf16 v[120:123], v[140:143], v[160:163], v[120:123]
	v_mfma_f32_16x16x32_bf16 v[116:119], v[148:151], v[168:171], v[116:119]
	v_mfma_f32_16x16x32_bf16 v[112:115], v[140:143], v[168:171], v[112:115]
	v_mfma_f32_16x16x32_bf16 v[108:111], v[148:151], v[176:179], v[108:111]
	v_mfma_f32_16x16x32_bf16 v[104:107], v[140:143], v[176:179], v[104:107]
	v_mfma_f32_16x16x32_bf16 v[100:103], v[148:151], v[184:187], v[100:103]
	v_mfma_f32_16x16x32_bf16 v[96:99], v[140:143], v[184:187], v[96:99]
	s_barrier
; #define LDA(dst, b, h) _Pragma("unroll") for (int m = 0; m < 4; ++m) _Pragma("unroll") for (int k = 0; k < 2; ++k) \
;     dst[m][k] = *reinterpret_cast<const bf16x8*>(SA(b, h) + lds_byte(wr * 64 + m * 16 + fr, k * 32 + fq * 8))
; #define LDB(dst, b, h) _Pragma("unroll") for (int n = 0; n < 2; ++n) _Pragma("unroll") for (int k = 0; k < 2; ++k) \
;     dst[n][k] = *reinterpret_cast<const bf16x8*>(SB(b, h) + lds_byte(wc * 32 + n * 16 + fr, k * 32 + fq * 8))
; #define WAIT_V(n) asm volatile("s_waitcnt vmcnt(" #n ")" ::: "memory")
; #define WAIT_L(n) asm volatile("s_waitcnt lgkmcnt(" #n ")" ::: "memory")
; #define BAR __builtin_amdgcn_s_barrier()
;     ...
;       LDB(B1, 1, 1); WAIT_V(0); BAR; WAIT_L(0); MMA(0, 1, At, B1); BAR;
;       LDA(At, 1, 1); BAR; WAIT_L(0); MMA(1, 0, At, B0); MMA(1, 1, At, B1); BAR; }
;     if (wr == 0) BAR;
	ds_read_b128 v[188:191], v135
	ds_read_b128 v[192:195], v136
	ds_read_b128 v[196:199], v137
	ds_read_b128 v[136:139], v138
	s_waitcnt vmcnt(0)
	s_barrier
	s_waitcnt lgkmcnt(0)
	v_mfma_f32_16x16x32_bf16 v[92:95], v[188:191], v[156:159], v[92:95]
	v_mfma_f32_16x16x32_bf16 v[88:91], v[196:199], v[156:159], v[88:91]
	v_mfma_f32_16x16x32_bf16 v[84:87], v[188:191], v[164:167], v[84:87]
	v_mfma_f32_16x16x32_bf16 v[80:83], v[196:199], v[164:167], v[80:83]
	v_mfma_f32_16x16x32_bf16 v[76:79], v[188:191], v[172:175], v[76:79]
	v_mfma_f32_16x16x32_bf16 v[72:75], v[196:199], v[172:175], v[72:75]
	v_mfma_f32_16x16x32_bf16 v[68:71], v[188:191], v[180:183], v[68:71]
	v_mfma_f32_16x16x32_bf16 v[64:67], v[196:199], v[180:183], v[64:67]
	v_mfma_f32_16x16x32_bf16 v[92:95], v[192:195], v[160:163], v[92:95]
	v_mfma_f32_16x16x32_bf16 v[88:91], v[136:139], v[160:163], v[88:91]
	v_mfma_f32_16x16x32_bf16 v[84:87], v[192:195], v[168:171], v[84:87]
	v_mfma_f32_16x16x32_bf16 v[80:83], v[136:139], v[168:171], v[80:83]
	v_mfma_f32_16x16x32_bf16 v[76:79], v[192:195], v[176:179], v[76:79]
	v_mfma_f32_16x16x32_bf16 v[72:75], v[136:139], v[176:179], v[72:75]
	v_mfma_f32_16x16x32_bf16 v[68:71], v[192:195], v[184:187], v[68:71]
	v_mfma_f32_16x16x32_bf16 v[64:67], v[136:139], v[184:187], v[64:67]
	s_barrier
	ds_read_b128 v[156:159], v131 offset:49152
	ds_read_b128 v[160:163], v131 offset:50176
	ds_read_b128 v[164:167], v134 offset:49152
	ds_read_b128 v[168:171], v134 offset:50176
	ds_read_b128 v[172:175], v133 offset:49152
	ds_read_b128 v[176:179], v133 offset:50176
	ds_read_b128 v[180:183], v132 offset:49152
	ds_read_b128 v[132:135], v132 offset:50176
	s_barrier
	s_waitcnt lgkmcnt(0)
	v_mfma_f32_16x16x32_bf16 v[60:63], v[144:147], v[156:159], v[60:63]
	v_mfma_f32_16x16x32_bf16 v[56:59], v[152:155], v[156:159], v[56:59]
	v_mfma_f32_16x16x32_bf16 v[52:55], v[144:147], v[164:167], v[52:55]
	v_mfma_f32_16x16x32_bf16 v[48:51], v[152:155], v[164:167], v[48:51]
	v_mfma_f32_16x16x32_bf16 v[44:47], v[144:147], v[172:175], v[44:47]
	v_mfma_f32_16x16x32_bf16 v[40:43], v[152:155], v[172:175], v[40:43]
	v_mfma_f32_16x16x32_bf16 v[36:39], v[144:147], v[180:183], v[36:39]
	v_mfma_f32_16x16x32_bf16 v[32:35], v[152:155], v[180:183], v[32:35]
	v_mfma_f32_16x16x32_bf16 v[60:63], v[148:151], v[160:163], v[60:63]
	v_mfma_f32_16x16x32_bf16 v[56:59], v[140:143], v[160:163], v[56:59]
	v_mfma_f32_16x16x32_bf16 v[52:55], v[148:151], v[168:171], v[52:55]
	v_mfma_f32_16x16x32_bf16 v[48:51], v[140:143], v[168:171], v[48:51]
	v_mfma_f32_16x16x32_bf16 v[44:47], v[148:151], v[176:179], v[44:47]
	v_mfma_f32_16x16x32_bf16 v[40:43], v[140:143], v[176:179], v[40:43]
	v_mfma_f32_16x16x32_bf16 v[36:39], v[148:151], v[132:135], v[36:39]
	v_mfma_f32_16x16x32_bf16 v[32:35], v[140:143], v[132:135], v[32:35]
	v_mfma_f32_16x16x32_bf16 v[28:31], v[188:191], v[156:159], v[28:31]
	v_mfma_f32_16x16x32_bf16 v[24:27], v[196:199], v[156:159], v[24:27]
	v_mfma_f32_16x16x32_bf16 v[20:23], v[188:191], v[164:167], v[20:23]
	v_mfma_f32_16x16x32_bf16 v[16:19], v[196:199], v[164:167], v[16:19]
	v_mfma_f32_16x16x32_bf16 v[12:15], v[188:191], v[172:175], v[12:15]
	v_mfma_f32_16x16x32_bf16 v[8:11], v[196:199], v[172:175], v[8:11]
	v_mfma_f32_16x16x32_bf16 v[4:7], v[188:191], v[180:183], v[4:7]
	v_mfma_f32_16x16x32_bf16 v[0:3], v[196:199], v[180:183], v[0:3]
	v_mfma_f32_16x16x32_bf16 v[28:31], v[192:195], v[160:163], v[28:31]
	v_mfma_f32_16x16x32_bf16 v[24:27], v[136:139], v[160:163], v[24:27]
	v_mfma_f32_16x16x32_bf16 v[20:23], v[192:195], v[168:171], v[20:23]
	v_mfma_f32_16x16x32_bf16 v[16:19], v[136:139], v[168:171], v[16:19]
	v_mfma_f32_16x16x32_bf16 v[12:15], v[192:195], v[176:179], v[12:15]
	v_mfma_f32_16x16x32_bf16 v[8:11], v[136:139], v[176:179], v[8:11]
	v_mfma_f32_16x16x32_bf16 v[4:7], v[192:195], v[132:135], v[4:7]
	v_mfma_f32_16x16x32_bf16 v[0:3], v[136:139], v[132:135], v[0:3]
	v_cmp_gt_u32_e32 vcc, s35, v130
	s_barrier
	s_and_saveexec_b64 s[10:11], vcc
	s_cbranch_execz .LBB0_213
	s_barrier

; #define STAGE(P, RS, SOFF, OFF, kt) do { const int _so = (SOFF) + (kt) * (BK * 2); \
;     _Pragma("unroll") for (int _i = 0; _i < 2; ++_i) { \
;       __builtin_amdgcn_raw_ptr_buffer_load_lds(RS, (__attribute__((address_space(3))) void*)((P) + wave * 1024 + _i * 8192), 16, OFF[_i], _so, 0, 0); } } while (0)
; #define LDA(dst, b, h) _Pragma("unroll") for (int m = 0; m < 4; ++m) _Pragma("unroll") for (int k = 0; k < 2; ++k) \
;     dst[m][k] = *reinterpret_cast<const bf16x8*>(SA(b, h) + lds_byte(wr * 64 + m * 16 + fr, k * 32 + fq * 8))
; #define LDB(dst, b, h) _Pragma("unroll") for (int n = 0; n < 2; ++n) _Pragma("unroll") for (int k = 0; k < 2; ++k) \
;     dst[n][k] = *reinterpret_cast<const bf16x8*>(SB(b, h) + lds_byte(wc * 32 + n * 16 + fr, k * 32 + fq * 8))
; #define WAIT_V(n) asm volatile("s_waitcnt vmcnt(" #n ")" ::: "memory")
; #define WAIT_L(n) asm volatile("s_waitcnt lgkmcnt(" #n ")" ::: "memory")
; #define BAR __builtin_amdgcn_s_barrier()
; #define SCHED __builtin_amdgcn_sched_barrier(0)
;     ...
;       LDB(B0, 0, 0); SCHED; LDA(At, 0, 0); STAGE(SA(1, 1), rsA, sA1, offA, t + 1);
;       WAIT_L(8); BAR; WAIT_L(0); MMA(0, 0, At, B0); BAR; SCHED;
;       LDB(B1, 0, 1); STAGE(SB(0, 0), rsB, sB0, offB, t + 2);
;       BAR; WAIT_L(0); MMA(0, 1, At, B1); BAR;
;       LDA(At, 0, 1); STAGE(SA(0, 0), rsA, sA0, offA, t + 2);
;       BAR; WAIT_L(0); MMA(1, 0, At, B0); BAR; SCHED;
;       STAGE(SB(0, 1), rsB, sB1, offB, t + 2);
;       WAIT_V(6); BAR; MMA(1, 1, At, B1); BAR;
.LBB0_225:
	ds_read_b128 v[152:155], v148
	ds_read_b128 v[156:159], v149
	ds_read_b128 v[160:163], v150
	ds_read_b128 v[164:167], v151
	s_add_i32 s18, s41, s17
	s_add_i32 s19, s18, 0x80
	s_mov_b32 m0, s33
	ds_read_b128 v[168:171], v130
	ds_read_b128 v[172:175], v130 offset:1024
	ds_read_b128 v[176:179], v133
	ds_read_b128 v[180:183], v133 offset:1024
	ds_read_b128 v[184:187], v132
	ds_read_b128 v[188:191], v132 offset:1024
	ds_read_b128 v[192:195], v131
	ds_read_b128 v[196:199], v131 offset:1024
	buffer_load_dwordx4 v142, s[4:7], s19 offen lds
	s_mov_b32 m0, s34
	s_nop 0
	buffer_load_dwordx4 v143, s[4:7], s19 offen lds
	s_waitcnt lgkmcnt(8)
	s_barrier
	s_waitcnt lgkmcnt(0)
	v_mfma_f32_16x16x32_bf16 v[124:127], v[168:171], v[152:155], v[124:127]
	v_mfma_f32_16x16x32_bf16 v[120:123], v[168:171], v[160:163], v[120:123]
	v_mfma_f32_16x16x32_bf16 v[116:119], v[176:179], v[152:155], v[116:119]
	v_mfma_f32_16x16x32_bf16 v[112:115], v[176:179], v[160:163], v[112:115]
	v_mfma_f32_16x16x32_bf16 v[108:111], v[184:187], v[152:155], v[108:111]
	v_mfma_f32_16x16x32_bf16 v[104:107], v[184:187], v[160:163], v[104:107]
	v_mfma_f32_16x16x32_bf16 v[100:103], v[192:195], v[152:155], v[100:103]
	v_mfma_f32_16x16x32_bf16 v[96:99], v[192:195], v[160:163], v[96:99]
	v_mfma_f32_16x16x32_bf16 v[124:127], v[172:175], v[156:159], v[124:127]
	v_mfma_f32_16x16x32_bf16 v[120:123], v[172:175], v[164:167], v[120:123]
	v_mfma_f32_16x16x32_bf16 v[116:119], v[180:183], v[156:159], v[116:119]
	v_mfma_f32_16x16x32_bf16 v[112:115], v[180:183], v[164:167], v[112:115]
	v_mfma_f32_16x16x32_bf16 v[108:111], v[188:191], v[156:159], v[108:111]
	v_mfma_f32_16x16x32_bf16 v[104:107], v[188:191], v[164:167], v[104:107]
	v_mfma_f32_16x16x32_bf16 v[100:103], v[196:199], v[156:159], v[100:103]
	v_mfma_f32_16x16x32_bf16 v[96:99], v[196:199], v[164:167], v[96:99]
	s_barrier
	s_add_i32 s19, s43, s17
	s_add_i32 s47, s19, 0x100
	s_mov_b32 m0, s1
	ds_read_b128 v[200:203], v144
	ds_read_b128 v[204:207], v145
	ds_read_b128 v[208:211], v146
	ds_read_b128 v[212:215], v147
	buffer_load_dwordx4 v142, s[8:11], s47 offen lds
	s_mov_b32 m0, s3
	s_nop 0
	buffer_load_dwordx4 v143, s[8:11], s47 offen lds
	s_barrier
	s_waitcnt lgkmcnt(0)
	v_mfma_f32_16x16x32_bf16 v[92:95], v[168:171], v[200:203], v[92:95]
	v_mfma_f32_16x16x32_bf16 v[88:91], v[168:171], v[208:211], v[88:91]
	v_mfma_f32_16x16x32_bf16 v[84:87], v[176:179], v[200:203], v[84:87]
	v_mfma_f32_16x16x32_bf16 v[80:83], v[176:179], v[208:211], v[80:83]
	v_mfma_f32_16x16x32_bf16 v[76:79], v[184:187], v[200:203], v[76:79]
	v_mfma_f32_16x16x32_bf16 v[72:75], v[184:187], v[208:211], v[72:75]
	v_mfma_f32_16x16x32_bf16 v[68:71], v[192:195], v[200:203], v[68:71]
	v_mfma_f32_16x16x32_bf16 v[64:67], v[192:195], v[208:211], v[64:67]
	v_mfma_f32_16x16x32_bf16 v[92:95], v[172:175], v[204:207], v[92:95]
	v_mfma_f32_16x16x32_bf16 v[88:91], v[172:175], v[212:215], v[88:91]
	v_mfma_f32_16x16x32_bf16 v[84:87], v[180:183], v[204:207], v[84:87]
	v_mfma_f32_16x16x32_bf16 v[80:83], v[180:183], v[212:215], v[80:83]
	v_mfma_f32_16x16x32_bf16 v[76:79], v[188:191], v[204:207], v[76:79]
	v_mfma_f32_16x16x32_bf16 v[72:75], v[188:191], v[212:215], v[72:75]
	v_mfma_f32_16x16x32_bf16 v[68:71], v[196:199], v[204:207], v[68:71]
	v_mfma_f32_16x16x32_bf16 v[64:67], v[196:199], v[212:215], v[64:67]
	s_barrier
	s_add_i32 s47, s42, s17
	s_add_i32 s48, s47, 0x100
	s_mov_b32 m0, s0
	ds_read_b128 v[168:171], v130 offset:16384
	ds_read_b128 v[172:175], v130 offset:17408
	ds_read_b128 v[176:179], v133 offset:16384
	ds_read_b128 v[180:183], v133 offset:17408
	ds_read_b128 v[184:187], v132 offset:16384
	ds_read_b128 v[188:191], v132 offset:17408
	ds_read_b128 v[192:195], v131 offset:16384
	ds_read_b128 v[196:199], v131 offset:17408
	buffer_load_dwordx4 v142, s[4:7], s48 offen lds
	s_mov_b32 m0, s20
	s_nop 0
	buffer_load_dwordx4 v143, s[4:7], s48 offen lds
	s_barrier
	s_waitcnt lgkmcnt(0)
	v_mfma_f32_16x16x32_bf16 v[60:63], v[168:171], v[152:155], v[60:63]
	v_mfma_f32_16x16x32_bf16 v[56:59], v[168:171], v[160:163], v[56:59]
	v_mfma_f32_16x16x32_bf16 v[52:55], v[176:179], v[152:155], v[52:55]
	v_mfma_f32_16x16x32_bf16 v[48:51], v[176:179], v[160:163], v[48:51]
	v_mfma_f32_16x16x32_bf16 v[44:47], v[184:187], v[152:155], v[44:47]
	v_mfma_f32_16x16x32_bf16 v[40:43], v[184:187], v[160:163], v[40:43]
	v_mfma_f32_16x16x32_bf16 v[36:39], v[192:195], v[152:155], v[36:39]
	v_mfma_f32_16x16x32_bf16 v[32:35], v[192:195], v[160:163], v[32:35]
	v_mfma_f32_16x16x32_bf16 v[60:63], v[172:175], v[156:159], v[60:63]
	v_mfma_f32_16x16x32_bf16 v[56:59], v[172:175], v[164:167], v[56:59]
	v_mfma_f32_16x16x32_bf16 v[52:55], v[180:183], v[156:159], v[52:55]
	v_mfma_f32_16x16x32_bf16 v[48:51], v[180:183], v[164:167], v[48:51]
	v_mfma_f32_16x16x32_bf16 v[44:47], v[188:191], v[156:159], v[44:47]
	v_mfma_f32_16x16x32_bf16 v[40:43], v[188:191], v[164:167], v[40:43]
	v_mfma_f32_16x16x32_bf16 v[36:39], v[196:199], v[156:159], v[36:39]
	v_mfma_f32_16x16x32_bf16 v[32:35], v[196:199], v[164:167], v[32:35]
	s_barrier
	s_add_i32 s48, s44, s17
	s_add_i32 s49, s48, 0x100
	s_mov_b32 m0, s21
	s_nop 0
	buffer_load_dwordx4 v142, s[8:11], s49 offen lds
	s_mov_b32 m0, s22
	s_nop 0
	buffer_load_dwordx4 v143, s[8:11], s49 offen lds
	s_waitcnt vmcnt(6)
	s_barrier
; #define STAGE(P, RS, SOFF, OFF, kt) do { const int _so = (SOFF) + (kt) * (BK * 2); \
;     _Pragma("unroll") for (int _i = 0; _i < 2; ++_i) { \
;       __builtin_amdgcn_raw_ptr_buffer_load_lds(RS, (__attribute__((address_space(3))) void*)((P) + wave * 1024 + _i * 8192), 16, OFF[_i], _so, 0, 0); } } while (0)
; #define LDA(dst, b, h) _Pragma("unroll") for (int m = 0; m < 4; ++m) _Pragma("unroll") for (int k = 0; k < 2; ++k) \
;     dst[m][k] = *reinterpret_cast<const bf16x8*>(SA(b, h) + lds_byte(wr * 64 + m * 16 + fr, k * 32 + fq * 8))
; #define LDB(dst, b, h) _Pragma("unroll") for (int n = 0; n < 2; ++n) _Pragma("unroll") for (int k = 0; k < 2; ++k) \
;     dst[n][k] = *reinterpret_cast<const bf16x8*>(SB(b, h) + lds_byte(wc * 32 + n * 16 + fr, k * 32 + fq * 8))
; #define WAIT_V(n) asm volatile("s_waitcnt vmcnt(" #n ")" ::: "memory")
; #define WAIT_L(n) asm volatile("s_waitcnt lgkmcnt(" #n ")" ::: "memory")
; #define BAR __builtin_amdgcn_s_barrier()
; #define SCHED __builtin_amdgcn_sched_barrier(0)
;     ...
;       WAIT_V(6); BAR; MMA(1, 1, At, B1); BAR;
;       LDB(B0, 1, 0); SCHED; LDA(At, 1, 0); STAGE(SA(0, 1), rsA, sA1, offA, t + 2);
;       WAIT_L(8); BAR; WAIT_L(0); MMA(0, 0, At, B0); BAR; SCHED;
;       LDB(B1, 1, 1); STAGE(SB(1, 0), rsB, sB0, offB, t + 3);
;       BAR; WAIT_L(0); MMA(0, 1, At, B1); BAR;
;       LDA(At, 1, 1); STAGE(SA(1, 0), rsA, sA0, offA, t + 3);
;       BAR; WAIT_L(0); MMA(1, 0, At, B0); BAR; SCHED;
	v_mfma_f32_16x16x32_bf16 v[28:31], v[168:171], v[200:203], v[28:31]
	v_mfma_f32_16x16x32_bf16 v[24:27], v[168:171], v[208:211], v[24:27]
	v_mfma_f32_16x16x32_bf16 v[20:23], v[176:179], v[200:203], v[20:23]
	v_mfma_f32_16x16x32_bf16 v[16:19], v[176:179], v[208:211], v[16:19]
	v_mfma_f32_16x16x32_bf16 v[12:15], v[184:187], v[200:203], v[12:15]
	v_mfma_f32_16x16x32_bf16 v[8:11], v[184:187], v[208:211], v[8:11]
	v_mfma_f32_16x16x32_bf16 v[4:7], v[192:195], v[200:203], v[4:7]
	v_mfma_f32_16x16x32_bf16 v[0:3], v[192:195], v[208:211], v[0:3]
	v_mfma_f32_16x16x32_bf16 v[28:31], v[172:175], v[204:207], v[28:31]
	v_mfma_f32_16x16x32_bf16 v[24:27], v[172:175], v[212:215], v[24:27]
	v_mfma_f32_16x16x32_bf16 v[20:23], v[180:183], v[204:207], v[20:23]
	v_mfma_f32_16x16x32_bf16 v[16:19], v[180:183], v[212:215], v[16:19]
	v_mfma_f32_16x16x32_bf16 v[12:15], v[188:191], v[204:207], v[12:15]
	v_mfma_f32_16x16x32_bf16 v[8:11], v[188:191], v[212:215], v[8:11]
	v_mfma_f32_16x16x32_bf16 v[4:7], v[196:199], v[204:207], v[4:7]
	v_mfma_f32_16x16x32_bf16 v[0:3], v[196:199], v[212:215], v[0:3]
	s_barrier
	ds_read_b128 v[152:155], v138
	ds_read_b128 v[156:159], v139
	ds_read_b128 v[160:163], v140
	ds_read_b128 v[164:167], v141
	s_addk_i32 s18, 0x100
	s_mov_b32 m0, s23
	ds_read_b128 v[168:171], v130 offset:32768
	ds_read_b128 v[172:175], v130 offset:33792
	ds_read_b128 v[176:179], v133 offset:32768
	ds_read_b128 v[180:183], v133 offset:33792
	ds_read_b128 v[184:187], v132 offset:32768
	ds_read_b128 v[188:191], v132 offset:33792
	ds_read_b128 v[192:195], v131 offset:32768
	ds_read_b128 v[196:199], v131 offset:33792
	buffer_load_dwordx4 v142, s[4:7], s18 offen lds
	s_mov_b32 m0, s24
	s_nop 0
	buffer_load_dwordx4 v143, s[4:7], s18 offen lds
	s_waitcnt lgkmcnt(8)
	s_barrier
	s_waitcnt lgkmcnt(0)
	v_mfma_f32_16x16x32_bf16 v[124:127], v[168:171], v[152:155], v[124:127]
	v_mfma_f32_16x16x32_bf16 v[120:123], v[168:171], v[160:163], v[120:123]
	v_mfma_f32_16x16x32_bf16 v[116:119], v[176:179], v[152:155], v[116:119]
	v_mfma_f32_16x16x32_bf16 v[112:115], v[176:179], v[160:163], v[112:115]
	v_mfma_f32_16x16x32_bf16 v[108:111], v[184:187], v[152:155], v[108:111]
	v_mfma_f32_16x16x32_bf16 v[104:107], v[184:187], v[160:163], v[104:107]
	v_mfma_f32_16x16x32_bf16 v[100:103], v[192:195], v[152:155], v[100:103]
	v_mfma_f32_16x16x32_bf16 v[96:99], v[192:195], v[160:163], v[96:99]
	v_mfma_f32_16x16x32_bf16 v[124:127], v[172:175], v[156:159], v[124:127]
	v_mfma_f32_16x16x32_bf16 v[120:123], v[172:175], v[164:167], v[120:123]
	v_mfma_f32_16x16x32_bf16 v[116:119], v[180:183], v[156:159], v[116:119]
	v_mfma_f32_16x16x32_bf16 v[112:115], v[180:183], v[164:167], v[112:115]
	v_mfma_f32_16x16x32_bf16 v[108:111], v[188:191], v[156:159], v[108:111]
	v_mfma_f32_16x16x32_bf16 v[104:107], v[188:191], v[164:167], v[104:107]
	v_mfma_f32_16x16x32_bf16 v[100:103], v[196:199], v[156:159], v[100:103]
	v_mfma_f32_16x16x32_bf16 v[96:99], v[196:199], v[164:167], v[96:99]
	s_barrier
	s_addk_i32 s19, 0x180
	s_mov_b32 m0, s25
	ds_read_b128 v[200:203], v134
	ds_read_b128 v[204:207], v135
	ds_read_b128 v[208:211], v136
	ds_read_b128 v[212:215], v137
	buffer_load_dwordx4 v142, s[8:11], s19 offen lds
	s_mov_b32 m0, s26
	s_nop 0
	buffer_load_dwordx4 v143, s[8:11], s19 offen lds
	s_barrier
	s_waitcnt lgkmcnt(0)
	v_mfma_f32_16x16x32_bf16 v[92:95], v[168:171], v[200:203], v[92:95]
	v_mfma_f32_16x16x32_bf16 v[88:91], v[168:171], v[208:211], v[88:91]
	v_mfma_f32_16x16x32_bf16 v[84:87], v[176:179], v[200:203], v[84:87]
	v_mfma_f32_16x16x32_bf16 v[80:83], v[176:179], v[208:211], v[80:83]
	v_mfma_f32_16x16x32_bf16 v[76:79], v[184:187], v[200:203], v[76:79]
	v_mfma_f32_16x16x32_bf16 v[72:75], v[184:187], v[208:211], v[72:75]
	v_mfma_f32_16x16x32_bf16 v[68:71], v[192:195], v[200:203], v[68:71]
	v_mfma_f32_16x16x32_bf16 v[64:67], v[192:195], v[208:211], v[64:67]
	v_mfma_f32_16x16x32_bf16 v[92:95], v[172:175], v[204:207], v[92:95]
	v_mfma_f32_16x16x32_bf16 v[88:91], v[172:175], v[212:215], v[88:91]
	v_mfma_f32_16x16x32_bf16 v[84:87], v[180:183], v[204:207], v[84:87]
	v_mfma_f32_16x16x32_bf16 v[80:83], v[180:183], v[212:215], v[80:83]
	v_mfma_f32_16x16x32_bf16 v[76:79], v[188:191], v[204:207], v[76:79]
	v_mfma_f32_16x16x32_bf16 v[72:75], v[188:191], v[212:215], v[72:75]
	v_mfma_f32_16x16x32_bf16 v[68:71], v[196:199], v[204:207], v[68:71]
	v_mfma_f32_16x16x32_bf16 v[64:67], v[196:199], v[212:215], v[64:67]
	s_barrier
	s_addk_i32 s47, 0x180
	s_mov_b32 m0, s27
	ds_read_b128 v[168:171], v130 offset:49152
	ds_read_b128 v[172:175], v130 offset:50176
	ds_read_b128 v[176:179], v133 offset:49152
	ds_read_b128 v[180:183], v133 offset:50176
	ds_read_b128 v[184:187], v132 offset:49152
	ds_read_b128 v[188:191], v132 offset:50176
	ds_read_b128 v[192:195], v131 offset:49152
	ds_read_b128 v[196:199], v131 offset:50176
	buffer_load_dwordx4 v142, s[4:7], s47 offen lds
	s_mov_b32 m0, s28
	s_nop 0
	buffer_load_dwordx4 v143, s[4:7], s47 offen lds
	s_barrier
	s_waitcnt lgkmcnt(0)
	v_mfma_f32_16x16x32_bf16 v[60:63], v[168:171], v[152:155], v[60:63]
	v_mfma_f32_16x16x32_bf16 v[56:59], v[168:171], v[160:163], v[56:59]
	v_mfma_f32_16x16x32_bf16 v[52:55], v[176:179], v[152:155], v[52:55]
	v_mfma_f32_16x16x32_bf16 v[48:51], v[176:179], v[160:163], v[48:51]
	v_mfma_f32_16x16x32_bf16 v[44:47], v[184:187], v[152:155], v[44:47]
	v_mfma_f32_16x16x32_bf16 v[40:43], v[184:187], v[160:163], v[40:43]
	v_mfma_f32_16x16x32_bf16 v[36:39], v[192:195], v[152:155], v[36:39]
	v_mfma_f32_16x16x32_bf16 v[32:35], v[192:195], v[160:163], v[32:35]
	v_mfma_f32_16x16x32_bf16 v[60:63], v[172:175], v[156:159], v[60:63]
	v_mfma_f32_16x16x32_bf16 v[56:59], v[172:175], v[164:167], v[56:59]
	v_mfma_f32_16x16x32_bf16 v[52:55], v[180:183], v[156:159], v[52:55]
	v_mfma_f32_16x16x32_bf16 v[48:51], v[180:183], v[164:167], v[48:51]
	v_mfma_f32_16x16x32_bf16 v[44:47], v[188:191], v[156:159], v[44:47]
	v_mfma_f32_16x16x32_bf16 v[40:43], v[188:191], v[164:167], v[40:43]
	v_mfma_f32_16x16x32_bf16 v[36:39], v[196:199], v[156:159], v[36:39]
	v_mfma_f32_16x16x32_bf16 v[32:35], v[196:199], v[164:167], v[32:35]
	s_barrier
; #define STAGE(P, RS, SOFF, OFF, kt) do { const int _so = (SOFF) + (kt) * (BK * 2); \
;     _Pragma("unroll") for (int _i = 0; _i < 2; ++_i) { \
;       __builtin_amdgcn_raw_ptr_buffer_load_lds(RS, (__attribute__((address_space(3))) void*)((P) + wave * 1024 + _i * 8192), 16, OFF[_i], _so, 0, 0); } } while (0)
; #define LDA(dst, b, h) _Pragma("unroll") for (int m = 0; m < 4; ++m) _Pragma("unroll") for (int k = 0; k < 2; ++k) \
;     dst[m][k] = *reinterpret_cast<const bf16x8*>(SA(b, h) + lds_byte(wr * 64 + m * 16 + fr, k * 32 + fq * 8))
; #define LDB(dst, b, h) _Pragma("unroll") for (int n = 0; n < 2; ++n) _Pragma("unroll") for (int k = 0; k < 2; ++k) \
;     dst[n][k] = *reinterpret_cast<const bf16x8*>(SB(b, h) + lds_byte(wc * 32 + n * 16 + fr, k * 32 + fq * 8))
; #define WAIT_V(n) asm volatile("s_waitcnt vmcnt(" #n ")" ::: "memory")
; #define WAIT_L(n) asm volatile("s_waitcnt lgkmcnt(" #n ")" ::: "memory")
; #define BAR __builtin_amdgcn_s_barrier()
;     ...
;       STAGE(SB(1, 1), rsB, sB1, offB, t + 3);
;       WAIT_V(6); BAR; MMA(1, 1, At, B1); BAR;
;     }
;     { LDB(B0, 0, 0); LDA(At, 0, 0); STAGE(SA(1, 1), rsA, sA1, offA, nt - 1);
;       BAR; WAIT_L(0); MMA(0, 0, At, B0); BAR;
;       LDB(B1, 0, 1); BAR; WAIT_L(0); MMA(0, 1, At, B1); BAR;
;       LDA(At, 0, 1); WAIT_V(4); BAR; WAIT_L(0); MMA(1, 0, At, B0); MMA(1, 1, At, B1); BAR; }
	s_addk_i32 s48, 0x180
	s_mov_b32 m0, s29
	s_nop 0
	buffer_load_dwordx4 v142, s[8:11], s48 offen lds
	s_mov_b32 m0, s30
	s_nop 0
	buffer_load_dwordx4 v143, s[8:11], s48 offen lds
	s_waitcnt vmcnt(6)
	s_barrier
	v_mfma_f32_16x16x32_bf16 v[28:31], v[168:171], v[200:203], v[28:31]
	v_mfma_f32_16x16x32_bf16 v[24:27], v[168:171], v[208:211], v[24:27]
	v_mfma_f32_16x16x32_bf16 v[20:23], v[176:179], v[200:203], v[20:23]
	v_mfma_f32_16x16x32_bf16 v[16:19], v[176:179], v[208:211], v[16:19]
	v_mfma_f32_16x16x32_bf16 v[12:15], v[184:187], v[200:203], v[12:15]
	v_mfma_f32_16x16x32_bf16 v[8:11], v[184:187], v[208:211], v[8:11]
	v_mfma_f32_16x16x32_bf16 v[4:7], v[192:195], v[200:203], v[4:7]
	v_mfma_f32_16x16x32_bf16 v[0:3], v[192:195], v[208:211], v[0:3]
	v_mfma_f32_16x16x32_bf16 v[28:31], v[172:175], v[204:207], v[28:31]
	v_mfma_f32_16x16x32_bf16 v[24:27], v[172:175], v[212:215], v[24:27]
	v_mfma_f32_16x16x32_bf16 v[20:23], v[180:183], v[204:207], v[20:23]
	v_mfma_f32_16x16x32_bf16 v[16:19], v[180:183], v[212:215], v[16:19]
	v_mfma_f32_16x16x32_bf16 v[12:15], v[188:191], v[204:207], v[12:15]
	v_mfma_f32_16x16x32_bf16 v[8:11], v[188:191], v[212:215], v[8:11]
	v_mfma_f32_16x16x32_bf16 v[4:7], v[196:199], v[204:207], v[4:7]
	v_mfma_f32_16x16x32_bf16 v[0:3], v[196:199], v[212:215], v[0:3]
	s_barrier
	s_add_i32 s16, s16, 2
	s_addk_i32 s17, 0x100
	s_cmp_gt_u32 s16, 27
	s_cbranch_scc0 .LBB0_225
	s_add_i32 s16, s41, 0xf80
	s_mov_b32 m0, s33
	ds_read_b128 v[152:155], v148
	ds_read_b128 v[156:159], v149
	ds_read_b128 v[160:163], v150
	ds_read_b128 v[148:151], v151
	ds_read_b128 v[164:167], v130
	ds_read_b128 v[168:171], v130 offset:1024
	ds_read_b128 v[172:175], v133
	ds_read_b128 v[176:179], v133 offset:1024
	ds_read_b128 v[180:183], v132
	ds_read_b128 v[184:187], v132 offset:1024
	ds_read_b128 v[188:191], v131
	ds_read_b128 v[192:195], v131 offset:1024
	buffer_load_dwordx4 v142, s[4:7], s16 offen lds
	s_mov_b32 m0, s34
	s_nop 0
	buffer_load_dwordx4 v143, s[4:7], s16 offen lds
	s_barrier
	s_waitcnt lgkmcnt(0)
	v_mfma_f32_16x16x32_bf16 v[124:127], v[164:167], v[152:155], v[124:127]
	v_mfma_f32_16x16x32_bf16 v[120:123], v[164:167], v[160:163], v[120:123]
	v_mfma_f32_16x16x32_bf16 v[116:119], v[172:175], v[152:155], v[116:119]
	v_mfma_f32_16x16x32_bf16 v[112:115], v[172:175], v[160:163], v[112:115]
	v_mfma_f32_16x16x32_bf16 v[108:111], v[180:183], v[152:155], v[108:111]
	v_mfma_f32_16x16x32_bf16 v[104:107], v[180:183], v[160:163], v[104:107]
	v_mfma_f32_16x16x32_bf16 v[100:103], v[188:191], v[152:155], v[100:103]
	v_mfma_f32_16x16x32_bf16 v[96:99], v[188:191], v[160:163], v[96:99]
	v_mfma_f32_16x16x32_bf16 v[124:127], v[168:171], v[156:159], v[124:127]
	v_mfma_f32_16x16x32_bf16 v[120:123], v[168:171], v[148:151], v[120:123]
	v_mfma_f32_16x16x32_bf16 v[116:119], v[176:179], v[156:159], v[116:119]
	v_mfma_f32_16x16x32_bf16 v[112:115], v[176:179], v[148:151], v[112:115]
	v_mfma_f32_16x16x32_bf16 v[108:111], v[184:187], v[156:159], v[108:111]
	v_mfma_f32_16x16x32_bf16 v[104:107], v[184:187], v[148:151], v[104:107]
	v_mfma_f32_16x16x32_bf16 v[100:103], v[192:195], v[156:159], v[100:103]
	v_mfma_f32_16x16x32_bf16 v[96:99], v[192:195], v[148:151], v[96:99]
	s_barrier
	ds_read_b128 v[196:199], v144
	ds_read_b128 v[142:145], v145
	ds_read_b128 v[200:203], v146
	ds_read_b128 v[204:207], v147
	s_barrier
	s_waitcnt lgkmcnt(0)
	v_mfma_f32_16x16x32_bf16 v[88:91], v[164:167], v[200:203], v[88:91]
	v_mfma_f32_16x16x32_bf16 v[84:87], v[172:175], v[196:199], v[84:87]
	v_mfma_f32_16x16x32_bf16 v[80:83], v[172:175], v[200:203], v[80:83]
	v_mfma_f32_16x16x32_bf16 v[76:79], v[180:183], v[196:199], v[76:79]
	v_mfma_f32_16x16x32_bf16 v[72:75], v[180:183], v[200:203], v[72:75]
	v_mfma_f32_16x16x32_bf16 v[68:71], v[188:191], v[196:199], v[68:71]
	v_mfma_f32_16x16x32_bf16 v[64:67], v[188:191], v[200:203], v[64:67]
	v_mfma_f32_16x16x32_bf16 v[92:95], v[164:167], v[196:199], v[92:95]
	v_mfma_f32_16x16x32_bf16 v[88:91], v[168:171], v[204:207], v[88:91]
	v_mfma_f32_16x16x32_bf16 v[84:87], v[176:179], v[142:145], v[84:87]
	v_mfma_f32_16x16x32_bf16 v[80:83], v[176:179], v[204:207], v[80:83]
	v_mfma_f32_16x16x32_bf16 v[76:79], v[184:187], v[142:145], v[76:79]
	v_mfma_f32_16x16x32_bf16 v[72:75], v[184:187], v[204:207], v[72:75]
	v_mfma_f32_16x16x32_bf16 v[68:71], v[192:195], v[142:145], v[68:71]
	v_mfma_f32_16x16x32_bf16 v[64:67], v[192:195], v[204:207], v[64:67]
	v_mfma_f32_16x16x32_bf16 v[164:167], v[168:171], v[142:145], v[92:95]
	s_barrier
	s_nop 0
	ds_read_b128 v[92:95], v130 offset:16384
	ds_read_b128 v[168:171], v130 offset:17408
	ds_read_b128 v[172:175], v133 offset:16384
	ds_read_b128 v[176:179], v133 offset:17408
	ds_read_b128 v[180:183], v132 offset:16384
	ds_read_b128 v[184:187], v132 offset:17408
	ds_read_b128 v[188:191], v131 offset:16384
	ds_read_b128 v[192:195], v131 offset:17408
	s_waitcnt vmcnt(4)
	s_barrier
; #define LDA(dst, b, h) _Pragma("unroll") for (int m = 0; m < 4; ++m) _Pragma("unroll") for (int k = 0; k < 2; ++k) \
;     dst[m][k] = *reinterpret_cast<const bf16x8*>(SA(b, h) + lds_byte(wr * 64 + m * 16 + fr, k * 32 + fq * 8))
; #define LDB(dst, b, h) _Pragma("unroll") for (int n = 0; n < 2; ++n) _Pragma("unroll") for (int k = 0; k < 2; ++k) \
;     dst[n][k] = *reinterpret_cast<const bf16x8*>(SB(b, h) + lds_byte(wc * 32 + n * 16 + fr, k * 32 + fq * 8))
; #define WAIT_V(n) asm volatile("s_waitcnt vmcnt(" #n ")" ::: "memory")
; #define WAIT_L(n) asm volatile("s_waitcnt lgkmcnt(" #n ")" ::: "memory")
; #define BAR __builtin_amdgcn_s_barrier()
;     ...
;       LDA(At, 0, 1); WAIT_V(4); BAR; WAIT_L(0); MMA(1, 0, At, B0); MMA(1, 1, At, B1); BAR; }
;     { LDB(B0, 1, 0); LDA(At, 1, 0); WAIT_V(2); BAR; WAIT_L(0); MMA(0, 0, At, B0); BAR;
	s_waitcnt lgkmcnt(0)
	v_mfma_f32_16x16x32_bf16 v[60:63], v[92:95], v[152:155], v[60:63]
	v_mfma_f32_16x16x32_bf16 v[56:59], v[92:95], v[160:163], v[56:59]
	v_mfma_f32_16x16x32_bf16 v[52:55], v[172:175], v[152:155], v[52:55]
	v_mfma_f32_16x16x32_bf16 v[48:51], v[172:175], v[160:163], v[48:51]
	v_mfma_f32_16x16x32_bf16 v[44:47], v[180:183], v[152:155], v[44:47]
	v_mfma_f32_16x16x32_bf16 v[40:43], v[180:183], v[160:163], v[40:43]
	v_mfma_f32_16x16x32_bf16 v[36:39], v[188:191], v[152:155], v[36:39]
	v_mfma_f32_16x16x32_bf16 v[32:35], v[188:191], v[160:163], v[32:35]
	v_mfma_f32_16x16x32_bf16 v[60:63], v[168:171], v[156:159], v[60:63]
	v_mfma_f32_16x16x32_bf16 v[56:59], v[168:171], v[148:151], v[56:59]
	v_mfma_f32_16x16x32_bf16 v[52:55], v[176:179], v[156:159], v[52:55]
	v_mfma_f32_16x16x32_bf16 v[48:51], v[176:179], v[148:151], v[48:51]
	v_mfma_f32_16x16x32_bf16 v[44:47], v[184:187], v[156:159], v[44:47]
	v_mfma_f32_16x16x32_bf16 v[40:43], v[184:187], v[148:151], v[40:43]
	v_mfma_f32_16x16x32_bf16 v[36:39], v[192:195], v[156:159], v[36:39]
	v_mfma_f32_16x16x32_bf16 v[32:35], v[192:195], v[148:151], v[32:35]
	v_mfma_f32_16x16x32_bf16 v[28:31], v[92:95], v[196:199], v[28:31]
	v_mfma_f32_16x16x32_bf16 v[24:27], v[92:95], v[200:203], v[24:27]
	v_mfma_f32_16x16x32_bf16 v[20:23], v[172:175], v[196:199], v[20:23]
	v_mfma_f32_16x16x32_bf16 v[16:19], v[172:175], v[200:203], v[16:19]
	v_mfma_f32_16x16x32_bf16 v[12:15], v[180:183], v[196:199], v[12:15]
	v_mfma_f32_16x16x32_bf16 v[8:11], v[180:183], v[200:203], v[8:11]
	v_mfma_f32_16x16x32_bf16 v[4:7], v[188:191], v[196:199], v[4:7]
	v_mfma_f32_16x16x32_bf16 v[0:3], v[188:191], v[200:203], v[0:3]
	v_mfma_f32_16x16x32_bf16 v[28:31], v[168:171], v[142:145], v[28:31]
	v_mfma_f32_16x16x32_bf16 v[24:27], v[168:171], v[204:207], v[24:27]
	v_mfma_f32_16x16x32_bf16 v[20:23], v[176:179], v[142:145], v[20:23]
	v_mfma_f32_16x16x32_bf16 v[16:19], v[176:179], v[204:207], v[16:19]
	v_mfma_f32_16x16x32_bf16 v[12:15], v[184:187], v[142:145], v[12:15]
	v_mfma_f32_16x16x32_bf16 v[8:11], v[184:187], v[204:207], v[8:11]
	v_mfma_f32_16x16x32_bf16 v[4:7], v[192:195], v[142:145], v[4:7]
	v_mfma_f32_16x16x32_bf16 v[0:3], v[192:195], v[204:207], v[0:3]
	s_barrier
	ds_read_b128 v[142:145], v138
	ds_read_b128 v[146:149], v139
	ds_read_b128 v[150:153], v140
	ds_read_b128 v[138:141], v141
	ds_read_b128 v[154:157], v130 offset:32768
	ds_read_b128 v[158:161], v130 offset:33792
	ds_read_b128 v[168:171], v133 offset:32768
	ds_read_b128 v[172:175], v133 offset:33792
	ds_read_b128 v[176:179], v132 offset:32768
	ds_read_b128 v[180:183], v132 offset:33792
	ds_read_b128 v[184:187], v131 offset:32768
	ds_read_b128 v[188:191], v131 offset:33792
	s_waitcnt vmcnt(2)
	s_barrier
	s_waitcnt lgkmcnt(0)
	v_mfma_f32_16x16x32_bf16 v[92:95], v[154:157], v[142:145], v[124:127]
	v_mfma_f32_16x16x32_bf16 v[120:123], v[154:157], v[150:153], v[120:123]
	v_mfma_f32_16x16x32_bf16 v[116:119], v[168:171], v[142:145], v[116:119]
	v_mfma_f32_16x16x32_bf16 v[112:115], v[168:171], v[150:153], v[112:115]
	v_mfma_f32_16x16x32_bf16 v[108:111], v[176:179], v[142:145], v[108:111]
	v_mfma_f32_16x16x32_bf16 v[104:107], v[176:179], v[150:153], v[104:107]
	v_mfma_f32_16x16x32_bf16 v[100:103], v[184:187], v[142:145], v[100:103]
	v_mfma_f32_16x16x32_bf16 v[96:99], v[184:187], v[150:153], v[96:99]
	v_mfma_f32_16x16x32_bf16 v[124:127], v[158:161], v[146:149], v[92:95]
	v_mfma_f32_16x16x32_bf16 v[120:123], v[158:161], v[138:141], v[120:123]
	v_mfma_f32_16x16x32_bf16 v[116:119], v[172:175], v[146:149], v[116:119]
	v_mfma_f32_16x16x32_bf16 v[112:115], v[172:175], v[138:141], v[112:115]
	v_mfma_f32_16x16x32_bf16 v[108:111], v[180:183], v[146:149], v[108:111]
	v_mfma_f32_16x16x32_bf16 v[104:107], v[180:183], v[138:141], v[104:107]
	v_mfma_f32_16x16x32_bf16 v[100:103], v[188:191], v[146:149], v[100:103]
	v_mfma_f32_16x16x32_bf16 v[92:95], v[188:191], v[138:141], v[96:99]
	s_barrier
; #define LDA(dst, b, h) _Pragma("unroll") for (int m = 0; m < 4; ++m) _Pragma("unroll") for (int k = 0; k < 2; ++k) \
;     dst[m][k] = *reinterpret_cast<const bf16x8*>(SA(b, h) + lds_byte(wr * 64 + m * 16 + fr, k * 32 + fq * 8))
; #define LDB(dst, b, h) _Pragma("unroll") for (int n = 0; n < 2; ++n) _Pragma("unroll") for (int k = 0; k < 2; ++k) \
;     dst[n][k] = *reinterpret_cast<const bf16x8*>(SB(b, h) + lds_byte(wc * 32 + n * 16 + fr, k * 32 + fq * 8))
; #define WAIT_V(n) asm volatile("s_waitcnt vmcnt(" #n ")" ::: "memory")
; #define WAIT_L(n) asm volatile("s_waitcnt lgkmcnt(" #n ")" ::: "memory")
; #define BAR __builtin_amdgcn_s_barrier()
;     ...
;       LDB(B1, 1, 1); WAIT_V(0); BAR; WAIT_L(0); MMA(0, 1, At, B1); BAR;
;       LDA(At, 1, 1); BAR; WAIT_L(0); MMA(1, 0, At, B0); MMA(1, 1, At, B1); BAR; }
;     if (wr == 0) BAR;
	ds_read_b128 v[192:195], v134
	ds_read_b128 v[196:199], v135
	ds_read_b128 v[200:203], v136
	ds_read_b128 v[134:137], v137
	s_waitcnt vmcnt(0)
	s_barrier
	s_waitcnt lgkmcnt(0)
	v_mfma_f32_16x16x32_bf16 v[96:99], v[154:157], v[192:195], v[164:167]
	v_mfma_f32_16x16x32_bf16 v[88:91], v[154:157], v[200:203], v[88:91]
	v_mfma_f32_16x16x32_bf16 v[84:87], v[168:171], v[192:195], v[84:87]
	v_mfma_f32_16x16x32_bf16 v[80:83], v[168:171], v[200:203], v[80:83]
	v_mfma_f32_16x16x32_bf16 v[76:79], v[176:179], v[192:195], v[76:79]
	v_mfma_f32_16x16x32_bf16 v[72:75], v[176:179], v[200:203], v[72:75]
	v_mfma_f32_16x16x32_bf16 v[68:71], v[184:187], v[192:195], v[68:71]
	v_mfma_f32_16x16x32_bf16 v[64:67], v[184:187], v[200:203], v[64:67]
	v_mfma_f32_16x16x32_bf16 v[96:99], v[158:161], v[196:199], v[96:99]
	v_mfma_f32_16x16x32_bf16 v[88:91], v[158:161], v[134:137], v[88:91]
	v_mfma_f32_16x16x32_bf16 v[84:87], v[172:175], v[196:199], v[84:87]
	v_mfma_f32_16x16x32_bf16 v[80:83], v[172:175], v[134:137], v[80:83]
	v_mfma_f32_16x16x32_bf16 v[76:79], v[180:183], v[196:199], v[76:79]
	v_mfma_f32_16x16x32_bf16 v[72:75], v[180:183], v[134:137], v[72:75]
	v_mfma_f32_16x16x32_bf16 v[68:71], v[188:191], v[196:199], v[68:71]
	v_mfma_f32_16x16x32_bf16 v[64:67], v[188:191], v[134:137], v[64:67]
	s_barrier
	ds_read_b128 v[154:157], v130 offset:49152
	ds_read_b128 v[158:161], v130 offset:50176
	ds_read_b128 v[162:165], v133 offset:49152
	ds_read_b128 v[166:169], v133 offset:50176
	ds_read_b128 v[170:173], v132 offset:49152
	ds_read_b128 v[174:177], v132 offset:50176
	ds_read_b128 v[178:181], v131 offset:49152
	ds_read_b128 v[130:133], v131 offset:50176
	s_barrier
	s_waitcnt lgkmcnt(0)
	v_mfma_f32_16x16x32_bf16 v[60:63], v[154:157], v[142:145], v[60:63]
	v_mfma_f32_16x16x32_bf16 v[56:59], v[154:157], v[150:153], v[56:59]
	v_mfma_f32_16x16x32_bf16 v[52:55], v[162:165], v[142:145], v[52:55]
	v_mfma_f32_16x16x32_bf16 v[48:51], v[162:165], v[150:153], v[48:51]
	v_mfma_f32_16x16x32_bf16 v[44:47], v[170:173], v[142:145], v[44:47]
	v_mfma_f32_16x16x32_bf16 v[40:43], v[170:173], v[150:153], v[40:43]
	v_mfma_f32_16x16x32_bf16 v[36:39], v[178:181], v[142:145], v[36:39]
	v_mfma_f32_16x16x32_bf16 v[32:35], v[178:181], v[150:153], v[32:35]
	v_mfma_f32_16x16x32_bf16 v[60:63], v[158:161], v[146:149], v[60:63]
	v_mfma_f32_16x16x32_bf16 v[56:59], v[158:161], v[138:141], v[56:59]
	v_mfma_f32_16x16x32_bf16 v[52:55], v[166:169], v[146:149], v[52:55]
	v_mfma_f32_16x16x32_bf16 v[48:51], v[166:169], v[138:141], v[48:51]
	v_mfma_f32_16x16x32_bf16 v[44:47], v[174:177], v[146:149], v[44:47]
	v_mfma_f32_16x16x32_bf16 v[40:43], v[174:177], v[138:141], v[40:43]
	v_mfma_f32_16x16x32_bf16 v[36:39], v[130:133], v[146:149], v[36:39]
	v_mfma_f32_16x16x32_bf16 v[32:35], v[130:133], v[138:141], v[32:35]
	v_mfma_f32_16x16x32_bf16 v[28:31], v[154:157], v[192:195], v[28:31]
	v_mfma_f32_16x16x32_bf16 v[24:27], v[154:157], v[200:203], v[24:27]
	v_mfma_f32_16x16x32_bf16 v[20:23], v[162:165], v[192:195], v[20:23]
	v_mfma_f32_16x16x32_bf16 v[16:19], v[162:165], v[200:203], v[16:19]
	v_mfma_f32_16x16x32_bf16 v[12:15], v[170:173], v[192:195], v[12:15]
	v_mfma_f32_16x16x32_bf16 v[8:11], v[170:173], v[200:203], v[8:11]
	v_mfma_f32_16x16x32_bf16 v[4:7], v[178:181], v[192:195], v[4:7]
	v_mfma_f32_16x16x32_bf16 v[0:3], v[178:181], v[200:203], v[0:3]
	v_mfma_f32_16x16x32_bf16 v[28:31], v[158:161], v[196:199], v[28:31]
	v_mfma_f32_16x16x32_bf16 v[24:27], v[158:161], v[134:137], v[24:27]
	v_mfma_f32_16x16x32_bf16 v[20:23], v[166:169], v[196:199], v[20:23]
	v_mfma_f32_16x16x32_bf16 v[16:19], v[166:169], v[134:137], v[16:19]
	v_mfma_f32_16x16x32_bf16 v[12:15], v[174:177], v[196:199], v[12:15]
	v_mfma_f32_16x16x32_bf16 v[8:11], v[174:177], v[134:137], v[8:11]
	v_mfma_f32_16x16x32_bf16 v[4:7], v[130:133], v[196:199], v[4:7]
	v_mfma_f32_16x16x32_bf16 v[0:3], v[130:133], v[134:137], v[0:3]
	v_cmp_gt_u32_e32 vcc, s37, v129
	s_barrier
	s_and_saveexec_b64 s[16:17], vcc
	s_cbranch_execz .LBB0_228
	s_barrier

; #define STAGE(P, RS, SOFF, OFF, kt) do { const int _so = (SOFF) + (kt) * (BK * 2); \
;     _Pragma("unroll") for (int _i = 0; _i < 2; ++_i) { \
;       __builtin_amdgcn_raw_ptr_buffer_load_lds(RS, (__attribute__((address_space(3))) void*)((P) + wave * 1024 + _i * 8192), 16, OFF[_i], _so, 0, 0); } } while (0)
; #define LDA(dst, b, h) _Pragma("unroll") for (int m = 0; m < 4; ++m) _Pragma("unroll") for (int k = 0; k < 2; ++k) \
;     dst[m][k] = *reinterpret_cast<const bf16x8*>(SA(b, h) + lds_byte(wr * 64 + m * 16 + fr, k * 32 + fq * 8))
; #define LDB(dst, b, h) _Pragma("unroll") for (int n = 0; n < 2; ++n) _Pragma("unroll") for (int k = 0; k < 2; ++k) \
;     dst[n][k] = *reinterpret_cast<const bf16x8*>(SB(b, h) + lds_byte(wc * 32 + n * 16 + fr, k * 32 + fq * 8))
; #define WAIT_V(n) asm volatile("s_waitcnt vmcnt(" #n ")" ::: "memory")
; #define WAIT_L(n) asm volatile("s_waitcnt lgkmcnt(" #n ")" ::: "memory")
; #define BAR __builtin_amdgcn_s_barrier()
; #define SCHED __builtin_amdgcn_sched_barrier(0)
;     ...
;       LDB(B0, 0, 0); SCHED; LDA(At, 0, 0); STAGE(SA(1, 1), rsA, sA1, offA, t + 1);
;       WAIT_L(8); BAR; WAIT_L(0); MMA(0, 0, At, B0); BAR; SCHED;
;       LDB(B1, 0, 1); STAGE(SB(0, 0), rsB, sB0, offB, t + 2);
;       BAR; WAIT_L(0); MMA(0, 1, At, B1); BAR;
;       LDA(At, 0, 1); STAGE(SA(0, 0), rsA, sA0, offA, t + 2);
;       BAR; WAIT_L(0); MMA(1, 0, At, B0); BAR; SCHED;
;       STAGE(SB(0, 1), rsB, sB1, offB, t + 2);
;       WAIT_V(6); BAR; MMA(1, 1, At, B1); BAR;
.LBB0_291:
	ds_read_b128 v[152:155], v147
	ds_read_b128 v[156:159], v148
	ds_read_b128 v[160:163], v149
	ds_read_b128 v[164:167], v150
	s_add_i32 s5, s94, s3
	s_add_i32 s6, s5, 0x80
	s_mov_b32 m0, s36
	ds_read_b128 v[168:171], v129
	ds_read_b128 v[172:175], v129 offset:1024
	ds_read_b128 v[176:179], v132
	ds_read_b128 v[180:183], v132 offset:1024
	ds_read_b128 v[184:187], v131
	ds_read_b128 v[188:191], v131 offset:1024
	ds_read_b128 v[192:195], v130
	ds_read_b128 v[196:199], v130 offset:1024
	buffer_load_dwordx4 v141, s[8:11], s6 offen lds
	s_mov_b32 m0, s61
	s_nop 0
	buffer_load_dwordx4 v142, s[8:11], s6 offen lds
	s_waitcnt lgkmcnt(8)
	s_barrier
	s_waitcnt lgkmcnt(0)
	v_mfma_f32_16x16x32_bf16 v[124:127], v[152:155], v[168:171], v[124:127]
	v_mfma_f32_16x16x32_bf16 v[120:123], v[160:163], v[168:171], v[120:123]
	v_mfma_f32_16x16x32_bf16 v[116:119], v[152:155], v[176:179], v[116:119]
	v_mfma_f32_16x16x32_bf16 v[112:115], v[160:163], v[176:179], v[112:115]
	v_mfma_f32_16x16x32_bf16 v[108:111], v[152:155], v[184:187], v[108:111]
	v_mfma_f32_16x16x32_bf16 v[104:107], v[160:163], v[184:187], v[104:107]
	v_mfma_f32_16x16x32_bf16 v[100:103], v[152:155], v[192:195], v[100:103]
	v_mfma_f32_16x16x32_bf16 v[96:99], v[160:163], v[192:195], v[96:99]
	v_mfma_f32_16x16x32_bf16 v[124:127], v[156:159], v[172:175], v[124:127]
	v_mfma_f32_16x16x32_bf16 v[120:123], v[164:167], v[172:175], v[120:123]
	v_mfma_f32_16x16x32_bf16 v[116:119], v[156:159], v[180:183], v[116:119]
	v_mfma_f32_16x16x32_bf16 v[112:115], v[164:167], v[180:183], v[112:115]
	v_mfma_f32_16x16x32_bf16 v[108:111], v[156:159], v[188:191], v[108:111]
	v_mfma_f32_16x16x32_bf16 v[104:107], v[164:167], v[188:191], v[104:107]
	v_mfma_f32_16x16x32_bf16 v[100:103], v[156:159], v[196:199], v[100:103]
	v_mfma_f32_16x16x32_bf16 v[96:99], v[164:167], v[196:199], v[96:99]
	s_barrier
	s_add_i32 s6, s96, s3
	s_add_i32 s7, s6, 0x100
	s_mov_b32 s14, s10
	s_mov_b32 s15, s11
	s_mov_b32 m0, s37
	ds_read_b128 v[200:203], v143
	ds_read_b128 v[204:207], v144
	ds_read_b128 v[208:211], v145
	ds_read_b128 v[212:215], v146
	buffer_load_dwordx4 v141, s[12:15], s7 offen lds
	s_mov_b32 m0, s48
	s_nop 0
	buffer_load_dwordx4 v142, s[12:15], s7 offen lds
	s_barrier
	s_waitcnt lgkmcnt(0)
	v_mfma_f32_16x16x32_bf16 v[92:95], v[200:203], v[168:171], v[92:95]
	v_mfma_f32_16x16x32_bf16 v[88:91], v[208:211], v[168:171], v[88:91]
	v_mfma_f32_16x16x32_bf16 v[80:83], v[200:203], v[176:179], v[80:83]
	v_mfma_f32_16x16x32_bf16 v[68:71], v[208:211], v[176:179], v[68:71]
	v_mfma_f32_16x16x32_bf16 v[60:63], v[200:203], v[184:187], v[60:63]
	v_mfma_f32_16x16x32_bf16 v[56:59], v[208:211], v[184:187], v[56:59]
	v_mfma_f32_16x16x32_bf16 v[52:55], v[200:203], v[192:195], v[52:55]
	v_mfma_f32_16x16x32_bf16 v[48:51], v[208:211], v[192:195], v[48:51]
	v_mfma_f32_16x16x32_bf16 v[92:95], v[204:207], v[172:175], v[92:95]
	v_mfma_f32_16x16x32_bf16 v[88:91], v[212:215], v[172:175], v[88:91]
	v_mfma_f32_16x16x32_bf16 v[80:83], v[204:207], v[180:183], v[80:83]
	v_mfma_f32_16x16x32_bf16 v[68:71], v[212:215], v[180:183], v[68:71]
	v_mfma_f32_16x16x32_bf16 v[60:63], v[204:207], v[188:191], v[60:63]
	v_mfma_f32_16x16x32_bf16 v[56:59], v[212:215], v[188:191], v[56:59]
	v_mfma_f32_16x16x32_bf16 v[52:55], v[204:207], v[196:199], v[52:55]
	v_mfma_f32_16x16x32_bf16 v[48:51], v[212:215], v[196:199], v[48:51]
	s_barrier
	s_add_i32 s7, s95, s3
	s_add_i32 s22, s7, 0x100
	s_mov_b32 m0, s35
	ds_read_b128 v[168:171], v129 offset:16384
	ds_read_b128 v[172:175], v129 offset:17408
	ds_read_b128 v[176:179], v132 offset:16384
	ds_read_b128 v[180:183], v132 offset:17408
	ds_read_b128 v[184:187], v131 offset:16384
	ds_read_b128 v[188:191], v131 offset:17408
	ds_read_b128 v[192:195], v130 offset:16384
	ds_read_b128 v[196:199], v130 offset:17408
	buffer_load_dwordx4 v141, s[8:11], s22 offen lds
	s_mov_b32 m0, s49
	s_nop 0
	buffer_load_dwordx4 v142, s[8:11], s22 offen lds
	s_barrier
	s_waitcnt lgkmcnt(0)
	v_mfma_f32_16x16x32_bf16 v[44:47], v[152:155], v[168:171], v[44:47]
	v_mfma_f32_16x16x32_bf16 v[40:43], v[160:163], v[168:171], v[40:43]
	v_mfma_f32_16x16x32_bf16 v[36:39], v[152:155], v[176:179], v[36:39]
	v_mfma_f32_16x16x32_bf16 v[32:35], v[160:163], v[176:179], v[32:35]
	v_mfma_f32_16x16x32_bf16 v[28:31], v[152:155], v[184:187], v[28:31]
	v_mfma_f32_16x16x32_bf16 v[24:27], v[160:163], v[184:187], v[24:27]
	v_mfma_f32_16x16x32_bf16 v[20:23], v[152:155], v[192:195], v[20:23]
	v_mfma_f32_16x16x32_bf16 v[16:19], v[160:163], v[192:195], v[16:19]
	v_mfma_f32_16x16x32_bf16 v[44:47], v[156:159], v[172:175], v[44:47]
	v_mfma_f32_16x16x32_bf16 v[40:43], v[164:167], v[172:175], v[40:43]
	v_mfma_f32_16x16x32_bf16 v[36:39], v[156:159], v[180:183], v[36:39]
	v_mfma_f32_16x16x32_bf16 v[32:35], v[164:167], v[180:183], v[32:35]
	v_mfma_f32_16x16x32_bf16 v[28:31], v[156:159], v[188:191], v[28:31]
	v_mfma_f32_16x16x32_bf16 v[24:27], v[164:167], v[188:191], v[24:27]
	v_mfma_f32_16x16x32_bf16 v[20:23], v[156:159], v[196:199], v[20:23]
	v_mfma_f32_16x16x32_bf16 v[16:19], v[164:167], v[196:199], v[16:19]
	s_barrier
	s_add_i32 s22, s97, s3
	s_add_i32 s23, s22, 0x100
	s_mov_b32 m0, s38
	s_nop 0
	buffer_load_dwordx4 v141, s[12:15], s23 offen lds
	s_mov_b32 m0, s54
	s_nop 0
	buffer_load_dwordx4 v142, s[12:15], s23 offen lds
	s_waitcnt vmcnt(6)
	s_barrier
; #define STAGE(P, RS, SOFF, OFF, kt) do { const int _so = (SOFF) + (kt) * (BK * 2); \
;     _Pragma("unroll") for (int _i = 0; _i < 2; ++_i) { \
;       __builtin_amdgcn_raw_ptr_buffer_load_lds(RS, (__attribute__((address_space(3))) void*)((P) + wave * 1024 + _i * 8192), 16, OFF[_i], _so, 0, 0); } } while (0)
; #define LDA(dst, b, h) _Pragma("unroll") for (int m = 0; m < 4; ++m) _Pragma("unroll") for (int k = 0; k < 2; ++k) \
;     dst[m][k] = *reinterpret_cast<const bf16x8*>(SA(b, h) + lds_byte(wr * 64 + m * 16 + fr, k * 32 + fq * 8))
; #define LDB(dst, b, h) _Pragma("unroll") for (int n = 0; n < 2; ++n) _Pragma("unroll") for (int k = 0; k < 2; ++k) \
;     dst[n][k] = *reinterpret_cast<const bf16x8*>(SB(b, h) + lds_byte(wc * 32 + n * 16 + fr, k * 32 + fq * 8))
; #define WAIT_V(n) asm volatile("s_waitcnt vmcnt(" #n ")" ::: "memory")
; #define WAIT_L(n) asm volatile("s_waitcnt lgkmcnt(" #n ")" ::: "memory")
; #define BAR __builtin_amdgcn_s_barrier()
; #define SCHED __builtin_amdgcn_sched_barrier(0)
;     ...
;       WAIT_V(6); BAR; MMA(1, 1, At, B1); BAR;
;       LDB(B0, 1, 0); SCHED; LDA(At, 1, 0); STAGE(SA(0, 1), rsA, sA1, offA, t + 2);
;       WAIT_L(8); BAR; WAIT_L(0); MMA(0, 0, At, B0); BAR; SCHED;
;       LDB(B1, 1, 1); STAGE(SB(1, 0), rsB, sB0, offB, t + 3);
;       BAR; WAIT_L(0); MMA(0, 1, At, B1); BAR;
;       LDA(At, 1, 1); STAGE(SA(1, 0), rsA, sA0, offA, t + 3);
;       BAR; WAIT_L(0); MMA(1, 0, At, B0); BAR; SCHED;
;       STAGE(SB(1, 1), rsB, sB1, offB, t + 3);
;       WAIT_V(6); BAR; MMA(1, 1, At, B1); BAR;
	v_mfma_f32_16x16x32_bf16 v[12:15], v[200:203], v[168:171], v[12:15]
	v_mfma_f32_16x16x32_bf16 v[8:11], v[208:211], v[168:171], v[8:11]
	v_mfma_f32_16x16x32_bf16 v[4:7], v[200:203], v[176:179], v[4:7]
	v_mfma_f32_16x16x32_bf16 v[0:3], v[208:211], v[176:179], v[0:3]
	v_mfma_f32_16x16x32_bf16 v[64:67], v[200:203], v[184:187], v[64:67]
	v_mfma_f32_16x16x32_bf16 v[72:75], v[208:211], v[184:187], v[72:75]
	v_mfma_f32_16x16x32_bf16 v[76:79], v[200:203], v[192:195], v[76:79]
	v_mfma_f32_16x16x32_bf16 v[84:87], v[208:211], v[192:195], v[84:87]
	v_mfma_f32_16x16x32_bf16 v[12:15], v[204:207], v[172:175], v[12:15]
	v_mfma_f32_16x16x32_bf16 v[8:11], v[212:215], v[172:175], v[8:11]
	v_mfma_f32_16x16x32_bf16 v[4:7], v[204:207], v[180:183], v[4:7]
	v_mfma_f32_16x16x32_bf16 v[0:3], v[212:215], v[180:183], v[0:3]
	v_mfma_f32_16x16x32_bf16 v[64:67], v[204:207], v[188:191], v[64:67]
	v_mfma_f32_16x16x32_bf16 v[72:75], v[212:215], v[188:191], v[72:75]
	v_mfma_f32_16x16x32_bf16 v[76:79], v[204:207], v[196:199], v[76:79]
	v_mfma_f32_16x16x32_bf16 v[84:87], v[212:215], v[196:199], v[84:87]
	s_barrier
	ds_read_b128 v[152:155], v137
	ds_read_b128 v[156:159], v138
	ds_read_b128 v[160:163], v139
	ds_read_b128 v[164:167], v140
	s_addk_i32 s5, 0x100
	s_mov_b32 m0, s39
	ds_read_b128 v[168:171], v129 offset:32768
	ds_read_b128 v[172:175], v129 offset:33792
	ds_read_b128 v[176:179], v132 offset:32768
	ds_read_b128 v[180:183], v132 offset:33792
	ds_read_b128 v[184:187], v131 offset:32768
	ds_read_b128 v[188:191], v131 offset:33792
	ds_read_b128 v[192:195], v130 offset:32768
	ds_read_b128 v[196:199], v130 offset:33792
	buffer_load_dwordx4 v141, s[8:11], s5 offen lds
	s_mov_b32 m0, s55
	s_nop 0
	buffer_load_dwordx4 v142, s[8:11], s5 offen lds
	s_waitcnt lgkmcnt(8)
	s_barrier
	s_waitcnt lgkmcnt(0)
	v_mfma_f32_16x16x32_bf16 v[124:127], v[152:155], v[168:171], v[124:127]
	v_mfma_f32_16x16x32_bf16 v[120:123], v[160:163], v[168:171], v[120:123]
	v_mfma_f32_16x16x32_bf16 v[116:119], v[152:155], v[176:179], v[116:119]
	v_mfma_f32_16x16x32_bf16 v[112:115], v[160:163], v[176:179], v[112:115]
	v_mfma_f32_16x16x32_bf16 v[108:111], v[152:155], v[184:187], v[108:111]
	v_mfma_f32_16x16x32_bf16 v[104:107], v[160:163], v[184:187], v[104:107]
	v_mfma_f32_16x16x32_bf16 v[100:103], v[152:155], v[192:195], v[100:103]
	v_mfma_f32_16x16x32_bf16 v[96:99], v[160:163], v[192:195], v[96:99]
	v_mfma_f32_16x16x32_bf16 v[124:127], v[156:159], v[172:175], v[124:127]
	v_mfma_f32_16x16x32_bf16 v[120:123], v[164:167], v[172:175], v[120:123]
	v_mfma_f32_16x16x32_bf16 v[116:119], v[156:159], v[180:183], v[116:119]
	v_mfma_f32_16x16x32_bf16 v[112:115], v[164:167], v[180:183], v[112:115]
	v_mfma_f32_16x16x32_bf16 v[108:111], v[156:159], v[188:191], v[108:111]
	v_mfma_f32_16x16x32_bf16 v[104:107], v[164:167], v[188:191], v[104:107]
	v_mfma_f32_16x16x32_bf16 v[100:103], v[156:159], v[196:199], v[100:103]
	v_mfma_f32_16x16x32_bf16 v[96:99], v[164:167], v[196:199], v[96:99]
	s_barrier
	s_addk_i32 s6, 0x180
	s_mov_b32 m0, s42
	ds_read_b128 v[200:203], v133
	ds_read_b128 v[204:207], v134
	ds_read_b128 v[208:211], v135
	ds_read_b128 v[212:215], v136
	buffer_load_dwordx4 v141, s[12:15], s6 offen lds
	s_mov_b32 m0, s58
	s_nop 0
	buffer_load_dwordx4 v142, s[12:15], s6 offen lds
	s_barrier
	s_waitcnt lgkmcnt(0)
	v_mfma_f32_16x16x32_bf16 v[92:95], v[200:203], v[168:171], v[92:95]
	v_mfma_f32_16x16x32_bf16 v[88:91], v[208:211], v[168:171], v[88:91]
	v_mfma_f32_16x16x32_bf16 v[80:83], v[200:203], v[176:179], v[80:83]
	v_mfma_f32_16x16x32_bf16 v[68:71], v[208:211], v[176:179], v[68:71]
	v_mfma_f32_16x16x32_bf16 v[60:63], v[200:203], v[184:187], v[60:63]
	v_mfma_f32_16x16x32_bf16 v[56:59], v[208:211], v[184:187], v[56:59]
	v_mfma_f32_16x16x32_bf16 v[52:55], v[200:203], v[192:195], v[52:55]
	v_mfma_f32_16x16x32_bf16 v[48:51], v[208:211], v[192:195], v[48:51]
	v_mfma_f32_16x16x32_bf16 v[92:95], v[204:207], v[172:175], v[92:95]
	v_mfma_f32_16x16x32_bf16 v[88:91], v[212:215], v[172:175], v[88:91]
	v_mfma_f32_16x16x32_bf16 v[80:83], v[204:207], v[180:183], v[80:83]
	v_mfma_f32_16x16x32_bf16 v[68:71], v[212:215], v[180:183], v[68:71]
	v_mfma_f32_16x16x32_bf16 v[60:63], v[204:207], v[188:191], v[60:63]
	v_mfma_f32_16x16x32_bf16 v[56:59], v[212:215], v[188:191], v[56:59]
	v_mfma_f32_16x16x32_bf16 v[52:55], v[204:207], v[196:199], v[52:55]
	v_mfma_f32_16x16x32_bf16 v[48:51], v[212:215], v[196:199], v[48:51]
	s_barrier
	s_addk_i32 s7, 0x180
	s_mov_b32 m0, s43
	ds_read_b128 v[168:171], v129 offset:49152
	ds_read_b128 v[172:175], v129 offset:50176
	ds_read_b128 v[176:179], v132 offset:49152
	ds_read_b128 v[180:183], v132 offset:50176
	ds_read_b128 v[184:187], v131 offset:49152
	ds_read_b128 v[188:191], v131 offset:50176
	ds_read_b128 v[192:195], v130 offset:49152
	ds_read_b128 v[196:199], v130 offset:50176
	buffer_load_dwordx4 v141, s[8:11], s7 offen lds
	s_mov_b32 m0, s59
	s_nop 0
	buffer_load_dwordx4 v142, s[8:11], s7 offen lds
	s_barrier
	s_waitcnt lgkmcnt(0)
	v_mfma_f32_16x16x32_bf16 v[44:47], v[152:155], v[168:171], v[44:47]
	v_mfma_f32_16x16x32_bf16 v[40:43], v[160:163], v[168:171], v[40:43]
	v_mfma_f32_16x16x32_bf16 v[36:39], v[152:155], v[176:179], v[36:39]
	v_mfma_f32_16x16x32_bf16 v[32:35], v[160:163], v[176:179], v[32:35]
	v_mfma_f32_16x16x32_bf16 v[28:31], v[152:155], v[184:187], v[28:31]
	v_mfma_f32_16x16x32_bf16 v[24:27], v[160:163], v[184:187], v[24:27]
	v_mfma_f32_16x16x32_bf16 v[20:23], v[152:155], v[192:195], v[20:23]
	v_mfma_f32_16x16x32_bf16 v[16:19], v[160:163], v[192:195], v[16:19]
	v_mfma_f32_16x16x32_bf16 v[44:47], v[156:159], v[172:175], v[44:47]
	v_mfma_f32_16x16x32_bf16 v[40:43], v[164:167], v[172:175], v[40:43]
	v_mfma_f32_16x16x32_bf16 v[36:39], v[156:159], v[180:183], v[36:39]
	v_mfma_f32_16x16x32_bf16 v[32:35], v[164:167], v[180:183], v[32:35]
	v_mfma_f32_16x16x32_bf16 v[28:31], v[156:159], v[188:191], v[28:31]
	v_mfma_f32_16x16x32_bf16 v[24:27], v[164:167], v[188:191], v[24:27]
	v_mfma_f32_16x16x32_bf16 v[20:23], v[156:159], v[196:199], v[20:23]
	v_mfma_f32_16x16x32_bf16 v[16:19], v[164:167], v[196:199], v[16:19]
	s_barrier
; #define STAGE(P, RS, SOFF, OFF, kt) do { const int _so = (SOFF) + (kt) * (BK * 2); \
;     _Pragma("unroll") for (int _i = 0; _i < 2; ++_i) { \
;       __builtin_amdgcn_raw_ptr_buffer_load_lds(RS, (__attribute__((address_space(3))) void*)((P) + wave * 1024 + _i * 8192), 16, OFF[_i], _so, 0, 0); } } while (0)
; #define LDA(dst, b, h) _Pragma("unroll") for (int m = 0; m < 4; ++m) _Pragma("unroll") for (int k = 0; k < 2; ++k) \
;     dst[m][k] = *reinterpret_cast<const bf16x8*>(SA(b, h) + lds_byte(wr * 64 + m * 16 + fr, k * 32 + fq * 8))
; #define LDB(dst, b, h) _Pragma("unroll") for (int n = 0; n < 2; ++n) _Pragma("unroll") for (int k = 0; k < 2; ++k) \
;     dst[n][k] = *reinterpret_cast<const bf16x8*>(SB(b, h) + lds_byte(wc * 32 + n * 16 + fr, k * 32 + fq * 8))
; #define WAIT_V(n) asm volatile("s_waitcnt vmcnt(" #n ")" ::: "memory")
; #define WAIT_L(n) asm volatile("s_waitcnt lgkmcnt(" #n ")" ::: "memory")
; #define BAR __builtin_amdgcn_s_barrier()
;     ...
;       WAIT_V(6); BAR; MMA(1, 1, At, B1); BAR;
;     }
;     { LDB(B0, 0, 0); LDA(At, 0, 0); STAGE(SA(1, 1), rsA, sA1, offA, nt - 1);
;       BAR; WAIT_L(0); MMA(0, 0, At, B0); BAR;
;       LDB(B1, 0, 1); BAR; WAIT_L(0); MMA(0, 1, At, B1); BAR;
;       LDA(At, 0, 1); WAIT_V(4); BAR; WAIT_L(0); MMA(1, 0, At, B0); MMA(1, 1, At, B1); BAR; }
	s_addk_i32 s22, 0x180
	s_mov_b32 m0, s44
	s_nop 0
	buffer_load_dwordx4 v141, s[12:15], s22 offen lds
	s_mov_b32 m0, s60
	s_nop 0
	buffer_load_dwordx4 v142, s[12:15], s22 offen lds
	s_waitcnt vmcnt(6)
	s_barrier
	v_mfma_f32_16x16x32_bf16 v[12:15], v[200:203], v[168:171], v[12:15]
	v_mfma_f32_16x16x32_bf16 v[8:11], v[208:211], v[168:171], v[8:11]
	v_mfma_f32_16x16x32_bf16 v[4:7], v[200:203], v[176:179], v[4:7]
	v_mfma_f32_16x16x32_bf16 v[0:3], v[208:211], v[176:179], v[0:3]
	v_mfma_f32_16x16x32_bf16 v[64:67], v[200:203], v[184:187], v[64:67]
	v_mfma_f32_16x16x32_bf16 v[72:75], v[208:211], v[184:187], v[72:75]
	v_mfma_f32_16x16x32_bf16 v[76:79], v[200:203], v[192:195], v[76:79]
	v_mfma_f32_16x16x32_bf16 v[84:87], v[208:211], v[192:195], v[84:87]
	v_mfma_f32_16x16x32_bf16 v[12:15], v[204:207], v[172:175], v[12:15]
	v_mfma_f32_16x16x32_bf16 v[8:11], v[212:215], v[172:175], v[8:11]
	v_mfma_f32_16x16x32_bf16 v[4:7], v[204:207], v[180:183], v[4:7]
	v_mfma_f32_16x16x32_bf16 v[0:3], v[212:215], v[180:183], v[0:3]
	v_mfma_f32_16x16x32_bf16 v[64:67], v[204:207], v[188:191], v[64:67]
	v_mfma_f32_16x16x32_bf16 v[72:75], v[212:215], v[188:191], v[72:75]
	v_mfma_f32_16x16x32_bf16 v[76:79], v[204:207], v[196:199], v[76:79]
	v_mfma_f32_16x16x32_bf16 v[84:87], v[212:215], v[196:199], v[84:87]
	s_barrier
	s_add_i32 s1, s1, 2
	s_addk_i32 s3, 0x100
	s_cmp_gt_u32 s1, 11
	s_cbranch_scc0 .LBB0_291
	s_add_i32 s1, s94, 0x780
	s_mov_b32 m0, s36
	ds_read_b128 v[152:155], v147
	ds_read_b128 v[156:159], v148
	ds_read_b128 v[160:163], v149
	ds_read_b128 v[148:151], v150
	ds_read_b128 v[164:167], v129
	ds_read_b128 v[168:171], v129 offset:1024
	ds_read_b128 v[172:175], v132
	ds_read_b128 v[176:179], v132 offset:1024
	ds_read_b128 v[180:183], v131
	ds_read_b128 v[184:187], v131 offset:1024
	ds_read_b128 v[188:191], v130
	ds_read_b128 v[192:195], v130 offset:1024
	buffer_load_dwordx4 v141, s[8:11], s1 offen lds
	s_mov_b32 m0, s61
	s_nop 0
	buffer_load_dwordx4 v142, s[8:11], s1 offen lds
	s_barrier
	s_waitcnt lgkmcnt(0)
	v_mfma_f32_16x16x32_bf16 v[124:127], v[152:155], v[164:167], v[124:127]
	v_mfma_f32_16x16x32_bf16 v[120:123], v[160:163], v[164:167], v[120:123]
	v_mfma_f32_16x16x32_bf16 v[116:119], v[152:155], v[172:175], v[116:119]
	v_mfma_f32_16x16x32_bf16 v[112:115], v[160:163], v[172:175], v[112:115]
	v_mfma_f32_16x16x32_bf16 v[108:111], v[152:155], v[180:183], v[108:111]
	v_mfma_f32_16x16x32_bf16 v[104:107], v[160:163], v[180:183], v[104:107]
	v_mfma_f32_16x16x32_bf16 v[100:103], v[152:155], v[188:191], v[100:103]
	v_mfma_f32_16x16x32_bf16 v[96:99], v[160:163], v[188:191], v[96:99]
	v_mfma_f32_16x16x32_bf16 v[124:127], v[156:159], v[168:171], v[124:127]
	v_mfma_f32_16x16x32_bf16 v[120:123], v[148:151], v[168:171], v[120:123]
	v_mfma_f32_16x16x32_bf16 v[116:119], v[156:159], v[176:179], v[116:119]
	v_mfma_f32_16x16x32_bf16 v[112:115], v[148:151], v[176:179], v[112:115]
	v_mfma_f32_16x16x32_bf16 v[108:111], v[156:159], v[184:187], v[108:111]
	v_mfma_f32_16x16x32_bf16 v[104:107], v[148:151], v[184:187], v[104:107]
	v_mfma_f32_16x16x32_bf16 v[100:103], v[156:159], v[192:195], v[100:103]
	v_mfma_f32_16x16x32_bf16 v[96:99], v[148:151], v[192:195], v[96:99]
	s_barrier
	ds_read_b128 v[196:199], v143
	ds_read_b128 v[200:203], v144
	ds_read_b128 v[142:145], v145
	ds_read_b128 v[204:207], v146
	s_barrier
	s_waitcnt lgkmcnt(0)
	v_mfma_f32_16x16x32_bf16 v[88:91], v[142:145], v[164:167], v[88:91]
	v_mfma_f32_16x16x32_bf16 v[80:83], v[196:199], v[172:175], v[80:83]
	v_mfma_f32_16x16x32_bf16 v[60:63], v[196:199], v[180:183], v[60:63]
	v_mfma_f32_16x16x32_bf16 v[56:59], v[142:145], v[180:183], v[56:59]
	v_mfma_f32_16x16x32_bf16 v[52:55], v[196:199], v[188:191], v[52:55]
	v_mfma_f32_16x16x32_bf16 v[48:51], v[142:145], v[188:191], v[48:51]
	v_mfma_f32_16x16x32_bf16 v[92:95], v[196:199], v[164:167], v[92:95]
	v_mfma_f32_16x16x32_bf16 v[68:71], v[142:145], v[172:175], v[68:71]
	v_mfma_f32_16x16x32_bf16 v[88:91], v[204:207], v[168:171], v[88:91]
	v_mfma_f32_16x16x32_bf16 v[80:83], v[200:203], v[176:179], v[80:83]
	v_mfma_f32_16x16x32_bf16 v[60:63], v[200:203], v[184:187], v[60:63]
	v_mfma_f32_16x16x32_bf16 v[56:59], v[204:207], v[184:187], v[56:59]
	v_mfma_f32_16x16x32_bf16 v[52:55], v[200:203], v[192:195], v[52:55]
	v_mfma_f32_16x16x32_bf16 v[48:51], v[204:207], v[192:195], v[48:51]
	v_mfma_f32_16x16x32_bf16 v[164:167], v[200:203], v[168:171], v[92:95]
	v_mfma_f32_16x16x32_bf16 v[168:171], v[204:207], v[176:179], v[68:71]
	s_barrier
	s_nop 0
	ds_read_b128 v[68:71], v129 offset:16384
	ds_read_b128 v[92:95], v129 offset:17408
	ds_read_b128 v[172:175], v132 offset:16384
	ds_read_b128 v[176:179], v132 offset:17408
	ds_read_b128 v[180:183], v131 offset:16384
	ds_read_b128 v[184:187], v131 offset:17408
	ds_read_b128 v[188:191], v130 offset:16384
	ds_read_b128 v[192:195], v130 offset:17408
	s_waitcnt vmcnt(4)
	s_barrier
; #define LDA(dst, b, h) _Pragma("unroll") for (int m = 0; m < 4; ++m) _Pragma("unroll") for (int k = 0; k < 2; ++k) \
;     dst[m][k] = *reinterpret_cast<const bf16x8*>(SA(b, h) + lds_byte(wr * 64 + m * 16 + fr, k * 32 + fq * 8))
; #define LDB(dst, b, h) _Pragma("unroll") for (int n = 0; n < 2; ++n) _Pragma("unroll") for (int k = 0; k < 2; ++k) \
;     dst[n][k] = *reinterpret_cast<const bf16x8*>(SB(b, h) + lds_byte(wc * 32 + n * 16 + fr, k * 32 + fq * 8))
; #define WAIT_V(n) asm volatile("s_waitcnt vmcnt(" #n ")" ::: "memory")
; #define WAIT_L(n) asm volatile("s_waitcnt lgkmcnt(" #n ")" ::: "memory")
; #define BAR __builtin_amdgcn_s_barrier()
;     ...
;       LDA(At, 0, 1); WAIT_V(4); BAR; WAIT_L(0); MMA(1, 0, At, B0); MMA(1, 1, At, B1); BAR; }
;     { LDB(B0, 1, 0); LDA(At, 1, 0); WAIT_V(2); BAR; WAIT_L(0); MMA(0, 0, At, B0); BAR;
;       LDB(B1, 1, 1); WAIT_V(0); BAR; WAIT_L(0); MMA(0, 1, At, B1); BAR;
	s_waitcnt lgkmcnt(0)
	v_mfma_f32_16x16x32_bf16 v[44:47], v[152:155], v[68:71], v[44:47]
	v_mfma_f32_16x16x32_bf16 v[40:43], v[160:163], v[68:71], v[40:43]
	v_mfma_f32_16x16x32_bf16 v[36:39], v[152:155], v[172:175], v[36:39]
	v_mfma_f32_16x16x32_bf16 v[32:35], v[160:163], v[172:175], v[32:35]
	v_mfma_f32_16x16x32_bf16 v[28:31], v[152:155], v[180:183], v[28:31]
	v_mfma_f32_16x16x32_bf16 v[24:27], v[160:163], v[180:183], v[24:27]
	v_mfma_f32_16x16x32_bf16 v[20:23], v[152:155], v[188:191], v[20:23]
	v_mfma_f32_16x16x32_bf16 v[16:19], v[160:163], v[188:191], v[16:19]
	v_mfma_f32_16x16x32_bf16 v[44:47], v[156:159], v[92:95], v[44:47]
	v_mfma_f32_16x16x32_bf16 v[40:43], v[148:151], v[92:95], v[40:43]
	v_mfma_f32_16x16x32_bf16 v[36:39], v[156:159], v[176:179], v[36:39]
	v_mfma_f32_16x16x32_bf16 v[32:35], v[148:151], v[176:179], v[32:35]
	v_mfma_f32_16x16x32_bf16 v[28:31], v[156:159], v[184:187], v[28:31]
	v_mfma_f32_16x16x32_bf16 v[24:27], v[148:151], v[184:187], v[24:27]
	v_mfma_f32_16x16x32_bf16 v[20:23], v[156:159], v[192:195], v[20:23]
	v_mfma_f32_16x16x32_bf16 v[16:19], v[148:151], v[192:195], v[16:19]
	v_mfma_f32_16x16x32_bf16 v[4:7], v[196:199], v[172:175], v[4:7]
	v_mfma_f32_16x16x32_bf16 v[0:3], v[142:145], v[172:175], v[0:3]
	v_mfma_f32_16x16x32_bf16 v[12:15], v[196:199], v[68:71], v[12:15]
	v_mfma_f32_16x16x32_bf16 v[8:11], v[142:145], v[68:71], v[8:11]
	v_mfma_f32_16x16x32_bf16 v[64:67], v[196:199], v[180:183], v[64:67]
	v_mfma_f32_16x16x32_bf16 v[68:71], v[142:145], v[180:183], v[72:75]
	v_mfma_f32_16x16x32_bf16 v[72:75], v[196:199], v[188:191], v[76:79]
	v_mfma_f32_16x16x32_bf16 v[76:79], v[142:145], v[188:191], v[84:87]
	v_mfma_f32_16x16x32_bf16 v[4:7], v[200:203], v[176:179], v[4:7]
	v_mfma_f32_16x16x32_bf16 v[0:3], v[204:207], v[176:179], v[0:3]
	v_mfma_f32_16x16x32_bf16 v[142:145], v[200:203], v[92:95], v[12:15]
	v_mfma_f32_16x16x32_bf16 v[146:149], v[204:207], v[92:95], v[8:11]
	v_mfma_f32_16x16x32_bf16 v[150:153], v[200:203], v[184:187], v[64:67]
	v_mfma_f32_16x16x32_bf16 v[154:157], v[204:207], v[184:187], v[68:71]
	v_mfma_f32_16x16x32_bf16 v[158:161], v[200:203], v[192:195], v[72:75]
	v_mfma_f32_16x16x32_bf16 v[172:175], v[204:207], v[192:195], v[76:79]
	s_barrier
	ds_read_b128 v[8:11], v137
	ds_read_b128 v[12:15], v138
	ds_read_b128 v[176:179], v139
	ds_read_b128 v[138:141], v140
	ds_read_b128 v[64:67], v129 offset:32768
	ds_read_b128 v[72:75], v129 offset:33792
	ds_read_b128 v[180:183], v132 offset:32768
	ds_read_b128 v[184:187], v132 offset:33792
	ds_read_b128 v[188:191], v131 offset:32768
	ds_read_b128 v[192:195], v131 offset:33792
	ds_read_b128 v[196:199], v130 offset:32768
	ds_read_b128 v[200:203], v130 offset:33792
	s_waitcnt vmcnt(2)
	s_barrier
	s_waitcnt lgkmcnt(0)
	v_mfma_f32_16x16x32_bf16 v[68:71], v[8:11], v[64:67], v[124:127]
	v_mfma_f32_16x16x32_bf16 v[76:79], v[176:179], v[64:67], v[120:123]
	v_mfma_f32_16x16x32_bf16 v[84:87], v[8:11], v[180:183], v[116:119]
	v_mfma_f32_16x16x32_bf16 v[92:95], v[176:179], v[180:183], v[112:115]
	v_mfma_f32_16x16x32_bf16 v[112:115], v[8:11], v[188:191], v[108:111]
	v_mfma_f32_16x16x32_bf16 v[104:107], v[176:179], v[188:191], v[104:107]
	v_mfma_f32_16x16x32_bf16 v[120:123], v[8:11], v[196:199], v[100:103]
	v_mfma_f32_16x16x32_bf16 v[96:99], v[176:179], v[196:199], v[96:99]
	v_mfma_f32_16x16x32_bf16 v[124:127], v[12:15], v[72:75], v[68:71]
	v_mfma_f32_16x16x32_bf16 v[116:119], v[138:141], v[72:75], v[76:79]
	v_mfma_f32_16x16x32_bf16 v[108:111], v[12:15], v[184:187], v[84:87]
	v_mfma_f32_16x16x32_bf16 v[100:103], v[138:141], v[184:187], v[92:95]
	v_mfma_f32_16x16x32_bf16 v[92:95], v[12:15], v[192:195], v[112:115]
	v_mfma_f32_16x16x32_bf16 v[84:87], v[138:141], v[192:195], v[104:107]
	v_mfma_f32_16x16x32_bf16 v[76:79], v[12:15], v[200:203], v[120:123]
	v_mfma_f32_16x16x32_bf16 v[68:71], v[138:141], v[200:203], v[96:99]
	s_barrier
; #define LDA(dst, b, h) _Pragma("unroll") for (int m = 0; m < 4; ++m) _Pragma("unroll") for (int k = 0; k < 2; ++k) \
;     dst[m][k] = *reinterpret_cast<const bf16x8*>(SA(b, h) + lds_byte(wr * 64 + m * 16 + fr, k * 32 + fq * 8))
; #define LDB(dst, b, h) _Pragma("unroll") for (int n = 0; n < 2; ++n) _Pragma("unroll") for (int k = 0; k < 2; ++k) \
;     dst[n][k] = *reinterpret_cast<const bf16x8*>(SB(b, h) + lds_byte(wc * 32 + n * 16 + fr, k * 32 + fq * 8))
; #define WAIT_V(n) asm volatile("s_waitcnt vmcnt(" #n ")" ::: "memory")
; #define WAIT_L(n) asm volatile("s_waitcnt lgkmcnt(" #n ")" ::: "memory")
; #define BAR __builtin_amdgcn_s_barrier()
;     ...
;       LDB(B1, 1, 1); WAIT_V(0); BAR; WAIT_L(0); MMA(0, 1, At, B1); BAR;
;       LDA(At, 1, 1); BAR; WAIT_L(0); MMA(1, 0, At, B0); MMA(1, 1, At, B1); BAR; }
;     if (wr == 0) BAR;
	ds_read_b128 v[204:207], v133
	ds_read_b128 v[208:211], v134
	ds_read_b128 v[212:215], v135
	ds_read_b128 v[134:137], v136
	s_waitcnt vmcnt(0)
	s_barrier
	s_waitcnt lgkmcnt(0)
	v_mfma_f32_16x16x32_bf16 v[96:99], v[204:207], v[64:67], v[164:167]
	v_mfma_f32_16x16x32_bf16 v[64:67], v[212:215], v[64:67], v[88:91]
	v_mfma_f32_16x16x32_bf16 v[80:83], v[204:207], v[180:183], v[80:83]
	v_mfma_f32_16x16x32_bf16 v[88:91], v[212:215], v[180:183], v[168:171]
	v_mfma_f32_16x16x32_bf16 v[60:63], v[204:207], v[188:191], v[60:63]
	v_mfma_f32_16x16x32_bf16 v[56:59], v[212:215], v[188:191], v[56:59]
	v_mfma_f32_16x16x32_bf16 v[52:55], v[204:207], v[196:199], v[52:55]
	v_mfma_f32_16x16x32_bf16 v[48:51], v[212:215], v[196:199], v[48:51]
	v_mfma_f32_16x16x32_bf16 v[120:123], v[208:211], v[72:75], v[96:99]
	v_mfma_f32_16x16x32_bf16 v[112:115], v[134:137], v[72:75], v[64:67]
	v_mfma_f32_16x16x32_bf16 v[104:107], v[208:211], v[184:187], v[80:83]
	v_mfma_f32_16x16x32_bf16 v[96:99], v[134:137], v[184:187], v[88:91]
	v_mfma_f32_16x16x32_bf16 v[88:91], v[208:211], v[192:195], v[60:63]
	v_mfma_f32_16x16x32_bf16 v[80:83], v[134:137], v[192:195], v[56:59]
	v_mfma_f32_16x16x32_bf16 v[72:75], v[208:211], v[200:203], v[52:55]
	v_mfma_f32_16x16x32_bf16 v[64:67], v[134:137], v[200:203], v[48:51]
	s_barrier
	s_nop 0
	ds_read_b128 v[48:51], v129 offset:49152
	ds_read_b128 v[162:165], v129 offset:50176
	ds_read_b128 v[52:55], v132 offset:49152
	ds_read_b128 v[166:169], v132 offset:50176
	ds_read_b128 v[180:183], v131 offset:49152
	ds_read_b128 v[184:187], v131 offset:50176
	ds_read_b128 v[188:191], v130 offset:49152
	ds_read_b128 v[130:133], v130 offset:50176
	s_barrier
	s_waitcnt lgkmcnt(0)
	v_mfma_f32_16x16x32_bf16 v[44:47], v[8:11], v[48:51], v[44:47]
	v_mfma_f32_16x16x32_bf16 v[40:43], v[176:179], v[48:51], v[40:43]
	v_mfma_f32_16x16x32_bf16 v[36:39], v[8:11], v[52:55], v[36:39]
	v_mfma_f32_16x16x32_bf16 v[32:35], v[176:179], v[52:55], v[32:35]
	v_mfma_f32_16x16x32_bf16 v[28:31], v[8:11], v[180:183], v[28:31]
	v_mfma_f32_16x16x32_bf16 v[24:27], v[176:179], v[180:183], v[24:27]
	v_mfma_f32_16x16x32_bf16 v[8:11], v[8:11], v[188:191], v[20:23]
	v_mfma_f32_16x16x32_bf16 v[16:19], v[176:179], v[188:191], v[16:19]
	v_mfma_f32_16x16x32_bf16 v[60:63], v[12:15], v[162:165], v[44:47]
	v_mfma_f32_16x16x32_bf16 v[56:59], v[138:141], v[162:165], v[40:43]
	v_mfma_f32_16x16x32_bf16 v[44:47], v[12:15], v[166:169], v[36:39]
	v_mfma_f32_16x16x32_bf16 v[40:43], v[138:141], v[166:169], v[32:35]
	v_mfma_f32_16x16x32_bf16 v[28:31], v[12:15], v[184:187], v[28:31]
	v_mfma_f32_16x16x32_bf16 v[24:27], v[138:141], v[184:187], v[24:27]
	v_mfma_f32_16x16x32_bf16 v[12:15], v[12:15], v[130:133], v[8:11]
	v_mfma_f32_16x16x32_bf16 v[8:11], v[138:141], v[130:133], v[16:19]
	v_mfma_f32_16x16x32_bf16 v[16:19], v[204:207], v[48:51], v[142:145]
	v_mfma_f32_16x16x32_bf16 v[20:23], v[212:215], v[48:51], v[146:149]
	v_mfma_f32_16x16x32_bf16 v[4:7], v[204:207], v[52:55], v[4:7]
	v_mfma_f32_16x16x32_bf16 v[0:3], v[212:215], v[52:55], v[0:3]
	v_mfma_f32_16x16x32_bf16 v[138:141], v[204:207], v[180:183], v[150:153]
	v_mfma_f32_16x16x32_bf16 v[142:145], v[212:215], v[180:183], v[154:157]
	v_mfma_f32_16x16x32_bf16 v[146:149], v[204:207], v[188:191], v[158:161]
	v_mfma_f32_16x16x32_bf16 v[150:153], v[212:215], v[188:191], v[172:175]
	v_mfma_f32_16x16x32_bf16 v[52:55], v[208:211], v[162:165], v[16:19]
	v_mfma_f32_16x16x32_bf16 v[48:51], v[134:137], v[162:165], v[20:23]
	v_mfma_f32_16x16x32_bf16 v[36:39], v[208:211], v[166:169], v[4:7]
	v_mfma_f32_16x16x32_bf16 v[32:35], v[134:137], v[166:169], v[0:3]
	v_mfma_f32_16x16x32_bf16 v[20:23], v[208:211], v[184:187], v[138:141]
	v_mfma_f32_16x16x32_bf16 v[16:19], v[134:137], v[184:187], v[142:145]
	v_mfma_f32_16x16x32_bf16 v[4:7], v[208:211], v[130:133], v[146:149]
	v_mfma_f32_16x16x32_bf16 v[0:3], v[134:137], v[130:133], v[150:153]
	v_cmp_gt_u32_e32 vcc, s46, v128
	s_barrier
	s_and_saveexec_b64 s[6:7], vcc
	s_cbranch_execz .LBB0_294
	s_barrier

; #define STAGE(P, RS, SOFF, OFF, kt) do { const int _so = (SOFF) + (kt) * (BK * 2); \
;     _Pragma("unroll") for (int _i = 0; _i < 2; ++_i) { \
;       __builtin_amdgcn_raw_ptr_buffer_load_lds(RS, (__attribute__((address_space(3))) void*)((P) + wave * 1024 + _i * 8192), 16, OFF[_i], _so, 0, 0); } } while (0)
; #define LDA(dst, b, h) _Pragma("unroll") for (int m = 0; m < 4; ++m) _Pragma("unroll") for (int k = 0; k < 2; ++k) \
;     dst[m][k] = *reinterpret_cast<const bf16x8*>(SA(b, h) + lds_byte(wr * 64 + m * 16 + fr, k * 32 + fq * 8))
; #define LDB(dst, b, h) _Pragma("unroll") for (int n = 0; n < 2; ++n) _Pragma("unroll") for (int k = 0; k < 2; ++k) \
;     dst[n][k] = *reinterpret_cast<const bf16x8*>(SB(b, h) + lds_byte(wc * 32 + n * 16 + fr, k * 32 + fq * 8))
; #define WAIT_V(n) asm volatile("s_waitcnt vmcnt(" #n ")" ::: "memory")
; #define WAIT_L(n) asm volatile("s_waitcnt lgkmcnt(" #n ")" ::: "memory")
; #define BAR __builtin_amdgcn_s_barrier()
; #define SCHED __builtin_amdgcn_sched_barrier(0)
;     ...
;       LDB(B0, 0, 0); SCHED; LDA(At, 0, 0); STAGE(SA(1, 1), rsA, sA1, offA, t + 1);
;       WAIT_L(8); BAR; WAIT_L(0); MMA(0, 0, At, B0); BAR; SCHED;
;       LDB(B1, 0, 1); STAGE(SB(0, 0), rsB, sB0, offB, t + 2);
;       BAR; WAIT_L(0); MMA(0, 1, At, B1); BAR;
;       LDA(At, 0, 1); STAGE(SA(0, 0), rsA, sA0, offA, t + 2);
;       BAR; WAIT_L(0); MMA(1, 0, At, B0); BAR; SCHED;
;       STAGE(SB(0, 1), rsB, sB1, offB, t + 2);
;       WAIT_V(6); BAR; MMA(1, 1, At, B1); BAR;
.LBB0_354:
	ds_read_b128 v[154:157], v149
	ds_read_b128 v[158:161], v150
	ds_read_b128 v[162:165], v151
	ds_read_b128 v[166:169], v152
	s_add_i32 s43, s37, s17
	s_add_i32 s10, s43, 0x80
	s_mov_b32 m0, s30
	ds_read_b128 v[170:173], v131
	ds_read_b128 v[174:177], v131 offset:1024
	ds_read_b128 v[178:181], v134
	ds_read_b128 v[182:185], v134 offset:1024
	ds_read_b128 v[186:189], v133
	ds_read_b128 v[190:193], v133 offset:1024
	ds_read_b128 v[194:197], v132
	ds_read_b128 v[198:201], v132 offset:1024
	buffer_load_dwordx4 v143, s[4:7], s10 offen lds
	s_mov_b32 m0, s31
	s_nop 0
	buffer_load_dwordx4 v144, s[4:7], s10 offen lds
	s_waitcnt lgkmcnt(8)
	s_barrier
	s_waitcnt lgkmcnt(0)
	v_mfma_f32_16x16x32_bf16 v[124:127], v[154:157], v[170:173], v[124:127]
	v_mfma_f32_16x16x32_bf16 v[120:123], v[162:165], v[170:173], v[120:123]
	v_mfma_f32_16x16x32_bf16 v[116:119], v[154:157], v[178:181], v[116:119]
	v_mfma_f32_16x16x32_bf16 v[112:115], v[162:165], v[178:181], v[112:115]
	v_mfma_f32_16x16x32_bf16 v[108:111], v[154:157], v[186:189], v[108:111]
	v_mfma_f32_16x16x32_bf16 v[104:107], v[162:165], v[186:189], v[104:107]
	v_mfma_f32_16x16x32_bf16 v[100:103], v[154:157], v[194:197], v[100:103]
	v_mfma_f32_16x16x32_bf16 v[96:99], v[162:165], v[194:197], v[96:99]
	v_mfma_f32_16x16x32_bf16 v[124:127], v[158:161], v[174:177], v[124:127]
	v_mfma_f32_16x16x32_bf16 v[120:123], v[166:169], v[174:177], v[120:123]
	v_mfma_f32_16x16x32_bf16 v[116:119], v[158:161], v[182:185], v[116:119]
	v_mfma_f32_16x16x32_bf16 v[112:115], v[166:169], v[182:185], v[112:115]
	v_mfma_f32_16x16x32_bf16 v[108:111], v[158:161], v[190:193], v[108:111]
	v_mfma_f32_16x16x32_bf16 v[104:107], v[166:169], v[190:193], v[104:107]
	v_mfma_f32_16x16x32_bf16 v[100:103], v[158:161], v[198:201], v[100:103]
	v_mfma_f32_16x16x32_bf16 v[96:99], v[166:169], v[198:201], v[96:99]
	s_barrier
	s_add_i32 s44, s39, s17
	s_add_i32 s45, s44, 0x100
	s_mov_b32 s10, s6
	s_mov_b32 s11, s7
	s_mov_b32 m0, s1
	ds_read_b128 v[202:205], v145
	ds_read_b128 v[206:209], v146
	ds_read_b128 v[210:213], v147
	ds_read_b128 v[214:217], v148
	buffer_load_dwordx4 v143, s[8:11], s45 offen lds
	s_mov_b32 m0, s3
	s_nop 0
	buffer_load_dwordx4 v144, s[8:11], s45 offen lds
	s_barrier
	s_waitcnt lgkmcnt(0)
	v_mfma_f32_16x16x32_bf16 v[92:95], v[202:205], v[170:173], v[92:95]
	v_mfma_f32_16x16x32_bf16 v[88:91], v[210:213], v[170:173], v[88:91]
	v_mfma_f32_16x16x32_bf16 v[84:87], v[202:205], v[178:181], v[84:87]
	v_mfma_f32_16x16x32_bf16 v[80:83], v[210:213], v[178:181], v[80:83]
	v_mfma_f32_16x16x32_bf16 v[76:79], v[202:205], v[186:189], v[76:79]
	v_mfma_f32_16x16x32_bf16 v[72:75], v[210:213], v[186:189], v[72:75]
	v_mfma_f32_16x16x32_bf16 v[68:71], v[202:205], v[194:197], v[68:71]
	v_mfma_f32_16x16x32_bf16 v[64:67], v[210:213], v[194:197], v[64:67]
	v_mfma_f32_16x16x32_bf16 v[92:95], v[206:209], v[174:177], v[92:95]
	v_mfma_f32_16x16x32_bf16 v[88:91], v[214:217], v[174:177], v[88:91]
	v_mfma_f32_16x16x32_bf16 v[84:87], v[206:209], v[182:185], v[84:87]
	v_mfma_f32_16x16x32_bf16 v[80:83], v[214:217], v[182:185], v[80:83]
	v_mfma_f32_16x16x32_bf16 v[76:79], v[206:209], v[190:193], v[76:79]
	v_mfma_f32_16x16x32_bf16 v[72:75], v[214:217], v[190:193], v[72:75]
	v_mfma_f32_16x16x32_bf16 v[68:71], v[206:209], v[198:201], v[68:71]
	v_mfma_f32_16x16x32_bf16 v[64:67], v[214:217], v[198:201], v[64:67]
	s_barrier
	s_add_i32 s45, s38, s17
	s_add_i32 s46, s45, 0x100
	s_mov_b32 m0, s0
	ds_read_b128 v[170:173], v131 offset:16384
	ds_read_b128 v[174:177], v131 offset:17408
	ds_read_b128 v[178:181], v134 offset:16384
	ds_read_b128 v[182:185], v134 offset:17408
	ds_read_b128 v[186:189], v133 offset:16384
	ds_read_b128 v[190:193], v133 offset:17408
	ds_read_b128 v[194:197], v132 offset:16384
	ds_read_b128 v[198:201], v132 offset:17408
	buffer_load_dwordx4 v143, s[4:7], s46 offen lds
	s_mov_b32 m0, s18
	s_nop 0
	buffer_load_dwordx4 v144, s[4:7], s46 offen lds
	s_barrier
	s_waitcnt lgkmcnt(0)
	v_mfma_f32_16x16x32_bf16 v[60:63], v[154:157], v[170:173], v[60:63]
	v_mfma_f32_16x16x32_bf16 v[56:59], v[162:165], v[170:173], v[56:59]
	v_mfma_f32_16x16x32_bf16 v[52:55], v[154:157], v[178:181], v[52:55]
	v_mfma_f32_16x16x32_bf16 v[48:51], v[162:165], v[178:181], v[48:51]
	v_mfma_f32_16x16x32_bf16 v[44:47], v[154:157], v[186:189], v[44:47]
	v_mfma_f32_16x16x32_bf16 v[40:43], v[162:165], v[186:189], v[40:43]
	v_mfma_f32_16x16x32_bf16 v[36:39], v[154:157], v[194:197], v[36:39]
	v_mfma_f32_16x16x32_bf16 v[32:35], v[162:165], v[194:197], v[32:35]
	v_mfma_f32_16x16x32_bf16 v[60:63], v[158:161], v[174:177], v[60:63]
	v_mfma_f32_16x16x32_bf16 v[56:59], v[166:169], v[174:177], v[56:59]
	v_mfma_f32_16x16x32_bf16 v[52:55], v[158:161], v[182:185], v[52:55]
	v_mfma_f32_16x16x32_bf16 v[48:51], v[166:169], v[182:185], v[48:51]
	v_mfma_f32_16x16x32_bf16 v[44:47], v[158:161], v[190:193], v[44:47]
	v_mfma_f32_16x16x32_bf16 v[40:43], v[166:169], v[190:193], v[40:43]
	v_mfma_f32_16x16x32_bf16 v[36:39], v[158:161], v[198:201], v[36:39]
	v_mfma_f32_16x16x32_bf16 v[32:35], v[166:169], v[198:201], v[32:35]
	s_barrier
	s_add_i32 s46, s40, s17
	s_add_i32 s47, s46, 0x100
	s_mov_b32 m0, s19
	s_nop 0
	buffer_load_dwordx4 v143, s[8:11], s47 offen lds
	s_mov_b32 m0, s20
	s_nop 0
	buffer_load_dwordx4 v144, s[8:11], s47 offen lds
	s_waitcnt vmcnt(6)
	s_barrier
; #define STAGE(P, RS, SOFF, OFF, kt) do { const int _so = (SOFF) + (kt) * (BK * 2); \
;     _Pragma("unroll") for (int _i = 0; _i < 2; ++_i) { \
;       __builtin_amdgcn_raw_ptr_buffer_load_lds(RS, (__attribute__((address_space(3))) void*)((P) + wave * 1024 + _i * 8192), 16, OFF[_i], _so, 0, 0); } } while (0)
; #define LDA(dst, b, h) _Pragma("unroll") for (int m = 0; m < 4; ++m) _Pragma("unroll") for (int k = 0; k < 2; ++k) \
;     dst[m][k] = *reinterpret_cast<const bf16x8*>(SA(b, h) + lds_byte(wr * 64 + m * 16 + fr, k * 32 + fq * 8))
; #define LDB(dst, b, h) _Pragma("unroll") for (int n = 0; n < 2; ++n) _Pragma("unroll") for (int k = 0; k < 2; ++k) \
;     dst[n][k] = *reinterpret_cast<const bf16x8*>(SB(b, h) + lds_byte(wc * 32 + n * 16 + fr, k * 32 + fq * 8))
; #define WAIT_V(n) asm volatile("s_waitcnt vmcnt(" #n ")" ::: "memory")
; #define WAIT_L(n) asm volatile("s_waitcnt lgkmcnt(" #n ")" ::: "memory")
; #define BAR __builtin_amdgcn_s_barrier()
; #define SCHED __builtin_amdgcn_sched_barrier(0)
;     ...
;       WAIT_V(6); BAR; MMA(1, 1, At, B1); BAR;
;       LDB(B0, 1, 0); SCHED; LDA(At, 1, 0); STAGE(SA(0, 1), rsA, sA1, offA, t + 2);
;       WAIT_L(8); BAR; WAIT_L(0); MMA(0, 0, At, B0); BAR; SCHED;
;       LDB(B1, 1, 1); STAGE(SB(1, 0), rsB, sB0, offB, t + 3);
;       BAR; WAIT_L(0); MMA(0, 1, At, B1); BAR;
;       LDA(At, 1, 1); STAGE(SA(1, 0), rsA, sA0, offA, t + 3);
;       BAR; WAIT_L(0); MMA(1, 0, At, B0); BAR; SCHED;
;       STAGE(SB(1, 1), rsB, sB1, offB, t + 3);
;       WAIT_V(6); BAR; MMA(1, 1, At, B1); BAR;
	v_mfma_f32_16x16x32_bf16 v[28:31], v[202:205], v[170:173], v[28:31]
	v_mfma_f32_16x16x32_bf16 v[24:27], v[210:213], v[170:173], v[24:27]
	v_mfma_f32_16x16x32_bf16 v[20:23], v[202:205], v[178:181], v[20:23]
	v_mfma_f32_16x16x32_bf16 v[16:19], v[210:213], v[178:181], v[16:19]
	v_mfma_f32_16x16x32_bf16 v[12:15], v[202:205], v[186:189], v[12:15]
	v_mfma_f32_16x16x32_bf16 v[8:11], v[210:213], v[186:189], v[8:11]
	v_mfma_f32_16x16x32_bf16 v[4:7], v[202:205], v[194:197], v[4:7]
	v_mfma_f32_16x16x32_bf16 v[0:3], v[210:213], v[194:197], v[0:3]
	v_mfma_f32_16x16x32_bf16 v[28:31], v[206:209], v[174:177], v[28:31]
	v_mfma_f32_16x16x32_bf16 v[24:27], v[214:217], v[174:177], v[24:27]
	v_mfma_f32_16x16x32_bf16 v[20:23], v[206:209], v[182:185], v[20:23]
	v_mfma_f32_16x16x32_bf16 v[16:19], v[214:217], v[182:185], v[16:19]
	v_mfma_f32_16x16x32_bf16 v[12:15], v[206:209], v[190:193], v[12:15]
	v_mfma_f32_16x16x32_bf16 v[8:11], v[214:217], v[190:193], v[8:11]
	v_mfma_f32_16x16x32_bf16 v[4:7], v[206:209], v[198:201], v[4:7]
	v_mfma_f32_16x16x32_bf16 v[0:3], v[214:217], v[198:201], v[0:3]
	s_barrier
	ds_read_b128 v[154:157], v139
	ds_read_b128 v[158:161], v140
	ds_read_b128 v[162:165], v141
	ds_read_b128 v[166:169], v142
	s_addk_i32 s43, 0x100
	s_mov_b32 m0, s21
	ds_read_b128 v[170:173], v131 offset:32768
	ds_read_b128 v[174:177], v131 offset:33792
	ds_read_b128 v[178:181], v134 offset:32768
	ds_read_b128 v[182:185], v134 offset:33792
	ds_read_b128 v[186:189], v133 offset:32768
	ds_read_b128 v[190:193], v133 offset:33792
	ds_read_b128 v[194:197], v132 offset:32768
	ds_read_b128 v[198:201], v132 offset:33792
	buffer_load_dwordx4 v143, s[4:7], s43 offen lds
	s_mov_b32 m0, s22
	s_nop 0
	buffer_load_dwordx4 v144, s[4:7], s43 offen lds
	s_waitcnt lgkmcnt(8)
	s_barrier
	s_waitcnt lgkmcnt(0)
	v_mfma_f32_16x16x32_bf16 v[124:127], v[154:157], v[170:173], v[124:127]
	v_mfma_f32_16x16x32_bf16 v[120:123], v[162:165], v[170:173], v[120:123]
	v_mfma_f32_16x16x32_bf16 v[116:119], v[154:157], v[178:181], v[116:119]
	v_mfma_f32_16x16x32_bf16 v[112:115], v[162:165], v[178:181], v[112:115]
	v_mfma_f32_16x16x32_bf16 v[108:111], v[154:157], v[186:189], v[108:111]
	v_mfma_f32_16x16x32_bf16 v[104:107], v[162:165], v[186:189], v[104:107]
	v_mfma_f32_16x16x32_bf16 v[100:103], v[154:157], v[194:197], v[100:103]
	v_mfma_f32_16x16x32_bf16 v[96:99], v[162:165], v[194:197], v[96:99]
	v_mfma_f32_16x16x32_bf16 v[124:127], v[158:161], v[174:177], v[124:127]
	v_mfma_f32_16x16x32_bf16 v[120:123], v[166:169], v[174:177], v[120:123]
	v_mfma_f32_16x16x32_bf16 v[116:119], v[158:161], v[182:185], v[116:119]
	v_mfma_f32_16x16x32_bf16 v[112:115], v[166:169], v[182:185], v[112:115]
	v_mfma_f32_16x16x32_bf16 v[108:111], v[158:161], v[190:193], v[108:111]
	v_mfma_f32_16x16x32_bf16 v[104:107], v[166:169], v[190:193], v[104:107]
	v_mfma_f32_16x16x32_bf16 v[100:103], v[158:161], v[198:201], v[100:103]
	v_mfma_f32_16x16x32_bf16 v[96:99], v[166:169], v[198:201], v[96:99]
	s_barrier
	s_addk_i32 s44, 0x180
	s_mov_b32 m0, s23
	ds_read_b128 v[202:205], v135
	ds_read_b128 v[206:209], v136
	ds_read_b128 v[210:213], v137
	ds_read_b128 v[214:217], v138
	buffer_load_dwordx4 v143, s[8:11], s44 offen lds
	s_mov_b32 m0, s24
	s_nop 0
	buffer_load_dwordx4 v144, s[8:11], s44 offen lds
	s_barrier
	s_waitcnt lgkmcnt(0)
	v_mfma_f32_16x16x32_bf16 v[92:95], v[202:205], v[170:173], v[92:95]
	v_mfma_f32_16x16x32_bf16 v[88:91], v[210:213], v[170:173], v[88:91]
	v_mfma_f32_16x16x32_bf16 v[84:87], v[202:205], v[178:181], v[84:87]
	v_mfma_f32_16x16x32_bf16 v[80:83], v[210:213], v[178:181], v[80:83]
	v_mfma_f32_16x16x32_bf16 v[76:79], v[202:205], v[186:189], v[76:79]
	v_mfma_f32_16x16x32_bf16 v[72:75], v[210:213], v[186:189], v[72:75]
	v_mfma_f32_16x16x32_bf16 v[68:71], v[202:205], v[194:197], v[68:71]
	v_mfma_f32_16x16x32_bf16 v[64:67], v[210:213], v[194:197], v[64:67]
	v_mfma_f32_16x16x32_bf16 v[92:95], v[206:209], v[174:177], v[92:95]
	v_mfma_f32_16x16x32_bf16 v[88:91], v[214:217], v[174:177], v[88:91]
	v_mfma_f32_16x16x32_bf16 v[84:87], v[206:209], v[182:185], v[84:87]
	v_mfma_f32_16x16x32_bf16 v[80:83], v[214:217], v[182:185], v[80:83]
	v_mfma_f32_16x16x32_bf16 v[76:79], v[206:209], v[190:193], v[76:79]
	v_mfma_f32_16x16x32_bf16 v[72:75], v[214:217], v[190:193], v[72:75]
	v_mfma_f32_16x16x32_bf16 v[68:71], v[206:209], v[198:201], v[68:71]
	v_mfma_f32_16x16x32_bf16 v[64:67], v[214:217], v[198:201], v[64:67]
	s_barrier
	s_addk_i32 s45, 0x180
	s_mov_b32 m0, s25
	ds_read_b128 v[170:173], v131 offset:49152
	ds_read_b128 v[174:177], v131 offset:50176
	ds_read_b128 v[178:181], v134 offset:49152
	ds_read_b128 v[182:185], v134 offset:50176
	ds_read_b128 v[186:189], v133 offset:49152
	ds_read_b128 v[190:193], v133 offset:50176
	ds_read_b128 v[194:197], v132 offset:49152
	ds_read_b128 v[198:201], v132 offset:50176
	buffer_load_dwordx4 v143, s[4:7], s45 offen lds
	s_mov_b32 m0, s26
	s_nop 0
	buffer_load_dwordx4 v144, s[4:7], s45 offen lds
	s_barrier
	s_waitcnt lgkmcnt(0)
	v_mfma_f32_16x16x32_bf16 v[60:63], v[154:157], v[170:173], v[60:63]
	v_mfma_f32_16x16x32_bf16 v[56:59], v[162:165], v[170:173], v[56:59]
	v_mfma_f32_16x16x32_bf16 v[52:55], v[154:157], v[178:181], v[52:55]
	v_mfma_f32_16x16x32_bf16 v[48:51], v[162:165], v[178:181], v[48:51]
	v_mfma_f32_16x16x32_bf16 v[44:47], v[154:157], v[186:189], v[44:47]
	v_mfma_f32_16x16x32_bf16 v[40:43], v[162:165], v[186:189], v[40:43]
	v_mfma_f32_16x16x32_bf16 v[36:39], v[154:157], v[194:197], v[36:39]
	v_mfma_f32_16x16x32_bf16 v[32:35], v[162:165], v[194:197], v[32:35]
	v_mfma_f32_16x16x32_bf16 v[60:63], v[158:161], v[174:177], v[60:63]
	v_mfma_f32_16x16x32_bf16 v[56:59], v[166:169], v[174:177], v[56:59]
	v_mfma_f32_16x16x32_bf16 v[52:55], v[158:161], v[182:185], v[52:55]
	v_mfma_f32_16x16x32_bf16 v[48:51], v[166:169], v[182:185], v[48:51]
	v_mfma_f32_16x16x32_bf16 v[44:47], v[158:161], v[190:193], v[44:47]
	v_mfma_f32_16x16x32_bf16 v[40:43], v[166:169], v[190:193], v[40:43]
	v_mfma_f32_16x16x32_bf16 v[36:39], v[158:161], v[198:201], v[36:39]
	v_mfma_f32_16x16x32_bf16 v[32:35], v[166:169], v[198:201], v[32:35]
	s_barrier
; #define STAGE(P, RS, SOFF, OFF, kt) do { const int _so = (SOFF) + (kt) * (BK * 2); \
;     _Pragma("unroll") for (int _i = 0; _i < 2; ++_i) { \
;       __builtin_amdgcn_raw_ptr_buffer_load_lds(RS, (__attribute__((address_space(3))) void*)((P) + wave * 1024 + _i * 8192), 16, OFF[_i], _so, 0, 0); } } while (0)
; #define LDA(dst, b, h) _Pragma("unroll") for (int m = 0; m < 4; ++m) _Pragma("unroll") for (int k = 0; k < 2; ++k) \
;     dst[m][k] = *reinterpret_cast<const bf16x8*>(SA(b, h) + lds_byte(wr * 64 + m * 16 + fr, k * 32 + fq * 8))
; #define LDB(dst, b, h) _Pragma("unroll") for (int n = 0; n < 2; ++n) _Pragma("unroll") for (int k = 0; k < 2; ++k) \
;     dst[n][k] = *reinterpret_cast<const bf16x8*>(SB(b, h) + lds_byte(wc * 32 + n * 16 + fr, k * 32 + fq * 8))
; #define WAIT_V(n) asm volatile("s_waitcnt vmcnt(" #n ")" ::: "memory")
; #define WAIT_L(n) asm volatile("s_waitcnt lgkmcnt(" #n ")" ::: "memory")
; #define BAR __builtin_amdgcn_s_barrier()
;     ...
;       WAIT_V(6); BAR; MMA(1, 1, At, B1); BAR;
;     }
;     { LDB(B0, 0, 0); LDA(At, 0, 0); STAGE(SA(1, 1), rsA, sA1, offA, nt - 1);
;       BAR; WAIT_L(0); MMA(0, 0, At, B0); BAR;
;       LDB(B1, 0, 1); BAR; WAIT_L(0); MMA(0, 1, At, B1); BAR;
;       LDA(At, 0, 1); WAIT_V(4); BAR; WAIT_L(0); MMA(1, 0, At, B0); MMA(1, 1, At, B1); BAR; }
	s_addk_i32 s46, 0x180
	s_mov_b32 m0, s27
	s_nop 0
	buffer_load_dwordx4 v143, s[8:11], s46 offen lds
	s_mov_b32 m0, s28
	s_nop 0
	buffer_load_dwordx4 v144, s[8:11], s46 offen lds
	s_waitcnt vmcnt(6)
	s_barrier
	v_mfma_f32_16x16x32_bf16 v[28:31], v[202:205], v[170:173], v[28:31]
	v_mfma_f32_16x16x32_bf16 v[24:27], v[210:213], v[170:173], v[24:27]
	v_mfma_f32_16x16x32_bf16 v[20:23], v[202:205], v[178:181], v[20:23]
	v_mfma_f32_16x16x32_bf16 v[16:19], v[210:213], v[178:181], v[16:19]
	v_mfma_f32_16x16x32_bf16 v[12:15], v[202:205], v[186:189], v[12:15]
	v_mfma_f32_16x16x32_bf16 v[8:11], v[210:213], v[186:189], v[8:11]
	v_mfma_f32_16x16x32_bf16 v[4:7], v[202:205], v[194:197], v[4:7]
	v_mfma_f32_16x16x32_bf16 v[0:3], v[210:213], v[194:197], v[0:3]
	v_mfma_f32_16x16x32_bf16 v[28:31], v[206:209], v[174:177], v[28:31]
	v_mfma_f32_16x16x32_bf16 v[24:27], v[214:217], v[174:177], v[24:27]
	v_mfma_f32_16x16x32_bf16 v[20:23], v[206:209], v[182:185], v[20:23]
	v_mfma_f32_16x16x32_bf16 v[16:19], v[214:217], v[182:185], v[16:19]
	v_mfma_f32_16x16x32_bf16 v[12:15], v[206:209], v[190:193], v[12:15]
	v_mfma_f32_16x16x32_bf16 v[8:11], v[214:217], v[190:193], v[8:11]
	v_mfma_f32_16x16x32_bf16 v[4:7], v[206:209], v[198:201], v[4:7]
	v_mfma_f32_16x16x32_bf16 v[0:3], v[214:217], v[198:201], v[0:3]
	s_barrier
	s_add_i32 s16, s16, 2
	s_addk_i32 s17, 0x100
	s_cmp_gt_u32 s16, 27
	s_cbranch_scc0 .LBB0_354
	s_add_i32 s10, s37, 0xf80
	s_mov_b32 m0, s30
	ds_read_b128 v[154:157], v149
	ds_read_b128 v[158:161], v150
	ds_read_b128 v[162:165], v151
	ds_read_b128 v[150:153], v152
	ds_read_b128 v[166:169], v131
	ds_read_b128 v[170:173], v131 offset:1024
	ds_read_b128 v[174:177], v134
	ds_read_b128 v[178:181], v134 offset:1024
	ds_read_b128 v[182:185], v133
	ds_read_b128 v[186:189], v133 offset:1024
	ds_read_b128 v[190:193], v132
	ds_read_b128 v[194:197], v132 offset:1024
	buffer_load_dwordx4 v143, s[4:7], s10 offen lds
	s_mov_b32 m0, s31
	s_nop 0
	buffer_load_dwordx4 v144, s[4:7], s10 offen lds
	s_barrier
	s_waitcnt lgkmcnt(0)
	v_mfma_f32_16x16x32_bf16 v[124:127], v[154:157], v[166:169], v[124:127]
	v_mfma_f32_16x16x32_bf16 v[120:123], v[162:165], v[166:169], v[120:123]
	v_mfma_f32_16x16x32_bf16 v[116:119], v[154:157], v[174:177], v[116:119]
	v_mfma_f32_16x16x32_bf16 v[112:115], v[162:165], v[174:177], v[112:115]
	v_mfma_f32_16x16x32_bf16 v[108:111], v[154:157], v[182:185], v[108:111]
	v_mfma_f32_16x16x32_bf16 v[104:107], v[162:165], v[182:185], v[104:107]
	v_mfma_f32_16x16x32_bf16 v[100:103], v[154:157], v[190:193], v[100:103]
	v_mfma_f32_16x16x32_bf16 v[96:99], v[162:165], v[190:193], v[96:99]
	v_mfma_f32_16x16x32_bf16 v[124:127], v[158:161], v[170:173], v[124:127]
	v_mfma_f32_16x16x32_bf16 v[120:123], v[150:153], v[170:173], v[120:123]
	v_mfma_f32_16x16x32_bf16 v[116:119], v[158:161], v[178:181], v[116:119]
	v_mfma_f32_16x16x32_bf16 v[112:115], v[150:153], v[178:181], v[112:115]
	v_mfma_f32_16x16x32_bf16 v[108:111], v[158:161], v[186:189], v[108:111]
	v_mfma_f32_16x16x32_bf16 v[104:107], v[150:153], v[186:189], v[104:107]
	v_mfma_f32_16x16x32_bf16 v[100:103], v[158:161], v[194:197], v[100:103]
	v_mfma_f32_16x16x32_bf16 v[96:99], v[150:153], v[194:197], v[96:99]
	s_barrier
	ds_read_b128 v[198:201], v145
	ds_read_b128 v[202:205], v146
	ds_read_b128 v[144:147], v147
	ds_read_b128 v[206:209], v148
	s_barrier
	s_waitcnt lgkmcnt(0)
	v_mfma_f32_16x16x32_bf16 v[92:95], v[198:201], v[166:169], v[92:95]
	v_mfma_f32_16x16x32_bf16 v[84:87], v[198:201], v[174:177], v[84:87]
	v_mfma_f32_16x16x32_bf16 v[76:79], v[198:201], v[182:185], v[76:79]
	v_mfma_f32_16x16x32_bf16 v[68:71], v[198:201], v[190:193], v[68:71]
	v_mfma_f32_16x16x32_bf16 v[88:91], v[144:147], v[166:169], v[88:91]
	v_mfma_f32_16x16x32_bf16 v[80:83], v[144:147], v[174:177], v[80:83]
	v_mfma_f32_16x16x32_bf16 v[72:75], v[144:147], v[182:185], v[72:75]
	v_mfma_f32_16x16x32_bf16 v[64:67], v[144:147], v[190:193], v[64:67]
	v_mfma_f32_16x16x32_bf16 v[92:95], v[202:205], v[170:173], v[92:95]
	v_mfma_f32_16x16x32_bf16 v[84:87], v[202:205], v[178:181], v[84:87]
	v_mfma_f32_16x16x32_bf16 v[76:79], v[202:205], v[186:189], v[76:79]
	v_mfma_f32_16x16x32_bf16 v[68:71], v[202:205], v[194:197], v[68:71]
	v_mfma_f32_16x16x32_bf16 v[166:169], v[206:209], v[170:173], v[88:91]
	v_mfma_f32_16x16x32_bf16 v[170:173], v[206:209], v[178:181], v[80:83]
	v_mfma_f32_16x16x32_bf16 v[174:177], v[206:209], v[186:189], v[72:75]
	v_mfma_f32_16x16x32_bf16 v[178:181], v[206:209], v[194:197], v[64:67]
	s_barrier
	s_nop 0
	ds_read_b128 v[64:67], v131 offset:16384
	ds_read_b128 v[72:75], v131 offset:17408
	ds_read_b128 v[80:83], v134 offset:16384
	ds_read_b128 v[88:91], v134 offset:17408
	ds_read_b128 v[182:185], v133 offset:16384
	ds_read_b128 v[186:189], v133 offset:17408
	ds_read_b128 v[190:193], v132 offset:16384
	ds_read_b128 v[194:197], v132 offset:17408
	s_waitcnt vmcnt(4)
	s_barrier
; #define LDA(dst, b, h) _Pragma("unroll") for (int m = 0; m < 4; ++m) _Pragma("unroll") for (int k = 0; k < 2; ++k) \
;     dst[m][k] = *reinterpret_cast<const bf16x8*>(SA(b, h) + lds_byte(wr * 64 + m * 16 + fr, k * 32 + fq * 8))
; #define LDB(dst, b, h) _Pragma("unroll") for (int n = 0; n < 2; ++n) _Pragma("unroll") for (int k = 0; k < 2; ++k) \
;     dst[n][k] = *reinterpret_cast<const bf16x8*>(SB(b, h) + lds_byte(wc * 32 + n * 16 + fr, k * 32 + fq * 8))
; #define WAIT_V(n) asm volatile("s_waitcnt vmcnt(" #n ")" ::: "memory")
; #define WAIT_L(n) asm volatile("s_waitcnt lgkmcnt(" #n ")" ::: "memory")
; #define BAR __builtin_amdgcn_s_barrier()
;     ...
;       LDA(At, 0, 1); WAIT_V(4); BAR; WAIT_L(0); MMA(1, 0, At, B0); MMA(1, 1, At, B1); BAR; }
;     { LDB(B0, 1, 0); LDA(At, 1, 0); WAIT_V(2); BAR; WAIT_L(0); MMA(0, 0, At, B0); BAR;
;       LDB(B1, 1, 1); WAIT_V(0); BAR; WAIT_L(0); MMA(0, 1, At, B1); BAR;
	s_waitcnt lgkmcnt(0)
	v_mfma_f32_16x16x32_bf16 v[60:63], v[154:157], v[64:67], v[60:63]
	v_mfma_f32_16x16x32_bf16 v[56:59], v[162:165], v[64:67], v[56:59]
	v_mfma_f32_16x16x32_bf16 v[52:55], v[154:157], v[80:83], v[52:55]
	v_mfma_f32_16x16x32_bf16 v[48:51], v[162:165], v[80:83], v[48:51]
	v_mfma_f32_16x16x32_bf16 v[44:47], v[154:157], v[182:185], v[44:47]
	v_mfma_f32_16x16x32_bf16 v[40:43], v[162:165], v[182:185], v[40:43]
	v_mfma_f32_16x16x32_bf16 v[36:39], v[154:157], v[190:193], v[36:39]
	v_mfma_f32_16x16x32_bf16 v[32:35], v[162:165], v[190:193], v[32:35]
	v_mfma_f32_16x16x32_bf16 v[60:63], v[158:161], v[72:75], v[60:63]
	v_mfma_f32_16x16x32_bf16 v[56:59], v[150:153], v[72:75], v[56:59]
	v_mfma_f32_16x16x32_bf16 v[52:55], v[158:161], v[88:91], v[52:55]
	v_mfma_f32_16x16x32_bf16 v[48:51], v[150:153], v[88:91], v[48:51]
	v_mfma_f32_16x16x32_bf16 v[44:47], v[158:161], v[186:189], v[44:47]
	v_mfma_f32_16x16x32_bf16 v[40:43], v[150:153], v[186:189], v[40:43]
	v_mfma_f32_16x16x32_bf16 v[36:39], v[158:161], v[194:197], v[36:39]
	v_mfma_f32_16x16x32_bf16 v[32:35], v[150:153], v[194:197], v[32:35]
	v_mfma_f32_16x16x32_bf16 v[28:31], v[198:201], v[64:67], v[28:31]
	v_mfma_f32_16x16x32_bf16 v[20:23], v[198:201], v[80:83], v[20:23]
	v_mfma_f32_16x16x32_bf16 v[12:15], v[198:201], v[182:185], v[12:15]
	v_mfma_f32_16x16x32_bf16 v[4:7], v[198:201], v[190:193], v[4:7]
	v_mfma_f32_16x16x32_bf16 v[24:27], v[144:147], v[64:67], v[24:27]
	v_mfma_f32_16x16x32_bf16 v[16:19], v[144:147], v[80:83], v[16:19]
	v_mfma_f32_16x16x32_bf16 v[8:11], v[144:147], v[182:185], v[8:11]
	v_mfma_f32_16x16x32_bf16 v[0:3], v[144:147], v[190:193], v[0:3]
	v_mfma_f32_16x16x32_bf16 v[28:31], v[202:205], v[72:75], v[28:31]
	v_mfma_f32_16x16x32_bf16 v[20:23], v[202:205], v[88:91], v[20:23]
	v_mfma_f32_16x16x32_bf16 v[12:15], v[202:205], v[186:189], v[12:15]
	v_mfma_f32_16x16x32_bf16 v[4:7], v[202:205], v[194:197], v[4:7]
	v_mfma_f32_16x16x32_bf16 v[144:147], v[206:209], v[72:75], v[24:27]
	v_mfma_f32_16x16x32_bf16 v[148:151], v[206:209], v[88:91], v[16:19]
	v_mfma_f32_16x16x32_bf16 v[152:155], v[206:209], v[186:189], v[8:11]
	v_mfma_f32_16x16x32_bf16 v[156:159], v[206:209], v[194:197], v[0:3]
	s_barrier
	s_nop 0
	ds_read_b128 v[0:3], v139
	ds_read_b128 v[8:11], v140
	ds_read_b128 v[16:19], v141
	ds_read_b128 v[140:143], v142
	ds_read_b128 v[24:27], v131 offset:32768
	ds_read_b128 v[160:163], v131 offset:33792
	ds_read_b128 v[182:185], v134 offset:32768
	ds_read_b128 v[186:189], v134 offset:33792
	ds_read_b128 v[190:193], v133 offset:32768
	ds_read_b128 v[194:197], v133 offset:33792
	ds_read_b128 v[198:201], v132 offset:32768
	ds_read_b128 v[202:205], v132 offset:33792
	s_waitcnt vmcnt(2)
	s_barrier
	s_waitcnt lgkmcnt(0)
	v_mfma_f32_16x16x32_bf16 v[64:67], v[0:3], v[24:27], v[124:127]
	v_mfma_f32_16x16x32_bf16 v[72:75], v[16:19], v[24:27], v[120:123]
	v_mfma_f32_16x16x32_bf16 v[80:83], v[0:3], v[182:185], v[116:119]
	v_mfma_f32_16x16x32_bf16 v[88:91], v[16:19], v[182:185], v[112:115]
	v_mfma_f32_16x16x32_bf16 v[108:111], v[0:3], v[190:193], v[108:111]
	v_mfma_f32_16x16x32_bf16 v[116:119], v[16:19], v[190:193], v[104:107]
	v_mfma_f32_16x16x32_bf16 v[100:103], v[0:3], v[198:201], v[100:103]
	v_mfma_f32_16x16x32_bf16 v[124:127], v[16:19], v[198:201], v[96:99]
	v_mfma_f32_16x16x32_bf16 v[120:123], v[8:11], v[160:163], v[64:67]
	v_mfma_f32_16x16x32_bf16 v[112:115], v[140:143], v[160:163], v[72:75]
	v_mfma_f32_16x16x32_bf16 v[104:107], v[8:11], v[186:189], v[80:83]
	v_mfma_f32_16x16x32_bf16 v[96:99], v[140:143], v[186:189], v[88:91]
	v_mfma_f32_16x16x32_bf16 v[88:91], v[8:11], v[194:197], v[108:111]
	v_mfma_f32_16x16x32_bf16 v[80:83], v[140:143], v[194:197], v[116:119]
	v_mfma_f32_16x16x32_bf16 v[72:75], v[8:11], v[202:205], v[100:103]
	v_mfma_f32_16x16x32_bf16 v[64:67], v[140:143], v[202:205], v[124:127]
	s_barrier
	ds_read_b128 v[206:209], v135
	ds_read_b128 v[210:213], v136
	ds_read_b128 v[214:217], v137
	ds_read_b128 v[136:139], v138
	s_waitcnt vmcnt(0)
	s_barrier
; #define LDA(dst, b, h) _Pragma("unroll") for (int m = 0; m < 4; ++m) _Pragma("unroll") for (int k = 0; k < 2; ++k) \
;     dst[m][k] = *reinterpret_cast<const bf16x8*>(SA(b, h) + lds_byte(wr * 64 + m * 16 + fr, k * 32 + fq * 8))
; #define LDB(dst, b, h) _Pragma("unroll") for (int n = 0; n < 2; ++n) _Pragma("unroll") for (int k = 0; k < 2; ++k) \
;     dst[n][k] = *reinterpret_cast<const bf16x8*>(SB(b, h) + lds_byte(wc * 32 + n * 16 + fr, k * 32 + fq * 8))
; #define WAIT_V(n) asm volatile("s_waitcnt vmcnt(" #n ")" ::: "memory")
; #define WAIT_L(n) asm volatile("s_waitcnt lgkmcnt(" #n ")" ::: "memory")
; #define BAR __builtin_amdgcn_s_barrier()
;     ...
;       LDB(B1, 1, 1); WAIT_V(0); BAR; WAIT_L(0); MMA(0, 1, At, B1); BAR;
;       LDA(At, 1, 1); BAR; WAIT_L(0); MMA(1, 0, At, B0); MMA(1, 1, At, B1); BAR; }
;     if (wr == 0) BAR;
	s_waitcnt lgkmcnt(0)
	v_mfma_f32_16x16x32_bf16 v[92:95], v[206:209], v[24:27], v[92:95]
	v_mfma_f32_16x16x32_bf16 v[24:27], v[214:217], v[24:27], v[166:169]
	v_mfma_f32_16x16x32_bf16 v[84:87], v[206:209], v[182:185], v[84:87]
	v_mfma_f32_16x16x32_bf16 v[100:103], v[214:217], v[182:185], v[170:173]
	v_mfma_f32_16x16x32_bf16 v[76:79], v[206:209], v[190:193], v[76:79]
	v_mfma_f32_16x16x32_bf16 v[164:167], v[214:217], v[190:193], v[174:177]
	v_mfma_f32_16x16x32_bf16 v[68:71], v[206:209], v[198:201], v[68:71]
	v_mfma_f32_16x16x32_bf16 v[168:171], v[214:217], v[198:201], v[178:181]
	v_mfma_f32_16x16x32_bf16 v[124:127], v[210:213], v[160:163], v[92:95]
	v_mfma_f32_16x16x32_bf16 v[116:119], v[136:139], v[160:163], v[24:27]
	v_mfma_f32_16x16x32_bf16 v[108:111], v[210:213], v[186:189], v[84:87]
	v_mfma_f32_16x16x32_bf16 v[100:103], v[136:139], v[186:189], v[100:103]
	v_mfma_f32_16x16x32_bf16 v[92:95], v[210:213], v[194:197], v[76:79]
	v_mfma_f32_16x16x32_bf16 v[84:87], v[136:139], v[194:197], v[164:167]
	v_mfma_f32_16x16x32_bf16 v[76:79], v[210:213], v[202:205], v[68:71]
	v_mfma_f32_16x16x32_bf16 v[68:71], v[136:139], v[202:205], v[168:171]
	s_barrier
	ds_read_b128 v[160:163], v131 offset:49152
	ds_read_b128 v[164:167], v131 offset:50176
	ds_read_b128 v[168:171], v134 offset:49152
	ds_read_b128 v[172:175], v134 offset:50176
	ds_read_b128 v[176:179], v133 offset:49152
	ds_read_b128 v[180:183], v133 offset:50176
	ds_read_b128 v[184:187], v132 offset:49152
	ds_read_b128 v[132:135], v132 offset:50176
	s_barrier
	s_waitcnt lgkmcnt(0)
	v_mfma_f32_16x16x32_bf16 v[24:27], v[0:3], v[160:163], v[60:63]
	v_mfma_f32_16x16x32_bf16 v[60:63], v[16:19], v[160:163], v[56:59]
	v_mfma_f32_16x16x32_bf16 v[52:55], v[0:3], v[168:171], v[52:55]
	v_mfma_f32_16x16x32_bf16 v[188:191], v[16:19], v[168:171], v[48:51]
	v_mfma_f32_16x16x32_bf16 v[44:47], v[0:3], v[176:179], v[44:47]
	v_mfma_f32_16x16x32_bf16 v[192:195], v[16:19], v[176:179], v[40:43]
	v_mfma_f32_16x16x32_bf16 v[0:3], v[0:3], v[184:187], v[36:39]
	v_mfma_f32_16x16x32_bf16 v[36:39], v[16:19], v[184:187], v[32:35]
	v_mfma_f32_16x16x32_bf16 v[56:59], v[8:11], v[164:167], v[24:27]
	v_mfma_f32_16x16x32_bf16 v[48:51], v[140:143], v[164:167], v[60:63]
	v_mfma_f32_16x16x32_bf16 v[40:43], v[8:11], v[172:175], v[52:55]
	v_mfma_f32_16x16x32_bf16 v[32:35], v[140:143], v[172:175], v[188:191]
	v_mfma_f32_16x16x32_bf16 v[24:27], v[8:11], v[180:183], v[44:47]
	v_mfma_f32_16x16x32_bf16 v[16:19], v[140:143], v[180:183], v[192:195]
	v_mfma_f32_16x16x32_bf16 v[8:11], v[8:11], v[132:135], v[0:3]
	v_mfma_f32_16x16x32_bf16 v[0:3], v[140:143], v[132:135], v[36:39]
	v_mfma_f32_16x16x32_bf16 v[28:31], v[206:209], v[160:163], v[28:31]
	v_mfma_f32_16x16x32_bf16 v[36:39], v[214:217], v[160:163], v[144:147]
	v_mfma_f32_16x16x32_bf16 v[20:23], v[206:209], v[168:171], v[20:23]
	v_mfma_f32_16x16x32_bf16 v[140:143], v[214:217], v[168:171], v[148:151]
	v_mfma_f32_16x16x32_bf16 v[12:15], v[206:209], v[176:179], v[12:15]
	v_mfma_f32_16x16x32_bf16 v[144:147], v[214:217], v[176:179], v[152:155]
	v_mfma_f32_16x16x32_bf16 v[4:7], v[206:209], v[184:187], v[4:7]
	v_mfma_f32_16x16x32_bf16 v[148:151], v[214:217], v[184:187], v[156:159]
	v_mfma_f32_16x16x32_bf16 v[60:63], v[210:213], v[164:167], v[28:31]
	v_mfma_f32_16x16x32_bf16 v[52:55], v[136:139], v[164:167], v[36:39]
	v_mfma_f32_16x16x32_bf16 v[44:47], v[210:213], v[172:175], v[20:23]
	v_mfma_f32_16x16x32_bf16 v[36:39], v[136:139], v[172:175], v[140:143]
	v_mfma_f32_16x16x32_bf16 v[28:31], v[210:213], v[180:183], v[12:15]
	v_mfma_f32_16x16x32_bf16 v[20:23], v[136:139], v[180:183], v[144:147]
	v_mfma_f32_16x16x32_bf16 v[12:15], v[210:213], v[132:135], v[4:7]
	v_mfma_f32_16x16x32_bf16 v[4:7], v[136:139], v[132:135], v[148:151]
	v_cmp_gt_u32_e32 vcc, s35, v130
	s_barrier
	s_and_saveexec_b64 s[10:11], vcc
	s_cbranch_execz .LBB0_357
	s_barrier

; #define STAGE(P, RS, SOFF, OFF, kt) do { const int _so = (SOFF) + (kt) * (BK * 2); \
;     _Pragma("unroll") for (int _i = 0; _i < 2; ++_i) { \
;       __builtin_amdgcn_raw_ptr_buffer_load_lds(RS, (__attribute__((address_space(3))) void*)((P) + wave * 1024 + _i * 8192), 16, OFF[_i], _so, 0, 0); } } while (0)
; #define LDA(dst, b, h) _Pragma("unroll") for (int m = 0; m < 4; ++m) _Pragma("unroll") for (int k = 0; k < 2; ++k) \
;     dst[m][k] = *reinterpret_cast<const bf16x8*>(SA(b, h) + lds_byte(wr * 64 + m * 16 + fr, k * 32 + fq * 8))
; #define LDB(dst, b, h) _Pragma("unroll") for (int n = 0; n < 2; ++n) _Pragma("unroll") for (int k = 0; k < 2; ++k) \
;     dst[n][k] = *reinterpret_cast<const bf16x8*>(SB(b, h) + lds_byte(wc * 32 + n * 16 + fr, k * 32 + fq * 8))
; #define WAIT_V(n) asm volatile("s_waitcnt vmcnt(" #n ")" ::: "memory")
; #define WAIT_L(n) asm volatile("s_waitcnt lgkmcnt(" #n ")" ::: "memory")
; #define BAR __builtin_amdgcn_s_barrier()
; #define SCHED __builtin_amdgcn_sched_barrier(0)
;     ...
;       LDB(B0, 0, 0); SCHED; LDA(At, 0, 0); STAGE(SA(1, 1), rsA, sA1, offA, t + 1);
;       WAIT_L(8); BAR; WAIT_L(0); MMA(0, 0, At, B0); BAR; SCHED;
;       LDB(B1, 0, 1); STAGE(SB(0, 0), rsB, sB0, offB, t + 2);
;       BAR; WAIT_L(0); MMA(0, 1, At, B1); BAR;
;       LDA(At, 0, 1); STAGE(SA(0, 0), rsA, sA0, offA, t + 2);
;       BAR; WAIT_L(0); MMA(1, 0, At, B0); BAR; SCHED;
;       STAGE(SB(0, 1), rsB, sB1, offB, t + 2);
;       WAIT_V(6); BAR; MMA(1, 1, At, B1); BAR;
.LBB0_392:
	ds_read_b128 v[152:155], v147
	ds_read_b128 v[156:159], v148
	ds_read_b128 v[160:163], v149
	ds_read_b128 v[164:167], v150
	s_add_i32 s5, s86, s3
	s_add_i32 s6, s5, 0x80
	s_mov_b32 m0, s36
	ds_read_b128 v[168:171], v129
	ds_read_b128 v[172:175], v129 offset:1024
	ds_read_b128 v[176:179], v132
	ds_read_b128 v[180:183], v132 offset:1024
	ds_read_b128 v[184:187], v131
	ds_read_b128 v[188:191], v131 offset:1024
	ds_read_b128 v[192:195], v130
	ds_read_b128 v[196:199], v130 offset:1024
	buffer_load_dwordx4 v141, s[8:11], s6 offen lds
	s_mov_b32 m0, s59
	s_nop 0
	buffer_load_dwordx4 v142, s[8:11], s6 offen lds
	s_waitcnt lgkmcnt(8)
	s_barrier
	s_waitcnt lgkmcnt(0)
	v_mfma_f32_16x16x32_bf16 v[124:127], v[152:155], v[168:171], v[124:127]
	v_mfma_f32_16x16x32_bf16 v[120:123], v[160:163], v[168:171], v[120:123]
	v_mfma_f32_16x16x32_bf16 v[116:119], v[152:155], v[176:179], v[116:119]
	v_mfma_f32_16x16x32_bf16 v[112:115], v[160:163], v[176:179], v[112:115]
	v_mfma_f32_16x16x32_bf16 v[108:111], v[152:155], v[184:187], v[108:111]
	v_mfma_f32_16x16x32_bf16 v[104:107], v[160:163], v[184:187], v[104:107]
	v_mfma_f32_16x16x32_bf16 v[100:103], v[152:155], v[192:195], v[100:103]
	v_mfma_f32_16x16x32_bf16 v[96:99], v[160:163], v[192:195], v[96:99]
	v_mfma_f32_16x16x32_bf16 v[124:127], v[156:159], v[172:175], v[124:127]
	v_mfma_f32_16x16x32_bf16 v[120:123], v[164:167], v[172:175], v[120:123]
	v_mfma_f32_16x16x32_bf16 v[116:119], v[156:159], v[180:183], v[116:119]
	v_mfma_f32_16x16x32_bf16 v[112:115], v[164:167], v[180:183], v[112:115]
	v_mfma_f32_16x16x32_bf16 v[108:111], v[156:159], v[188:191], v[108:111]
	v_mfma_f32_16x16x32_bf16 v[104:107], v[164:167], v[188:191], v[104:107]
	v_mfma_f32_16x16x32_bf16 v[100:103], v[156:159], v[196:199], v[100:103]
	v_mfma_f32_16x16x32_bf16 v[96:99], v[164:167], v[196:199], v[96:99]
	s_barrier
	s_add_i32 s6, s92, s3
	s_add_i32 s7, s6, 0x100
	s_mov_b32 s14, s10
	s_mov_b32 s15, s11
	s_mov_b32 m0, s37
	ds_read_b128 v[200:203], v143
	ds_read_b128 v[204:207], v144
	ds_read_b128 v[208:211], v145
	ds_read_b128 v[212:215], v146
	buffer_load_dwordx4 v141, s[12:15], s7 offen lds
	s_mov_b32 m0, s48
	s_nop 0
	buffer_load_dwordx4 v142, s[12:15], s7 offen lds
	s_barrier
	s_waitcnt lgkmcnt(0)
	v_mfma_f32_16x16x32_bf16 v[92:95], v[200:203], v[168:171], v[92:95]
	v_mfma_f32_16x16x32_bf16 v[88:91], v[208:211], v[168:171], v[88:91]
	v_mfma_f32_16x16x32_bf16 v[80:83], v[200:203], v[176:179], v[80:83]
	v_mfma_f32_16x16x32_bf16 v[68:71], v[208:211], v[176:179], v[68:71]
	v_mfma_f32_16x16x32_bf16 v[60:63], v[200:203], v[184:187], v[60:63]
	v_mfma_f32_16x16x32_bf16 v[56:59], v[208:211], v[184:187], v[56:59]
	v_mfma_f32_16x16x32_bf16 v[52:55], v[200:203], v[192:195], v[52:55]
	v_mfma_f32_16x16x32_bf16 v[48:51], v[208:211], v[192:195], v[48:51]
	v_mfma_f32_16x16x32_bf16 v[92:95], v[204:207], v[172:175], v[92:95]
	v_mfma_f32_16x16x32_bf16 v[88:91], v[212:215], v[172:175], v[88:91]
	v_mfma_f32_16x16x32_bf16 v[80:83], v[204:207], v[180:183], v[80:83]
	v_mfma_f32_16x16x32_bf16 v[68:71], v[212:215], v[180:183], v[68:71]
	v_mfma_f32_16x16x32_bf16 v[60:63], v[204:207], v[188:191], v[60:63]
	v_mfma_f32_16x16x32_bf16 v[56:59], v[212:215], v[188:191], v[56:59]
	v_mfma_f32_16x16x32_bf16 v[52:55], v[204:207], v[196:199], v[52:55]
	v_mfma_f32_16x16x32_bf16 v[48:51], v[212:215], v[196:199], v[48:51]
	s_barrier
	s_add_i32 s7, s87, s3
	s_add_i32 s22, s7, 0x100
	s_mov_b32 m0, s35
	ds_read_b128 v[168:171], v129 offset:16384
	ds_read_b128 v[172:175], v129 offset:17408
	ds_read_b128 v[176:179], v132 offset:16384
	ds_read_b128 v[180:183], v132 offset:17408
	ds_read_b128 v[184:187], v131 offset:16384
	ds_read_b128 v[188:191], v131 offset:17408
	ds_read_b128 v[192:195], v130 offset:16384
	ds_read_b128 v[196:199], v130 offset:17408
	buffer_load_dwordx4 v141, s[8:11], s22 offen lds
	s_mov_b32 m0, s49
	s_nop 0
	buffer_load_dwordx4 v142, s[8:11], s22 offen lds
	s_barrier
	s_waitcnt lgkmcnt(0)
	v_mfma_f32_16x16x32_bf16 v[44:47], v[152:155], v[168:171], v[44:47]
	v_mfma_f32_16x16x32_bf16 v[40:43], v[160:163], v[168:171], v[40:43]
	v_mfma_f32_16x16x32_bf16 v[36:39], v[152:155], v[176:179], v[36:39]
	v_mfma_f32_16x16x32_bf16 v[32:35], v[160:163], v[176:179], v[32:35]
	v_mfma_f32_16x16x32_bf16 v[28:31], v[152:155], v[184:187], v[28:31]
	v_mfma_f32_16x16x32_bf16 v[24:27], v[160:163], v[184:187], v[24:27]
	v_mfma_f32_16x16x32_bf16 v[20:23], v[152:155], v[192:195], v[20:23]
	v_mfma_f32_16x16x32_bf16 v[16:19], v[160:163], v[192:195], v[16:19]
	v_mfma_f32_16x16x32_bf16 v[44:47], v[156:159], v[172:175], v[44:47]
	v_mfma_f32_16x16x32_bf16 v[40:43], v[164:167], v[172:175], v[40:43]
	v_mfma_f32_16x16x32_bf16 v[36:39], v[156:159], v[180:183], v[36:39]
	v_mfma_f32_16x16x32_bf16 v[32:35], v[164:167], v[180:183], v[32:35]
	v_mfma_f32_16x16x32_bf16 v[28:31], v[156:159], v[188:191], v[28:31]
	v_mfma_f32_16x16x32_bf16 v[24:27], v[164:167], v[188:191], v[24:27]
	v_mfma_f32_16x16x32_bf16 v[20:23], v[156:159], v[196:199], v[20:23]
	v_mfma_f32_16x16x32_bf16 v[16:19], v[164:167], v[196:199], v[16:19]
	s_barrier
	s_add_i32 s22, s93, s3
	s_add_i32 s23, s22, 0x100
	s_mov_b32 m0, s38
	s_nop 0
	buffer_load_dwordx4 v141, s[12:15], s23 offen lds
	s_mov_b32 m0, s54
	s_nop 0
	buffer_load_dwordx4 v142, s[12:15], s23 offen lds
	s_waitcnt vmcnt(6)
	s_barrier
; #define STAGE(P, RS, SOFF, OFF, kt) do { const int _so = (SOFF) + (kt) * (BK * 2); \
;     _Pragma("unroll") for (int _i = 0; _i < 2; ++_i) { \
;       __builtin_amdgcn_raw_ptr_buffer_load_lds(RS, (__attribute__((address_space(3))) void*)((P) + wave * 1024 + _i * 8192), 16, OFF[_i], _so, 0, 0); } } while (0)
; #define LDA(dst, b, h) _Pragma("unroll") for (int m = 0; m < 4; ++m) _Pragma("unroll") for (int k = 0; k < 2; ++k) \
;     dst[m][k] = *reinterpret_cast<const bf16x8*>(SA(b, h) + lds_byte(wr * 64 + m * 16 + fr, k * 32 + fq * 8))
; #define LDB(dst, b, h) _Pragma("unroll") for (int n = 0; n < 2; ++n) _Pragma("unroll") for (int k = 0; k < 2; ++k) \
;     dst[n][k] = *reinterpret_cast<const bf16x8*>(SB(b, h) + lds_byte(wc * 32 + n * 16 + fr, k * 32 + fq * 8))
; #define WAIT_V(n) asm volatile("s_waitcnt vmcnt(" #n ")" ::: "memory")
; #define WAIT_L(n) asm volatile("s_waitcnt lgkmcnt(" #n ")" ::: "memory")
; #define BAR __builtin_amdgcn_s_barrier()
; #define SCHED __builtin_amdgcn_sched_barrier(0)
;     ...
;       WAIT_V(6); BAR; MMA(1, 1, At, B1); BAR;
;       LDB(B0, 1, 0); SCHED; LDA(At, 1, 0); STAGE(SA(0, 1), rsA, sA1, offA, t + 2);
;       WAIT_L(8); BAR; WAIT_L(0); MMA(0, 0, At, B0); BAR; SCHED;
;       LDB(B1, 1, 1); STAGE(SB(1, 0), rsB, sB0, offB, t + 3);
;       BAR; WAIT_L(0); MMA(0, 1, At, B1); BAR;
;       LDA(At, 1, 1); STAGE(SA(1, 0), rsA, sA0, offA, t + 3);
;       BAR; WAIT_L(0); MMA(1, 0, At, B0); BAR; SCHED;
;       STAGE(SB(1, 1), rsB, sB1, offB, t + 3);
;       WAIT_V(6); BAR; MMA(1, 1, At, B1); BAR;
	v_mfma_f32_16x16x32_bf16 v[12:15], v[200:203], v[168:171], v[12:15]
	v_mfma_f32_16x16x32_bf16 v[8:11], v[208:211], v[168:171], v[8:11]
	v_mfma_f32_16x16x32_bf16 v[4:7], v[200:203], v[176:179], v[4:7]
	v_mfma_f32_16x16x32_bf16 v[0:3], v[208:211], v[176:179], v[0:3]
	v_mfma_f32_16x16x32_bf16 v[64:67], v[200:203], v[184:187], v[64:67]
	v_mfma_f32_16x16x32_bf16 v[72:75], v[208:211], v[184:187], v[72:75]
	v_mfma_f32_16x16x32_bf16 v[76:79], v[200:203], v[192:195], v[76:79]
	v_mfma_f32_16x16x32_bf16 v[84:87], v[208:211], v[192:195], v[84:87]
	v_mfma_f32_16x16x32_bf16 v[12:15], v[204:207], v[172:175], v[12:15]
	v_mfma_f32_16x16x32_bf16 v[8:11], v[212:215], v[172:175], v[8:11]
	v_mfma_f32_16x16x32_bf16 v[4:7], v[204:207], v[180:183], v[4:7]
	v_mfma_f32_16x16x32_bf16 v[0:3], v[212:215], v[180:183], v[0:3]
	v_mfma_f32_16x16x32_bf16 v[64:67], v[204:207], v[188:191], v[64:67]
	v_mfma_f32_16x16x32_bf16 v[72:75], v[212:215], v[188:191], v[72:75]
	v_mfma_f32_16x16x32_bf16 v[76:79], v[204:207], v[196:199], v[76:79]
	v_mfma_f32_16x16x32_bf16 v[84:87], v[212:215], v[196:199], v[84:87]
	s_barrier
	ds_read_b128 v[152:155], v137
	ds_read_b128 v[156:159], v138
	ds_read_b128 v[160:163], v139
	ds_read_b128 v[164:167], v140
	s_addk_i32 s5, 0x100
	s_mov_b32 m0, s39
	ds_read_b128 v[168:171], v129 offset:32768
	ds_read_b128 v[172:175], v129 offset:33792
	ds_read_b128 v[176:179], v132 offset:32768
	ds_read_b128 v[180:183], v132 offset:33792
	ds_read_b128 v[184:187], v131 offset:32768
	ds_read_b128 v[188:191], v131 offset:33792
	ds_read_b128 v[192:195], v130 offset:32768
	ds_read_b128 v[196:199], v130 offset:33792
	buffer_load_dwordx4 v141, s[8:11], s5 offen lds
	s_mov_b32 m0, s55
	s_nop 0
	buffer_load_dwordx4 v142, s[8:11], s5 offen lds
	s_waitcnt lgkmcnt(8)
	s_barrier
	s_waitcnt lgkmcnt(0)
	v_mfma_f32_16x16x32_bf16 v[124:127], v[152:155], v[168:171], v[124:127]
	v_mfma_f32_16x16x32_bf16 v[120:123], v[160:163], v[168:171], v[120:123]
	v_mfma_f32_16x16x32_bf16 v[116:119], v[152:155], v[176:179], v[116:119]
	v_mfma_f32_16x16x32_bf16 v[112:115], v[160:163], v[176:179], v[112:115]
	v_mfma_f32_16x16x32_bf16 v[108:111], v[152:155], v[184:187], v[108:111]
	v_mfma_f32_16x16x32_bf16 v[104:107], v[160:163], v[184:187], v[104:107]
	v_mfma_f32_16x16x32_bf16 v[100:103], v[152:155], v[192:195], v[100:103]
	v_mfma_f32_16x16x32_bf16 v[96:99], v[160:163], v[192:195], v[96:99]
	v_mfma_f32_16x16x32_bf16 v[124:127], v[156:159], v[172:175], v[124:127]
	v_mfma_f32_16x16x32_bf16 v[120:123], v[164:167], v[172:175], v[120:123]
	v_mfma_f32_16x16x32_bf16 v[116:119], v[156:159], v[180:183], v[116:119]
	v_mfma_f32_16x16x32_bf16 v[112:115], v[164:167], v[180:183], v[112:115]
	v_mfma_f32_16x16x32_bf16 v[108:111], v[156:159], v[188:191], v[108:111]
	v_mfma_f32_16x16x32_bf16 v[104:107], v[164:167], v[188:191], v[104:107]
	v_mfma_f32_16x16x32_bf16 v[100:103], v[156:159], v[196:199], v[100:103]
	v_mfma_f32_16x16x32_bf16 v[96:99], v[164:167], v[196:199], v[96:99]
	s_barrier
	s_addk_i32 s6, 0x180
	s_mov_b32 m0, s42
	ds_read_b128 v[200:203], v133
	ds_read_b128 v[204:207], v134
	ds_read_b128 v[208:211], v135
	ds_read_b128 v[212:215], v136
	buffer_load_dwordx4 v141, s[12:15], s6 offen lds
	s_mov_b32 m0, s56
	s_nop 0
	buffer_load_dwordx4 v142, s[12:15], s6 offen lds
	s_barrier
	s_waitcnt lgkmcnt(0)
	v_mfma_f32_16x16x32_bf16 v[92:95], v[200:203], v[168:171], v[92:95]
	v_mfma_f32_16x16x32_bf16 v[88:91], v[208:211], v[168:171], v[88:91]
	v_mfma_f32_16x16x32_bf16 v[80:83], v[200:203], v[176:179], v[80:83]
	v_mfma_f32_16x16x32_bf16 v[68:71], v[208:211], v[176:179], v[68:71]
	v_mfma_f32_16x16x32_bf16 v[60:63], v[200:203], v[184:187], v[60:63]
	v_mfma_f32_16x16x32_bf16 v[56:59], v[208:211], v[184:187], v[56:59]
	v_mfma_f32_16x16x32_bf16 v[52:55], v[200:203], v[192:195], v[52:55]
	v_mfma_f32_16x16x32_bf16 v[48:51], v[208:211], v[192:195], v[48:51]
	v_mfma_f32_16x16x32_bf16 v[92:95], v[204:207], v[172:175], v[92:95]
	v_mfma_f32_16x16x32_bf16 v[88:91], v[212:215], v[172:175], v[88:91]
	v_mfma_f32_16x16x32_bf16 v[80:83], v[204:207], v[180:183], v[80:83]
	v_mfma_f32_16x16x32_bf16 v[68:71], v[212:215], v[180:183], v[68:71]
	v_mfma_f32_16x16x32_bf16 v[60:63], v[204:207], v[188:191], v[60:63]
	v_mfma_f32_16x16x32_bf16 v[56:59], v[212:215], v[188:191], v[56:59]
	v_mfma_f32_16x16x32_bf16 v[52:55], v[204:207], v[196:199], v[52:55]
	v_mfma_f32_16x16x32_bf16 v[48:51], v[212:215], v[196:199], v[48:51]
	s_barrier
	s_addk_i32 s7, 0x180
	s_mov_b32 m0, s43
	ds_read_b128 v[168:171], v129 offset:49152
	ds_read_b128 v[172:175], v129 offset:50176
	ds_read_b128 v[176:179], v132 offset:49152
	ds_read_b128 v[180:183], v132 offset:50176
	ds_read_b128 v[184:187], v131 offset:49152
	ds_read_b128 v[188:191], v131 offset:50176
	ds_read_b128 v[192:195], v130 offset:49152
	ds_read_b128 v[196:199], v130 offset:50176
	buffer_load_dwordx4 v141, s[8:11], s7 offen lds
	s_mov_b32 m0, s57
	s_nop 0
	buffer_load_dwordx4 v142, s[8:11], s7 offen lds
	s_barrier
	s_waitcnt lgkmcnt(0)
	v_mfma_f32_16x16x32_bf16 v[44:47], v[152:155], v[168:171], v[44:47]
	v_mfma_f32_16x16x32_bf16 v[40:43], v[160:163], v[168:171], v[40:43]
	v_mfma_f32_16x16x32_bf16 v[36:39], v[152:155], v[176:179], v[36:39]
	v_mfma_f32_16x16x32_bf16 v[32:35], v[160:163], v[176:179], v[32:35]
	v_mfma_f32_16x16x32_bf16 v[28:31], v[152:155], v[184:187], v[28:31]
	v_mfma_f32_16x16x32_bf16 v[24:27], v[160:163], v[184:187], v[24:27]
	v_mfma_f32_16x16x32_bf16 v[20:23], v[152:155], v[192:195], v[20:23]
	v_mfma_f32_16x16x32_bf16 v[16:19], v[160:163], v[192:195], v[16:19]
	v_mfma_f32_16x16x32_bf16 v[44:47], v[156:159], v[172:175], v[44:47]
	v_mfma_f32_16x16x32_bf16 v[40:43], v[164:167], v[172:175], v[40:43]
	v_mfma_f32_16x16x32_bf16 v[36:39], v[156:159], v[180:183], v[36:39]
	v_mfma_f32_16x16x32_bf16 v[32:35], v[164:167], v[180:183], v[32:35]
	v_mfma_f32_16x16x32_bf16 v[28:31], v[156:159], v[188:191], v[28:31]
	v_mfma_f32_16x16x32_bf16 v[24:27], v[164:167], v[188:191], v[24:27]
	v_mfma_f32_16x16x32_bf16 v[20:23], v[156:159], v[196:199], v[20:23]
	v_mfma_f32_16x16x32_bf16 v[16:19], v[164:167], v[196:199], v[16:19]
	s_barrier
; #define STAGE(P, RS, SOFF, OFF, kt) do { const int _so = (SOFF) + (kt) * (BK * 2); \
;     _Pragma("unroll") for (int _i = 0; _i < 2; ++_i) { \
;       __builtin_amdgcn_raw_ptr_buffer_load_lds(RS, (__attribute__((address_space(3))) void*)((P) + wave * 1024 + _i * 8192), 16, OFF[_i], _so, 0, 0); } } while (0)
; #define LDA(dst, b, h) _Pragma("unroll") for (int m = 0; m < 4; ++m) _Pragma("unroll") for (int k = 0; k < 2; ++k) \
;     dst[m][k] = *reinterpret_cast<const bf16x8*>(SA(b, h) + lds_byte(wr * 64 + m * 16 + fr, k * 32 + fq * 8))
; #define LDB(dst, b, h) _Pragma("unroll") for (int n = 0; n < 2; ++n) _Pragma("unroll") for (int k = 0; k < 2; ++k) \
;     dst[n][k] = *reinterpret_cast<const bf16x8*>(SB(b, h) + lds_byte(wc * 32 + n * 16 + fr, k * 32 + fq * 8))
; #define WAIT_V(n) asm volatile("s_waitcnt vmcnt(" #n ")" ::: "memory")
; #define WAIT_L(n) asm volatile("s_waitcnt lgkmcnt(" #n ")" ::: "memory")
; #define BAR __builtin_amdgcn_s_barrier()
;     ...
;       WAIT_V(6); BAR; MMA(1, 1, At, B1); BAR;
;     }
;     { LDB(B0, 0, 0); LDA(At, 0, 0); STAGE(SA(1, 1), rsA, sA1, offA, nt - 1);
;       BAR; WAIT_L(0); MMA(0, 0, At, B0); BAR;
;       LDB(B1, 0, 1); BAR; WAIT_L(0); MMA(0, 1, At, B1); BAR;
;       LDA(At, 0, 1); WAIT_V(4); BAR; WAIT_L(0); MMA(1, 0, At, B0); MMA(1, 1, At, B1); BAR; }
	s_addk_i32 s22, 0x180
	s_mov_b32 m0, s44
	s_nop 0
	buffer_load_dwordx4 v141, s[12:15], s22 offen lds
	s_mov_b32 m0, s58
	s_nop 0
	buffer_load_dwordx4 v142, s[12:15], s22 offen lds
	s_waitcnt vmcnt(6)
	s_barrier
	v_mfma_f32_16x16x32_bf16 v[12:15], v[200:203], v[168:171], v[12:15]
	v_mfma_f32_16x16x32_bf16 v[8:11], v[208:211], v[168:171], v[8:11]
	v_mfma_f32_16x16x32_bf16 v[4:7], v[200:203], v[176:179], v[4:7]
	v_mfma_f32_16x16x32_bf16 v[0:3], v[208:211], v[176:179], v[0:3]
	v_mfma_f32_16x16x32_bf16 v[64:67], v[200:203], v[184:187], v[64:67]
	v_mfma_f32_16x16x32_bf16 v[72:75], v[208:211], v[184:187], v[72:75]
	v_mfma_f32_16x16x32_bf16 v[76:79], v[200:203], v[192:195], v[76:79]
	v_mfma_f32_16x16x32_bf16 v[84:87], v[208:211], v[192:195], v[84:87]
	v_mfma_f32_16x16x32_bf16 v[12:15], v[204:207], v[172:175], v[12:15]
	v_mfma_f32_16x16x32_bf16 v[8:11], v[212:215], v[172:175], v[8:11]
	v_mfma_f32_16x16x32_bf16 v[4:7], v[204:207], v[180:183], v[4:7]
	v_mfma_f32_16x16x32_bf16 v[0:3], v[212:215], v[180:183], v[0:3]
	v_mfma_f32_16x16x32_bf16 v[64:67], v[204:207], v[188:191], v[64:67]
	v_mfma_f32_16x16x32_bf16 v[72:75], v[212:215], v[188:191], v[72:75]
	v_mfma_f32_16x16x32_bf16 v[76:79], v[204:207], v[196:199], v[76:79]
	v_mfma_f32_16x16x32_bf16 v[84:87], v[212:215], v[196:199], v[84:87]
	s_barrier
	s_add_i32 s1, s1, 2
	s_addk_i32 s3, 0x100
	s_cmp_gt_u32 s1, 59
	s_cbranch_scc0 .LBB0_392
	s_add_i32 s1, s86, 0x1f80
	s_mov_b32 m0, s36
	ds_read_b128 v[152:155], v147
	ds_read_b128 v[156:159], v148
	ds_read_b128 v[160:163], v149
	ds_read_b128 v[148:151], v150
	ds_read_b128 v[164:167], v129
	ds_read_b128 v[168:171], v129 offset:1024
	ds_read_b128 v[172:175], v132
	ds_read_b128 v[176:179], v132 offset:1024
	ds_read_b128 v[180:183], v131
	ds_read_b128 v[184:187], v131 offset:1024
	ds_read_b128 v[188:191], v130
	ds_read_b128 v[192:195], v130 offset:1024
	buffer_load_dwordx4 v141, s[8:11], s1 offen lds
	s_mov_b32 m0, s59
	s_nop 0
	buffer_load_dwordx4 v142, s[8:11], s1 offen lds
	s_barrier
	s_waitcnt lgkmcnt(0)
	v_mfma_f32_16x16x32_bf16 v[124:127], v[152:155], v[164:167], v[124:127]
	v_mfma_f32_16x16x32_bf16 v[120:123], v[160:163], v[164:167], v[120:123]
	v_mfma_f32_16x16x32_bf16 v[116:119], v[152:155], v[172:175], v[116:119]
	v_mfma_f32_16x16x32_bf16 v[112:115], v[160:163], v[172:175], v[112:115]
	v_mfma_f32_16x16x32_bf16 v[108:111], v[152:155], v[180:183], v[108:111]
	v_mfma_f32_16x16x32_bf16 v[104:107], v[160:163], v[180:183], v[104:107]
	v_mfma_f32_16x16x32_bf16 v[100:103], v[152:155], v[188:191], v[100:103]
	v_mfma_f32_16x16x32_bf16 v[96:99], v[160:163], v[188:191], v[96:99]
	v_mfma_f32_16x16x32_bf16 v[124:127], v[156:159], v[168:171], v[124:127]
	v_mfma_f32_16x16x32_bf16 v[120:123], v[148:151], v[168:171], v[120:123]
	v_mfma_f32_16x16x32_bf16 v[116:119], v[156:159], v[176:179], v[116:119]
	v_mfma_f32_16x16x32_bf16 v[112:115], v[148:151], v[176:179], v[112:115]
	v_mfma_f32_16x16x32_bf16 v[108:111], v[156:159], v[184:187], v[108:111]
	v_mfma_f32_16x16x32_bf16 v[104:107], v[148:151], v[184:187], v[104:107]
	v_mfma_f32_16x16x32_bf16 v[100:103], v[156:159], v[192:195], v[100:103]
	v_mfma_f32_16x16x32_bf16 v[96:99], v[148:151], v[192:195], v[96:99]
	s_barrier
	ds_read_b128 v[196:199], v143
	ds_read_b128 v[200:203], v144
	ds_read_b128 v[142:145], v145
	ds_read_b128 v[204:207], v146
	s_barrier
	s_waitcnt lgkmcnt(0)
	v_mfma_f32_16x16x32_bf16 v[80:83], v[196:199], v[172:175], v[80:83]
	v_mfma_f32_16x16x32_bf16 v[68:71], v[142:145], v[172:175], v[68:71]
	v_mfma_f32_16x16x32_bf16 v[60:63], v[196:199], v[180:183], v[60:63]
	v_mfma_f32_16x16x32_bf16 v[56:59], v[142:145], v[180:183], v[56:59]
	v_mfma_f32_16x16x32_bf16 v[52:55], v[196:199], v[188:191], v[52:55]
	v_mfma_f32_16x16x32_bf16 v[48:51], v[142:145], v[188:191], v[48:51]
	v_mfma_f32_16x16x32_bf16 v[92:95], v[196:199], v[164:167], v[92:95]
	v_mfma_f32_16x16x32_bf16 v[88:91], v[142:145], v[164:167], v[88:91]
	v_mfma_f32_16x16x32_bf16 v[80:83], v[200:203], v[176:179], v[80:83]
	v_mfma_f32_16x16x32_bf16 v[68:71], v[204:207], v[176:179], v[68:71]
	v_mfma_f32_16x16x32_bf16 v[60:63], v[200:203], v[184:187], v[60:63]
	v_mfma_f32_16x16x32_bf16 v[56:59], v[204:207], v[184:187], v[56:59]
	v_mfma_f32_16x16x32_bf16 v[52:55], v[200:203], v[192:195], v[52:55]
	v_mfma_f32_16x16x32_bf16 v[48:51], v[204:207], v[192:195], v[48:51]
	v_mfma_f32_16x16x32_bf16 v[164:167], v[200:203], v[168:171], v[92:95]
	v_mfma_f32_16x16x32_bf16 v[168:171], v[204:207], v[168:171], v[88:91]
	s_barrier
	s_nop 0
	ds_read_b128 v[88:91], v129 offset:16384
	ds_read_b128 v[92:95], v129 offset:17408
	ds_read_b128 v[172:175], v132 offset:16384
	ds_read_b128 v[176:179], v132 offset:17408
	ds_read_b128 v[180:183], v131 offset:16384
	ds_read_b128 v[184:187], v131 offset:17408
	ds_read_b128 v[188:191], v130 offset:16384
	ds_read_b128 v[192:195], v130 offset:17408
	s_waitcnt vmcnt(4)
	s_barrier
; #define LDA(dst, b, h) _Pragma("unroll") for (int m = 0; m < 4; ++m) _Pragma("unroll") for (int k = 0; k < 2; ++k) \
;     dst[m][k] = *reinterpret_cast<const bf16x8*>(SA(b, h) + lds_byte(wr * 64 + m * 16 + fr, k * 32 + fq * 8))
; #define LDB(dst, b, h) _Pragma("unroll") for (int n = 0; n < 2; ++n) _Pragma("unroll") for (int k = 0; k < 2; ++k) \
;     dst[n][k] = *reinterpret_cast<const bf16x8*>(SB(b, h) + lds_byte(wc * 32 + n * 16 + fr, k * 32 + fq * 8))
; #define WAIT_V(n) asm volatile("s_waitcnt vmcnt(" #n ")" ::: "memory")
; #define WAIT_L(n) asm volatile("s_waitcnt lgkmcnt(" #n ")" ::: "memory")
; #define BAR __builtin_amdgcn_s_barrier()
;     ...
;       LDA(At, 0, 1); WAIT_V(4); BAR; WAIT_L(0); MMA(1, 0, At, B0); MMA(1, 1, At, B1); BAR; }
;     { LDB(B0, 1, 0); LDA(At, 1, 0); WAIT_V(2); BAR; WAIT_L(0); MMA(0, 0, At, B0); BAR;
;       LDB(B1, 1, 1); WAIT_V(0); BAR; WAIT_L(0); MMA(0, 1, At, B1); BAR;
	s_waitcnt lgkmcnt(0)
	v_mfma_f32_16x16x32_bf16 v[44:47], v[152:155], v[88:91], v[44:47]
	v_mfma_f32_16x16x32_bf16 v[40:43], v[160:163], v[88:91], v[40:43]
	v_mfma_f32_16x16x32_bf16 v[36:39], v[152:155], v[172:175], v[36:39]
	v_mfma_f32_16x16x32_bf16 v[32:35], v[160:163], v[172:175], v[32:35]
	v_mfma_f32_16x16x32_bf16 v[28:31], v[152:155], v[180:183], v[28:31]
	v_mfma_f32_16x16x32_bf16 v[24:27], v[160:163], v[180:183], v[24:27]
	v_mfma_f32_16x16x32_bf16 v[20:23], v[152:155], v[188:191], v[20:23]
	v_mfma_f32_16x16x32_bf16 v[16:19], v[160:163], v[188:191], v[16:19]
	v_mfma_f32_16x16x32_bf16 v[44:47], v[156:159], v[92:95], v[44:47]
	v_mfma_f32_16x16x32_bf16 v[40:43], v[148:151], v[92:95], v[40:43]
	v_mfma_f32_16x16x32_bf16 v[36:39], v[156:159], v[176:179], v[36:39]
	v_mfma_f32_16x16x32_bf16 v[32:35], v[148:151], v[176:179], v[32:35]
	v_mfma_f32_16x16x32_bf16 v[28:31], v[156:159], v[184:187], v[28:31]
	v_mfma_f32_16x16x32_bf16 v[24:27], v[148:151], v[184:187], v[24:27]
	v_mfma_f32_16x16x32_bf16 v[20:23], v[156:159], v[192:195], v[20:23]
	v_mfma_f32_16x16x32_bf16 v[16:19], v[148:151], v[192:195], v[16:19]
	v_mfma_f32_16x16x32_bf16 v[4:7], v[196:199], v[172:175], v[4:7]
	v_mfma_f32_16x16x32_bf16 v[0:3], v[142:145], v[172:175], v[0:3]
	v_mfma_f32_16x16x32_bf16 v[12:15], v[196:199], v[88:91], v[12:15]
	v_mfma_f32_16x16x32_bf16 v[8:11], v[142:145], v[88:91], v[8:11]
	v_mfma_f32_16x16x32_bf16 v[64:67], v[196:199], v[180:183], v[64:67]
	v_mfma_f32_16x16x32_bf16 v[72:75], v[142:145], v[180:183], v[72:75]
	v_mfma_f32_16x16x32_bf16 v[76:79], v[196:199], v[188:191], v[76:79]
	v_mfma_f32_16x16x32_bf16 v[84:87], v[142:145], v[188:191], v[84:87]
	v_mfma_f32_16x16x32_bf16 v[4:7], v[200:203], v[176:179], v[4:7]
	v_mfma_f32_16x16x32_bf16 v[0:3], v[204:207], v[176:179], v[0:3]
	v_mfma_f32_16x16x32_bf16 v[142:145], v[200:203], v[92:95], v[12:15]
	v_mfma_f32_16x16x32_bf16 v[146:149], v[204:207], v[92:95], v[8:11]
	v_mfma_f32_16x16x32_bf16 v[150:153], v[200:203], v[184:187], v[64:67]
	v_mfma_f32_16x16x32_bf16 v[154:157], v[204:207], v[184:187], v[72:75]
	v_mfma_f32_16x16x32_bf16 v[158:161], v[200:203], v[192:195], v[76:79]
	v_mfma_f32_16x16x32_bf16 v[172:175], v[204:207], v[192:195], v[84:87]
	s_barrier
	ds_read_b128 v[8:11], v137
	ds_read_b128 v[12:15], v138
	ds_read_b128 v[176:179], v139
	ds_read_b128 v[138:141], v140
	ds_read_b128 v[64:67], v129 offset:32768
	ds_read_b128 v[84:87], v129 offset:33792
	ds_read_b128 v[180:183], v132 offset:32768
	ds_read_b128 v[184:187], v132 offset:33792
	ds_read_b128 v[188:191], v131 offset:32768
	ds_read_b128 v[192:195], v131 offset:33792
	ds_read_b128 v[196:199], v130 offset:32768
	ds_read_b128 v[200:203], v130 offset:33792
	s_waitcnt vmcnt(2)
	s_barrier
	s_waitcnt lgkmcnt(0)
	v_mfma_f32_16x16x32_bf16 v[72:75], v[8:11], v[64:67], v[124:127]
	v_mfma_f32_16x16x32_bf16 v[76:79], v[176:179], v[64:67], v[120:123]
	v_mfma_f32_16x16x32_bf16 v[88:91], v[8:11], v[180:183], v[116:119]
	v_mfma_f32_16x16x32_bf16 v[92:95], v[176:179], v[180:183], v[112:115]
	v_mfma_f32_16x16x32_bf16 v[112:115], v[8:11], v[188:191], v[108:111]
	v_mfma_f32_16x16x32_bf16 v[120:123], v[176:179], v[188:191], v[104:107]
	v_mfma_f32_16x16x32_bf16 v[100:103], v[8:11], v[196:199], v[100:103]
	v_mfma_f32_16x16x32_bf16 v[96:99], v[176:179], v[196:199], v[96:99]
	v_mfma_f32_16x16x32_bf16 v[124:127], v[12:15], v[84:87], v[72:75]
	v_mfma_f32_16x16x32_bf16 v[116:119], v[138:141], v[84:87], v[76:79]
	v_mfma_f32_16x16x32_bf16 v[108:111], v[12:15], v[184:187], v[88:91]
	v_mfma_f32_16x16x32_bf16 v[104:107], v[138:141], v[184:187], v[92:95]
	v_mfma_f32_16x16x32_bf16 v[92:95], v[12:15], v[192:195], v[112:115]
	v_mfma_f32_16x16x32_bf16 v[88:91], v[138:141], v[192:195], v[120:123]
	v_mfma_f32_16x16x32_bf16 v[76:79], v[12:15], v[200:203], v[100:103]
	v_mfma_f32_16x16x32_bf16 v[72:75], v[138:141], v[200:203], v[96:99]
	s_barrier
; #define LDA(dst, b, h) _Pragma("unroll") for (int m = 0; m < 4; ++m) _Pragma("unroll") for (int k = 0; k < 2; ++k) \
;     dst[m][k] = *reinterpret_cast<const bf16x8*>(SA(b, h) + lds_byte(wr * 64 + m * 16 + fr, k * 32 + fq * 8))
; #define LDB(dst, b, h) _Pragma("unroll") for (int n = 0; n < 2; ++n) _Pragma("unroll") for (int k = 0; k < 2; ++k) \
;     dst[n][k] = *reinterpret_cast<const bf16x8*>(SB(b, h) + lds_byte(wc * 32 + n * 16 + fr, k * 32 + fq * 8))
; #define WAIT_V(n) asm volatile("s_waitcnt vmcnt(" #n ")" ::: "memory")
; #define WAIT_L(n) asm volatile("s_waitcnt lgkmcnt(" #n ")" ::: "memory")
; #define BAR __builtin_amdgcn_s_barrier()
;     ...
;       LDB(B1, 1, 1); WAIT_V(0); BAR; WAIT_L(0); MMA(0, 1, At, B1); BAR;
;       LDA(At, 1, 1); BAR; WAIT_L(0); MMA(1, 0, At, B0); MMA(1, 1, At, B1); BAR; }
;     if (wr == 0) BAR;
	ds_read_b128 v[204:207], v133
	ds_read_b128 v[208:211], v134
	ds_read_b128 v[212:215], v135
	ds_read_b128 v[134:137], v136
	s_waitcnt vmcnt(0)
	s_barrier
	s_waitcnt lgkmcnt(0)
	v_mfma_f32_16x16x32_bf16 v[96:99], v[204:207], v[64:67], v[164:167]
	v_mfma_f32_16x16x32_bf16 v[64:67], v[212:215], v[64:67], v[168:171]
	v_mfma_f32_16x16x32_bf16 v[80:83], v[204:207], v[180:183], v[80:83]
	v_mfma_f32_16x16x32_bf16 v[68:71], v[212:215], v[180:183], v[68:71]
	v_mfma_f32_16x16x32_bf16 v[60:63], v[204:207], v[188:191], v[60:63]
	v_mfma_f32_16x16x32_bf16 v[56:59], v[212:215], v[188:191], v[56:59]
	v_mfma_f32_16x16x32_bf16 v[52:55], v[204:207], v[196:199], v[52:55]
	v_mfma_f32_16x16x32_bf16 v[48:51], v[212:215], v[196:199], v[48:51]
	v_mfma_f32_16x16x32_bf16 v[120:123], v[208:211], v[84:87], v[96:99]
	v_mfma_f32_16x16x32_bf16 v[112:115], v[134:137], v[84:87], v[64:67]
	v_mfma_f32_16x16x32_bf16 v[100:103], v[208:211], v[184:187], v[80:83]
	v_mfma_f32_16x16x32_bf16 v[96:99], v[134:137], v[184:187], v[68:71]
	v_mfma_f32_16x16x32_bf16 v[84:87], v[208:211], v[192:195], v[60:63]
	v_mfma_f32_16x16x32_bf16 v[80:83], v[134:137], v[192:195], v[56:59]
	v_mfma_f32_16x16x32_bf16 v[68:71], v[208:211], v[200:203], v[52:55]
	v_mfma_f32_16x16x32_bf16 v[64:67], v[134:137], v[200:203], v[48:51]
	s_barrier
	s_nop 0
	ds_read_b128 v[48:51], v129 offset:49152
	ds_read_b128 v[162:165], v129 offset:50176
	ds_read_b128 v[52:55], v132 offset:49152
	ds_read_b128 v[166:169], v132 offset:50176
	ds_read_b128 v[180:183], v131 offset:49152
	ds_read_b128 v[184:187], v131 offset:50176
	ds_read_b128 v[188:191], v130 offset:49152
	ds_read_b128 v[130:133], v130 offset:50176
	s_barrier
	s_waitcnt lgkmcnt(0)
	v_mfma_f32_16x16x32_bf16 v[44:47], v[8:11], v[48:51], v[44:47]
	v_mfma_f32_16x16x32_bf16 v[40:43], v[176:179], v[48:51], v[40:43]
	v_mfma_f32_16x16x32_bf16 v[36:39], v[8:11], v[52:55], v[36:39]
	v_mfma_f32_16x16x32_bf16 v[32:35], v[176:179], v[52:55], v[32:35]
	v_mfma_f32_16x16x32_bf16 v[28:31], v[8:11], v[180:183], v[28:31]
	v_mfma_f32_16x16x32_bf16 v[24:27], v[176:179], v[180:183], v[24:27]
	v_mfma_f32_16x16x32_bf16 v[8:11], v[8:11], v[188:191], v[20:23]
	v_mfma_f32_16x16x32_bf16 v[16:19], v[176:179], v[188:191], v[16:19]
	v_mfma_f32_16x16x32_bf16 v[60:63], v[12:15], v[162:165], v[44:47]
	v_mfma_f32_16x16x32_bf16 v[56:59], v[138:141], v[162:165], v[40:43]
	v_mfma_f32_16x16x32_bf16 v[44:47], v[12:15], v[166:169], v[36:39]
	v_mfma_f32_16x16x32_bf16 v[40:43], v[138:141], v[166:169], v[32:35]
	v_mfma_f32_16x16x32_bf16 v[28:31], v[12:15], v[184:187], v[28:31]
	v_mfma_f32_16x16x32_bf16 v[24:27], v[138:141], v[184:187], v[24:27]
	v_mfma_f32_16x16x32_bf16 v[12:15], v[12:15], v[130:133], v[8:11]
	v_mfma_f32_16x16x32_bf16 v[8:11], v[138:141], v[130:133], v[16:19]
	v_mfma_f32_16x16x32_bf16 v[16:19], v[204:207], v[48:51], v[142:145]
	v_mfma_f32_16x16x32_bf16 v[20:23], v[212:215], v[48:51], v[146:149]
	v_mfma_f32_16x16x32_bf16 v[4:7], v[204:207], v[52:55], v[4:7]
	v_mfma_f32_16x16x32_bf16 v[0:3], v[212:215], v[52:55], v[0:3]
	v_mfma_f32_16x16x32_bf16 v[138:141], v[204:207], v[180:183], v[150:153]
	v_mfma_f32_16x16x32_bf16 v[142:145], v[212:215], v[180:183], v[154:157]
	v_mfma_f32_16x16x32_bf16 v[146:149], v[204:207], v[188:191], v[158:161]
	v_mfma_f32_16x16x32_bf16 v[150:153], v[212:215], v[188:191], v[172:175]
	v_mfma_f32_16x16x32_bf16 v[52:55], v[208:211], v[162:165], v[16:19]
	v_mfma_f32_16x16x32_bf16 v[48:51], v[134:137], v[162:165], v[20:23]
	v_mfma_f32_16x16x32_bf16 v[36:39], v[208:211], v[166:169], v[4:7]
	v_mfma_f32_16x16x32_bf16 v[32:35], v[134:137], v[166:169], v[0:3]
	v_mfma_f32_16x16x32_bf16 v[20:23], v[208:211], v[184:187], v[138:141]
	v_mfma_f32_16x16x32_bf16 v[16:19], v[134:137], v[184:187], v[142:145]
	v_mfma_f32_16x16x32_bf16 v[4:7], v[208:211], v[130:133], v[146:149]
	v_mfma_f32_16x16x32_bf16 v[0:3], v[134:137], v[130:133], v[150:153]
	v_cmp_gt_u32_e32 vcc, s40, v128
	s_barrier
	s_and_saveexec_b64 s[6:7], vcc
	s_cbranch_execz .LBB0_395
	s_barrier

; #define STAGE(P, RS, SOFF, OFF, kt) do { const int _so = (SOFF) + (kt) * (BK * 2); \
;     _Pragma("unroll") for (int _i = 0; _i < 2; ++_i) { \
;       __builtin_amdgcn_raw_ptr_buffer_load_lds(RS, (__attribute__((address_space(3))) void*)((P) + wave * 1024 + _i * 8192), 16, OFF[_i], _so, 0, 0); } } while (0)
; #define LDA(dst, b, h) _Pragma("unroll") for (int m = 0; m < 4; ++m) _Pragma("unroll") for (int k = 0; k < 2; ++k) \
;     dst[m][k] = *reinterpret_cast<const bf16x8*>(SA(b, h) + lds_byte(wr * 64 + m * 16 + fr, k * 32 + fq * 8))
; #define LDB(dst, b, h) _Pragma("unroll") for (int n = 0; n < 2; ++n) _Pragma("unroll") for (int k = 0; k < 2; ++k) \
;     dst[n][k] = *reinterpret_cast<const bf16x8*>(SB(b, h) + lds_byte(wc * 32 + n * 16 + fr, k * 32 + fq * 8))
; #define WAIT_V(n) asm volatile("s_waitcnt vmcnt(" #n ")" ::: "memory")
; #define WAIT_L(n) asm volatile("s_waitcnt lgkmcnt(" #n ")" ::: "memory")
; #define BAR __builtin_amdgcn_s_barrier()
; #define SCHED __builtin_amdgcn_sched_barrier(0)
;     ...
;       LDB(B0, 0, 0); SCHED; LDA(At, 0, 0); STAGE(SA(1, 1), rsA, sA1, offA, t + 1);
;       WAIT_L(8); BAR; WAIT_L(0); MMA(0, 0, At, B0); BAR; SCHED;
;       LDB(B1, 0, 1); STAGE(SB(0, 0), rsB, sB0, offB, t + 2);
;       BAR; WAIT_L(0); MMA(0, 1, At, B1); BAR;
;       LDA(At, 0, 1); STAGE(SA(0, 0), rsA, sA0, offA, t + 2);
;       BAR; WAIT_L(0); MMA(1, 0, At, B0); BAR; SCHED;
;       STAGE(SB(0, 1), rsB, sB1, offB, t + 2);
;       WAIT_V(6); BAR; MMA(1, 1, At, B1); BAR;
.LBB0_494:
	ds_read_b128 v[152:155], v147
	ds_read_b128 v[156:159], v148
	ds_read_b128 v[160:163], v149
	ds_read_b128 v[164:167], v150
	s_add_i32 s5, s82, s3
	s_add_i32 s6, s5, 0x80
	s_mov_b32 m0, s36
	ds_read_b128 v[168:171], v129
	ds_read_b128 v[172:175], v129 offset:1024
	ds_read_b128 v[176:179], v132
	ds_read_b128 v[180:183], v132 offset:1024
	ds_read_b128 v[184:187], v131
	ds_read_b128 v[188:191], v131 offset:1024
	ds_read_b128 v[192:195], v130
	ds_read_b128 v[196:199], v130 offset:1024
	buffer_load_dwordx4 v141, s[8:11], s6 offen lds
	s_mov_b32 m0, s59
	s_nop 0
	buffer_load_dwordx4 v142, s[8:11], s6 offen lds
	s_waitcnt lgkmcnt(8)
	s_barrier
	s_waitcnt lgkmcnt(0)
	v_mfma_f32_16x16x32_bf16 v[124:127], v[152:155], v[168:171], v[124:127]
	v_mfma_f32_16x16x32_bf16 v[120:123], v[160:163], v[168:171], v[120:123]
	v_mfma_f32_16x16x32_bf16 v[116:119], v[152:155], v[176:179], v[116:119]
	v_mfma_f32_16x16x32_bf16 v[112:115], v[160:163], v[176:179], v[112:115]
	v_mfma_f32_16x16x32_bf16 v[108:111], v[152:155], v[184:187], v[108:111]
	v_mfma_f32_16x16x32_bf16 v[104:107], v[160:163], v[184:187], v[104:107]
	v_mfma_f32_16x16x32_bf16 v[100:103], v[152:155], v[192:195], v[100:103]
	v_mfma_f32_16x16x32_bf16 v[96:99], v[160:163], v[192:195], v[96:99]
	v_mfma_f32_16x16x32_bf16 v[124:127], v[156:159], v[172:175], v[124:127]
	v_mfma_f32_16x16x32_bf16 v[120:123], v[164:167], v[172:175], v[120:123]
	v_mfma_f32_16x16x32_bf16 v[116:119], v[156:159], v[180:183], v[116:119]
	v_mfma_f32_16x16x32_bf16 v[112:115], v[164:167], v[180:183], v[112:115]
	v_mfma_f32_16x16x32_bf16 v[108:111], v[156:159], v[188:191], v[108:111]
	v_mfma_f32_16x16x32_bf16 v[104:107], v[164:167], v[188:191], v[104:107]
	v_mfma_f32_16x16x32_bf16 v[100:103], v[156:159], v[196:199], v[100:103]
	v_mfma_f32_16x16x32_bf16 v[96:99], v[164:167], v[196:199], v[96:99]
	s_barrier
	s_add_i32 s6, s84, s3
	s_add_i32 s7, s6, 0x100
	s_mov_b32 s14, s10
	s_mov_b32 s15, s11
	s_mov_b32 m0, s37
	ds_read_b128 v[200:203], v143
	ds_read_b128 v[204:207], v144
	ds_read_b128 v[208:211], v145
	ds_read_b128 v[212:215], v146
	buffer_load_dwordx4 v141, s[12:15], s7 offen lds
	s_mov_b32 m0, s70
	s_nop 0
	buffer_load_dwordx4 v142, s[12:15], s7 offen lds
	s_barrier
	s_waitcnt lgkmcnt(0)
	v_mfma_f32_16x16x32_bf16 v[92:95], v[200:203], v[168:171], v[92:95]
	v_mfma_f32_16x16x32_bf16 v[88:91], v[208:211], v[168:171], v[88:91]
	v_mfma_f32_16x16x32_bf16 v[80:83], v[200:203], v[176:179], v[80:83]
	v_mfma_f32_16x16x32_bf16 v[68:71], v[208:211], v[176:179], v[68:71]
	v_mfma_f32_16x16x32_bf16 v[60:63], v[200:203], v[184:187], v[60:63]
	v_mfma_f32_16x16x32_bf16 v[56:59], v[208:211], v[184:187], v[56:59]
	v_mfma_f32_16x16x32_bf16 v[52:55], v[200:203], v[192:195], v[52:55]
	v_mfma_f32_16x16x32_bf16 v[48:51], v[208:211], v[192:195], v[48:51]
	v_mfma_f32_16x16x32_bf16 v[92:95], v[204:207], v[172:175], v[92:95]
	v_mfma_f32_16x16x32_bf16 v[88:91], v[212:215], v[172:175], v[88:91]
	v_mfma_f32_16x16x32_bf16 v[80:83], v[204:207], v[180:183], v[80:83]
	v_mfma_f32_16x16x32_bf16 v[68:71], v[212:215], v[180:183], v[68:71]
	v_mfma_f32_16x16x32_bf16 v[60:63], v[204:207], v[188:191], v[60:63]
	v_mfma_f32_16x16x32_bf16 v[56:59], v[212:215], v[188:191], v[56:59]
	v_mfma_f32_16x16x32_bf16 v[52:55], v[204:207], v[196:199], v[52:55]
	v_mfma_f32_16x16x32_bf16 v[48:51], v[212:215], v[196:199], v[48:51]
	s_barrier
	s_add_i32 s7, s83, s3
	s_add_i32 s22, s7, 0x100
	s_mov_b32 m0, s35
	ds_read_b128 v[168:171], v129 offset:16384
	ds_read_b128 v[172:175], v129 offset:17408
	ds_read_b128 v[176:179], v132 offset:16384
	ds_read_b128 v[180:183], v132 offset:17408
	ds_read_b128 v[184:187], v131 offset:16384
	ds_read_b128 v[188:191], v131 offset:17408
	ds_read_b128 v[192:195], v130 offset:16384
	ds_read_b128 v[196:199], v130 offset:17408
	buffer_load_dwordx4 v141, s[8:11], s22 offen lds
	s_mov_b32 m0, s95
	s_nop 0
	buffer_load_dwordx4 v142, s[8:11], s22 offen lds
	s_barrier
	s_waitcnt lgkmcnt(0)
	v_mfma_f32_16x16x32_bf16 v[44:47], v[152:155], v[168:171], v[44:47]
	v_mfma_f32_16x16x32_bf16 v[40:43], v[160:163], v[168:171], v[40:43]
	v_mfma_f32_16x16x32_bf16 v[36:39], v[152:155], v[176:179], v[36:39]
	v_mfma_f32_16x16x32_bf16 v[32:35], v[160:163], v[176:179], v[32:35]
	v_mfma_f32_16x16x32_bf16 v[28:31], v[152:155], v[184:187], v[28:31]
	v_mfma_f32_16x16x32_bf16 v[24:27], v[160:163], v[184:187], v[24:27]
	v_mfma_f32_16x16x32_bf16 v[20:23], v[152:155], v[192:195], v[20:23]
	v_mfma_f32_16x16x32_bf16 v[16:19], v[160:163], v[192:195], v[16:19]
	v_mfma_f32_16x16x32_bf16 v[44:47], v[156:159], v[172:175], v[44:47]
	v_mfma_f32_16x16x32_bf16 v[40:43], v[164:167], v[172:175], v[40:43]
	v_mfma_f32_16x16x32_bf16 v[36:39], v[156:159], v[180:183], v[36:39]
	v_mfma_f32_16x16x32_bf16 v[32:35], v[164:167], v[180:183], v[32:35]
	v_mfma_f32_16x16x32_bf16 v[28:31], v[156:159], v[188:191], v[28:31]
	v_mfma_f32_16x16x32_bf16 v[24:27], v[164:167], v[188:191], v[24:27]
	v_mfma_f32_16x16x32_bf16 v[20:23], v[156:159], v[196:199], v[20:23]
	v_mfma_f32_16x16x32_bf16 v[16:19], v[164:167], v[196:199], v[16:19]
	s_barrier
	s_add_i32 s22, s85, s3
	s_add_i32 s23, s22, 0x100
	s_mov_b32 m0, s38
	s_nop 0
	buffer_load_dwordx4 v141, s[12:15], s23 offen lds
	s_mov_b32 m0, s71
	s_nop 0
	buffer_load_dwordx4 v142, s[12:15], s23 offen lds
	s_waitcnt vmcnt(6)
	s_barrier
; #define STAGE(P, RS, SOFF, OFF, kt) do { const int _so = (SOFF) + (kt) * (BK * 2); \
;     _Pragma("unroll") for (int _i = 0; _i < 2; ++_i) { \
;       __builtin_amdgcn_raw_ptr_buffer_load_lds(RS, (__attribute__((address_space(3))) void*)((P) + wave * 1024 + _i * 8192), 16, OFF[_i], _so, 0, 0); } } while (0)
; #define LDA(dst, b, h) _Pragma("unroll") for (int m = 0; m < 4; ++m) _Pragma("unroll") for (int k = 0; k < 2; ++k) \
;     dst[m][k] = *reinterpret_cast<const bf16x8*>(SA(b, h) + lds_byte(wr * 64 + m * 16 + fr, k * 32 + fq * 8))
; #define LDB(dst, b, h) _Pragma("unroll") for (int n = 0; n < 2; ++n) _Pragma("unroll") for (int k = 0; k < 2; ++k) \
;     dst[n][k] = *reinterpret_cast<const bf16x8*>(SB(b, h) + lds_byte(wc * 32 + n * 16 + fr, k * 32 + fq * 8))
; #define WAIT_V(n) asm volatile("s_waitcnt vmcnt(" #n ")" ::: "memory")
; #define WAIT_L(n) asm volatile("s_waitcnt lgkmcnt(" #n ")" ::: "memory")
; #define BAR __builtin_amdgcn_s_barrier()
; #define SCHED __builtin_amdgcn_sched_barrier(0)
;     ...
;       WAIT_V(6); BAR; MMA(1, 1, At, B1); BAR;
;       LDB(B0, 1, 0); SCHED; LDA(At, 1, 0); STAGE(SA(0, 1), rsA, sA1, offA, t + 2);
;       WAIT_L(8); BAR; WAIT_L(0); MMA(0, 0, At, B0); BAR; SCHED;
;       LDB(B1, 1, 1); STAGE(SB(1, 0), rsB, sB0, offB, t + 3);
;       BAR; WAIT_L(0); MMA(0, 1, At, B1); BAR;
;       LDA(At, 1, 1); STAGE(SA(1, 0), rsA, sA0, offA, t + 3);
;       BAR; WAIT_L(0); MMA(1, 0, At, B0); BAR; SCHED;
;       STAGE(SB(1, 1), rsB, sB1, offB, t + 3);
;       WAIT_V(6); BAR; MMA(1, 1, At, B1); BAR;
	v_mfma_f32_16x16x32_bf16 v[12:15], v[200:203], v[168:171], v[12:15]
	v_mfma_f32_16x16x32_bf16 v[8:11], v[208:211], v[168:171], v[8:11]
	v_mfma_f32_16x16x32_bf16 v[4:7], v[200:203], v[176:179], v[4:7]
	v_mfma_f32_16x16x32_bf16 v[0:3], v[208:211], v[176:179], v[0:3]
	v_mfma_f32_16x16x32_bf16 v[64:67], v[200:203], v[184:187], v[64:67]
	v_mfma_f32_16x16x32_bf16 v[72:75], v[208:211], v[184:187], v[72:75]
	v_mfma_f32_16x16x32_bf16 v[76:79], v[200:203], v[192:195], v[76:79]
	v_mfma_f32_16x16x32_bf16 v[84:87], v[208:211], v[192:195], v[84:87]
	v_mfma_f32_16x16x32_bf16 v[12:15], v[204:207], v[172:175], v[12:15]
	v_mfma_f32_16x16x32_bf16 v[8:11], v[212:215], v[172:175], v[8:11]
	v_mfma_f32_16x16x32_bf16 v[4:7], v[204:207], v[180:183], v[4:7]
	v_mfma_f32_16x16x32_bf16 v[0:3], v[212:215], v[180:183], v[0:3]
	v_mfma_f32_16x16x32_bf16 v[64:67], v[204:207], v[188:191], v[64:67]
	v_mfma_f32_16x16x32_bf16 v[72:75], v[212:215], v[188:191], v[72:75]
	v_mfma_f32_16x16x32_bf16 v[76:79], v[204:207], v[196:199], v[76:79]
	v_mfma_f32_16x16x32_bf16 v[84:87], v[212:215], v[196:199], v[84:87]
	s_barrier
	ds_read_b128 v[152:155], v137
	ds_read_b128 v[156:159], v138
	ds_read_b128 v[160:163], v139
	ds_read_b128 v[164:167], v140
	s_addk_i32 s5, 0x100
	s_mov_b32 m0, s39
	ds_read_b128 v[168:171], v129 offset:32768
	ds_read_b128 v[172:175], v129 offset:33792
	ds_read_b128 v[176:179], v132 offset:32768
	ds_read_b128 v[180:183], v132 offset:33792
	ds_read_b128 v[184:187], v131 offset:32768
	ds_read_b128 v[188:191], v131 offset:33792
	ds_read_b128 v[192:195], v130 offset:32768
	ds_read_b128 v[196:199], v130 offset:33792
	buffer_load_dwordx4 v141, s[8:11], s5 offen lds
	s_mov_b32 m0, s97
	s_nop 0
	buffer_load_dwordx4 v142, s[8:11], s5 offen lds
	s_waitcnt lgkmcnt(8)
	s_barrier
	s_waitcnt lgkmcnt(0)
	v_mfma_f32_16x16x32_bf16 v[124:127], v[152:155], v[168:171], v[124:127]
	v_mfma_f32_16x16x32_bf16 v[120:123], v[160:163], v[168:171], v[120:123]
	v_mfma_f32_16x16x32_bf16 v[116:119], v[152:155], v[176:179], v[116:119]
	v_mfma_f32_16x16x32_bf16 v[112:115], v[160:163], v[176:179], v[112:115]
	v_mfma_f32_16x16x32_bf16 v[108:111], v[152:155], v[184:187], v[108:111]
	v_mfma_f32_16x16x32_bf16 v[104:107], v[160:163], v[184:187], v[104:107]
	v_mfma_f32_16x16x32_bf16 v[100:103], v[152:155], v[192:195], v[100:103]
	v_mfma_f32_16x16x32_bf16 v[96:99], v[160:163], v[192:195], v[96:99]
	v_mfma_f32_16x16x32_bf16 v[124:127], v[156:159], v[172:175], v[124:127]
	v_mfma_f32_16x16x32_bf16 v[120:123], v[164:167], v[172:175], v[120:123]
	v_mfma_f32_16x16x32_bf16 v[116:119], v[156:159], v[180:183], v[116:119]
	v_mfma_f32_16x16x32_bf16 v[112:115], v[164:167], v[180:183], v[112:115]
	v_mfma_f32_16x16x32_bf16 v[108:111], v[156:159], v[188:191], v[108:111]
	v_mfma_f32_16x16x32_bf16 v[104:107], v[164:167], v[188:191], v[104:107]
	v_mfma_f32_16x16x32_bf16 v[100:103], v[156:159], v[196:199], v[100:103]
	v_mfma_f32_16x16x32_bf16 v[96:99], v[164:167], v[196:199], v[96:99]
	s_barrier
	s_addk_i32 s6, 0x180
	s_mov_b32 m0, s92
	ds_read_b128 v[200:203], v133
	ds_read_b128 v[204:207], v134
	ds_read_b128 v[208:211], v135
	ds_read_b128 v[212:215], v136
	buffer_load_dwordx4 v141, s[12:15], s6 offen lds
	s_mov_b32 m0, s56
	s_nop 0
	buffer_load_dwordx4 v142, s[12:15], s6 offen lds
	s_barrier
	s_waitcnt lgkmcnt(0)
	v_mfma_f32_16x16x32_bf16 v[92:95], v[200:203], v[168:171], v[92:95]
	v_mfma_f32_16x16x32_bf16 v[88:91], v[208:211], v[168:171], v[88:91]
	v_mfma_f32_16x16x32_bf16 v[80:83], v[200:203], v[176:179], v[80:83]
	v_mfma_f32_16x16x32_bf16 v[68:71], v[208:211], v[176:179], v[68:71]
	v_mfma_f32_16x16x32_bf16 v[60:63], v[200:203], v[184:187], v[60:63]
	v_mfma_f32_16x16x32_bf16 v[56:59], v[208:211], v[184:187], v[56:59]
	v_mfma_f32_16x16x32_bf16 v[52:55], v[200:203], v[192:195], v[52:55]
	v_mfma_f32_16x16x32_bf16 v[48:51], v[208:211], v[192:195], v[48:51]
	v_mfma_f32_16x16x32_bf16 v[92:95], v[204:207], v[172:175], v[92:95]
	v_mfma_f32_16x16x32_bf16 v[88:91], v[212:215], v[172:175], v[88:91]
	v_mfma_f32_16x16x32_bf16 v[80:83], v[204:207], v[180:183], v[80:83]
	v_mfma_f32_16x16x32_bf16 v[68:71], v[212:215], v[180:183], v[68:71]
	v_mfma_f32_16x16x32_bf16 v[60:63], v[204:207], v[188:191], v[60:63]
	v_mfma_f32_16x16x32_bf16 v[56:59], v[212:215], v[188:191], v[56:59]
	v_mfma_f32_16x16x32_bf16 v[52:55], v[204:207], v[196:199], v[52:55]
	v_mfma_f32_16x16x32_bf16 v[48:51], v[212:215], v[196:199], v[48:51]
	s_barrier
	s_addk_i32 s7, 0x180
	s_mov_b32 m0, s93
	ds_read_b128 v[168:171], v129 offset:49152
	ds_read_b128 v[172:175], v129 offset:50176
	ds_read_b128 v[176:179], v132 offset:49152
	ds_read_b128 v[180:183], v132 offset:50176
	ds_read_b128 v[184:187], v131 offset:49152
	ds_read_b128 v[188:191], v131 offset:50176
	ds_read_b128 v[192:195], v130 offset:49152
	ds_read_b128 v[196:199], v130 offset:50176
	buffer_load_dwordx4 v141, s[8:11], s7 offen lds
	s_mov_b32 m0, s57
	s_nop 0
	buffer_load_dwordx4 v142, s[8:11], s7 offen lds
	s_barrier
	s_waitcnt lgkmcnt(0)
	v_mfma_f32_16x16x32_bf16 v[44:47], v[152:155], v[168:171], v[44:47]
	v_mfma_f32_16x16x32_bf16 v[40:43], v[160:163], v[168:171], v[40:43]
	v_mfma_f32_16x16x32_bf16 v[36:39], v[152:155], v[176:179], v[36:39]
	v_mfma_f32_16x16x32_bf16 v[32:35], v[160:163], v[176:179], v[32:35]
	v_mfma_f32_16x16x32_bf16 v[28:31], v[152:155], v[184:187], v[28:31]
	v_mfma_f32_16x16x32_bf16 v[24:27], v[160:163], v[184:187], v[24:27]
	v_mfma_f32_16x16x32_bf16 v[20:23], v[152:155], v[192:195], v[20:23]
	v_mfma_f32_16x16x32_bf16 v[16:19], v[160:163], v[192:195], v[16:19]
	v_mfma_f32_16x16x32_bf16 v[44:47], v[156:159], v[172:175], v[44:47]
	v_mfma_f32_16x16x32_bf16 v[40:43], v[164:167], v[172:175], v[40:43]
	v_mfma_f32_16x16x32_bf16 v[36:39], v[156:159], v[180:183], v[36:39]
	v_mfma_f32_16x16x32_bf16 v[32:35], v[164:167], v[180:183], v[32:35]
	v_mfma_f32_16x16x32_bf16 v[28:31], v[156:159], v[188:191], v[28:31]
	v_mfma_f32_16x16x32_bf16 v[24:27], v[164:167], v[188:191], v[24:27]
	v_mfma_f32_16x16x32_bf16 v[20:23], v[156:159], v[196:199], v[20:23]
	v_mfma_f32_16x16x32_bf16 v[16:19], v[164:167], v[196:199], v[16:19]
	s_barrier
; #define STAGE(P, RS, SOFF, OFF, kt) do { const int _so = (SOFF) + (kt) * (BK * 2); \
;     _Pragma("unroll") for (int _i = 0; _i < 2; ++_i) { \
;       __builtin_amdgcn_raw_ptr_buffer_load_lds(RS, (__attribute__((address_space(3))) void*)((P) + wave * 1024 + _i * 8192), 16, OFF[_i], _so, 0, 0); } } while (0)
; #define LDA(dst, b, h) _Pragma("unroll") for (int m = 0; m < 4; ++m) _Pragma("unroll") for (int k = 0; k < 2; ++k) \
;     dst[m][k] = *reinterpret_cast<const bf16x8*>(SA(b, h) + lds_byte(wr * 64 + m * 16 + fr, k * 32 + fq * 8))
; #define LDB(dst, b, h) _Pragma("unroll") for (int n = 0; n < 2; ++n) _Pragma("unroll") for (int k = 0; k < 2; ++k) \
;     dst[n][k] = *reinterpret_cast<const bf16x8*>(SB(b, h) + lds_byte(wc * 32 + n * 16 + fr, k * 32 + fq * 8))
; #define WAIT_V(n) asm volatile("s_waitcnt vmcnt(" #n ")" ::: "memory")
; #define WAIT_L(n) asm volatile("s_waitcnt lgkmcnt(" #n ")" ::: "memory")
; #define BAR __builtin_amdgcn_s_barrier()
;     ...
;       WAIT_V(6); BAR; MMA(1, 1, At, B1); BAR;
;     }
;     { LDB(B0, 0, 0); LDA(At, 0, 0); STAGE(SA(1, 1), rsA, sA1, offA, nt - 1);
;       BAR; WAIT_L(0); MMA(0, 0, At, B0); BAR;
;       LDB(B1, 0, 1); BAR; WAIT_L(0); MMA(0, 1, At, B1); BAR;
;       LDA(At, 0, 1); WAIT_V(4); BAR; WAIT_L(0); MMA(1, 0, At, B0); MMA(1, 1, At, B1); BAR; }
	s_addk_i32 s22, 0x180
	s_mov_b32 m0, s94
	s_nop 0
	buffer_load_dwordx4 v141, s[12:15], s22 offen lds
	s_mov_b32 m0, s58
	s_nop 0
	buffer_load_dwordx4 v142, s[12:15], s22 offen lds
	s_waitcnt vmcnt(6)
	s_barrier
	v_mfma_f32_16x16x32_bf16 v[12:15], v[200:203], v[168:171], v[12:15]
	v_mfma_f32_16x16x32_bf16 v[8:11], v[208:211], v[168:171], v[8:11]
	v_mfma_f32_16x16x32_bf16 v[4:7], v[200:203], v[176:179], v[4:7]
	v_mfma_f32_16x16x32_bf16 v[0:3], v[208:211], v[176:179], v[0:3]
	v_mfma_f32_16x16x32_bf16 v[64:67], v[200:203], v[184:187], v[64:67]
	v_mfma_f32_16x16x32_bf16 v[72:75], v[208:211], v[184:187], v[72:75]
	v_mfma_f32_16x16x32_bf16 v[76:79], v[200:203], v[192:195], v[76:79]
	v_mfma_f32_16x16x32_bf16 v[84:87], v[208:211], v[192:195], v[84:87]
	v_mfma_f32_16x16x32_bf16 v[12:15], v[204:207], v[172:175], v[12:15]
	v_mfma_f32_16x16x32_bf16 v[8:11], v[212:215], v[172:175], v[8:11]
	v_mfma_f32_16x16x32_bf16 v[4:7], v[204:207], v[180:183], v[4:7]
	v_mfma_f32_16x16x32_bf16 v[0:3], v[212:215], v[180:183], v[0:3]
	v_mfma_f32_16x16x32_bf16 v[64:67], v[204:207], v[188:191], v[64:67]
	v_mfma_f32_16x16x32_bf16 v[72:75], v[212:215], v[188:191], v[72:75]
	v_mfma_f32_16x16x32_bf16 v[76:79], v[204:207], v[196:199], v[76:79]
	v_mfma_f32_16x16x32_bf16 v[84:87], v[212:215], v[196:199], v[84:87]
	s_barrier
	s_add_i32 s1, s1, 2
	s_addk_i32 s3, 0x100
	s_cmp_gt_u32 s1, 59
	s_cbranch_scc0 .LBB0_494
	s_add_i32 s1, s82, 0x1f80
	s_mov_b32 m0, s36
	ds_read_b128 v[152:155], v147
	ds_read_b128 v[156:159], v148
	ds_read_b128 v[160:163], v149
	ds_read_b128 v[148:151], v150
	ds_read_b128 v[164:167], v129
	ds_read_b128 v[168:171], v129 offset:1024
	ds_read_b128 v[172:175], v132
	ds_read_b128 v[176:179], v132 offset:1024
	ds_read_b128 v[180:183], v131
	ds_read_b128 v[184:187], v131 offset:1024
	ds_read_b128 v[188:191], v130
	ds_read_b128 v[192:195], v130 offset:1024
	buffer_load_dwordx4 v141, s[8:11], s1 offen lds
	s_mov_b32 m0, s59
	s_nop 0
	buffer_load_dwordx4 v142, s[8:11], s1 offen lds
	s_barrier
	s_waitcnt lgkmcnt(0)
	v_mfma_f32_16x16x32_bf16 v[124:127], v[152:155], v[164:167], v[124:127]
	v_mfma_f32_16x16x32_bf16 v[120:123], v[160:163], v[164:167], v[120:123]
	v_mfma_f32_16x16x32_bf16 v[116:119], v[152:155], v[172:175], v[116:119]
	v_mfma_f32_16x16x32_bf16 v[112:115], v[160:163], v[172:175], v[112:115]
	v_mfma_f32_16x16x32_bf16 v[108:111], v[152:155], v[180:183], v[108:111]
	v_mfma_f32_16x16x32_bf16 v[104:107], v[160:163], v[180:183], v[104:107]
	v_mfma_f32_16x16x32_bf16 v[100:103], v[152:155], v[188:191], v[100:103]
	v_mfma_f32_16x16x32_bf16 v[96:99], v[160:163], v[188:191], v[96:99]
	v_mfma_f32_16x16x32_bf16 v[124:127], v[156:159], v[168:171], v[124:127]
	v_mfma_f32_16x16x32_bf16 v[120:123], v[148:151], v[168:171], v[120:123]
	v_mfma_f32_16x16x32_bf16 v[116:119], v[156:159], v[176:179], v[116:119]
	v_mfma_f32_16x16x32_bf16 v[112:115], v[148:151], v[176:179], v[112:115]
	v_mfma_f32_16x16x32_bf16 v[108:111], v[156:159], v[184:187], v[108:111]
	v_mfma_f32_16x16x32_bf16 v[104:107], v[148:151], v[184:187], v[104:107]
	v_mfma_f32_16x16x32_bf16 v[100:103], v[156:159], v[192:195], v[100:103]
	v_mfma_f32_16x16x32_bf16 v[96:99], v[148:151], v[192:195], v[96:99]
	s_barrier
	ds_read_b128 v[196:199], v143
	ds_read_b128 v[200:203], v144
	ds_read_b128 v[142:145], v145
	ds_read_b128 v[204:207], v146
	s_barrier
	s_waitcnt lgkmcnt(0)
	v_mfma_f32_16x16x32_bf16 v[80:83], v[196:199], v[172:175], v[80:83]
	v_mfma_f32_16x16x32_bf16 v[68:71], v[142:145], v[172:175], v[68:71]
	v_mfma_f32_16x16x32_bf16 v[60:63], v[196:199], v[180:183], v[60:63]
	v_mfma_f32_16x16x32_bf16 v[56:59], v[142:145], v[180:183], v[56:59]
	v_mfma_f32_16x16x32_bf16 v[52:55], v[196:199], v[188:191], v[52:55]
	v_mfma_f32_16x16x32_bf16 v[48:51], v[142:145], v[188:191], v[48:51]
	v_mfma_f32_16x16x32_bf16 v[92:95], v[196:199], v[164:167], v[92:95]
	v_mfma_f32_16x16x32_bf16 v[88:91], v[142:145], v[164:167], v[88:91]
	v_mfma_f32_16x16x32_bf16 v[80:83], v[200:203], v[176:179], v[80:83]
	v_mfma_f32_16x16x32_bf16 v[68:71], v[204:207], v[176:179], v[68:71]
	v_mfma_f32_16x16x32_bf16 v[60:63], v[200:203], v[184:187], v[60:63]
	v_mfma_f32_16x16x32_bf16 v[56:59], v[204:207], v[184:187], v[56:59]
	v_mfma_f32_16x16x32_bf16 v[52:55], v[200:203], v[192:195], v[52:55]
	v_mfma_f32_16x16x32_bf16 v[48:51], v[204:207], v[192:195], v[48:51]
	v_mfma_f32_16x16x32_bf16 v[164:167], v[200:203], v[168:171], v[92:95]
	v_mfma_f32_16x16x32_bf16 v[168:171], v[204:207], v[168:171], v[88:91]
	s_barrier
	s_nop 0
	ds_read_b128 v[88:91], v129 offset:16384
	ds_read_b128 v[92:95], v129 offset:17408
	ds_read_b128 v[172:175], v132 offset:16384
	ds_read_b128 v[176:179], v132 offset:17408
	ds_read_b128 v[180:183], v131 offset:16384
	ds_read_b128 v[184:187], v131 offset:17408
	ds_read_b128 v[188:191], v130 offset:16384
	ds_read_b128 v[192:195], v130 offset:17408
	s_waitcnt vmcnt(4)
	s_barrier
; #define LDA(dst, b, h) _Pragma("unroll") for (int m = 0; m < 4; ++m) _Pragma("unroll") for (int k = 0; k < 2; ++k) \
;     dst[m][k] = *reinterpret_cast<const bf16x8*>(SA(b, h) + lds_byte(wr * 64 + m * 16 + fr, k * 32 + fq * 8))
; #define LDB(dst, b, h) _Pragma("unroll") for (int n = 0; n < 2; ++n) _Pragma("unroll") for (int k = 0; k < 2; ++k) \
;     dst[n][k] = *reinterpret_cast<const bf16x8*>(SB(b, h) + lds_byte(wc * 32 + n * 16 + fr, k * 32 + fq * 8))
; #define WAIT_V(n) asm volatile("s_waitcnt vmcnt(" #n ")" ::: "memory")
; #define WAIT_L(n) asm volatile("s_waitcnt lgkmcnt(" #n ")" ::: "memory")
; #define BAR __builtin_amdgcn_s_barrier()
;     ...
;       LDA(At, 0, 1); WAIT_V(4); BAR; WAIT_L(0); MMA(1, 0, At, B0); MMA(1, 1, At, B1); BAR; }
;     { LDB(B0, 1, 0); LDA(At, 1, 0); WAIT_V(2); BAR; WAIT_L(0); MMA(0, 0, At, B0); BAR;
;       LDB(B1, 1, 1); WAIT_V(0); BAR; WAIT_L(0); MMA(0, 1, At, B1); BAR;
	s_waitcnt lgkmcnt(0)
	v_mfma_f32_16x16x32_bf16 v[44:47], v[152:155], v[88:91], v[44:47]
	v_mfma_f32_16x16x32_bf16 v[40:43], v[160:163], v[88:91], v[40:43]
	v_mfma_f32_16x16x32_bf16 v[36:39], v[152:155], v[172:175], v[36:39]
	v_mfma_f32_16x16x32_bf16 v[32:35], v[160:163], v[172:175], v[32:35]
	v_mfma_f32_16x16x32_bf16 v[28:31], v[152:155], v[180:183], v[28:31]
	v_mfma_f32_16x16x32_bf16 v[24:27], v[160:163], v[180:183], v[24:27]
	v_mfma_f32_16x16x32_bf16 v[20:23], v[152:155], v[188:191], v[20:23]
	v_mfma_f32_16x16x32_bf16 v[16:19], v[160:163], v[188:191], v[16:19]
	v_mfma_f32_16x16x32_bf16 v[44:47], v[156:159], v[92:95], v[44:47]
	v_mfma_f32_16x16x32_bf16 v[40:43], v[148:151], v[92:95], v[40:43]
	v_mfma_f32_16x16x32_bf16 v[36:39], v[156:159], v[176:179], v[36:39]
	v_mfma_f32_16x16x32_bf16 v[32:35], v[148:151], v[176:179], v[32:35]
	v_mfma_f32_16x16x32_bf16 v[28:31], v[156:159], v[184:187], v[28:31]
	v_mfma_f32_16x16x32_bf16 v[24:27], v[148:151], v[184:187], v[24:27]
	v_mfma_f32_16x16x32_bf16 v[20:23], v[156:159], v[192:195], v[20:23]
	v_mfma_f32_16x16x32_bf16 v[16:19], v[148:151], v[192:195], v[16:19]
	v_mfma_f32_16x16x32_bf16 v[4:7], v[196:199], v[172:175], v[4:7]
	v_mfma_f32_16x16x32_bf16 v[0:3], v[142:145], v[172:175], v[0:3]
	v_mfma_f32_16x16x32_bf16 v[12:15], v[196:199], v[88:91], v[12:15]
	v_mfma_f32_16x16x32_bf16 v[8:11], v[142:145], v[88:91], v[8:11]
	v_mfma_f32_16x16x32_bf16 v[64:67], v[196:199], v[180:183], v[64:67]
	v_mfma_f32_16x16x32_bf16 v[72:75], v[142:145], v[180:183], v[72:75]
	v_mfma_f32_16x16x32_bf16 v[76:79], v[196:199], v[188:191], v[76:79]
	v_mfma_f32_16x16x32_bf16 v[84:87], v[142:145], v[188:191], v[84:87]
	v_mfma_f32_16x16x32_bf16 v[4:7], v[200:203], v[176:179], v[4:7]
	v_mfma_f32_16x16x32_bf16 v[0:3], v[204:207], v[176:179], v[0:3]
	v_mfma_f32_16x16x32_bf16 v[142:145], v[200:203], v[92:95], v[12:15]
	v_mfma_f32_16x16x32_bf16 v[146:149], v[204:207], v[92:95], v[8:11]
	v_mfma_f32_16x16x32_bf16 v[150:153], v[200:203], v[184:187], v[64:67]
	v_mfma_f32_16x16x32_bf16 v[154:157], v[204:207], v[184:187], v[72:75]
	v_mfma_f32_16x16x32_bf16 v[158:161], v[200:203], v[192:195], v[76:79]
	v_mfma_f32_16x16x32_bf16 v[172:175], v[204:207], v[192:195], v[84:87]
	s_barrier
	ds_read_b128 v[8:11], v137
	ds_read_b128 v[12:15], v138
	ds_read_b128 v[176:179], v139
	ds_read_b128 v[138:141], v140
	ds_read_b128 v[64:67], v129 offset:32768
	ds_read_b128 v[84:87], v129 offset:33792
	ds_read_b128 v[180:183], v132 offset:32768
	ds_read_b128 v[184:187], v132 offset:33792
	ds_read_b128 v[188:191], v131 offset:32768
	ds_read_b128 v[192:195], v131 offset:33792
	ds_read_b128 v[196:199], v130 offset:32768
	ds_read_b128 v[200:203], v130 offset:33792
	s_waitcnt vmcnt(2)
	s_barrier
	s_waitcnt lgkmcnt(0)
	v_mfma_f32_16x16x32_bf16 v[72:75], v[8:11], v[64:67], v[124:127]
	v_mfma_f32_16x16x32_bf16 v[76:79], v[176:179], v[64:67], v[120:123]
	v_mfma_f32_16x16x32_bf16 v[88:91], v[8:11], v[180:183], v[116:119]
	v_mfma_f32_16x16x32_bf16 v[92:95], v[176:179], v[180:183], v[112:115]
	v_mfma_f32_16x16x32_bf16 v[112:115], v[8:11], v[188:191], v[108:111]
	v_mfma_f32_16x16x32_bf16 v[120:123], v[176:179], v[188:191], v[104:107]
	v_mfma_f32_16x16x32_bf16 v[100:103], v[8:11], v[196:199], v[100:103]
	v_mfma_f32_16x16x32_bf16 v[96:99], v[176:179], v[196:199], v[96:99]
	v_mfma_f32_16x16x32_bf16 v[124:127], v[12:15], v[84:87], v[72:75]
	v_mfma_f32_16x16x32_bf16 v[116:119], v[138:141], v[84:87], v[76:79]
	v_mfma_f32_16x16x32_bf16 v[108:111], v[12:15], v[184:187], v[88:91]
	v_mfma_f32_16x16x32_bf16 v[104:107], v[138:141], v[184:187], v[92:95]
	v_mfma_f32_16x16x32_bf16 v[92:95], v[12:15], v[192:195], v[112:115]
	v_mfma_f32_16x16x32_bf16 v[88:91], v[138:141], v[192:195], v[120:123]
	v_mfma_f32_16x16x32_bf16 v[76:79], v[12:15], v[200:203], v[100:103]
	v_mfma_f32_16x16x32_bf16 v[72:75], v[138:141], v[200:203], v[96:99]
	s_barrier
; #define LDA(dst, b, h) _Pragma("unroll") for (int m = 0; m < 4; ++m) _Pragma("unroll") for (int k = 0; k < 2; ++k) \
;     dst[m][k] = *reinterpret_cast<const bf16x8*>(SA(b, h) + lds_byte(wr * 64 + m * 16 + fr, k * 32 + fq * 8))
; #define LDB(dst, b, h) _Pragma("unroll") for (int n = 0; n < 2; ++n) _Pragma("unroll") for (int k = 0; k < 2; ++k) \
;     dst[n][k] = *reinterpret_cast<const bf16x8*>(SB(b, h) + lds_byte(wc * 32 + n * 16 + fr, k * 32 + fq * 8))
; #define WAIT_V(n) asm volatile("s_waitcnt vmcnt(" #n ")" ::: "memory")
; #define WAIT_L(n) asm volatile("s_waitcnt lgkmcnt(" #n ")" ::: "memory")
; #define BAR __builtin_amdgcn_s_barrier()
;     ...
;       LDB(B1, 1, 1); WAIT_V(0); BAR; WAIT_L(0); MMA(0, 1, At, B1); BAR;
;       LDA(At, 1, 1); BAR; WAIT_L(0); MMA(1, 0, At, B0); MMA(1, 1, At, B1); BAR; }
;     if (wr == 0) BAR;
	ds_read_b128 v[204:207], v133
	ds_read_b128 v[208:211], v134
	ds_read_b128 v[212:215], v135
	ds_read_b128 v[134:137], v136
	s_waitcnt vmcnt(0)
	s_barrier
	s_waitcnt lgkmcnt(0)
	v_mfma_f32_16x16x32_bf16 v[96:99], v[204:207], v[64:67], v[164:167]
	v_mfma_f32_16x16x32_bf16 v[64:67], v[212:215], v[64:67], v[168:171]
	v_mfma_f32_16x16x32_bf16 v[80:83], v[204:207], v[180:183], v[80:83]
	v_mfma_f32_16x16x32_bf16 v[68:71], v[212:215], v[180:183], v[68:71]
	v_mfma_f32_16x16x32_bf16 v[60:63], v[204:207], v[188:191], v[60:63]
	v_mfma_f32_16x16x32_bf16 v[56:59], v[212:215], v[188:191], v[56:59]
	v_mfma_f32_16x16x32_bf16 v[52:55], v[204:207], v[196:199], v[52:55]
	v_mfma_f32_16x16x32_bf16 v[48:51], v[212:215], v[196:199], v[48:51]
	v_mfma_f32_16x16x32_bf16 v[120:123], v[208:211], v[84:87], v[96:99]
	v_mfma_f32_16x16x32_bf16 v[112:115], v[134:137], v[84:87], v[64:67]
	v_mfma_f32_16x16x32_bf16 v[100:103], v[208:211], v[184:187], v[80:83]
	v_mfma_f32_16x16x32_bf16 v[96:99], v[134:137], v[184:187], v[68:71]
	v_mfma_f32_16x16x32_bf16 v[84:87], v[208:211], v[192:195], v[60:63]
	v_mfma_f32_16x16x32_bf16 v[80:83], v[134:137], v[192:195], v[56:59]
	v_mfma_f32_16x16x32_bf16 v[68:71], v[208:211], v[200:203], v[52:55]
	v_mfma_f32_16x16x32_bf16 v[64:67], v[134:137], v[200:203], v[48:51]
	s_barrier
	s_nop 0
	ds_read_b128 v[48:51], v129 offset:49152
	ds_read_b128 v[162:165], v129 offset:50176
	ds_read_b128 v[52:55], v132 offset:49152
	ds_read_b128 v[166:169], v132 offset:50176
	ds_read_b128 v[180:183], v131 offset:49152
	ds_read_b128 v[184:187], v131 offset:50176
	ds_read_b128 v[188:191], v130 offset:49152
	ds_read_b128 v[130:133], v130 offset:50176
	s_barrier
	s_waitcnt lgkmcnt(0)
	v_mfma_f32_16x16x32_bf16 v[44:47], v[8:11], v[48:51], v[44:47]
	v_mfma_f32_16x16x32_bf16 v[40:43], v[176:179], v[48:51], v[40:43]
	v_mfma_f32_16x16x32_bf16 v[36:39], v[8:11], v[52:55], v[36:39]
	v_mfma_f32_16x16x32_bf16 v[32:35], v[176:179], v[52:55], v[32:35]
	v_mfma_f32_16x16x32_bf16 v[28:31], v[8:11], v[180:183], v[28:31]
	v_mfma_f32_16x16x32_bf16 v[24:27], v[176:179], v[180:183], v[24:27]
	v_mfma_f32_16x16x32_bf16 v[8:11], v[8:11], v[188:191], v[20:23]
	v_mfma_f32_16x16x32_bf16 v[16:19], v[176:179], v[188:191], v[16:19]
	v_mfma_f32_16x16x32_bf16 v[60:63], v[12:15], v[162:165], v[44:47]
	v_mfma_f32_16x16x32_bf16 v[56:59], v[138:141], v[162:165], v[40:43]
	v_mfma_f32_16x16x32_bf16 v[44:47], v[12:15], v[166:169], v[36:39]
	v_mfma_f32_16x16x32_bf16 v[40:43], v[138:141], v[166:169], v[32:35]
	v_mfma_f32_16x16x32_bf16 v[28:31], v[12:15], v[184:187], v[28:31]
	v_mfma_f32_16x16x32_bf16 v[24:27], v[138:141], v[184:187], v[24:27]
	v_mfma_f32_16x16x32_bf16 v[12:15], v[12:15], v[130:133], v[8:11]
	v_mfma_f32_16x16x32_bf16 v[8:11], v[138:141], v[130:133], v[16:19]
	v_mfma_f32_16x16x32_bf16 v[16:19], v[204:207], v[48:51], v[142:145]
	v_mfma_f32_16x16x32_bf16 v[20:23], v[212:215], v[48:51], v[146:149]
	v_mfma_f32_16x16x32_bf16 v[4:7], v[204:207], v[52:55], v[4:7]
	v_mfma_f32_16x16x32_bf16 v[0:3], v[212:215], v[52:55], v[0:3]
	v_mfma_f32_16x16x32_bf16 v[138:141], v[204:207], v[180:183], v[150:153]
	v_mfma_f32_16x16x32_bf16 v[142:145], v[212:215], v[180:183], v[154:157]
	v_mfma_f32_16x16x32_bf16 v[146:149], v[204:207], v[188:191], v[158:161]
	v_mfma_f32_16x16x32_bf16 v[150:153], v[212:215], v[188:191], v[172:175]
	v_mfma_f32_16x16x32_bf16 v[52:55], v[208:211], v[162:165], v[16:19]
	v_mfma_f32_16x16x32_bf16 v[48:51], v[134:137], v[162:165], v[20:23]
	v_mfma_f32_16x16x32_bf16 v[36:39], v[208:211], v[166:169], v[4:7]
	v_mfma_f32_16x16x32_bf16 v[32:35], v[134:137], v[166:169], v[0:3]
	v_mfma_f32_16x16x32_bf16 v[20:23], v[208:211], v[184:187], v[138:141]
	v_mfma_f32_16x16x32_bf16 v[16:19], v[134:137], v[184:187], v[142:145]
	v_mfma_f32_16x16x32_bf16 v[4:7], v[208:211], v[130:133], v[146:149]
	v_mfma_f32_16x16x32_bf16 v[0:3], v[134:137], v[130:133], v[150:153]
	v_cmp_gt_u32_e32 vcc, s76, v128
	s_barrier
	s_and_saveexec_b64 s[6:7], vcc
	s_cbranch_execz .LBB0_497
	s_barrier

; #define STAGE(P, RS, SOFF, OFF, kt) do { const int _so = (SOFF) + (kt) * (BK * 2); \
;     _Pragma("unroll") for (int _i = 0; _i < 2; ++_i) { \
;       __builtin_amdgcn_raw_ptr_buffer_load_lds(RS, (__attribute__((address_space(3))) void*)((P) + wave * 1024 + _i * 8192), 16, OFF[_i], _so, 0, 0); } } while (0)
; #define LDA(dst, b, h) _Pragma("unroll") for (int m = 0; m < 4; ++m) _Pragma("unroll") for (int k = 0; k < 2; ++k) \
;     dst[m][k] = *reinterpret_cast<const bf16x8*>(SA(b, h) + lds_byte(wr * 64 + m * 16 + fr, k * 32 + fq * 8))
; #define LDB(dst, b, h) _Pragma("unroll") for (int n = 0; n < 2; ++n) _Pragma("unroll") for (int k = 0; k < 2; ++k) \
;     dst[n][k] = *reinterpret_cast<const bf16x8*>(SB(b, h) + lds_byte(wc * 32 + n * 16 + fr, k * 32 + fq * 8))
; #define WAIT_V(n) asm volatile("s_waitcnt vmcnt(" #n ")" ::: "memory")
; #define WAIT_L(n) asm volatile("s_waitcnt lgkmcnt(" #n ")" ::: "memory")
; #define BAR __builtin_amdgcn_s_barrier()
; #define SCHED __builtin_amdgcn_sched_barrier(0)
;     ...
;       LDB(B0, 0, 0); SCHED; LDA(At, 0, 0); STAGE(SA(1, 1), rsA, sA1, offA, t + 1);
;       WAIT_L(8); BAR; WAIT_L(0); MMA(0, 0, At, B0); BAR; SCHED;
;       LDB(B1, 0, 1); STAGE(SB(0, 0), rsB, sB0, offB, t + 2);
;       BAR; WAIT_L(0); MMA(0, 1, At, B1); BAR;
;       LDA(At, 0, 1); STAGE(SA(0, 0), rsA, sA0, offA, t + 2);
;       BAR; WAIT_L(0); MMA(1, 0, At, B0); BAR; SCHED;
;       STAGE(SB(0, 1), rsB, sB1, offB, t + 2);
;       WAIT_V(6); BAR; MMA(1, 1, At, B1); BAR;
.LBB0_556:
	ds_read_b128 v[154:157], v149
	ds_read_b128 v[158:161], v150
	ds_read_b128 v[162:165], v151
	ds_read_b128 v[166:169], v152
	s_add_i32 s43, s37, s17
	s_add_i32 s10, s43, 0x80
	s_mov_b32 m0, s30
	ds_read_b128 v[170:173], v131
	ds_read_b128 v[174:177], v131 offset:1024
	ds_read_b128 v[178:181], v134
	ds_read_b128 v[182:185], v134 offset:1024
	ds_read_b128 v[186:189], v133
	ds_read_b128 v[190:193], v133 offset:1024
	ds_read_b128 v[194:197], v132
	ds_read_b128 v[198:201], v132 offset:1024
	buffer_load_dwordx4 v143, s[4:7], s10 offen lds
	s_mov_b32 m0, s31
	s_nop 0
	buffer_load_dwordx4 v144, s[4:7], s10 offen lds
	s_waitcnt lgkmcnt(8)
	s_barrier
	s_waitcnt lgkmcnt(0)
	v_mfma_f32_16x16x32_bf16 v[124:127], v[154:157], v[170:173], v[124:127]
	v_mfma_f32_16x16x32_bf16 v[120:123], v[162:165], v[170:173], v[120:123]
	v_mfma_f32_16x16x32_bf16 v[116:119], v[154:157], v[178:181], v[116:119]
	v_mfma_f32_16x16x32_bf16 v[112:115], v[162:165], v[178:181], v[112:115]
	v_mfma_f32_16x16x32_bf16 v[108:111], v[154:157], v[186:189], v[108:111]
	v_mfma_f32_16x16x32_bf16 v[104:107], v[162:165], v[186:189], v[104:107]
	v_mfma_f32_16x16x32_bf16 v[100:103], v[154:157], v[194:197], v[100:103]
	v_mfma_f32_16x16x32_bf16 v[96:99], v[162:165], v[194:197], v[96:99]
	v_mfma_f32_16x16x32_bf16 v[124:127], v[158:161], v[174:177], v[124:127]
	v_mfma_f32_16x16x32_bf16 v[120:123], v[166:169], v[174:177], v[120:123]
	v_mfma_f32_16x16x32_bf16 v[116:119], v[158:161], v[182:185], v[116:119]
	v_mfma_f32_16x16x32_bf16 v[112:115], v[166:169], v[182:185], v[112:115]
	v_mfma_f32_16x16x32_bf16 v[108:111], v[158:161], v[190:193], v[108:111]
	v_mfma_f32_16x16x32_bf16 v[104:107], v[166:169], v[190:193], v[104:107]
	v_mfma_f32_16x16x32_bf16 v[100:103], v[158:161], v[198:201], v[100:103]
	v_mfma_f32_16x16x32_bf16 v[96:99], v[166:169], v[198:201], v[96:99]
	s_barrier
	s_add_i32 s44, s39, s17
	s_add_i32 s45, s44, 0x100
	s_mov_b32 s10, s6
	s_mov_b32 s11, s7
	s_mov_b32 m0, s1
	ds_read_b128 v[202:205], v145
	ds_read_b128 v[206:209], v146
	ds_read_b128 v[210:213], v147
	ds_read_b128 v[214:217], v148
	buffer_load_dwordx4 v143, s[8:11], s45 offen lds
	s_mov_b32 m0, s3
	s_nop 0
	buffer_load_dwordx4 v144, s[8:11], s45 offen lds
	s_barrier
	s_waitcnt lgkmcnt(0)
	v_mfma_f32_16x16x32_bf16 v[92:95], v[202:205], v[170:173], v[92:95]
	v_mfma_f32_16x16x32_bf16 v[88:91], v[210:213], v[170:173], v[88:91]
	v_mfma_f32_16x16x32_bf16 v[84:87], v[202:205], v[178:181], v[84:87]
	v_mfma_f32_16x16x32_bf16 v[80:83], v[210:213], v[178:181], v[80:83]
	v_mfma_f32_16x16x32_bf16 v[76:79], v[202:205], v[186:189], v[76:79]
	v_mfma_f32_16x16x32_bf16 v[72:75], v[210:213], v[186:189], v[72:75]
	v_mfma_f32_16x16x32_bf16 v[68:71], v[202:205], v[194:197], v[68:71]
	v_mfma_f32_16x16x32_bf16 v[64:67], v[210:213], v[194:197], v[64:67]
	v_mfma_f32_16x16x32_bf16 v[92:95], v[206:209], v[174:177], v[92:95]
	v_mfma_f32_16x16x32_bf16 v[88:91], v[214:217], v[174:177], v[88:91]
	v_mfma_f32_16x16x32_bf16 v[84:87], v[206:209], v[182:185], v[84:87]
	v_mfma_f32_16x16x32_bf16 v[80:83], v[214:217], v[182:185], v[80:83]
	v_mfma_f32_16x16x32_bf16 v[76:79], v[206:209], v[190:193], v[76:79]
	v_mfma_f32_16x16x32_bf16 v[72:75], v[214:217], v[190:193], v[72:75]
	v_mfma_f32_16x16x32_bf16 v[68:71], v[206:209], v[198:201], v[68:71]
	v_mfma_f32_16x16x32_bf16 v[64:67], v[214:217], v[198:201], v[64:67]
	s_barrier
	s_add_i32 s45, s38, s17
	s_add_i32 s46, s45, 0x100
	s_mov_b32 m0, s0
	ds_read_b128 v[170:173], v131 offset:16384
	ds_read_b128 v[174:177], v131 offset:17408
	ds_read_b128 v[178:181], v134 offset:16384
	ds_read_b128 v[182:185], v134 offset:17408
	ds_read_b128 v[186:189], v133 offset:16384
	ds_read_b128 v[190:193], v133 offset:17408
	ds_read_b128 v[194:197], v132 offset:16384
	ds_read_b128 v[198:201], v132 offset:17408
	buffer_load_dwordx4 v143, s[4:7], s46 offen lds
	s_mov_b32 m0, s18
	s_nop 0
	buffer_load_dwordx4 v144, s[4:7], s46 offen lds
	s_barrier
	s_waitcnt lgkmcnt(0)
	v_mfma_f32_16x16x32_bf16 v[60:63], v[154:157], v[170:173], v[60:63]
	v_mfma_f32_16x16x32_bf16 v[56:59], v[162:165], v[170:173], v[56:59]
	v_mfma_f32_16x16x32_bf16 v[52:55], v[154:157], v[178:181], v[52:55]
	v_mfma_f32_16x16x32_bf16 v[48:51], v[162:165], v[178:181], v[48:51]
	v_mfma_f32_16x16x32_bf16 v[44:47], v[154:157], v[186:189], v[44:47]
	v_mfma_f32_16x16x32_bf16 v[40:43], v[162:165], v[186:189], v[40:43]
	v_mfma_f32_16x16x32_bf16 v[36:39], v[154:157], v[194:197], v[36:39]
	v_mfma_f32_16x16x32_bf16 v[32:35], v[162:165], v[194:197], v[32:35]
	v_mfma_f32_16x16x32_bf16 v[60:63], v[158:161], v[174:177], v[60:63]
	v_mfma_f32_16x16x32_bf16 v[56:59], v[166:169], v[174:177], v[56:59]
	v_mfma_f32_16x16x32_bf16 v[52:55], v[158:161], v[182:185], v[52:55]
	v_mfma_f32_16x16x32_bf16 v[48:51], v[166:169], v[182:185], v[48:51]
	v_mfma_f32_16x16x32_bf16 v[44:47], v[158:161], v[190:193], v[44:47]
	v_mfma_f32_16x16x32_bf16 v[40:43], v[166:169], v[190:193], v[40:43]
	v_mfma_f32_16x16x32_bf16 v[36:39], v[158:161], v[198:201], v[36:39]
	v_mfma_f32_16x16x32_bf16 v[32:35], v[166:169], v[198:201], v[32:35]
	s_barrier
	s_add_i32 s46, s40, s17
	s_add_i32 s47, s46, 0x100
	s_mov_b32 m0, s19
	s_nop 0
	buffer_load_dwordx4 v143, s[8:11], s47 offen lds
	s_mov_b32 m0, s20
	s_nop 0
	buffer_load_dwordx4 v144, s[8:11], s47 offen lds
	s_waitcnt vmcnt(6)
	s_barrier
; #define STAGE(P, RS, SOFF, OFF, kt) do { const int _so = (SOFF) + (kt) * (BK * 2); \
;     _Pragma("unroll") for (int _i = 0; _i < 2; ++_i) { \
;       __builtin_amdgcn_raw_ptr_buffer_load_lds(RS, (__attribute__((address_space(3))) void*)((P) + wave * 1024 + _i * 8192), 16, OFF[_i], _so, 0, 0); } } while (0)
; #define LDA(dst, b, h) _Pragma("unroll") for (int m = 0; m < 4; ++m) _Pragma("unroll") for (int k = 0; k < 2; ++k) \
;     dst[m][k] = *reinterpret_cast<const bf16x8*>(SA(b, h) + lds_byte(wr * 64 + m * 16 + fr, k * 32 + fq * 8))
; #define LDB(dst, b, h) _Pragma("unroll") for (int n = 0; n < 2; ++n) _Pragma("unroll") for (int k = 0; k < 2; ++k) \
;     dst[n][k] = *reinterpret_cast<const bf16x8*>(SB(b, h) + lds_byte(wc * 32 + n * 16 + fr, k * 32 + fq * 8))
; #define WAIT_V(n) asm volatile("s_waitcnt vmcnt(" #n ")" ::: "memory")
; #define WAIT_L(n) asm volatile("s_waitcnt lgkmcnt(" #n ")" ::: "memory")
; #define BAR __builtin_amdgcn_s_barrier()
; #define SCHED __builtin_amdgcn_sched_barrier(0)
;     ...
;       WAIT_V(6); BAR; MMA(1, 1, At, B1); BAR;
;       LDB(B0, 1, 0); SCHED; LDA(At, 1, 0); STAGE(SA(0, 1), rsA, sA1, offA, t + 2);
;       WAIT_L(8); BAR; WAIT_L(0); MMA(0, 0, At, B0); BAR; SCHED;
;       LDB(B1, 1, 1); STAGE(SB(1, 0), rsB, sB0, offB, t + 3);
;       BAR; WAIT_L(0); MMA(0, 1, At, B1); BAR;
;       LDA(At, 1, 1); STAGE(SA(1, 0), rsA, sA0, offA, t + 3);
;       BAR; WAIT_L(0); MMA(1, 0, At, B0); BAR; SCHED;
;       STAGE(SB(1, 1), rsB, sB1, offB, t + 3);
;       WAIT_V(6); BAR; MMA(1, 1, At, B1); BAR;
	v_mfma_f32_16x16x32_bf16 v[28:31], v[202:205], v[170:173], v[28:31]
	v_mfma_f32_16x16x32_bf16 v[24:27], v[210:213], v[170:173], v[24:27]
	v_mfma_f32_16x16x32_bf16 v[20:23], v[202:205], v[178:181], v[20:23]
	v_mfma_f32_16x16x32_bf16 v[16:19], v[210:213], v[178:181], v[16:19]
	v_mfma_f32_16x16x32_bf16 v[12:15], v[202:205], v[186:189], v[12:15]
	v_mfma_f32_16x16x32_bf16 v[8:11], v[210:213], v[186:189], v[8:11]
	v_mfma_f32_16x16x32_bf16 v[4:7], v[202:205], v[194:197], v[4:7]
	v_mfma_f32_16x16x32_bf16 v[0:3], v[210:213], v[194:197], v[0:3]
	v_mfma_f32_16x16x32_bf16 v[28:31], v[206:209], v[174:177], v[28:31]
	v_mfma_f32_16x16x32_bf16 v[24:27], v[214:217], v[174:177], v[24:27]
	v_mfma_f32_16x16x32_bf16 v[20:23], v[206:209], v[182:185], v[20:23]
	v_mfma_f32_16x16x32_bf16 v[16:19], v[214:217], v[182:185], v[16:19]
	v_mfma_f32_16x16x32_bf16 v[12:15], v[206:209], v[190:193], v[12:15]
	v_mfma_f32_16x16x32_bf16 v[8:11], v[214:217], v[190:193], v[8:11]
	v_mfma_f32_16x16x32_bf16 v[4:7], v[206:209], v[198:201], v[4:7]
	v_mfma_f32_16x16x32_bf16 v[0:3], v[214:217], v[198:201], v[0:3]
	s_barrier
	ds_read_b128 v[154:157], v139
	ds_read_b128 v[158:161], v140
	ds_read_b128 v[162:165], v141
	ds_read_b128 v[166:169], v142
	s_addk_i32 s43, 0x100
	s_mov_b32 m0, s21
	ds_read_b128 v[170:173], v131 offset:32768
	ds_read_b128 v[174:177], v131 offset:33792
	ds_read_b128 v[178:181], v134 offset:32768
	ds_read_b128 v[182:185], v134 offset:33792
	ds_read_b128 v[186:189], v133 offset:32768
	ds_read_b128 v[190:193], v133 offset:33792
	ds_read_b128 v[194:197], v132 offset:32768
	ds_read_b128 v[198:201], v132 offset:33792
	buffer_load_dwordx4 v143, s[4:7], s43 offen lds
	s_mov_b32 m0, s22
	s_nop 0
	buffer_load_dwordx4 v144, s[4:7], s43 offen lds
	s_waitcnt lgkmcnt(8)
	s_barrier
	s_waitcnt lgkmcnt(0)
	v_mfma_f32_16x16x32_bf16 v[124:127], v[154:157], v[170:173], v[124:127]
	v_mfma_f32_16x16x32_bf16 v[120:123], v[162:165], v[170:173], v[120:123]
	v_mfma_f32_16x16x32_bf16 v[116:119], v[154:157], v[178:181], v[116:119]
	v_mfma_f32_16x16x32_bf16 v[112:115], v[162:165], v[178:181], v[112:115]
	v_mfma_f32_16x16x32_bf16 v[108:111], v[154:157], v[186:189], v[108:111]
	v_mfma_f32_16x16x32_bf16 v[104:107], v[162:165], v[186:189], v[104:107]
	v_mfma_f32_16x16x32_bf16 v[100:103], v[154:157], v[194:197], v[100:103]
	v_mfma_f32_16x16x32_bf16 v[96:99], v[162:165], v[194:197], v[96:99]
	v_mfma_f32_16x16x32_bf16 v[124:127], v[158:161], v[174:177], v[124:127]
	v_mfma_f32_16x16x32_bf16 v[120:123], v[166:169], v[174:177], v[120:123]
	v_mfma_f32_16x16x32_bf16 v[116:119], v[158:161], v[182:185], v[116:119]
	v_mfma_f32_16x16x32_bf16 v[112:115], v[166:169], v[182:185], v[112:115]
	v_mfma_f32_16x16x32_bf16 v[108:111], v[158:161], v[190:193], v[108:111]
	v_mfma_f32_16x16x32_bf16 v[104:107], v[166:169], v[190:193], v[104:107]
	v_mfma_f32_16x16x32_bf16 v[100:103], v[158:161], v[198:201], v[100:103]
	v_mfma_f32_16x16x32_bf16 v[96:99], v[166:169], v[198:201], v[96:99]
	s_barrier
	s_addk_i32 s44, 0x180
	s_mov_b32 m0, s23
	ds_read_b128 v[202:205], v135
	ds_read_b128 v[206:209], v136
	ds_read_b128 v[210:213], v137
	ds_read_b128 v[214:217], v138
	buffer_load_dwordx4 v143, s[8:11], s44 offen lds
	s_mov_b32 m0, s24
	s_nop 0
	buffer_load_dwordx4 v144, s[8:11], s44 offen lds
	s_barrier
	s_waitcnt lgkmcnt(0)
	v_mfma_f32_16x16x32_bf16 v[92:95], v[202:205], v[170:173], v[92:95]
	v_mfma_f32_16x16x32_bf16 v[88:91], v[210:213], v[170:173], v[88:91]
	v_mfma_f32_16x16x32_bf16 v[84:87], v[202:205], v[178:181], v[84:87]
	v_mfma_f32_16x16x32_bf16 v[80:83], v[210:213], v[178:181], v[80:83]
	v_mfma_f32_16x16x32_bf16 v[76:79], v[202:205], v[186:189], v[76:79]
	v_mfma_f32_16x16x32_bf16 v[72:75], v[210:213], v[186:189], v[72:75]
	v_mfma_f32_16x16x32_bf16 v[68:71], v[202:205], v[194:197], v[68:71]
	v_mfma_f32_16x16x32_bf16 v[64:67], v[210:213], v[194:197], v[64:67]
	v_mfma_f32_16x16x32_bf16 v[92:95], v[206:209], v[174:177], v[92:95]
	v_mfma_f32_16x16x32_bf16 v[88:91], v[214:217], v[174:177], v[88:91]
	v_mfma_f32_16x16x32_bf16 v[84:87], v[206:209], v[182:185], v[84:87]
	v_mfma_f32_16x16x32_bf16 v[80:83], v[214:217], v[182:185], v[80:83]
	v_mfma_f32_16x16x32_bf16 v[76:79], v[206:209], v[190:193], v[76:79]
	v_mfma_f32_16x16x32_bf16 v[72:75], v[214:217], v[190:193], v[72:75]
	v_mfma_f32_16x16x32_bf16 v[68:71], v[206:209], v[198:201], v[68:71]
	v_mfma_f32_16x16x32_bf16 v[64:67], v[214:217], v[198:201], v[64:67]
	s_barrier
	s_addk_i32 s45, 0x180
	s_mov_b32 m0, s25
	ds_read_b128 v[170:173], v131 offset:49152
	ds_read_b128 v[174:177], v131 offset:50176
	ds_read_b128 v[178:181], v134 offset:49152
	ds_read_b128 v[182:185], v134 offset:50176
	ds_read_b128 v[186:189], v133 offset:49152
	ds_read_b128 v[190:193], v133 offset:50176
	ds_read_b128 v[194:197], v132 offset:49152
	ds_read_b128 v[198:201], v132 offset:50176
	buffer_load_dwordx4 v143, s[4:7], s45 offen lds
	s_mov_b32 m0, s26
	s_nop 0
	buffer_load_dwordx4 v144, s[4:7], s45 offen lds
	s_barrier
	s_waitcnt lgkmcnt(0)
	v_mfma_f32_16x16x32_bf16 v[60:63], v[154:157], v[170:173], v[60:63]
	v_mfma_f32_16x16x32_bf16 v[56:59], v[162:165], v[170:173], v[56:59]
	v_mfma_f32_16x16x32_bf16 v[52:55], v[154:157], v[178:181], v[52:55]
	v_mfma_f32_16x16x32_bf16 v[48:51], v[162:165], v[178:181], v[48:51]
	v_mfma_f32_16x16x32_bf16 v[44:47], v[154:157], v[186:189], v[44:47]
	v_mfma_f32_16x16x32_bf16 v[40:43], v[162:165], v[186:189], v[40:43]
	v_mfma_f32_16x16x32_bf16 v[36:39], v[154:157], v[194:197], v[36:39]
	v_mfma_f32_16x16x32_bf16 v[32:35], v[162:165], v[194:197], v[32:35]
	v_mfma_f32_16x16x32_bf16 v[60:63], v[158:161], v[174:177], v[60:63]
	v_mfma_f32_16x16x32_bf16 v[56:59], v[166:169], v[174:177], v[56:59]
	v_mfma_f32_16x16x32_bf16 v[52:55], v[158:161], v[182:185], v[52:55]
	v_mfma_f32_16x16x32_bf16 v[48:51], v[166:169], v[182:185], v[48:51]
	v_mfma_f32_16x16x32_bf16 v[44:47], v[158:161], v[190:193], v[44:47]
	v_mfma_f32_16x16x32_bf16 v[40:43], v[166:169], v[190:193], v[40:43]
	v_mfma_f32_16x16x32_bf16 v[36:39], v[158:161], v[198:201], v[36:39]
	v_mfma_f32_16x16x32_bf16 v[32:35], v[166:169], v[198:201], v[32:35]
	s_barrier
; #define STAGE(P, RS, SOFF, OFF, kt) do { const int _so = (SOFF) + (kt) * (BK * 2); \
;     _Pragma("unroll") for (int _i = 0; _i < 2; ++_i) { \
;       __builtin_amdgcn_raw_ptr_buffer_load_lds(RS, (__attribute__((address_space(3))) void*)((P) + wave * 1024 + _i * 8192), 16, OFF[_i], _so, 0, 0); } } while (0)
; #define LDA(dst, b, h) _Pragma("unroll") for (int m = 0; m < 4; ++m) _Pragma("unroll") for (int k = 0; k < 2; ++k) \
;     dst[m][k] = *reinterpret_cast<const bf16x8*>(SA(b, h) + lds_byte(wr * 64 + m * 16 + fr, k * 32 + fq * 8))
; #define LDB(dst, b, h) _Pragma("unroll") for (int n = 0; n < 2; ++n) _Pragma("unroll") for (int k = 0; k < 2; ++k) \
;     dst[n][k] = *reinterpret_cast<const bf16x8*>(SB(b, h) + lds_byte(wc * 32 + n * 16 + fr, k * 32 + fq * 8))
; #define WAIT_V(n) asm volatile("s_waitcnt vmcnt(" #n ")" ::: "memory")
; #define WAIT_L(n) asm volatile("s_waitcnt lgkmcnt(" #n ")" ::: "memory")
; #define BAR __builtin_amdgcn_s_barrier()
;     ...
;       WAIT_V(6); BAR; MMA(1, 1, At, B1); BAR;
;     }
;     { LDB(B0, 0, 0); LDA(At, 0, 0); STAGE(SA(1, 1), rsA, sA1, offA, nt - 1);
;       BAR; WAIT_L(0); MMA(0, 0, At, B0); BAR;
;       LDB(B1, 0, 1); BAR; WAIT_L(0); MMA(0, 1, At, B1); BAR;
;       LDA(At, 0, 1); WAIT_V(4); BAR; WAIT_L(0); MMA(1, 0, At, B0); MMA(1, 1, At, B1); BAR; }
	s_addk_i32 s46, 0x180
	s_mov_b32 m0, s27
	s_nop 0
	buffer_load_dwordx4 v143, s[8:11], s46 offen lds
	s_mov_b32 m0, s28
	s_nop 0
	buffer_load_dwordx4 v144, s[8:11], s46 offen lds
	s_waitcnt vmcnt(6)
	s_barrier
	v_mfma_f32_16x16x32_bf16 v[28:31], v[202:205], v[170:173], v[28:31]
	v_mfma_f32_16x16x32_bf16 v[24:27], v[210:213], v[170:173], v[24:27]
	v_mfma_f32_16x16x32_bf16 v[20:23], v[202:205], v[178:181], v[20:23]
	v_mfma_f32_16x16x32_bf16 v[16:19], v[210:213], v[178:181], v[16:19]
	v_mfma_f32_16x16x32_bf16 v[12:15], v[202:205], v[186:189], v[12:15]
	v_mfma_f32_16x16x32_bf16 v[8:11], v[210:213], v[186:189], v[8:11]
	v_mfma_f32_16x16x32_bf16 v[4:7], v[202:205], v[194:197], v[4:7]
	v_mfma_f32_16x16x32_bf16 v[0:3], v[210:213], v[194:197], v[0:3]
	v_mfma_f32_16x16x32_bf16 v[28:31], v[206:209], v[174:177], v[28:31]
	v_mfma_f32_16x16x32_bf16 v[24:27], v[214:217], v[174:177], v[24:27]
	v_mfma_f32_16x16x32_bf16 v[20:23], v[206:209], v[182:185], v[20:23]
	v_mfma_f32_16x16x32_bf16 v[16:19], v[214:217], v[182:185], v[16:19]
	v_mfma_f32_16x16x32_bf16 v[12:15], v[206:209], v[190:193], v[12:15]
	v_mfma_f32_16x16x32_bf16 v[8:11], v[214:217], v[190:193], v[8:11]
	v_mfma_f32_16x16x32_bf16 v[4:7], v[206:209], v[198:201], v[4:7]
	v_mfma_f32_16x16x32_bf16 v[0:3], v[214:217], v[198:201], v[0:3]
	s_barrier
	s_add_i32 s16, s16, 2
	s_addk_i32 s17, 0x100
	s_cmp_gt_u32 s16, 27
	s_cbranch_scc0 .LBB0_556
	s_add_i32 s10, s37, 0xf80
	s_mov_b32 m0, s30
	ds_read_b128 v[154:157], v149
	ds_read_b128 v[158:161], v150
	ds_read_b128 v[162:165], v151
	ds_read_b128 v[150:153], v152
	ds_read_b128 v[166:169], v131
	ds_read_b128 v[170:173], v131 offset:1024
	ds_read_b128 v[174:177], v134
	ds_read_b128 v[178:181], v134 offset:1024
	ds_read_b128 v[182:185], v133
	ds_read_b128 v[186:189], v133 offset:1024
	ds_read_b128 v[190:193], v132
	ds_read_b128 v[194:197], v132 offset:1024
	buffer_load_dwordx4 v143, s[4:7], s10 offen lds
	s_mov_b32 m0, s31
	s_nop 0
	buffer_load_dwordx4 v144, s[4:7], s10 offen lds
	s_barrier
	s_waitcnt lgkmcnt(0)
	v_mfma_f32_16x16x32_bf16 v[124:127], v[154:157], v[166:169], v[124:127]
	v_mfma_f32_16x16x32_bf16 v[120:123], v[162:165], v[166:169], v[120:123]
	v_mfma_f32_16x16x32_bf16 v[116:119], v[154:157], v[174:177], v[116:119]
	v_mfma_f32_16x16x32_bf16 v[112:115], v[162:165], v[174:177], v[112:115]
	v_mfma_f32_16x16x32_bf16 v[108:111], v[154:157], v[182:185], v[108:111]
	v_mfma_f32_16x16x32_bf16 v[104:107], v[162:165], v[182:185], v[104:107]
	v_mfma_f32_16x16x32_bf16 v[100:103], v[154:157], v[190:193], v[100:103]
	v_mfma_f32_16x16x32_bf16 v[96:99], v[162:165], v[190:193], v[96:99]
	v_mfma_f32_16x16x32_bf16 v[124:127], v[158:161], v[170:173], v[124:127]
	v_mfma_f32_16x16x32_bf16 v[120:123], v[150:153], v[170:173], v[120:123]
	v_mfma_f32_16x16x32_bf16 v[116:119], v[158:161], v[178:181], v[116:119]
	v_mfma_f32_16x16x32_bf16 v[112:115], v[150:153], v[178:181], v[112:115]
	v_mfma_f32_16x16x32_bf16 v[108:111], v[158:161], v[186:189], v[108:111]
	v_mfma_f32_16x16x32_bf16 v[104:107], v[150:153], v[186:189], v[104:107]
	v_mfma_f32_16x16x32_bf16 v[100:103], v[158:161], v[194:197], v[100:103]
	v_mfma_f32_16x16x32_bf16 v[96:99], v[150:153], v[194:197], v[96:99]
	s_barrier
	ds_read_b128 v[198:201], v145
	ds_read_b128 v[202:205], v146
	ds_read_b128 v[144:147], v147
	ds_read_b128 v[206:209], v148
	s_barrier
	s_waitcnt lgkmcnt(0)
	v_mfma_f32_16x16x32_bf16 v[92:95], v[198:201], v[166:169], v[92:95]
	v_mfma_f32_16x16x32_bf16 v[88:91], v[144:147], v[166:169], v[88:91]
	v_mfma_f32_16x16x32_bf16 v[84:87], v[198:201], v[174:177], v[84:87]
	v_mfma_f32_16x16x32_bf16 v[80:83], v[144:147], v[174:177], v[80:83]
	v_mfma_f32_16x16x32_bf16 v[76:79], v[198:201], v[182:185], v[76:79]
	v_mfma_f32_16x16x32_bf16 v[72:75], v[144:147], v[182:185], v[72:75]
	v_mfma_f32_16x16x32_bf16 v[68:71], v[198:201], v[190:193], v[68:71]
	v_mfma_f32_16x16x32_bf16 v[64:67], v[144:147], v[190:193], v[64:67]
	v_mfma_f32_16x16x32_bf16 v[92:95], v[202:205], v[170:173], v[92:95]
	v_mfma_f32_16x16x32_bf16 v[88:91], v[206:209], v[170:173], v[88:91]
	v_mfma_f32_16x16x32_bf16 v[84:87], v[202:205], v[178:181], v[84:87]
	v_mfma_f32_16x16x32_bf16 v[80:83], v[206:209], v[178:181], v[80:83]
	v_mfma_f32_16x16x32_bf16 v[76:79], v[202:205], v[186:189], v[76:79]
	v_mfma_f32_16x16x32_bf16 v[72:75], v[206:209], v[186:189], v[72:75]
	v_mfma_f32_16x16x32_bf16 v[68:71], v[202:205], v[194:197], v[68:71]
	v_mfma_f32_16x16x32_bf16 v[64:67], v[206:209], v[194:197], v[64:67]
	s_barrier
	ds_read_b128 v[166:169], v131 offset:16384
	ds_read_b128 v[170:173], v131 offset:17408
	ds_read_b128 v[174:177], v134 offset:16384
	ds_read_b128 v[178:181], v134 offset:17408
	ds_read_b128 v[182:185], v133 offset:16384
	ds_read_b128 v[186:189], v133 offset:17408
	ds_read_b128 v[190:193], v132 offset:16384
	ds_read_b128 v[194:197], v132 offset:17408
	s_waitcnt vmcnt(4)
	s_barrier
; #define LDA(dst, b, h) _Pragma("unroll") for (int m = 0; m < 4; ++m) _Pragma("unroll") for (int k = 0; k < 2; ++k) \
;     dst[m][k] = *reinterpret_cast<const bf16x8*>(SA(b, h) + lds_byte(wr * 64 + m * 16 + fr, k * 32 + fq * 8))
; #define LDB(dst, b, h) _Pragma("unroll") for (int n = 0; n < 2; ++n) _Pragma("unroll") for (int k = 0; k < 2; ++k) \
;     dst[n][k] = *reinterpret_cast<const bf16x8*>(SB(b, h) + lds_byte(wc * 32 + n * 16 + fr, k * 32 + fq * 8))
; #define WAIT_V(n) asm volatile("s_waitcnt vmcnt(" #n ")" ::: "memory")
; #define WAIT_L(n) asm volatile("s_waitcnt lgkmcnt(" #n ")" ::: "memory")
; #define BAR __builtin_amdgcn_s_barrier()
;     ...
;       LDA(At, 0, 1); WAIT_V(4); BAR; WAIT_L(0); MMA(1, 0, At, B0); MMA(1, 1, At, B1); BAR; }
;     { LDB(B0, 1, 0); LDA(At, 1, 0); WAIT_V(2); BAR; WAIT_L(0); MMA(0, 0, At, B0); BAR;
	s_waitcnt lgkmcnt(0)
	v_mfma_f32_16x16x32_bf16 v[60:63], v[154:157], v[166:169], v[60:63]
	v_mfma_f32_16x16x32_bf16 v[56:59], v[162:165], v[166:169], v[56:59]
	v_mfma_f32_16x16x32_bf16 v[52:55], v[154:157], v[174:177], v[52:55]
	v_mfma_f32_16x16x32_bf16 v[48:51], v[162:165], v[174:177], v[48:51]
	v_mfma_f32_16x16x32_bf16 v[44:47], v[154:157], v[182:185], v[44:47]
	v_mfma_f32_16x16x32_bf16 v[40:43], v[162:165], v[182:185], v[40:43]
	v_mfma_f32_16x16x32_bf16 v[36:39], v[154:157], v[190:193], v[36:39]
	v_mfma_f32_16x16x32_bf16 v[32:35], v[162:165], v[190:193], v[32:35]
	v_mfma_f32_16x16x32_bf16 v[60:63], v[158:161], v[170:173], v[60:63]
	v_mfma_f32_16x16x32_bf16 v[56:59], v[150:153], v[170:173], v[56:59]
	v_mfma_f32_16x16x32_bf16 v[52:55], v[158:161], v[178:181], v[52:55]
	v_mfma_f32_16x16x32_bf16 v[48:51], v[150:153], v[178:181], v[48:51]
	v_mfma_f32_16x16x32_bf16 v[44:47], v[158:161], v[186:189], v[44:47]
	v_mfma_f32_16x16x32_bf16 v[40:43], v[150:153], v[186:189], v[40:43]
	v_mfma_f32_16x16x32_bf16 v[36:39], v[158:161], v[194:197], v[36:39]
	v_mfma_f32_16x16x32_bf16 v[32:35], v[150:153], v[194:197], v[32:35]
	v_mfma_f32_16x16x32_bf16 v[28:31], v[198:201], v[166:169], v[28:31]
	v_mfma_f32_16x16x32_bf16 v[24:27], v[144:147], v[166:169], v[24:27]
	v_mfma_f32_16x16x32_bf16 v[20:23], v[198:201], v[174:177], v[20:23]
	v_mfma_f32_16x16x32_bf16 v[16:19], v[144:147], v[174:177], v[16:19]
	v_mfma_f32_16x16x32_bf16 v[12:15], v[198:201], v[182:185], v[12:15]
	v_mfma_f32_16x16x32_bf16 v[8:11], v[144:147], v[182:185], v[8:11]
	v_mfma_f32_16x16x32_bf16 v[4:7], v[198:201], v[190:193], v[4:7]
	v_mfma_f32_16x16x32_bf16 v[0:3], v[144:147], v[190:193], v[0:3]
	v_mfma_f32_16x16x32_bf16 v[28:31], v[202:205], v[170:173], v[28:31]
	v_mfma_f32_16x16x32_bf16 v[24:27], v[206:209], v[170:173], v[24:27]
	v_mfma_f32_16x16x32_bf16 v[20:23], v[202:205], v[178:181], v[20:23]
	v_mfma_f32_16x16x32_bf16 v[16:19], v[206:209], v[178:181], v[16:19]
	v_mfma_f32_16x16x32_bf16 v[12:15], v[202:205], v[186:189], v[12:15]
	v_mfma_f32_16x16x32_bf16 v[8:11], v[206:209], v[186:189], v[8:11]
	v_mfma_f32_16x16x32_bf16 v[4:7], v[202:205], v[194:197], v[4:7]
	v_mfma_f32_16x16x32_bf16 v[0:3], v[206:209], v[194:197], v[0:3]
	s_barrier
	ds_read_b128 v[144:147], v139
	ds_read_b128 v[148:151], v140
	ds_read_b128 v[152:155], v141
	ds_read_b128 v[140:143], v142
	ds_read_b128 v[156:159], v131 offset:32768
	ds_read_b128 v[160:163], v131 offset:33792
	ds_read_b128 v[164:167], v134 offset:32768
	ds_read_b128 v[168:171], v134 offset:33792
	ds_read_b128 v[172:175], v133 offset:32768
	ds_read_b128 v[176:179], v133 offset:33792
	ds_read_b128 v[180:183], v132 offset:32768
	ds_read_b128 v[184:187], v132 offset:33792
	s_waitcnt vmcnt(2)
	s_barrier
	s_waitcnt lgkmcnt(0)
	v_mfma_f32_16x16x32_bf16 v[124:127], v[144:147], v[156:159], v[124:127]
	v_mfma_f32_16x16x32_bf16 v[120:123], v[152:155], v[156:159], v[120:123]
	v_mfma_f32_16x16x32_bf16 v[116:119], v[144:147], v[164:167], v[116:119]
	v_mfma_f32_16x16x32_bf16 v[112:115], v[152:155], v[164:167], v[112:115]
	v_mfma_f32_16x16x32_bf16 v[108:111], v[144:147], v[172:175], v[108:111]
	v_mfma_f32_16x16x32_bf16 v[104:107], v[152:155], v[172:175], v[104:107]
	v_mfma_f32_16x16x32_bf16 v[100:103], v[144:147], v[180:183], v[100:103]
	v_mfma_f32_16x16x32_bf16 v[96:99], v[152:155], v[180:183], v[96:99]
	v_mfma_f32_16x16x32_bf16 v[124:127], v[148:151], v[160:163], v[124:127]
	v_mfma_f32_16x16x32_bf16 v[120:123], v[140:143], v[160:163], v[120:123]
	v_mfma_f32_16x16x32_bf16 v[116:119], v[148:151], v[168:171], v[116:119]
	v_mfma_f32_16x16x32_bf16 v[112:115], v[140:143], v[168:171], v[112:115]
	v_mfma_f32_16x16x32_bf16 v[108:111], v[148:151], v[176:179], v[108:111]
	v_mfma_f32_16x16x32_bf16 v[104:107], v[140:143], v[176:179], v[104:107]
	v_mfma_f32_16x16x32_bf16 v[100:103], v[148:151], v[184:187], v[100:103]
	v_mfma_f32_16x16x32_bf16 v[96:99], v[140:143], v[184:187], v[96:99]
	s_barrier
; #define LDA(dst, b, h) _Pragma("unroll") for (int m = 0; m < 4; ++m) _Pragma("unroll") for (int k = 0; k < 2; ++k) \
;     dst[m][k] = *reinterpret_cast<const bf16x8*>(SA(b, h) + lds_byte(wr * 64 + m * 16 + fr, k * 32 + fq * 8))
; #define LDB(dst, b, h) _Pragma("unroll") for (int n = 0; n < 2; ++n) _Pragma("unroll") for (int k = 0; k < 2; ++k) \
;     dst[n][k] = *reinterpret_cast<const bf16x8*>(SB(b, h) + lds_byte(wc * 32 + n * 16 + fr, k * 32 + fq * 8))
; #define WAIT_V(n) asm volatile("s_waitcnt vmcnt(" #n ")" ::: "memory")
; #define WAIT_L(n) asm volatile("s_waitcnt lgkmcnt(" #n ")" ::: "memory")
; #define BAR __builtin_amdgcn_s_barrier()
;     ...
;     { LDB(B0, 1, 0); LDA(At, 1, 0); WAIT_V(2); BAR; WAIT_L(0); MMA(0, 0, At, B0); BAR;
;       LDB(B1, 1, 1); WAIT_V(0); BAR; WAIT_L(0); MMA(0, 1, At, B1); BAR;
;       LDA(At, 1, 1); BAR; WAIT_L(0); MMA(1, 0, At, B0); MMA(1, 1, At, B1); BAR; }
;     if (wr == 0) BAR;
	ds_read_b128 v[188:191], v135
	ds_read_b128 v[192:195], v136
	ds_read_b128 v[196:199], v137
	ds_read_b128 v[136:139], v138
	s_waitcnt vmcnt(0)
	s_barrier
	s_waitcnt lgkmcnt(0)
	v_mfma_f32_16x16x32_bf16 v[92:95], v[188:191], v[156:159], v[92:95]
	v_mfma_f32_16x16x32_bf16 v[88:91], v[196:199], v[156:159], v[88:91]
	v_mfma_f32_16x16x32_bf16 v[84:87], v[188:191], v[164:167], v[84:87]
	v_mfma_f32_16x16x32_bf16 v[80:83], v[196:199], v[164:167], v[80:83]
	v_mfma_f32_16x16x32_bf16 v[76:79], v[188:191], v[172:175], v[76:79]
	v_mfma_f32_16x16x32_bf16 v[72:75], v[196:199], v[172:175], v[72:75]
	v_mfma_f32_16x16x32_bf16 v[68:71], v[188:191], v[180:183], v[68:71]
	v_mfma_f32_16x16x32_bf16 v[64:67], v[196:199], v[180:183], v[64:67]
	v_mfma_f32_16x16x32_bf16 v[92:95], v[192:195], v[160:163], v[92:95]
	v_mfma_f32_16x16x32_bf16 v[88:91], v[136:139], v[160:163], v[88:91]
	v_mfma_f32_16x16x32_bf16 v[84:87], v[192:195], v[168:171], v[84:87]
	v_mfma_f32_16x16x32_bf16 v[80:83], v[136:139], v[168:171], v[80:83]
	v_mfma_f32_16x16x32_bf16 v[76:79], v[192:195], v[176:179], v[76:79]
	v_mfma_f32_16x16x32_bf16 v[72:75], v[136:139], v[176:179], v[72:75]
	v_mfma_f32_16x16x32_bf16 v[68:71], v[192:195], v[184:187], v[68:71]
	v_mfma_f32_16x16x32_bf16 v[64:67], v[136:139], v[184:187], v[64:67]
	s_barrier
	ds_read_b128 v[156:159], v131 offset:49152
	ds_read_b128 v[160:163], v131 offset:50176
	ds_read_b128 v[164:167], v134 offset:49152
	ds_read_b128 v[168:171], v134 offset:50176
	ds_read_b128 v[172:175], v133 offset:49152
	ds_read_b128 v[176:179], v133 offset:50176
	ds_read_b128 v[180:183], v132 offset:49152
	ds_read_b128 v[132:135], v132 offset:50176
	s_barrier
	s_waitcnt lgkmcnt(0)
	v_mfma_f32_16x16x32_bf16 v[60:63], v[144:147], v[156:159], v[60:63]
	v_mfma_f32_16x16x32_bf16 v[56:59], v[152:155], v[156:159], v[56:59]
	v_mfma_f32_16x16x32_bf16 v[52:55], v[144:147], v[164:167], v[52:55]
	v_mfma_f32_16x16x32_bf16 v[48:51], v[152:155], v[164:167], v[48:51]
	v_mfma_f32_16x16x32_bf16 v[44:47], v[144:147], v[172:175], v[44:47]
	v_mfma_f32_16x16x32_bf16 v[40:43], v[152:155], v[172:175], v[40:43]
	v_mfma_f32_16x16x32_bf16 v[36:39], v[144:147], v[180:183], v[36:39]
	v_mfma_f32_16x16x32_bf16 v[32:35], v[152:155], v[180:183], v[32:35]
	v_mfma_f32_16x16x32_bf16 v[60:63], v[148:151], v[160:163], v[60:63]
	v_mfma_f32_16x16x32_bf16 v[56:59], v[140:143], v[160:163], v[56:59]
	v_mfma_f32_16x16x32_bf16 v[52:55], v[148:151], v[168:171], v[52:55]
	v_mfma_f32_16x16x32_bf16 v[48:51], v[140:143], v[168:171], v[48:51]
	v_mfma_f32_16x16x32_bf16 v[44:47], v[148:151], v[176:179], v[44:47]
	v_mfma_f32_16x16x32_bf16 v[40:43], v[140:143], v[176:179], v[40:43]
	v_mfma_f32_16x16x32_bf16 v[36:39], v[148:151], v[132:135], v[36:39]
	v_mfma_f32_16x16x32_bf16 v[32:35], v[140:143], v[132:135], v[32:35]
	v_mfma_f32_16x16x32_bf16 v[28:31], v[188:191], v[156:159], v[28:31]
	v_mfma_f32_16x16x32_bf16 v[24:27], v[196:199], v[156:159], v[24:27]
	v_mfma_f32_16x16x32_bf16 v[20:23], v[188:191], v[164:167], v[20:23]
	v_mfma_f32_16x16x32_bf16 v[16:19], v[196:199], v[164:167], v[16:19]
	v_mfma_f32_16x16x32_bf16 v[12:15], v[188:191], v[172:175], v[12:15]
	v_mfma_f32_16x16x32_bf16 v[8:11], v[196:199], v[172:175], v[8:11]
	v_mfma_f32_16x16x32_bf16 v[4:7], v[188:191], v[180:183], v[4:7]
	v_mfma_f32_16x16x32_bf16 v[0:3], v[196:199], v[180:183], v[0:3]
	v_mfma_f32_16x16x32_bf16 v[28:31], v[192:195], v[160:163], v[28:31]
	v_mfma_f32_16x16x32_bf16 v[24:27], v[136:139], v[160:163], v[24:27]
	v_mfma_f32_16x16x32_bf16 v[20:23], v[192:195], v[168:171], v[20:23]
	v_mfma_f32_16x16x32_bf16 v[16:19], v[136:139], v[168:171], v[16:19]
	v_mfma_f32_16x16x32_bf16 v[12:15], v[192:195], v[176:179], v[12:15]
	v_mfma_f32_16x16x32_bf16 v[8:11], v[136:139], v[176:179], v[8:11]
	v_mfma_f32_16x16x32_bf16 v[4:7], v[192:195], v[132:135], v[4:7]
	v_mfma_f32_16x16x32_bf16 v[0:3], v[136:139], v[132:135], v[0:3]
	v_cmp_gt_u32_e32 vcc, s35, v130
	s_barrier
	s_and_saveexec_b64 s[10:11], vcc
	s_cbranch_execz .LBB0_559
	s_barrier

; #define STAGE(P, RS, SOFF, OFF, kt) do { const int _so = (SOFF) + (kt) * (BK * 2); \
;     _Pragma("unroll") for (int _i = 0; _i < 2; ++_i) { \
;       __builtin_amdgcn_raw_ptr_buffer_load_lds(RS, (__attribute__((address_space(3))) void*)((P) + wave * 1024 + _i * 8192), 16, OFF[_i], _so, 0, 0); } } while (0)
; #define LDA(dst, b, h) _Pragma("unroll") for (int m = 0; m < 4; ++m) _Pragma("unroll") for (int k = 0; k < 2; ++k) \
;     dst[m][k] = *reinterpret_cast<const bf16x8*>(SA(b, h) + lds_byte(wr * 64 + m * 16 + fr, k * 32 + fq * 8))
; #define LDB(dst, b, h) _Pragma("unroll") for (int n = 0; n < 2; ++n) _Pragma("unroll") for (int k = 0; k < 2; ++k) \
;     dst[n][k] = *reinterpret_cast<const bf16x8*>(SB(b, h) + lds_byte(wc * 32 + n * 16 + fr, k * 32 + fq * 8))
; #define WAIT_V(n) asm volatile("s_waitcnt vmcnt(" #n ")" ::: "memory")
; #define WAIT_L(n) asm volatile("s_waitcnt lgkmcnt(" #n ")" ::: "memory")
; #define BAR __builtin_amdgcn_s_barrier()
; #define SCHED __builtin_amdgcn_sched_barrier(0)
;     ...
;     for (int t = 0; t < nt - 2; t += 2) {
;       LDB(B0, 0, 0); SCHED; LDA(At, 0, 0); STAGE(SA(1, 1), rsA, sA1, offA, t + 1);
;       WAIT_L(8); BAR; WAIT_L(0); MMA(0, 0, At, B0); BAR; SCHED;
;       LDB(B1, 0, 1); STAGE(SB(0, 0), rsB, sB0, offB, t + 2);
;       BAR; WAIT_L(0); MMA(0, 1, At, B1); BAR;
;       LDA(At, 0, 1); STAGE(SA(0, 0), rsA, sA0, offA, t + 2);
;       BAR; WAIT_L(0); MMA(1, 0, At, B0); BAR; SCHED;
;       STAGE(SB(0, 1), rsB, sB1, offB, t + 2);
;       WAIT_V(6); BAR; MMA(1, 1, At, B1); BAR;
.LBB0_657:
	ds_read_b128 v[152:155], v147
	ds_read_b128 v[156:159], v148
	ds_read_b128 v[160:163], v149
	ds_read_b128 v[164:167], v150
	s_add_i32 s5, s81, s3
	s_add_i32 s6, s5, 0x80
	s_mov_b32 m0, s39
	ds_read_b128 v[168:171], v129
	ds_read_b128 v[172:175], v129 offset:1024
	ds_read_b128 v[176:179], v132
	ds_read_b128 v[180:183], v132 offset:1024
	ds_read_b128 v[184:187], v131
	ds_read_b128 v[188:191], v131 offset:1024
	ds_read_b128 v[192:195], v130
	ds_read_b128 v[196:199], v130 offset:1024
	buffer_load_dwordx4 v141, s[8:11], s6 offen lds
	s_mov_b32 m0, s58
	s_nop 0
	buffer_load_dwordx4 v142, s[8:11], s6 offen lds
	s_waitcnt lgkmcnt(8)
	s_barrier
	s_waitcnt lgkmcnt(0)
	v_mfma_f32_16x16x32_bf16 v[124:127], v[152:155], v[168:171], v[124:127]
	v_mfma_f32_16x16x32_bf16 v[120:123], v[160:163], v[168:171], v[120:123]
	v_mfma_f32_16x16x32_bf16 v[116:119], v[152:155], v[176:179], v[116:119]
	v_mfma_f32_16x16x32_bf16 v[112:115], v[160:163], v[176:179], v[112:115]
	v_mfma_f32_16x16x32_bf16 v[108:111], v[152:155], v[184:187], v[108:111]
	v_mfma_f32_16x16x32_bf16 v[104:107], v[160:163], v[184:187], v[104:107]
	v_mfma_f32_16x16x32_bf16 v[100:103], v[152:155], v[192:195], v[100:103]
	v_mfma_f32_16x16x32_bf16 v[96:99], v[160:163], v[192:195], v[96:99]
	v_mfma_f32_16x16x32_bf16 v[124:127], v[156:159], v[172:175], v[124:127]
	v_mfma_f32_16x16x32_bf16 v[120:123], v[164:167], v[172:175], v[120:123]
	v_mfma_f32_16x16x32_bf16 v[116:119], v[156:159], v[180:183], v[116:119]
	v_mfma_f32_16x16x32_bf16 v[112:115], v[164:167], v[180:183], v[112:115]
	v_mfma_f32_16x16x32_bf16 v[108:111], v[156:159], v[188:191], v[108:111]
	v_mfma_f32_16x16x32_bf16 v[104:107], v[164:167], v[188:191], v[104:107]
	v_mfma_f32_16x16x32_bf16 v[100:103], v[156:159], v[196:199], v[100:103]
	v_mfma_f32_16x16x32_bf16 v[96:99], v[164:167], v[196:199], v[96:99]
	s_barrier
	s_add_i32 s6, s83, s3
	s_add_i32 s7, s6, 0x100
	s_mov_b32 s14, s10
	s_mov_b32 s15, s11
	s_mov_b32 m0, s85
	ds_read_b128 v[200:203], v143
	ds_read_b128 v[204:207], v144
	ds_read_b128 v[208:211], v145
	ds_read_b128 v[212:215], v146
	buffer_load_dwordx4 v141, s[12:15], s7 offen lds
	s_mov_b32 m0, s75
	s_nop 0
	buffer_load_dwordx4 v142, s[12:15], s7 offen lds
	s_barrier
	s_waitcnt lgkmcnt(0)
	v_mfma_f32_16x16x32_bf16 v[92:95], v[200:203], v[168:171], v[92:95]
	v_mfma_f32_16x16x32_bf16 v[88:91], v[208:211], v[168:171], v[88:91]
	v_mfma_f32_16x16x32_bf16 v[80:83], v[200:203], v[176:179], v[80:83]
	v_mfma_f32_16x16x32_bf16 v[68:71], v[208:211], v[176:179], v[68:71]
	v_mfma_f32_16x16x32_bf16 v[60:63], v[200:203], v[184:187], v[60:63]
	v_mfma_f32_16x16x32_bf16 v[56:59], v[208:211], v[184:187], v[56:59]
	v_mfma_f32_16x16x32_bf16 v[52:55], v[200:203], v[192:195], v[52:55]
	v_mfma_f32_16x16x32_bf16 v[48:51], v[208:211], v[192:195], v[48:51]
	v_mfma_f32_16x16x32_bf16 v[92:95], v[204:207], v[172:175], v[92:95]
	v_mfma_f32_16x16x32_bf16 v[88:91], v[212:215], v[172:175], v[88:91]
	v_mfma_f32_16x16x32_bf16 v[80:83], v[204:207], v[180:183], v[80:83]
	v_mfma_f32_16x16x32_bf16 v[68:71], v[212:215], v[180:183], v[68:71]
	v_mfma_f32_16x16x32_bf16 v[60:63], v[204:207], v[188:191], v[60:63]
	v_mfma_f32_16x16x32_bf16 v[56:59], v[212:215], v[188:191], v[56:59]
	v_mfma_f32_16x16x32_bf16 v[52:55], v[204:207], v[196:199], v[52:55]
	v_mfma_f32_16x16x32_bf16 v[48:51], v[212:215], v[196:199], v[48:51]
	s_barrier
	s_add_i32 s7, s82, s3
	s_add_i32 s22, s7, 0x100
	s_mov_b32 m0, s38
	ds_read_b128 v[168:171], v129 offset:16384
	ds_read_b128 v[172:175], v129 offset:17408
	ds_read_b128 v[176:179], v132 offset:16384
	ds_read_b128 v[180:183], v132 offset:17408
	ds_read_b128 v[184:187], v131 offset:16384
	ds_read_b128 v[188:191], v131 offset:17408
	ds_read_b128 v[192:195], v130 offset:16384
	ds_read_b128 v[196:199], v130 offset:17408
	buffer_load_dwordx4 v141, s[8:11], s22 offen lds
	s_mov_b32 m0, s95
	s_nop 0
	buffer_load_dwordx4 v142, s[8:11], s22 offen lds
	s_barrier
	s_waitcnt lgkmcnt(0)
	v_mfma_f32_16x16x32_bf16 v[44:47], v[152:155], v[168:171], v[44:47]
	v_mfma_f32_16x16x32_bf16 v[40:43], v[160:163], v[168:171], v[40:43]
	v_mfma_f32_16x16x32_bf16 v[36:39], v[152:155], v[176:179], v[36:39]
	v_mfma_f32_16x16x32_bf16 v[32:35], v[160:163], v[176:179], v[32:35]
	v_mfma_f32_16x16x32_bf16 v[28:31], v[152:155], v[184:187], v[28:31]
	v_mfma_f32_16x16x32_bf16 v[24:27], v[160:163], v[184:187], v[24:27]
	v_mfma_f32_16x16x32_bf16 v[20:23], v[152:155], v[192:195], v[20:23]
	v_mfma_f32_16x16x32_bf16 v[16:19], v[160:163], v[192:195], v[16:19]
	v_mfma_f32_16x16x32_bf16 v[44:47], v[156:159], v[172:175], v[44:47]
	v_mfma_f32_16x16x32_bf16 v[40:43], v[164:167], v[172:175], v[40:43]
	v_mfma_f32_16x16x32_bf16 v[36:39], v[156:159], v[180:183], v[36:39]
	v_mfma_f32_16x16x32_bf16 v[32:35], v[164:167], v[180:183], v[32:35]
	v_mfma_f32_16x16x32_bf16 v[28:31], v[156:159], v[188:191], v[28:31]
	v_mfma_f32_16x16x32_bf16 v[24:27], v[164:167], v[188:191], v[24:27]
	v_mfma_f32_16x16x32_bf16 v[20:23], v[156:159], v[196:199], v[20:23]
	v_mfma_f32_16x16x32_bf16 v[16:19], v[164:167], v[196:199], v[16:19]
	s_barrier
	s_add_i32 s22, s84, s3
	s_add_i32 s23, s22, 0x100
	s_mov_b32 m0, s86
	s_nop 0
	buffer_load_dwordx4 v141, s[12:15], s23 offen lds
	s_mov_b32 m0, s28
	s_nop 0
	buffer_load_dwordx4 v142, s[12:15], s23 offen lds
	s_waitcnt vmcnt(6)
	s_barrier
; #define STAGE(P, RS, SOFF, OFF, kt) do { const int _so = (SOFF) + (kt) * (BK * 2); \
;     _Pragma("unroll") for (int _i = 0; _i < 2; ++_i) { \
;       __builtin_amdgcn_raw_ptr_buffer_load_lds(RS, (__attribute__((address_space(3))) void*)((P) + wave * 1024 + _i * 8192), 16, OFF[_i], _so, 0, 0); } } while (0)
; #define LDA(dst, b, h) _Pragma("unroll") for (int m = 0; m < 4; ++m) _Pragma("unroll") for (int k = 0; k < 2; ++k) \
;     dst[m][k] = *reinterpret_cast<const bf16x8*>(SA(b, h) + lds_byte(wr * 64 + m * 16 + fr, k * 32 + fq * 8))
; #define LDB(dst, b, h) _Pragma("unroll") for (int n = 0; n < 2; ++n) _Pragma("unroll") for (int k = 0; k < 2; ++k) \
;     dst[n][k] = *reinterpret_cast<const bf16x8*>(SB(b, h) + lds_byte(wc * 32 + n * 16 + fr, k * 32 + fq * 8))
; #define WAIT_V(n) asm volatile("s_waitcnt vmcnt(" #n ")" ::: "memory")
; #define WAIT_L(n) asm volatile("s_waitcnt lgkmcnt(" #n ")" ::: "memory")
; #define BAR __builtin_amdgcn_s_barrier()
; #define SCHED __builtin_amdgcn_sched_barrier(0)
;     ...
;       WAIT_V(6); BAR; MMA(1, 1, At, B1); BAR;
;       LDB(B0, 1, 0); SCHED; LDA(At, 1, 0); STAGE(SA(0, 1), rsA, sA1, offA, t + 2);
;       WAIT_L(8); BAR; WAIT_L(0); MMA(0, 0, At, B0); BAR; SCHED;
;       LDB(B1, 1, 1); STAGE(SB(1, 0), rsB, sB0, offB, t + 3);
;       BAR; WAIT_L(0); MMA(0, 1, At, B1); BAR;
;       LDA(At, 1, 1); STAGE(SA(1, 0), rsA, sA0, offA, t + 3);
;       BAR; WAIT_L(0); MMA(1, 0, At, B0); BAR; SCHED;
;       STAGE(SB(1, 1), rsB, sB1, offB, t + 3);
;       WAIT_V(6); BAR; MMA(1, 1, At, B1); BAR;
	v_mfma_f32_16x16x32_bf16 v[12:15], v[200:203], v[168:171], v[12:15]
	v_mfma_f32_16x16x32_bf16 v[8:11], v[208:211], v[168:171], v[8:11]
	v_mfma_f32_16x16x32_bf16 v[4:7], v[200:203], v[176:179], v[4:7]
	v_mfma_f32_16x16x32_bf16 v[0:3], v[208:211], v[176:179], v[0:3]
	v_mfma_f32_16x16x32_bf16 v[64:67], v[200:203], v[184:187], v[64:67]
	v_mfma_f32_16x16x32_bf16 v[72:75], v[208:211], v[184:187], v[72:75]
	v_mfma_f32_16x16x32_bf16 v[76:79], v[200:203], v[192:195], v[76:79]
	v_mfma_f32_16x16x32_bf16 v[84:87], v[208:211], v[192:195], v[84:87]
	v_mfma_f32_16x16x32_bf16 v[12:15], v[204:207], v[172:175], v[12:15]
	v_mfma_f32_16x16x32_bf16 v[8:11], v[212:215], v[172:175], v[8:11]
	v_mfma_f32_16x16x32_bf16 v[4:7], v[204:207], v[180:183], v[4:7]
	v_mfma_f32_16x16x32_bf16 v[0:3], v[212:215], v[180:183], v[0:3]
	v_mfma_f32_16x16x32_bf16 v[64:67], v[204:207], v[188:191], v[64:67]
	v_mfma_f32_16x16x32_bf16 v[72:75], v[212:215], v[188:191], v[72:75]
	v_mfma_f32_16x16x32_bf16 v[76:79], v[204:207], v[196:199], v[76:79]
	v_mfma_f32_16x16x32_bf16 v[84:87], v[212:215], v[196:199], v[84:87]
	s_barrier
	ds_read_b128 v[152:155], v137
	ds_read_b128 v[156:159], v138
	ds_read_b128 v[160:163], v139
	ds_read_b128 v[164:167], v140
	s_addk_i32 s5, 0x100
	s_mov_b32 m0, s87
	ds_read_b128 v[168:171], v129 offset:32768
	ds_read_b128 v[172:175], v129 offset:33792
	ds_read_b128 v[176:179], v132 offset:32768
	ds_read_b128 v[180:183], v132 offset:33792
	ds_read_b128 v[184:187], v131 offset:32768
	ds_read_b128 v[188:191], v131 offset:33792
	ds_read_b128 v[192:195], v130 offset:32768
	ds_read_b128 v[196:199], v130 offset:33792
	buffer_load_dwordx4 v141, s[8:11], s5 offen lds
	s_mov_b32 m0, s97
	s_nop 0
	buffer_load_dwordx4 v142, s[8:11], s5 offen lds
	s_waitcnt lgkmcnt(8)
	s_barrier
	s_waitcnt lgkmcnt(0)
	v_mfma_f32_16x16x32_bf16 v[124:127], v[152:155], v[168:171], v[124:127]
	v_mfma_f32_16x16x32_bf16 v[120:123], v[160:163], v[168:171], v[120:123]
	v_mfma_f32_16x16x32_bf16 v[116:119], v[152:155], v[176:179], v[116:119]
	v_mfma_f32_16x16x32_bf16 v[112:115], v[160:163], v[176:179], v[112:115]
	v_mfma_f32_16x16x32_bf16 v[108:111], v[152:155], v[184:187], v[108:111]
	v_mfma_f32_16x16x32_bf16 v[104:107], v[160:163], v[184:187], v[104:107]
	v_mfma_f32_16x16x32_bf16 v[100:103], v[152:155], v[192:195], v[100:103]
	v_mfma_f32_16x16x32_bf16 v[96:99], v[160:163], v[192:195], v[96:99]
	v_mfma_f32_16x16x32_bf16 v[124:127], v[156:159], v[172:175], v[124:127]
	v_mfma_f32_16x16x32_bf16 v[120:123], v[164:167], v[172:175], v[120:123]
	v_mfma_f32_16x16x32_bf16 v[116:119], v[156:159], v[180:183], v[116:119]
	v_mfma_f32_16x16x32_bf16 v[112:115], v[164:167], v[180:183], v[112:115]
	v_mfma_f32_16x16x32_bf16 v[108:111], v[156:159], v[188:191], v[108:111]
	v_mfma_f32_16x16x32_bf16 v[104:107], v[164:167], v[188:191], v[104:107]
	v_mfma_f32_16x16x32_bf16 v[100:103], v[156:159], v[196:199], v[100:103]
	v_mfma_f32_16x16x32_bf16 v[96:99], v[164:167], v[196:199], v[96:99]
	s_barrier
	s_addk_i32 s6, 0x180
	s_mov_b32 m0, s92
	ds_read_b128 v[200:203], v133
	ds_read_b128 v[204:207], v134
	ds_read_b128 v[208:211], v135
	ds_read_b128 v[212:215], v136
	buffer_load_dwordx4 v141, s[12:15], s6 offen lds
	s_mov_b32 m0, s29
	s_nop 0
	buffer_load_dwordx4 v142, s[12:15], s6 offen lds
	s_barrier
	s_waitcnt lgkmcnt(0)
	v_mfma_f32_16x16x32_bf16 v[92:95], v[200:203], v[168:171], v[92:95]
	v_mfma_f32_16x16x32_bf16 v[88:91], v[208:211], v[168:171], v[88:91]
	v_mfma_f32_16x16x32_bf16 v[80:83], v[200:203], v[176:179], v[80:83]
	v_mfma_f32_16x16x32_bf16 v[68:71], v[208:211], v[176:179], v[68:71]
	v_mfma_f32_16x16x32_bf16 v[60:63], v[200:203], v[184:187], v[60:63]
	v_mfma_f32_16x16x32_bf16 v[56:59], v[208:211], v[184:187], v[56:59]
	v_mfma_f32_16x16x32_bf16 v[52:55], v[200:203], v[192:195], v[52:55]
	v_mfma_f32_16x16x32_bf16 v[48:51], v[208:211], v[192:195], v[48:51]
	v_mfma_f32_16x16x32_bf16 v[92:95], v[204:207], v[172:175], v[92:95]
	v_mfma_f32_16x16x32_bf16 v[88:91], v[212:215], v[172:175], v[88:91]
	v_mfma_f32_16x16x32_bf16 v[80:83], v[204:207], v[180:183], v[80:83]
	v_mfma_f32_16x16x32_bf16 v[68:71], v[212:215], v[180:183], v[68:71]
	v_mfma_f32_16x16x32_bf16 v[60:63], v[204:207], v[188:191], v[60:63]
	v_mfma_f32_16x16x32_bf16 v[56:59], v[212:215], v[188:191], v[56:59]
	v_mfma_f32_16x16x32_bf16 v[52:55], v[204:207], v[196:199], v[52:55]
	v_mfma_f32_16x16x32_bf16 v[48:51], v[212:215], v[196:199], v[48:51]
	s_barrier
	s_addk_i32 s7, 0x180
	s_mov_b32 m0, s93
	ds_read_b128 v[168:171], v129 offset:49152
	ds_read_b128 v[172:175], v129 offset:50176
	ds_read_b128 v[176:179], v132 offset:49152
	ds_read_b128 v[180:183], v132 offset:50176
	ds_read_b128 v[184:187], v131 offset:49152
	ds_read_b128 v[188:191], v131 offset:50176
	ds_read_b128 v[192:195], v130 offset:49152
	ds_read_b128 v[196:199], v130 offset:50176
	buffer_load_dwordx4 v141, s[8:11], s7 offen lds
	s_mov_b32 m0, s56
	s_nop 0
	buffer_load_dwordx4 v142, s[8:11], s7 offen lds
	s_barrier
	s_waitcnt lgkmcnt(0)
	v_mfma_f32_16x16x32_bf16 v[44:47], v[152:155], v[168:171], v[44:47]
	v_mfma_f32_16x16x32_bf16 v[40:43], v[160:163], v[168:171], v[40:43]
	v_mfma_f32_16x16x32_bf16 v[36:39], v[152:155], v[176:179], v[36:39]
	v_mfma_f32_16x16x32_bf16 v[32:35], v[160:163], v[176:179], v[32:35]
	v_mfma_f32_16x16x32_bf16 v[28:31], v[152:155], v[184:187], v[28:31]
	v_mfma_f32_16x16x32_bf16 v[24:27], v[160:163], v[184:187], v[24:27]
	v_mfma_f32_16x16x32_bf16 v[20:23], v[152:155], v[192:195], v[20:23]
	v_mfma_f32_16x16x32_bf16 v[16:19], v[160:163], v[192:195], v[16:19]
	v_mfma_f32_16x16x32_bf16 v[44:47], v[156:159], v[172:175], v[44:47]
	v_mfma_f32_16x16x32_bf16 v[40:43], v[164:167], v[172:175], v[40:43]
	v_mfma_f32_16x16x32_bf16 v[36:39], v[156:159], v[180:183], v[36:39]
	v_mfma_f32_16x16x32_bf16 v[32:35], v[164:167], v[180:183], v[32:35]
	v_mfma_f32_16x16x32_bf16 v[28:31], v[156:159], v[188:191], v[28:31]
	v_mfma_f32_16x16x32_bf16 v[24:27], v[164:167], v[188:191], v[24:27]
	v_mfma_f32_16x16x32_bf16 v[20:23], v[156:159], v[196:199], v[20:23]
	v_mfma_f32_16x16x32_bf16 v[16:19], v[164:167], v[196:199], v[16:19]
	s_barrier
; #define STAGE(P, RS, SOFF, OFF, kt) do { const int _so = (SOFF) + (kt) * (BK * 2); \
;     _Pragma("unroll") for (int _i = 0; _i < 2; ++_i) { \
;       __builtin_amdgcn_raw_ptr_buffer_load_lds(RS, (__attribute__((address_space(3))) void*)((P) + wave * 1024 + _i * 8192), 16, OFF[_i], _so, 0, 0); } } while (0)
; #define LDA(dst, b, h) _Pragma("unroll") for (int m = 0; m < 4; ++m) _Pragma("unroll") for (int k = 0; k < 2; ++k) \
;     dst[m][k] = *reinterpret_cast<const bf16x8*>(SA(b, h) + lds_byte(wr * 64 + m * 16 + fr, k * 32 + fq * 8))
; #define LDB(dst, b, h) _Pragma("unroll") for (int n = 0; n < 2; ++n) _Pragma("unroll") for (int k = 0; k < 2; ++k) \
;     dst[n][k] = *reinterpret_cast<const bf16x8*>(SB(b, h) + lds_byte(wc * 32 + n * 16 + fr, k * 32 + fq * 8))
; #define WAIT_V(n) asm volatile("s_waitcnt vmcnt(" #n ")" ::: "memory")
; #define WAIT_L(n) asm volatile("s_waitcnt lgkmcnt(" #n ")" ::: "memory")
; #define BAR __builtin_amdgcn_s_barrier()
;     ...
;       WAIT_V(6); BAR; MMA(1, 1, At, B1); BAR;
;     }
;     { LDB(B0, 0, 0); LDA(At, 0, 0); STAGE(SA(1, 1), rsA, sA1, offA, nt - 1);
;       BAR; WAIT_L(0); MMA(0, 0, At, B0); BAR;
;       LDB(B1, 0, 1); BAR; WAIT_L(0); MMA(0, 1, At, B1); BAR;
;       LDA(At, 0, 1); WAIT_V(4); BAR; WAIT_L(0); MMA(1, 0, At, B0); MMA(1, 1, At, B1); BAR; }
	s_addk_i32 s22, 0x180
	s_mov_b32 m0, s94
	s_nop 0
	buffer_load_dwordx4 v141, s[12:15], s22 offen lds
	s_mov_b32 m0, s57
	s_nop 0
	buffer_load_dwordx4 v142, s[12:15], s22 offen lds
	s_waitcnt vmcnt(6)
	s_barrier
	v_mfma_f32_16x16x32_bf16 v[12:15], v[200:203], v[168:171], v[12:15]
	v_mfma_f32_16x16x32_bf16 v[8:11], v[208:211], v[168:171], v[8:11]
	v_mfma_f32_16x16x32_bf16 v[4:7], v[200:203], v[176:179], v[4:7]
	v_mfma_f32_16x16x32_bf16 v[0:3], v[208:211], v[176:179], v[0:3]
	v_mfma_f32_16x16x32_bf16 v[64:67], v[200:203], v[184:187], v[64:67]
	v_mfma_f32_16x16x32_bf16 v[72:75], v[208:211], v[184:187], v[72:75]
	v_mfma_f32_16x16x32_bf16 v[76:79], v[200:203], v[192:195], v[76:79]
	v_mfma_f32_16x16x32_bf16 v[84:87], v[208:211], v[192:195], v[84:87]
	v_mfma_f32_16x16x32_bf16 v[12:15], v[204:207], v[172:175], v[12:15]
	v_mfma_f32_16x16x32_bf16 v[8:11], v[212:215], v[172:175], v[8:11]
	v_mfma_f32_16x16x32_bf16 v[4:7], v[204:207], v[180:183], v[4:7]
	v_mfma_f32_16x16x32_bf16 v[0:3], v[212:215], v[180:183], v[0:3]
	v_mfma_f32_16x16x32_bf16 v[64:67], v[204:207], v[188:191], v[64:67]
	v_mfma_f32_16x16x32_bf16 v[72:75], v[212:215], v[188:191], v[72:75]
	v_mfma_f32_16x16x32_bf16 v[76:79], v[204:207], v[196:199], v[76:79]
	v_mfma_f32_16x16x32_bf16 v[84:87], v[212:215], v[196:199], v[84:87]
	s_barrier
	s_add_i32 s1, s1, 2
	s_addk_i32 s3, 0x100
	s_cmp_gt_u32 s1, 27
	s_cbranch_scc0 .LBB0_657
	s_add_i32 s1, s81, 0xf80
	s_mov_b32 m0, s39
	ds_read_b128 v[152:155], v147
	ds_read_b128 v[156:159], v148
	ds_read_b128 v[160:163], v149
	ds_read_b128 v[148:151], v150
	ds_read_b128 v[164:167], v129
	ds_read_b128 v[168:171], v129 offset:1024
	ds_read_b128 v[172:175], v132
	ds_read_b128 v[176:179], v132 offset:1024
	ds_read_b128 v[180:183], v131
	ds_read_b128 v[184:187], v131 offset:1024
	ds_read_b128 v[188:191], v130
	ds_read_b128 v[192:195], v130 offset:1024
	buffer_load_dwordx4 v141, s[8:11], s1 offen lds
	s_mov_b32 m0, s58
	s_nop 0
	buffer_load_dwordx4 v142, s[8:11], s1 offen lds
	s_barrier
	s_waitcnt lgkmcnt(0)
	v_mfma_f32_16x16x32_bf16 v[124:127], v[152:155], v[164:167], v[124:127]
	v_mfma_f32_16x16x32_bf16 v[120:123], v[160:163], v[164:167], v[120:123]
	v_mfma_f32_16x16x32_bf16 v[116:119], v[152:155], v[172:175], v[116:119]
	v_mfma_f32_16x16x32_bf16 v[112:115], v[160:163], v[172:175], v[112:115]
	v_mfma_f32_16x16x32_bf16 v[108:111], v[152:155], v[180:183], v[108:111]
	v_mfma_f32_16x16x32_bf16 v[104:107], v[160:163], v[180:183], v[104:107]
	v_mfma_f32_16x16x32_bf16 v[100:103], v[152:155], v[188:191], v[100:103]
	v_mfma_f32_16x16x32_bf16 v[96:99], v[160:163], v[188:191], v[96:99]
	v_mfma_f32_16x16x32_bf16 v[124:127], v[156:159], v[168:171], v[124:127]
	v_mfma_f32_16x16x32_bf16 v[120:123], v[148:151], v[168:171], v[120:123]
	v_mfma_f32_16x16x32_bf16 v[116:119], v[156:159], v[176:179], v[116:119]
	v_mfma_f32_16x16x32_bf16 v[112:115], v[148:151], v[176:179], v[112:115]
	v_mfma_f32_16x16x32_bf16 v[108:111], v[156:159], v[184:187], v[108:111]
	v_mfma_f32_16x16x32_bf16 v[104:107], v[148:151], v[184:187], v[104:107]
	v_mfma_f32_16x16x32_bf16 v[100:103], v[156:159], v[192:195], v[100:103]
	v_mfma_f32_16x16x32_bf16 v[96:99], v[148:151], v[192:195], v[96:99]
	s_barrier
	ds_read_b128 v[196:199], v143
	ds_read_b128 v[200:203], v144
	ds_read_b128 v[142:145], v145
	ds_read_b128 v[204:207], v146
	s_barrier
	s_waitcnt lgkmcnt(0)
	v_mfma_f32_16x16x32_bf16 v[88:91], v[142:145], v[164:167], v[88:91]
	v_mfma_f32_16x16x32_bf16 v[80:83], v[196:199], v[172:175], v[80:83]
	v_mfma_f32_16x16x32_bf16 v[60:63], v[196:199], v[180:183], v[60:63]
	v_mfma_f32_16x16x32_bf16 v[56:59], v[142:145], v[180:183], v[56:59]
	v_mfma_f32_16x16x32_bf16 v[52:55], v[196:199], v[188:191], v[52:55]
	v_mfma_f32_16x16x32_bf16 v[48:51], v[142:145], v[188:191], v[48:51]
	v_mfma_f32_16x16x32_bf16 v[92:95], v[196:199], v[164:167], v[92:95]
	v_mfma_f32_16x16x32_bf16 v[68:71], v[142:145], v[172:175], v[68:71]
	v_mfma_f32_16x16x32_bf16 v[88:91], v[204:207], v[168:171], v[88:91]
	v_mfma_f32_16x16x32_bf16 v[80:83], v[200:203], v[176:179], v[80:83]
	v_mfma_f32_16x16x32_bf16 v[60:63], v[200:203], v[184:187], v[60:63]
	v_mfma_f32_16x16x32_bf16 v[56:59], v[204:207], v[184:187], v[56:59]
	v_mfma_f32_16x16x32_bf16 v[52:55], v[200:203], v[192:195], v[52:55]
	v_mfma_f32_16x16x32_bf16 v[48:51], v[204:207], v[192:195], v[48:51]
	v_mfma_f32_16x16x32_bf16 v[164:167], v[200:203], v[168:171], v[92:95]
	v_mfma_f32_16x16x32_bf16 v[168:171], v[204:207], v[176:179], v[68:71]
	s_barrier
	s_nop 0
	ds_read_b128 v[68:71], v129 offset:16384
	ds_read_b128 v[92:95], v129 offset:17408
	ds_read_b128 v[172:175], v132 offset:16384
	ds_read_b128 v[176:179], v132 offset:17408
	ds_read_b128 v[180:183], v131 offset:16384
	ds_read_b128 v[184:187], v131 offset:17408
	ds_read_b128 v[188:191], v130 offset:16384
	ds_read_b128 v[192:195], v130 offset:17408
	s_waitcnt vmcnt(4)
	s_barrier
; #define LDA(dst, b, h) _Pragma("unroll") for (int m = 0; m < 4; ++m) _Pragma("unroll") for (int k = 0; k < 2; ++k) \
;     dst[m][k] = *reinterpret_cast<const bf16x8*>(SA(b, h) + lds_byte(wr * 64 + m * 16 + fr, k * 32 + fq * 8))
; #define LDB(dst, b, h) _Pragma("unroll") for (int n = 0; n < 2; ++n) _Pragma("unroll") for (int k = 0; k < 2; ++k) \
;     dst[n][k] = *reinterpret_cast<const bf16x8*>(SB(b, h) + lds_byte(wc * 32 + n * 16 + fr, k * 32 + fq * 8))
; #define WAIT_V(n) asm volatile("s_waitcnt vmcnt(" #n ")" ::: "memory")
; #define WAIT_L(n) asm volatile("s_waitcnt lgkmcnt(" #n ")" ::: "memory")
; #define BAR __builtin_amdgcn_s_barrier()
;     ...
;       LDA(At, 0, 1); WAIT_V(4); BAR; WAIT_L(0); MMA(1, 0, At, B0); MMA(1, 1, At, B1); BAR; }
;     { LDB(B0, 1, 0); LDA(At, 1, 0); WAIT_V(2); BAR; WAIT_L(0); MMA(0, 0, At, B0); BAR;
	s_waitcnt lgkmcnt(0)
	v_mfma_f32_16x16x32_bf16 v[44:47], v[152:155], v[68:71], v[44:47]
	v_mfma_f32_16x16x32_bf16 v[40:43], v[160:163], v[68:71], v[40:43]
	v_mfma_f32_16x16x32_bf16 v[36:39], v[152:155], v[172:175], v[36:39]
	v_mfma_f32_16x16x32_bf16 v[32:35], v[160:163], v[172:175], v[32:35]
	v_mfma_f32_16x16x32_bf16 v[28:31], v[152:155], v[180:183], v[28:31]
	v_mfma_f32_16x16x32_bf16 v[24:27], v[160:163], v[180:183], v[24:27]
	v_mfma_f32_16x16x32_bf16 v[20:23], v[152:155], v[188:191], v[20:23]
	v_mfma_f32_16x16x32_bf16 v[16:19], v[160:163], v[188:191], v[16:19]
	v_mfma_f32_16x16x32_bf16 v[44:47], v[156:159], v[92:95], v[44:47]
	v_mfma_f32_16x16x32_bf16 v[40:43], v[148:151], v[92:95], v[40:43]
	v_mfma_f32_16x16x32_bf16 v[36:39], v[156:159], v[176:179], v[36:39]
	v_mfma_f32_16x16x32_bf16 v[32:35], v[148:151], v[176:179], v[32:35]
	v_mfma_f32_16x16x32_bf16 v[28:31], v[156:159], v[184:187], v[28:31]
	v_mfma_f32_16x16x32_bf16 v[24:27], v[148:151], v[184:187], v[24:27]
	v_mfma_f32_16x16x32_bf16 v[20:23], v[156:159], v[192:195], v[20:23]
	v_mfma_f32_16x16x32_bf16 v[16:19], v[148:151], v[192:195], v[16:19]
	v_mfma_f32_16x16x32_bf16 v[4:7], v[196:199], v[172:175], v[4:7]
	v_mfma_f32_16x16x32_bf16 v[0:3], v[142:145], v[172:175], v[0:3]
	v_mfma_f32_16x16x32_bf16 v[12:15], v[196:199], v[68:71], v[12:15]
	v_mfma_f32_16x16x32_bf16 v[8:11], v[142:145], v[68:71], v[8:11]
	v_mfma_f32_16x16x32_bf16 v[64:67], v[196:199], v[180:183], v[64:67]
	v_mfma_f32_16x16x32_bf16 v[68:71], v[142:145], v[180:183], v[72:75]
	v_mfma_f32_16x16x32_bf16 v[72:75], v[196:199], v[188:191], v[76:79]
	v_mfma_f32_16x16x32_bf16 v[76:79], v[142:145], v[188:191], v[84:87]
	v_mfma_f32_16x16x32_bf16 v[4:7], v[200:203], v[176:179], v[4:7]
	v_mfma_f32_16x16x32_bf16 v[0:3], v[204:207], v[176:179], v[0:3]
	v_mfma_f32_16x16x32_bf16 v[142:145], v[200:203], v[92:95], v[12:15]
	v_mfma_f32_16x16x32_bf16 v[146:149], v[204:207], v[92:95], v[8:11]
	v_mfma_f32_16x16x32_bf16 v[150:153], v[200:203], v[184:187], v[64:67]
	v_mfma_f32_16x16x32_bf16 v[154:157], v[204:207], v[184:187], v[68:71]
	v_mfma_f32_16x16x32_bf16 v[158:161], v[200:203], v[192:195], v[72:75]
	v_mfma_f32_16x16x32_bf16 v[172:175], v[204:207], v[192:195], v[76:79]
	s_barrier
	ds_read_b128 v[8:11], v137
	ds_read_b128 v[12:15], v138
	ds_read_b128 v[176:179], v139
	ds_read_b128 v[138:141], v140
	ds_read_b128 v[64:67], v129 offset:32768
	ds_read_b128 v[72:75], v129 offset:33792
	ds_read_b128 v[180:183], v132 offset:32768
	ds_read_b128 v[184:187], v132 offset:33792
	ds_read_b128 v[188:191], v131 offset:32768
	ds_read_b128 v[192:195], v131 offset:33792
	ds_read_b128 v[196:199], v130 offset:32768
	ds_read_b128 v[200:203], v130 offset:33792
	s_waitcnt vmcnt(2)
	s_barrier
	s_waitcnt lgkmcnt(0)
	v_mfma_f32_16x16x32_bf16 v[68:71], v[8:11], v[64:67], v[124:127]
	v_mfma_f32_16x16x32_bf16 v[76:79], v[176:179], v[64:67], v[120:123]
	v_mfma_f32_16x16x32_bf16 v[84:87], v[8:11], v[180:183], v[116:119]
	v_mfma_f32_16x16x32_bf16 v[92:95], v[176:179], v[180:183], v[112:115]
	v_mfma_f32_16x16x32_bf16 v[112:115], v[8:11], v[188:191], v[108:111]
	v_mfma_f32_16x16x32_bf16 v[104:107], v[176:179], v[188:191], v[104:107]
	v_mfma_f32_16x16x32_bf16 v[120:123], v[8:11], v[196:199], v[100:103]
	v_mfma_f32_16x16x32_bf16 v[96:99], v[176:179], v[196:199], v[96:99]
	v_mfma_f32_16x16x32_bf16 v[124:127], v[12:15], v[72:75], v[68:71]
	v_mfma_f32_16x16x32_bf16 v[116:119], v[138:141], v[72:75], v[76:79]
	v_mfma_f32_16x16x32_bf16 v[108:111], v[12:15], v[184:187], v[84:87]
	v_mfma_f32_16x16x32_bf16 v[100:103], v[138:141], v[184:187], v[92:95]
	v_mfma_f32_16x16x32_bf16 v[92:95], v[12:15], v[192:195], v[112:115]
	v_mfma_f32_16x16x32_bf16 v[84:87], v[138:141], v[192:195], v[104:107]
	v_mfma_f32_16x16x32_bf16 v[76:79], v[12:15], v[200:203], v[120:123]
	v_mfma_f32_16x16x32_bf16 v[68:71], v[138:141], v[200:203], v[96:99]
	s_barrier
; #define LDA(dst, b, h) _Pragma("unroll") for (int m = 0; m < 4; ++m) _Pragma("unroll") for (int k = 0; k < 2; ++k) \
;     dst[m][k] = *reinterpret_cast<const bf16x8*>(SA(b, h) + lds_byte(wr * 64 + m * 16 + fr, k * 32 + fq * 8))
; #define LDB(dst, b, h) _Pragma("unroll") for (int n = 0; n < 2; ++n) _Pragma("unroll") for (int k = 0; k < 2; ++k) \
;     dst[n][k] = *reinterpret_cast<const bf16x8*>(SB(b, h) + lds_byte(wc * 32 + n * 16 + fr, k * 32 + fq * 8))
; #define WAIT_V(n) asm volatile("s_waitcnt vmcnt(" #n ")" ::: "memory")
; #define WAIT_L(n) asm volatile("s_waitcnt lgkmcnt(" #n ")" ::: "memory")
; #define BAR __builtin_amdgcn_s_barrier()
;     ...
;       LDB(B1, 1, 1); WAIT_V(0); BAR; WAIT_L(0); MMA(0, 1, At, B1); BAR;
;       LDA(At, 1, 1); BAR; WAIT_L(0); MMA(1, 0, At, B0); MMA(1, 1, At, B1); BAR; }
;     if (wr == 0) BAR;
	ds_read_b128 v[204:207], v133
	ds_read_b128 v[208:211], v134
	ds_read_b128 v[212:215], v135
	ds_read_b128 v[134:137], v136
	s_waitcnt vmcnt(0)
	s_barrier
	s_waitcnt lgkmcnt(0)
	v_mfma_f32_16x16x32_bf16 v[96:99], v[204:207], v[64:67], v[164:167]
	v_mfma_f32_16x16x32_bf16 v[64:67], v[212:215], v[64:67], v[88:91]
	v_mfma_f32_16x16x32_bf16 v[80:83], v[204:207], v[180:183], v[80:83]
	v_mfma_f32_16x16x32_bf16 v[88:91], v[212:215], v[180:183], v[168:171]
	v_mfma_f32_16x16x32_bf16 v[60:63], v[204:207], v[188:191], v[60:63]
	v_mfma_f32_16x16x32_bf16 v[56:59], v[212:215], v[188:191], v[56:59]
	v_mfma_f32_16x16x32_bf16 v[52:55], v[204:207], v[196:199], v[52:55]
	v_mfma_f32_16x16x32_bf16 v[48:51], v[212:215], v[196:199], v[48:51]
	v_mfma_f32_16x16x32_bf16 v[120:123], v[208:211], v[72:75], v[96:99]
	v_mfma_f32_16x16x32_bf16 v[112:115], v[134:137], v[72:75], v[64:67]
	v_mfma_f32_16x16x32_bf16 v[104:107], v[208:211], v[184:187], v[80:83]
	v_mfma_f32_16x16x32_bf16 v[96:99], v[134:137], v[184:187], v[88:91]
	v_mfma_f32_16x16x32_bf16 v[88:91], v[208:211], v[192:195], v[60:63]
	v_mfma_f32_16x16x32_bf16 v[80:83], v[134:137], v[192:195], v[56:59]
	v_mfma_f32_16x16x32_bf16 v[72:75], v[208:211], v[200:203], v[52:55]
	v_mfma_f32_16x16x32_bf16 v[64:67], v[134:137], v[200:203], v[48:51]
	s_barrier
	s_nop 0
	ds_read_b128 v[48:51], v129 offset:49152
	ds_read_b128 v[162:165], v129 offset:50176
	ds_read_b128 v[52:55], v132 offset:49152
	ds_read_b128 v[166:169], v132 offset:50176
	ds_read_b128 v[180:183], v131 offset:49152
	ds_read_b128 v[184:187], v131 offset:50176
	ds_read_b128 v[188:191], v130 offset:49152
	ds_read_b128 v[130:133], v130 offset:50176
	s_barrier
	s_waitcnt lgkmcnt(0)
	v_mfma_f32_16x16x32_bf16 v[44:47], v[8:11], v[48:51], v[44:47]
	v_mfma_f32_16x16x32_bf16 v[40:43], v[176:179], v[48:51], v[40:43]
	v_mfma_f32_16x16x32_bf16 v[36:39], v[8:11], v[52:55], v[36:39]
	v_mfma_f32_16x16x32_bf16 v[32:35], v[176:179], v[52:55], v[32:35]
	v_mfma_f32_16x16x32_bf16 v[28:31], v[8:11], v[180:183], v[28:31]
	v_mfma_f32_16x16x32_bf16 v[24:27], v[176:179], v[180:183], v[24:27]
	v_mfma_f32_16x16x32_bf16 v[8:11], v[8:11], v[188:191], v[20:23]
	v_mfma_f32_16x16x32_bf16 v[16:19], v[176:179], v[188:191], v[16:19]
	v_mfma_f32_16x16x32_bf16 v[60:63], v[12:15], v[162:165], v[44:47]
	v_mfma_f32_16x16x32_bf16 v[56:59], v[138:141], v[162:165], v[40:43]
	v_mfma_f32_16x16x32_bf16 v[44:47], v[12:15], v[166:169], v[36:39]
	v_mfma_f32_16x16x32_bf16 v[40:43], v[138:141], v[166:169], v[32:35]
	v_mfma_f32_16x16x32_bf16 v[28:31], v[12:15], v[184:187], v[28:31]
	v_mfma_f32_16x16x32_bf16 v[24:27], v[138:141], v[184:187], v[24:27]
	v_mfma_f32_16x16x32_bf16 v[12:15], v[12:15], v[130:133], v[8:11]
	v_mfma_f32_16x16x32_bf16 v[8:11], v[138:141], v[130:133], v[16:19]
	v_mfma_f32_16x16x32_bf16 v[16:19], v[204:207], v[48:51], v[142:145]
	v_mfma_f32_16x16x32_bf16 v[20:23], v[212:215], v[48:51], v[146:149]
	v_mfma_f32_16x16x32_bf16 v[4:7], v[204:207], v[52:55], v[4:7]
	v_mfma_f32_16x16x32_bf16 v[0:3], v[212:215], v[52:55], v[0:3]
	v_mfma_f32_16x16x32_bf16 v[138:141], v[204:207], v[180:183], v[150:153]
	v_mfma_f32_16x16x32_bf16 v[142:145], v[212:215], v[180:183], v[154:157]
	v_mfma_f32_16x16x32_bf16 v[146:149], v[204:207], v[188:191], v[158:161]
	v_mfma_f32_16x16x32_bf16 v[150:153], v[212:215], v[188:191], v[172:175]
	v_mfma_f32_16x16x32_bf16 v[52:55], v[208:211], v[162:165], v[16:19]
	v_mfma_f32_16x16x32_bf16 v[48:51], v[134:137], v[162:165], v[20:23]
	v_mfma_f32_16x16x32_bf16 v[36:39], v[208:211], v[166:169], v[4:7]
	v_mfma_f32_16x16x32_bf16 v[32:35], v[134:137], v[166:169], v[0:3]
	v_mfma_f32_16x16x32_bf16 v[20:23], v[208:211], v[184:187], v[138:141]
	v_mfma_f32_16x16x32_bf16 v[16:19], v[134:137], v[184:187], v[142:145]
	v_mfma_f32_16x16x32_bf16 v[4:7], v[208:211], v[130:133], v[146:149]
	v_mfma_f32_16x16x32_bf16 v[0:3], v[134:137], v[130:133], v[150:153]
	v_cmp_gt_u32_e32 vcc, s73, v128
	s_barrier
	s_and_saveexec_b64 s[6:7], vcc
	s_cbranch_execz .LBB0_660
	s_barrier

; #define STAGE(P, RS, SOFF, OFF, kt) do { const int _so = (SOFF) + (kt) * (BK * 2); \
;     _Pragma("unroll") for (int _i = 0; _i < 2; ++_i) { \
;       __builtin_amdgcn_raw_ptr_buffer_load_lds(RS, (__attribute__((address_space(3))) void*)((P) + wave * 1024 + _i * 8192), 16, OFF[_i], _so, 0, 0); } } while (0)
; #define LDA(dst, b, h) _Pragma("unroll") for (int m = 0; m < 4; ++m) _Pragma("unroll") for (int k = 0; k < 2; ++k) \
;     dst[m][k] = *reinterpret_cast<const bf16x8*>(SA(b, h) + lds_byte(wr * 64 + m * 16 + fr, k * 32 + fq * 8))
; #define LDB(dst, b, h) _Pragma("unroll") for (int n = 0; n < 2; ++n) _Pragma("unroll") for (int k = 0; k < 2; ++k) \
;     dst[n][k] = *reinterpret_cast<const bf16x8*>(SB(b, h) + lds_byte(wc * 32 + n * 16 + fr, k * 32 + fq * 8))
; #define WAIT_V(n) asm volatile("s_waitcnt vmcnt(" #n ")" ::: "memory")
; #define WAIT_L(n) asm volatile("s_waitcnt lgkmcnt(" #n ")" ::: "memory")
; #define BAR __builtin_amdgcn_s_barrier()
; #define SCHED __builtin_amdgcn_sched_barrier(0)
;     ...
;     for (int t = 0; t < nt - 2; t += 2) {
;       LDB(B0, 0, 0); SCHED; LDA(At, 0, 0); STAGE(SA(1, 1), rsA, sA1, offA, t + 1);
;       WAIT_L(8); BAR; WAIT_L(0); MMA(0, 0, At, B0); BAR; SCHED;
;       LDB(B1, 0, 1); STAGE(SB(0, 0), rsB, sB0, offB, t + 2);
;       BAR; WAIT_L(0); MMA(0, 1, At, B1); BAR;
;       LDA(At, 0, 1); STAGE(SA(0, 0), rsA, sA0, offA, t + 2);
;       BAR; WAIT_L(0); MMA(1, 0, At, B0); BAR; SCHED;
;       STAGE(SB(0, 1), rsB, sB1, offB, t + 2);
;       WAIT_V(6); BAR; MMA(1, 1, At, B1); BAR;
.LBB0_757:
	ds_read_b128 v[152:155], v147
	ds_read_b128 v[156:159], v148
	ds_read_b128 v[160:163], v149
	ds_read_b128 v[164:167], v150
	s_add_i32 s6, s85, s5
	s_add_i32 s7, s6, 0x80
	s_mov_b32 m0, s39
	ds_read_b128 v[168:171], v129
	ds_read_b128 v[172:175], v129 offset:1024
	ds_read_b128 v[176:179], v132
	ds_read_b128 v[180:183], v132 offset:1024
	ds_read_b128 v[184:187], v131
	ds_read_b128 v[188:191], v131 offset:1024
	ds_read_b128 v[192:195], v130
	ds_read_b128 v[196:199], v130 offset:1024
	buffer_load_dwordx4 v141, s[8:11], s7 offen lds
	s_mov_b32 m0, s56
	s_nop 0
	buffer_load_dwordx4 v142, s[8:11], s7 offen lds
	s_waitcnt lgkmcnt(8)
	s_barrier
	s_waitcnt lgkmcnt(0)
	v_mfma_f32_16x16x32_bf16 v[124:127], v[152:155], v[168:171], v[124:127]
	v_mfma_f32_16x16x32_bf16 v[120:123], v[160:163], v[168:171], v[120:123]
	v_mfma_f32_16x16x32_bf16 v[116:119], v[152:155], v[176:179], v[116:119]
	v_mfma_f32_16x16x32_bf16 v[112:115], v[160:163], v[176:179], v[112:115]
	v_mfma_f32_16x16x32_bf16 v[108:111], v[152:155], v[184:187], v[108:111]
	v_mfma_f32_16x16x32_bf16 v[104:107], v[160:163], v[184:187], v[104:107]
	v_mfma_f32_16x16x32_bf16 v[100:103], v[152:155], v[192:195], v[100:103]
	v_mfma_f32_16x16x32_bf16 v[96:99], v[160:163], v[192:195], v[96:99]
	v_mfma_f32_16x16x32_bf16 v[124:127], v[156:159], v[172:175], v[124:127]
	v_mfma_f32_16x16x32_bf16 v[120:123], v[164:167], v[172:175], v[120:123]
	v_mfma_f32_16x16x32_bf16 v[116:119], v[156:159], v[180:183], v[116:119]
	v_mfma_f32_16x16x32_bf16 v[112:115], v[164:167], v[180:183], v[112:115]
	v_mfma_f32_16x16x32_bf16 v[108:111], v[156:159], v[188:191], v[108:111]
	v_mfma_f32_16x16x32_bf16 v[104:107], v[164:167], v[188:191], v[104:107]
	v_mfma_f32_16x16x32_bf16 v[100:103], v[156:159], v[196:199], v[100:103]
	v_mfma_f32_16x16x32_bf16 v[96:99], v[164:167], v[196:199], v[96:99]
	s_barrier
	s_add_i32 s7, s87, s5
	s_add_i32 s23, s7, 0x100
	s_mov_b32 s14, s10
	s_mov_b32 s15, s11
	s_mov_b32 m0, s42
	ds_read_b128 v[200:203], v143
	ds_read_b128 v[204:207], v144
	ds_read_b128 v[208:211], v145
	ds_read_b128 v[212:215], v146
	buffer_load_dwordx4 v141, s[12:15], s23 offen lds
	s_mov_b32 m0, s49
	s_nop 0
	buffer_load_dwordx4 v142, s[12:15], s23 offen lds
	s_barrier
	s_waitcnt lgkmcnt(0)
	v_mfma_f32_16x16x32_bf16 v[92:95], v[200:203], v[168:171], v[92:95]
	v_mfma_f32_16x16x32_bf16 v[88:91], v[208:211], v[168:171], v[88:91]
	v_mfma_f32_16x16x32_bf16 v[80:83], v[200:203], v[176:179], v[80:83]
	v_mfma_f32_16x16x32_bf16 v[68:71], v[208:211], v[176:179], v[68:71]
	v_mfma_f32_16x16x32_bf16 v[60:63], v[200:203], v[184:187], v[60:63]
	v_mfma_f32_16x16x32_bf16 v[56:59], v[208:211], v[184:187], v[56:59]
	v_mfma_f32_16x16x32_bf16 v[52:55], v[200:203], v[192:195], v[52:55]
	v_mfma_f32_16x16x32_bf16 v[48:51], v[208:211], v[192:195], v[48:51]
	v_mfma_f32_16x16x32_bf16 v[92:95], v[204:207], v[172:175], v[92:95]
	v_mfma_f32_16x16x32_bf16 v[88:91], v[212:215], v[172:175], v[88:91]
	v_mfma_f32_16x16x32_bf16 v[80:83], v[204:207], v[180:183], v[80:83]
	v_mfma_f32_16x16x32_bf16 v[68:71], v[212:215], v[180:183], v[68:71]
	v_mfma_f32_16x16x32_bf16 v[60:63], v[204:207], v[188:191], v[60:63]
	v_mfma_f32_16x16x32_bf16 v[56:59], v[212:215], v[188:191], v[56:59]
	v_mfma_f32_16x16x32_bf16 v[52:55], v[204:207], v[196:199], v[52:55]
	v_mfma_f32_16x16x32_bf16 v[48:51], v[212:215], v[196:199], v[48:51]
	s_barrier
	s_add_i32 s23, s86, s5
	s_add_i32 s26, s23, 0x100
	s_mov_b32 m0, s33
	ds_read_b128 v[168:171], v129 offset:16384
	ds_read_b128 v[172:175], v129 offset:17408
	ds_read_b128 v[176:179], v132 offset:16384
	ds_read_b128 v[180:183], v132 offset:17408
	ds_read_b128 v[184:187], v131 offset:16384
	ds_read_b128 v[188:191], v131 offset:17408
	ds_read_b128 v[192:195], v130 offset:16384
	ds_read_b128 v[196:199], v130 offset:17408
	buffer_load_dwordx4 v141, s[8:11], s26 offen lds
	s_mov_b32 m0, s50
	s_nop 0
	buffer_load_dwordx4 v142, s[8:11], s26 offen lds
	s_barrier
	s_waitcnt lgkmcnt(0)
	v_mfma_f32_16x16x32_bf16 v[44:47], v[152:155], v[168:171], v[44:47]
	v_mfma_f32_16x16x32_bf16 v[40:43], v[160:163], v[168:171], v[40:43]
	v_mfma_f32_16x16x32_bf16 v[36:39], v[152:155], v[176:179], v[36:39]
	v_mfma_f32_16x16x32_bf16 v[32:35], v[160:163], v[176:179], v[32:35]
	v_mfma_f32_16x16x32_bf16 v[28:31], v[152:155], v[184:187], v[28:31]
	v_mfma_f32_16x16x32_bf16 v[24:27], v[160:163], v[184:187], v[24:27]
	v_mfma_f32_16x16x32_bf16 v[20:23], v[152:155], v[192:195], v[20:23]
	v_mfma_f32_16x16x32_bf16 v[16:19], v[160:163], v[192:195], v[16:19]
	v_mfma_f32_16x16x32_bf16 v[44:47], v[156:159], v[172:175], v[44:47]
	v_mfma_f32_16x16x32_bf16 v[40:43], v[164:167], v[172:175], v[40:43]
	v_mfma_f32_16x16x32_bf16 v[36:39], v[156:159], v[180:183], v[36:39]
	v_mfma_f32_16x16x32_bf16 v[32:35], v[164:167], v[180:183], v[32:35]
	v_mfma_f32_16x16x32_bf16 v[28:31], v[156:159], v[188:191], v[28:31]
	v_mfma_f32_16x16x32_bf16 v[24:27], v[164:167], v[188:191], v[24:27]
	v_mfma_f32_16x16x32_bf16 v[20:23], v[156:159], v[196:199], v[20:23]
	v_mfma_f32_16x16x32_bf16 v[16:19], v[164:167], v[196:199], v[16:19]
	s_barrier
	s_add_i32 s26, s90, s5
	s_add_i32 s27, s26, 0x100
	s_mov_b32 m0, s43
	s_nop 0
	buffer_load_dwordx4 v141, s[12:15], s27 offen lds
	s_mov_b32 m0, s51
	s_nop 0
	buffer_load_dwordx4 v142, s[12:15], s27 offen lds
	s_waitcnt vmcnt(6)
	s_barrier
; #define STAGE(P, RS, SOFF, OFF, kt) do { const int _so = (SOFF) + (kt) * (BK * 2); \
;     _Pragma("unroll") for (int _i = 0; _i < 2; ++_i) { \
;       __builtin_amdgcn_raw_ptr_buffer_load_lds(RS, (__attribute__((address_space(3))) void*)((P) + wave * 1024 + _i * 8192), 16, OFF[_i], _so, 0, 0); } } while (0)
; #define LDA(dst, b, h) _Pragma("unroll") for (int m = 0; m < 4; ++m) _Pragma("unroll") for (int k = 0; k < 2; ++k) \
;     dst[m][k] = *reinterpret_cast<const bf16x8*>(SA(b, h) + lds_byte(wr * 64 + m * 16 + fr, k * 32 + fq * 8))
; #define LDB(dst, b, h) _Pragma("unroll") for (int n = 0; n < 2; ++n) _Pragma("unroll") for (int k = 0; k < 2; ++k) \
;     dst[n][k] = *reinterpret_cast<const bf16x8*>(SB(b, h) + lds_byte(wc * 32 + n * 16 + fr, k * 32 + fq * 8))
; #define WAIT_V(n) asm volatile("s_waitcnt vmcnt(" #n ")" ::: "memory")
; #define WAIT_L(n) asm volatile("s_waitcnt lgkmcnt(" #n ")" ::: "memory")
; #define BAR __builtin_amdgcn_s_barrier()
; #define SCHED __builtin_amdgcn_sched_barrier(0)
;     ...
;       WAIT_V(6); BAR; MMA(1, 1, At, B1); BAR;
;       LDB(B0, 1, 0); SCHED; LDA(At, 1, 0); STAGE(SA(0, 1), rsA, sA1, offA, t + 2);
;       WAIT_L(8); BAR; WAIT_L(0); MMA(0, 0, At, B0); BAR; SCHED;
;       LDB(B1, 1, 1); STAGE(SB(1, 0), rsB, sB0, offB, t + 3);
;       BAR; WAIT_L(0); MMA(0, 1, At, B1); BAR;
;       LDA(At, 1, 1); STAGE(SA(1, 0), rsA, sA0, offA, t + 3);
;       BAR; WAIT_L(0); MMA(1, 0, At, B0); BAR; SCHED;
;       STAGE(SB(1, 1), rsB, sB1, offB, t + 3);
;       WAIT_V(6); BAR; MMA(1, 1, At, B1); BAR;
	v_mfma_f32_16x16x32_bf16 v[12:15], v[200:203], v[168:171], v[12:15]
	v_mfma_f32_16x16x32_bf16 v[8:11], v[208:211], v[168:171], v[8:11]
	v_mfma_f32_16x16x32_bf16 v[4:7], v[200:203], v[176:179], v[4:7]
	v_mfma_f32_16x16x32_bf16 v[0:3], v[208:211], v[176:179], v[0:3]
	v_mfma_f32_16x16x32_bf16 v[64:67], v[200:203], v[184:187], v[64:67]
	v_mfma_f32_16x16x32_bf16 v[72:75], v[208:211], v[184:187], v[72:75]
	v_mfma_f32_16x16x32_bf16 v[76:79], v[200:203], v[192:195], v[76:79]
	v_mfma_f32_16x16x32_bf16 v[84:87], v[208:211], v[192:195], v[84:87]
	v_mfma_f32_16x16x32_bf16 v[12:15], v[204:207], v[172:175], v[12:15]
	v_mfma_f32_16x16x32_bf16 v[8:11], v[212:215], v[172:175], v[8:11]
	v_mfma_f32_16x16x32_bf16 v[4:7], v[204:207], v[180:183], v[4:7]
	v_mfma_f32_16x16x32_bf16 v[0:3], v[212:215], v[180:183], v[0:3]
	v_mfma_f32_16x16x32_bf16 v[64:67], v[204:207], v[188:191], v[64:67]
	v_mfma_f32_16x16x32_bf16 v[72:75], v[212:215], v[188:191], v[72:75]
	v_mfma_f32_16x16x32_bf16 v[76:79], v[204:207], v[196:199], v[76:79]
	v_mfma_f32_16x16x32_bf16 v[84:87], v[212:215], v[196:199], v[84:87]
	s_barrier
	ds_read_b128 v[152:155], v137
	ds_read_b128 v[156:159], v138
	ds_read_b128 v[160:163], v139
	ds_read_b128 v[164:167], v140
	s_addk_i32 s6, 0x100
	s_mov_b32 m0, s44
	ds_read_b128 v[168:171], v129 offset:32768
	ds_read_b128 v[172:175], v129 offset:33792
	ds_read_b128 v[176:179], v132 offset:32768
	ds_read_b128 v[180:183], v132 offset:33792
	ds_read_b128 v[184:187], v131 offset:32768
	ds_read_b128 v[188:191], v131 offset:33792
	ds_read_b128 v[192:195], v130 offset:32768
	ds_read_b128 v[196:199], v130 offset:33792
	buffer_load_dwordx4 v141, s[8:11], s6 offen lds
	s_mov_b32 m0, s52
	s_nop 0
	buffer_load_dwordx4 v142, s[8:11], s6 offen lds
	s_waitcnt lgkmcnt(8)
	s_barrier
	s_waitcnt lgkmcnt(0)
	v_mfma_f32_16x16x32_bf16 v[124:127], v[152:155], v[168:171], v[124:127]
	v_mfma_f32_16x16x32_bf16 v[120:123], v[160:163], v[168:171], v[120:123]
	v_mfma_f32_16x16x32_bf16 v[116:119], v[152:155], v[176:179], v[116:119]
	v_mfma_f32_16x16x32_bf16 v[112:115], v[160:163], v[176:179], v[112:115]
	v_mfma_f32_16x16x32_bf16 v[108:111], v[152:155], v[184:187], v[108:111]
	v_mfma_f32_16x16x32_bf16 v[104:107], v[160:163], v[184:187], v[104:107]
	v_mfma_f32_16x16x32_bf16 v[100:103], v[152:155], v[192:195], v[100:103]
	v_mfma_f32_16x16x32_bf16 v[96:99], v[160:163], v[192:195], v[96:99]
	v_mfma_f32_16x16x32_bf16 v[124:127], v[156:159], v[172:175], v[124:127]
	v_mfma_f32_16x16x32_bf16 v[120:123], v[164:167], v[172:175], v[120:123]
	v_mfma_f32_16x16x32_bf16 v[116:119], v[156:159], v[180:183], v[116:119]
	v_mfma_f32_16x16x32_bf16 v[112:115], v[164:167], v[180:183], v[112:115]
	v_mfma_f32_16x16x32_bf16 v[108:111], v[156:159], v[188:191], v[108:111]
	v_mfma_f32_16x16x32_bf16 v[104:107], v[164:167], v[188:191], v[104:107]
	v_mfma_f32_16x16x32_bf16 v[100:103], v[156:159], v[196:199], v[100:103]
	v_mfma_f32_16x16x32_bf16 v[96:99], v[164:167], v[196:199], v[96:99]
	s_barrier
	s_addk_i32 s7, 0x180
	s_mov_b32 m0, s45
	ds_read_b128 v[200:203], v133
	ds_read_b128 v[204:207], v134
	ds_read_b128 v[208:211], v135
	ds_read_b128 v[212:215], v136
	buffer_load_dwordx4 v141, s[12:15], s7 offen lds
	s_mov_b32 m0, s53
	s_nop 0
	buffer_load_dwordx4 v142, s[12:15], s7 offen lds
	s_barrier
	s_waitcnt lgkmcnt(0)
	v_mfma_f32_16x16x32_bf16 v[92:95], v[200:203], v[168:171], v[92:95]
	v_mfma_f32_16x16x32_bf16 v[88:91], v[208:211], v[168:171], v[88:91]
	v_mfma_f32_16x16x32_bf16 v[80:83], v[200:203], v[176:179], v[80:83]
	v_mfma_f32_16x16x32_bf16 v[68:71], v[208:211], v[176:179], v[68:71]
	v_mfma_f32_16x16x32_bf16 v[60:63], v[200:203], v[184:187], v[60:63]
	v_mfma_f32_16x16x32_bf16 v[56:59], v[208:211], v[184:187], v[56:59]
	v_mfma_f32_16x16x32_bf16 v[52:55], v[200:203], v[192:195], v[52:55]
	v_mfma_f32_16x16x32_bf16 v[48:51], v[208:211], v[192:195], v[48:51]
	v_mfma_f32_16x16x32_bf16 v[92:95], v[204:207], v[172:175], v[92:95]
	v_mfma_f32_16x16x32_bf16 v[88:91], v[212:215], v[172:175], v[88:91]
	v_mfma_f32_16x16x32_bf16 v[80:83], v[204:207], v[180:183], v[80:83]
	v_mfma_f32_16x16x32_bf16 v[68:71], v[212:215], v[180:183], v[68:71]
	v_mfma_f32_16x16x32_bf16 v[60:63], v[204:207], v[188:191], v[60:63]
	v_mfma_f32_16x16x32_bf16 v[56:59], v[212:215], v[188:191], v[56:59]
	v_mfma_f32_16x16x32_bf16 v[52:55], v[204:207], v[196:199], v[52:55]
	v_mfma_f32_16x16x32_bf16 v[48:51], v[212:215], v[196:199], v[48:51]
	s_barrier
	s_addk_i32 s23, 0x180
	s_mov_b32 m0, s46
	ds_read_b128 v[168:171], v129 offset:49152
	ds_read_b128 v[172:175], v129 offset:50176
	ds_read_b128 v[176:179], v132 offset:49152
	ds_read_b128 v[180:183], v132 offset:50176
	ds_read_b128 v[184:187], v131 offset:49152
	ds_read_b128 v[188:191], v131 offset:50176
	ds_read_b128 v[192:195], v130 offset:49152
	ds_read_b128 v[196:199], v130 offset:50176
	buffer_load_dwordx4 v141, s[8:11], s23 offen lds
	s_mov_b32 m0, s54
	s_nop 0
	buffer_load_dwordx4 v142, s[8:11], s23 offen lds
	s_barrier
	s_waitcnt lgkmcnt(0)
	v_mfma_f32_16x16x32_bf16 v[44:47], v[152:155], v[168:171], v[44:47]
	v_mfma_f32_16x16x32_bf16 v[40:43], v[160:163], v[168:171], v[40:43]
	v_mfma_f32_16x16x32_bf16 v[36:39], v[152:155], v[176:179], v[36:39]
	v_mfma_f32_16x16x32_bf16 v[32:35], v[160:163], v[176:179], v[32:35]
	v_mfma_f32_16x16x32_bf16 v[28:31], v[152:155], v[184:187], v[28:31]
	v_mfma_f32_16x16x32_bf16 v[24:27], v[160:163], v[184:187], v[24:27]
	v_mfma_f32_16x16x32_bf16 v[20:23], v[152:155], v[192:195], v[20:23]
	v_mfma_f32_16x16x32_bf16 v[16:19], v[160:163], v[192:195], v[16:19]
	v_mfma_f32_16x16x32_bf16 v[44:47], v[156:159], v[172:175], v[44:47]
	v_mfma_f32_16x16x32_bf16 v[40:43], v[164:167], v[172:175], v[40:43]
	v_mfma_f32_16x16x32_bf16 v[36:39], v[156:159], v[180:183], v[36:39]
	v_mfma_f32_16x16x32_bf16 v[32:35], v[164:167], v[180:183], v[32:35]
	v_mfma_f32_16x16x32_bf16 v[28:31], v[156:159], v[188:191], v[28:31]
	v_mfma_f32_16x16x32_bf16 v[24:27], v[164:167], v[188:191], v[24:27]
	v_mfma_f32_16x16x32_bf16 v[20:23], v[156:159], v[196:199], v[20:23]
	v_mfma_f32_16x16x32_bf16 v[16:19], v[164:167], v[196:199], v[16:19]
	s_barrier
; #define STAGE(P, RS, SOFF, OFF, kt) do { const int _so = (SOFF) + (kt) * (BK * 2); \
;     _Pragma("unroll") for (int _i = 0; _i < 2; ++_i) { \
;       __builtin_amdgcn_raw_ptr_buffer_load_lds(RS, (__attribute__((address_space(3))) void*)((P) + wave * 1024 + _i * 8192), 16, OFF[_i], _so, 0, 0); } } while (0)
; #define LDA(dst, b, h) _Pragma("unroll") for (int m = 0; m < 4; ++m) _Pragma("unroll") for (int k = 0; k < 2; ++k) \
;     dst[m][k] = *reinterpret_cast<const bf16x8*>(SA(b, h) + lds_byte(wr * 64 + m * 16 + fr, k * 32 + fq * 8))
; #define LDB(dst, b, h) _Pragma("unroll") for (int n = 0; n < 2; ++n) _Pragma("unroll") for (int k = 0; k < 2; ++k) \
;     dst[n][k] = *reinterpret_cast<const bf16x8*>(SB(b, h) + lds_byte(wc * 32 + n * 16 + fr, k * 32 + fq * 8))
; #define WAIT_V(n) asm volatile("s_waitcnt vmcnt(" #n ")" ::: "memory")
; #define WAIT_L(n) asm volatile("s_waitcnt lgkmcnt(" #n ")" ::: "memory")
; #define BAR __builtin_amdgcn_s_barrier()
;     ...
;       WAIT_V(6); BAR; MMA(1, 1, At, B1); BAR;
;     }
;     { LDB(B0, 0, 0); LDA(At, 0, 0); STAGE(SA(1, 1), rsA, sA1, offA, nt - 1);
;       BAR; WAIT_L(0); MMA(0, 0, At, B0); BAR;
;       LDB(B1, 0, 1); BAR; WAIT_L(0); MMA(0, 1, At, B1); BAR;
;       LDA(At, 0, 1); WAIT_V(4); BAR; WAIT_L(0); MMA(1, 0, At, B0); MMA(1, 1, At, B1); BAR; }
	s_addk_i32 s26, 0x180
	s_mov_b32 m0, s47
	s_nop 0
	buffer_load_dwordx4 v141, s[12:15], s26 offen lds
	s_mov_b32 m0, s55
	s_nop 0
	buffer_load_dwordx4 v142, s[12:15], s26 offen lds
	s_waitcnt vmcnt(6)
	s_barrier
	v_mfma_f32_16x16x32_bf16 v[12:15], v[200:203], v[168:171], v[12:15]
	v_mfma_f32_16x16x32_bf16 v[8:11], v[208:211], v[168:171], v[8:11]
	v_mfma_f32_16x16x32_bf16 v[4:7], v[200:203], v[176:179], v[4:7]
	v_mfma_f32_16x16x32_bf16 v[0:3], v[208:211], v[176:179], v[0:3]
	v_mfma_f32_16x16x32_bf16 v[64:67], v[200:203], v[184:187], v[64:67]
	v_mfma_f32_16x16x32_bf16 v[72:75], v[208:211], v[184:187], v[72:75]
	v_mfma_f32_16x16x32_bf16 v[76:79], v[200:203], v[192:195], v[76:79]
	v_mfma_f32_16x16x32_bf16 v[84:87], v[208:211], v[192:195], v[84:87]
	v_mfma_f32_16x16x32_bf16 v[12:15], v[204:207], v[172:175], v[12:15]
	v_mfma_f32_16x16x32_bf16 v[8:11], v[212:215], v[172:175], v[8:11]
	v_mfma_f32_16x16x32_bf16 v[4:7], v[204:207], v[180:183], v[4:7]
	v_mfma_f32_16x16x32_bf16 v[0:3], v[212:215], v[180:183], v[0:3]
	v_mfma_f32_16x16x32_bf16 v[64:67], v[204:207], v[188:191], v[64:67]
	v_mfma_f32_16x16x32_bf16 v[72:75], v[212:215], v[188:191], v[72:75]
	v_mfma_f32_16x16x32_bf16 v[76:79], v[204:207], v[196:199], v[76:79]
	v_mfma_f32_16x16x32_bf16 v[84:87], v[212:215], v[196:199], v[84:87]
	s_barrier
	s_add_i32 s4, s4, 2
	s_addk_i32 s5, 0x100
	s_cmp_gt_u32 s4, 59
	s_cbranch_scc0 .LBB0_757
	s_add_i32 s4, s85, 0x1f80
	s_mov_b32 m0, s39
	ds_read_b128 v[152:155], v147
	ds_read_b128 v[156:159], v148
	ds_read_b128 v[160:163], v149
	ds_read_b128 v[148:151], v150
	ds_read_b128 v[164:167], v129
	ds_read_b128 v[168:171], v129 offset:1024
	ds_read_b128 v[172:175], v132
	ds_read_b128 v[176:179], v132 offset:1024
	ds_read_b128 v[180:183], v131
	ds_read_b128 v[184:187], v131 offset:1024
	ds_read_b128 v[188:191], v130
	ds_read_b128 v[192:195], v130 offset:1024
	buffer_load_dwordx4 v141, s[8:11], s4 offen lds
	s_mov_b32 m0, s56
	s_nop 0
	buffer_load_dwordx4 v142, s[8:11], s4 offen lds
	s_barrier
	s_waitcnt lgkmcnt(0)
	v_mfma_f32_16x16x32_bf16 v[124:127], v[152:155], v[164:167], v[124:127]
	v_mfma_f32_16x16x32_bf16 v[120:123], v[160:163], v[164:167], v[120:123]
	v_mfma_f32_16x16x32_bf16 v[116:119], v[152:155], v[172:175], v[116:119]
	v_mfma_f32_16x16x32_bf16 v[112:115], v[160:163], v[172:175], v[112:115]
	v_mfma_f32_16x16x32_bf16 v[108:111], v[152:155], v[180:183], v[108:111]
	v_mfma_f32_16x16x32_bf16 v[104:107], v[160:163], v[180:183], v[104:107]
	v_mfma_f32_16x16x32_bf16 v[100:103], v[152:155], v[188:191], v[100:103]
	v_mfma_f32_16x16x32_bf16 v[96:99], v[160:163], v[188:191], v[96:99]
	v_mfma_f32_16x16x32_bf16 v[124:127], v[156:159], v[168:171], v[124:127]
	v_mfma_f32_16x16x32_bf16 v[120:123], v[148:151], v[168:171], v[120:123]
	v_mfma_f32_16x16x32_bf16 v[116:119], v[156:159], v[176:179], v[116:119]
	v_mfma_f32_16x16x32_bf16 v[112:115], v[148:151], v[176:179], v[112:115]
	v_mfma_f32_16x16x32_bf16 v[108:111], v[156:159], v[184:187], v[108:111]
	v_mfma_f32_16x16x32_bf16 v[104:107], v[148:151], v[184:187], v[104:107]
	v_mfma_f32_16x16x32_bf16 v[100:103], v[156:159], v[192:195], v[100:103]
	v_mfma_f32_16x16x32_bf16 v[96:99], v[148:151], v[192:195], v[96:99]
	s_barrier
	ds_read_b128 v[196:199], v143
	ds_read_b128 v[200:203], v144
	ds_read_b128 v[142:145], v145
	ds_read_b128 v[204:207], v146
	s_barrier
	s_waitcnt lgkmcnt(0)
	v_mfma_f32_16x16x32_bf16 v[88:91], v[142:145], v[164:167], v[88:91]
	v_mfma_f32_16x16x32_bf16 v[80:83], v[196:199], v[172:175], v[80:83]
	v_mfma_f32_16x16x32_bf16 v[60:63], v[196:199], v[180:183], v[60:63]
	v_mfma_f32_16x16x32_bf16 v[56:59], v[142:145], v[180:183], v[56:59]
	v_mfma_f32_16x16x32_bf16 v[52:55], v[196:199], v[188:191], v[52:55]
	v_mfma_f32_16x16x32_bf16 v[48:51], v[142:145], v[188:191], v[48:51]
	v_mfma_f32_16x16x32_bf16 v[92:95], v[196:199], v[164:167], v[92:95]
	v_mfma_f32_16x16x32_bf16 v[68:71], v[142:145], v[172:175], v[68:71]
	v_mfma_f32_16x16x32_bf16 v[88:91], v[204:207], v[168:171], v[88:91]
	v_mfma_f32_16x16x32_bf16 v[80:83], v[200:203], v[176:179], v[80:83]
	v_mfma_f32_16x16x32_bf16 v[60:63], v[200:203], v[184:187], v[60:63]
	v_mfma_f32_16x16x32_bf16 v[56:59], v[204:207], v[184:187], v[56:59]
	v_mfma_f32_16x16x32_bf16 v[52:55], v[200:203], v[192:195], v[52:55]
	v_mfma_f32_16x16x32_bf16 v[48:51], v[204:207], v[192:195], v[48:51]
	v_mfma_f32_16x16x32_bf16 v[164:167], v[200:203], v[168:171], v[92:95]
	v_mfma_f32_16x16x32_bf16 v[168:171], v[204:207], v[176:179], v[68:71]
	s_barrier
	s_nop 0
	ds_read_b128 v[68:71], v129 offset:16384
	ds_read_b128 v[92:95], v129 offset:17408
	ds_read_b128 v[172:175], v132 offset:16384
	ds_read_b128 v[176:179], v132 offset:17408
	ds_read_b128 v[180:183], v131 offset:16384
	ds_read_b128 v[184:187], v131 offset:17408
	ds_read_b128 v[188:191], v130 offset:16384
	ds_read_b128 v[192:195], v130 offset:17408
	s_waitcnt vmcnt(4)
	s_barrier
; #define LDA(dst, b, h) _Pragma("unroll") for (int m = 0; m < 4; ++m) _Pragma("unroll") for (int k = 0; k < 2; ++k) \
;     dst[m][k] = *reinterpret_cast<const bf16x8*>(SA(b, h) + lds_byte(wr * 64 + m * 16 + fr, k * 32 + fq * 8))
; #define LDB(dst, b, h) _Pragma("unroll") for (int n = 0; n < 2; ++n) _Pragma("unroll") for (int k = 0; k < 2; ++k) \
;     dst[n][k] = *reinterpret_cast<const bf16x8*>(SB(b, h) + lds_byte(wc * 32 + n * 16 + fr, k * 32 + fq * 8))
; #define WAIT_V(n) asm volatile("s_waitcnt vmcnt(" #n ")" ::: "memory")
; #define WAIT_L(n) asm volatile("s_waitcnt lgkmcnt(" #n ")" ::: "memory")
; #define BAR __builtin_amdgcn_s_barrier()
;     ...
;       LDA(At, 0, 1); WAIT_V(4); BAR; WAIT_L(0); MMA(1, 0, At, B0); MMA(1, 1, At, B1); BAR; }
;     { LDB(B0, 1, 0); LDA(At, 1, 0); WAIT_V(2); BAR; WAIT_L(0); MMA(0, 0, At, B0); BAR;
	s_waitcnt lgkmcnt(0)
	v_mfma_f32_16x16x32_bf16 v[44:47], v[152:155], v[68:71], v[44:47]
	v_mfma_f32_16x16x32_bf16 v[40:43], v[160:163], v[68:71], v[40:43]
	v_mfma_f32_16x16x32_bf16 v[36:39], v[152:155], v[172:175], v[36:39]
	v_mfma_f32_16x16x32_bf16 v[32:35], v[160:163], v[172:175], v[32:35]
	v_mfma_f32_16x16x32_bf16 v[28:31], v[152:155], v[180:183], v[28:31]
	v_mfma_f32_16x16x32_bf16 v[24:27], v[160:163], v[180:183], v[24:27]
	v_mfma_f32_16x16x32_bf16 v[20:23], v[152:155], v[188:191], v[20:23]
	v_mfma_f32_16x16x32_bf16 v[16:19], v[160:163], v[188:191], v[16:19]
	v_mfma_f32_16x16x32_bf16 v[44:47], v[156:159], v[92:95], v[44:47]
	v_mfma_f32_16x16x32_bf16 v[40:43], v[148:151], v[92:95], v[40:43]
	v_mfma_f32_16x16x32_bf16 v[36:39], v[156:159], v[176:179], v[36:39]
	v_mfma_f32_16x16x32_bf16 v[32:35], v[148:151], v[176:179], v[32:35]
	v_mfma_f32_16x16x32_bf16 v[28:31], v[156:159], v[184:187], v[28:31]
	v_mfma_f32_16x16x32_bf16 v[24:27], v[148:151], v[184:187], v[24:27]
	v_mfma_f32_16x16x32_bf16 v[20:23], v[156:159], v[192:195], v[20:23]
	v_mfma_f32_16x16x32_bf16 v[16:19], v[148:151], v[192:195], v[16:19]
	v_mfma_f32_16x16x32_bf16 v[4:7], v[196:199], v[172:175], v[4:7]
	v_mfma_f32_16x16x32_bf16 v[0:3], v[142:145], v[172:175], v[0:3]
	v_mfma_f32_16x16x32_bf16 v[12:15], v[196:199], v[68:71], v[12:15]
	v_mfma_f32_16x16x32_bf16 v[8:11], v[142:145], v[68:71], v[8:11]
	v_mfma_f32_16x16x32_bf16 v[64:67], v[196:199], v[180:183], v[64:67]
	v_mfma_f32_16x16x32_bf16 v[68:71], v[142:145], v[180:183], v[72:75]
	v_mfma_f32_16x16x32_bf16 v[72:75], v[196:199], v[188:191], v[76:79]
	v_mfma_f32_16x16x32_bf16 v[76:79], v[142:145], v[188:191], v[84:87]
	v_mfma_f32_16x16x32_bf16 v[4:7], v[200:203], v[176:179], v[4:7]
	v_mfma_f32_16x16x32_bf16 v[0:3], v[204:207], v[176:179], v[0:3]
	v_mfma_f32_16x16x32_bf16 v[142:145], v[200:203], v[92:95], v[12:15]
	v_mfma_f32_16x16x32_bf16 v[146:149], v[204:207], v[92:95], v[8:11]
	v_mfma_f32_16x16x32_bf16 v[150:153], v[200:203], v[184:187], v[64:67]
	v_mfma_f32_16x16x32_bf16 v[154:157], v[204:207], v[184:187], v[68:71]
	v_mfma_f32_16x16x32_bf16 v[158:161], v[200:203], v[192:195], v[72:75]
	v_mfma_f32_16x16x32_bf16 v[172:175], v[204:207], v[192:195], v[76:79]
	s_barrier
	ds_read_b128 v[8:11], v137
	ds_read_b128 v[12:15], v138
	ds_read_b128 v[176:179], v139
	ds_read_b128 v[138:141], v140
	ds_read_b128 v[64:67], v129 offset:32768
	ds_read_b128 v[72:75], v129 offset:33792
	ds_read_b128 v[180:183], v132 offset:32768
	ds_read_b128 v[184:187], v132 offset:33792
	ds_read_b128 v[188:191], v131 offset:32768
	ds_read_b128 v[192:195], v131 offset:33792
	ds_read_b128 v[196:199], v130 offset:32768
	ds_read_b128 v[200:203], v130 offset:33792
	s_waitcnt vmcnt(2)
	s_barrier
	s_waitcnt lgkmcnt(0)
	v_mfma_f32_16x16x32_bf16 v[68:71], v[8:11], v[64:67], v[124:127]
	v_mfma_f32_16x16x32_bf16 v[76:79], v[176:179], v[64:67], v[120:123]
	v_mfma_f32_16x16x32_bf16 v[84:87], v[8:11], v[180:183], v[116:119]
	v_mfma_f32_16x16x32_bf16 v[92:95], v[176:179], v[180:183], v[112:115]
	v_mfma_f32_16x16x32_bf16 v[112:115], v[8:11], v[188:191], v[108:111]
	v_mfma_f32_16x16x32_bf16 v[104:107], v[176:179], v[188:191], v[104:107]
	v_mfma_f32_16x16x32_bf16 v[120:123], v[8:11], v[196:199], v[100:103]
	v_mfma_f32_16x16x32_bf16 v[96:99], v[176:179], v[196:199], v[96:99]
	v_mfma_f32_16x16x32_bf16 v[124:127], v[12:15], v[72:75], v[68:71]
	v_mfma_f32_16x16x32_bf16 v[116:119], v[138:141], v[72:75], v[76:79]
	v_mfma_f32_16x16x32_bf16 v[108:111], v[12:15], v[184:187], v[84:87]
	v_mfma_f32_16x16x32_bf16 v[100:103], v[138:141], v[184:187], v[92:95]
	v_mfma_f32_16x16x32_bf16 v[92:95], v[12:15], v[192:195], v[112:115]
	v_mfma_f32_16x16x32_bf16 v[84:87], v[138:141], v[192:195], v[104:107]
	v_mfma_f32_16x16x32_bf16 v[76:79], v[12:15], v[200:203], v[120:123]
	v_mfma_f32_16x16x32_bf16 v[68:71], v[138:141], v[200:203], v[96:99]
	s_barrier
; #define LDA(dst, b, h) _Pragma("unroll") for (int m = 0; m < 4; ++m) _Pragma("unroll") for (int k = 0; k < 2; ++k) \
;     dst[m][k] = *reinterpret_cast<const bf16x8*>(SA(b, h) + lds_byte(wr * 64 + m * 16 + fr, k * 32 + fq * 8))
; #define LDB(dst, b, h) _Pragma("unroll") for (int n = 0; n < 2; ++n) _Pragma("unroll") for (int k = 0; k < 2; ++k) \
;     dst[n][k] = *reinterpret_cast<const bf16x8*>(SB(b, h) + lds_byte(wc * 32 + n * 16 + fr, k * 32 + fq * 8))
; #define WAIT_V(n) asm volatile("s_waitcnt vmcnt(" #n ")" ::: "memory")
; #define WAIT_L(n) asm volatile("s_waitcnt lgkmcnt(" #n ")" ::: "memory")
; #define BAR __builtin_amdgcn_s_barrier()
;     ...
;       LDB(B1, 1, 1); WAIT_V(0); BAR; WAIT_L(0); MMA(0, 1, At, B1); BAR;
;       LDA(At, 1, 1); BAR; WAIT_L(0); MMA(1, 0, At, B0); MMA(1, 1, At, B1); BAR; }
;     if (wr == 0) BAR;
	ds_read_b128 v[204:207], v133
	ds_read_b128 v[208:211], v134
	ds_read_b128 v[212:215], v135
	ds_read_b128 v[134:137], v136
	s_waitcnt vmcnt(0)
	s_barrier
	s_waitcnt lgkmcnt(0)
	v_mfma_f32_16x16x32_bf16 v[96:99], v[204:207], v[64:67], v[164:167]
	v_mfma_f32_16x16x32_bf16 v[64:67], v[212:215], v[64:67], v[88:91]
	v_mfma_f32_16x16x32_bf16 v[80:83], v[204:207], v[180:183], v[80:83]
	v_mfma_f32_16x16x32_bf16 v[88:91], v[212:215], v[180:183], v[168:171]
	v_mfma_f32_16x16x32_bf16 v[60:63], v[204:207], v[188:191], v[60:63]
	v_mfma_f32_16x16x32_bf16 v[56:59], v[212:215], v[188:191], v[56:59]
	v_mfma_f32_16x16x32_bf16 v[52:55], v[204:207], v[196:199], v[52:55]
	v_mfma_f32_16x16x32_bf16 v[48:51], v[212:215], v[196:199], v[48:51]
	v_mfma_f32_16x16x32_bf16 v[120:123], v[208:211], v[72:75], v[96:99]
	v_mfma_f32_16x16x32_bf16 v[112:115], v[134:137], v[72:75], v[64:67]
	v_mfma_f32_16x16x32_bf16 v[104:107], v[208:211], v[184:187], v[80:83]
	v_mfma_f32_16x16x32_bf16 v[96:99], v[134:137], v[184:187], v[88:91]
	v_mfma_f32_16x16x32_bf16 v[88:91], v[208:211], v[192:195], v[60:63]
	v_mfma_f32_16x16x32_bf16 v[80:83], v[134:137], v[192:195], v[56:59]
	v_mfma_f32_16x16x32_bf16 v[72:75], v[208:211], v[200:203], v[52:55]
	v_mfma_f32_16x16x32_bf16 v[64:67], v[134:137], v[200:203], v[48:51]
	s_barrier
	s_nop 0
	ds_read_b128 v[48:51], v129 offset:49152
	ds_read_b128 v[162:165], v129 offset:50176
	ds_read_b128 v[52:55], v132 offset:49152
	ds_read_b128 v[166:169], v132 offset:50176
	ds_read_b128 v[180:183], v131 offset:49152
	ds_read_b128 v[184:187], v131 offset:50176
	ds_read_b128 v[188:191], v130 offset:49152
	ds_read_b128 v[130:133], v130 offset:50176
	s_barrier
	s_waitcnt lgkmcnt(0)
	v_mfma_f32_16x16x32_bf16 v[44:47], v[8:11], v[48:51], v[44:47]
	v_mfma_f32_16x16x32_bf16 v[40:43], v[176:179], v[48:51], v[40:43]
	v_mfma_f32_16x16x32_bf16 v[36:39], v[8:11], v[52:55], v[36:39]
	v_mfma_f32_16x16x32_bf16 v[32:35], v[176:179], v[52:55], v[32:35]
	v_mfma_f32_16x16x32_bf16 v[28:31], v[8:11], v[180:183], v[28:31]
	v_mfma_f32_16x16x32_bf16 v[24:27], v[176:179], v[180:183], v[24:27]
	v_mfma_f32_16x16x32_bf16 v[8:11], v[8:11], v[188:191], v[20:23]
	v_mfma_f32_16x16x32_bf16 v[16:19], v[176:179], v[188:191], v[16:19]
	v_mfma_f32_16x16x32_bf16 v[60:63], v[12:15], v[162:165], v[44:47]
	v_mfma_f32_16x16x32_bf16 v[56:59], v[138:141], v[162:165], v[40:43]
	v_mfma_f32_16x16x32_bf16 v[44:47], v[12:15], v[166:169], v[36:39]
	v_mfma_f32_16x16x32_bf16 v[40:43], v[138:141], v[166:169], v[32:35]
	v_mfma_f32_16x16x32_bf16 v[28:31], v[12:15], v[184:187], v[28:31]
	v_mfma_f32_16x16x32_bf16 v[24:27], v[138:141], v[184:187], v[24:27]
	v_mfma_f32_16x16x32_bf16 v[12:15], v[12:15], v[130:133], v[8:11]
	v_mfma_f32_16x16x32_bf16 v[8:11], v[138:141], v[130:133], v[16:19]
	v_mfma_f32_16x16x32_bf16 v[16:19], v[204:207], v[48:51], v[142:145]
	v_mfma_f32_16x16x32_bf16 v[20:23], v[212:215], v[48:51], v[146:149]
	v_mfma_f32_16x16x32_bf16 v[4:7], v[204:207], v[52:55], v[4:7]
	v_mfma_f32_16x16x32_bf16 v[0:3], v[212:215], v[52:55], v[0:3]
	v_mfma_f32_16x16x32_bf16 v[138:141], v[204:207], v[180:183], v[150:153]
	v_mfma_f32_16x16x32_bf16 v[142:145], v[212:215], v[180:183], v[154:157]
	v_mfma_f32_16x16x32_bf16 v[146:149], v[204:207], v[188:191], v[158:161]
	v_mfma_f32_16x16x32_bf16 v[150:153], v[212:215], v[188:191], v[172:175]
	v_mfma_f32_16x16x32_bf16 v[52:55], v[208:211], v[162:165], v[16:19]
	v_mfma_f32_16x16x32_bf16 v[48:51], v[134:137], v[162:165], v[20:23]
	v_mfma_f32_16x16x32_bf16 v[36:39], v[208:211], v[166:169], v[4:7]
	v_mfma_f32_16x16x32_bf16 v[32:35], v[134:137], v[166:169], v[0:3]
	v_mfma_f32_16x16x32_bf16 v[20:23], v[208:211], v[184:187], v[138:141]
	v_mfma_f32_16x16x32_bf16 v[16:19], v[134:137], v[184:187], v[142:145]
	v_mfma_f32_16x16x32_bf16 v[4:7], v[208:211], v[130:133], v[146:149]
	v_mfma_f32_16x16x32_bf16 v[0:3], v[134:137], v[130:133], v[150:153]
	v_cmp_gt_u32_e32 vcc, s74, v128
	s_barrier
	s_and_saveexec_b64 s[4:5], vcc
	s_cbranch_execz .LBB0_760
	s_barrier
